# k34: k27 + the redundant second lgkmcnt(0) wait after each K-loop segment barrier removed (72 waits; the wait before the barrier already covers the LDS reads)
# speedup vs baseline: 1.0032x; 1.0032x over previous
.LBB0_202:
	ds_read_b128 v[148:151], v167
	ds_read_b128 v[152:155], v167 offset:1024
	ds_read_b128 v[156:159], v167 offset:2048
	ds_read_b128 v[160:163], v167 offset:3072
	ds_read_b128 v[172:175], v168
	ds_read_b128 v[176:179], v168 offset:1024
	ds_read_b128 v[180:183], v168 offset:2048
	ds_read_b128 v[184:187], v168 offset:3072
	s_add_u32 s0, s28, 0xfffc0080
	s_addc_u32 s1, s29, -1
	s_cmp_eq_u32 s51, 12
	s_cselect_b32 s31, s21, s1
	s_cselect_b32 s30, s47, s0
	s_cselect_b32 s3, s19, s50
	s_cselect_b32 s2, s48, s49
	v_lshl_add_u64 v[220:221], s[28:29], 0, v[140:141]
	s_add_i32 m0, s27, 0xc000
	ds_read_b128 v[188:191], v169
	ds_read_b128 v[192:195], v169 offset:1024
	ds_read_b128 v[196:199], v169 offset:2048
	ds_read_b128 v[200:203], v169 offset:3072
	ds_read_b128 v[204:207], v169 offset:4096
	ds_read_b128 v[208:211], v169 offset:5120
	ds_read_b128 v[212:215], v169 offset:6144
	ds_read_b128 v[216:219], v169 offset:7168
	global_load_lds_dwordx4 v[220:221], off
	v_lshl_add_u64 v[220:221], s[28:29], 0, v[142:143]
	s_add_i32 m0, s27, 0xe000
	s_nop 0
	global_load_lds_dwordx4 v[220:221], off
	s_waitcnt vmcnt(8)
	s_waitcnt lgkmcnt(0)
	s_barrier
	s_setprio 1
	v_mfma_f32_16x16x32_bf16 v[126:129], v[148:151], v[188:191], v[126:129]
	v_mfma_f32_16x16x32_bf16 v[126:129], v[152:155], v[192:195], v[126:129]
	v_mfma_f32_16x16x32_bf16 v[118:121], v[156:159], v[188:191], v[118:121]
	v_mfma_f32_16x16x32_bf16 v[118:121], v[160:163], v[192:195], v[118:121]
	v_mfma_f32_16x16x32_bf16 v[110:113], v[148:151], v[196:199], v[110:113]
	v_mfma_f32_16x16x32_bf16 v[110:113], v[152:155], v[200:203], v[110:113]
	v_mfma_f32_16x16x32_bf16 v[106:109], v[156:159], v[196:199], v[106:109]
	v_mfma_f32_16x16x32_bf16 v[106:109], v[160:163], v[200:203], v[106:109]
	v_mfma_f32_16x16x32_bf16 v[94:97], v[148:151], v[204:207], v[94:97]
	v_mfma_f32_16x16x32_bf16 v[94:97], v[152:155], v[208:211], v[94:97]
	v_mfma_f32_16x16x32_bf16 v[90:93], v[156:159], v[204:207], v[90:93]
	v_mfma_f32_16x16x32_bf16 v[90:93], v[160:163], v[208:211], v[90:93]
	v_mfma_f32_16x16x32_bf16 v[78:81], v[148:151], v[212:215], v[78:81]
	v_mfma_f32_16x16x32_bf16 v[78:81], v[152:155], v[216:219], v[78:81]
	v_mfma_f32_16x16x32_bf16 v[74:77], v[156:159], v[212:215], v[74:77]
	v_mfma_f32_16x16x32_bf16 v[74:77], v[160:163], v[216:219], v[74:77]
	s_setprio 0
	s_setprio 1
	v_mfma_f32_16x16x32_bf16 v[122:125], v[172:175], v[188:191], v[122:125]
	v_mfma_f32_16x16x32_bf16 v[122:125], v[176:179], v[192:195], v[122:125]
	v_mfma_f32_16x16x32_bf16 v[114:117], v[180:183], v[188:191], v[114:117]
	v_mfma_f32_16x16x32_bf16 v[114:117], v[184:187], v[192:195], v[114:117]
	v_mfma_f32_16x16x32_bf16 v[102:105], v[172:175], v[196:199], v[102:105]
	v_mfma_f32_16x16x32_bf16 v[102:105], v[176:179], v[200:203], v[102:105]
	v_mfma_f32_16x16x32_bf16 v[98:101], v[180:183], v[196:199], v[98:101]
	v_mfma_f32_16x16x32_bf16 v[98:101], v[184:187], v[200:203], v[98:101]
	v_mfma_f32_16x16x32_bf16 v[86:89], v[172:175], v[204:207], v[86:89]
	v_mfma_f32_16x16x32_bf16 v[86:89], v[176:179], v[208:211], v[86:89]
	v_mfma_f32_16x16x32_bf16 v[82:85], v[180:183], v[204:207], v[82:85]
	v_mfma_f32_16x16x32_bf16 v[82:85], v[184:187], v[208:211], v[82:85]
	v_mfma_f32_16x16x32_bf16 v[70:73], v[172:175], v[212:215], v[70:73]
	v_mfma_f32_16x16x32_bf16 v[70:73], v[176:179], v[216:219], v[70:73]
	v_mfma_f32_16x16x32_bf16 v[66:69], v[180:183], v[212:215], v[66:69]
	v_mfma_f32_16x16x32_bf16 v[66:69], v[184:187], v[216:219], v[66:69]
	s_setprio 0
	s_barrier
	s_add_i32 s0, s43, s36
	v_lshl_add_u64 v[220:221], s[2:3], 0, v[132:133]
	s_mov_b32 m0, s0
	ds_read_b128 v[188:191], v169 offset:16384
	ds_read_b128 v[192:195], v169 offset:17408
	ds_read_b128 v[196:199], v169 offset:18432
	ds_read_b128 v[200:203], v169 offset:19456
	ds_read_b128 v[204:207], v169 offset:20480
	ds_read_b128 v[208:211], v169 offset:21504
	ds_read_b128 v[212:215], v169 offset:22528
	ds_read_b128 v[216:219], v169 offset:23552
	global_load_lds_dwordx4 v[220:221], off
	s_add_i32 m0, s0, 0x2000
	s_add_u32 s0, s2, 0x40000
	v_lshl_add_u64 v[222:223], s[2:3], 0, v[136:137]
	s_addc_u32 s1, s3, 0
	s_add_i32 s52, s44, s36
	global_load_lds_dwordx4 v[222:223], off
	v_lshl_add_u64 v[224:225], s[0:1], 0, v[132:133]
	s_mov_b32 m0, s52
	v_lshl_add_u64 v[226:227], s[30:31], 0, v[134:135]
	global_load_lds_dwordx4 v[224:225], off
	v_lshl_add_u64 v[224:225], s[0:1], 0, v[136:137]
	s_add_i32 m0, s52, 0x2000
	s_nop 0
	global_load_lds_dwordx4 v[224:225], off
	v_lshl_add_u64 v[224:225], s[30:31], 0, v[130:131]
	s_mov_b32 m0, s27
	s_nop 0
	global_load_lds_dwordx4 v[224:225], off
	s_mov_b32 m0, s37
	s_nop 0
	global_load_lds_dwordx4 v[226:227], off
	s_waitcnt vmcnt(8)
	s_waitcnt lgkmcnt(0)
	s_barrier
	s_setprio 1
	v_mfma_f32_16x16x32_bf16 v[62:65], v[148:151], v[188:191], v[62:65]
	v_mfma_f32_16x16x32_bf16 v[62:65], v[152:155], v[192:195], v[62:65]
	v_mfma_f32_16x16x32_bf16 v[58:61], v[156:159], v[188:191], v[58:61]
	v_mfma_f32_16x16x32_bf16 v[58:61], v[160:163], v[192:195], v[58:61]
	v_mfma_f32_16x16x32_bf16 v[46:49], v[148:151], v[196:199], v[46:49]
	v_mfma_f32_16x16x32_bf16 v[46:49], v[152:155], v[200:203], v[46:49]
	v_mfma_f32_16x16x32_bf16 v[42:45], v[156:159], v[196:199], v[42:45]
	v_mfma_f32_16x16x32_bf16 v[42:45], v[160:163], v[200:203], v[42:45]
	v_mfma_f32_16x16x32_bf16 v[30:33], v[148:151], v[204:207], v[30:33]
	v_mfma_f32_16x16x32_bf16 v[30:33], v[152:155], v[208:211], v[30:33]
	v_mfma_f32_16x16x32_bf16 v[26:29], v[156:159], v[204:207], v[26:29]
	v_mfma_f32_16x16x32_bf16 v[26:29], v[160:163], v[208:211], v[26:29]
	v_mfma_f32_16x16x32_bf16 v[14:17], v[148:151], v[212:215], v[14:17]
	v_mfma_f32_16x16x32_bf16 v[14:17], v[152:155], v[216:219], v[14:17]
	v_mfma_f32_16x16x32_bf16 v[10:13], v[156:159], v[212:215], v[10:13]
	v_mfma_f32_16x16x32_bf16 v[10:13], v[160:163], v[216:219], v[10:13]
	s_setprio 0
	s_setprio 1
	v_mfma_f32_16x16x32_bf16 v[54:57], v[172:175], v[188:191], v[54:57]
	v_mfma_f32_16x16x32_bf16 v[54:57], v[176:179], v[192:195], v[54:57]
	v_mfma_f32_16x16x32_bf16 v[50:53], v[180:183], v[188:191], v[50:53]
	v_mfma_f32_16x16x32_bf16 v[50:53], v[184:187], v[192:195], v[50:53]
	v_mfma_f32_16x16x32_bf16 v[38:41], v[172:175], v[196:199], v[38:41]
	v_mfma_f32_16x16x32_bf16 v[38:41], v[176:179], v[200:203], v[38:41]
	v_mfma_f32_16x16x32_bf16 v[34:37], v[180:183], v[196:199], v[34:37]
	v_mfma_f32_16x16x32_bf16 v[34:37], v[184:187], v[200:203], v[34:37]
	v_mfma_f32_16x16x32_bf16 v[22:25], v[172:175], v[204:207], v[22:25]
	v_mfma_f32_16x16x32_bf16 v[22:25], v[176:179], v[208:211], v[22:25]
	v_mfma_f32_16x16x32_bf16 v[18:21], v[180:183], v[204:207], v[18:21]
	v_mfma_f32_16x16x32_bf16 v[18:21], v[184:187], v[208:211], v[18:21]
	v_mfma_f32_16x16x32_bf16 v[6:9], v[172:175], v[212:215], v[6:9]
	v_mfma_f32_16x16x32_bf16 v[6:9], v[176:179], v[216:219], v[6:9]
	v_mfma_f32_16x16x32_bf16 v[2:5], v[180:183], v[212:215], v[2:5]
	v_mfma_f32_16x16x32_bf16 v[2:5], v[184:187], v[216:219], v[2:5]
	s_setprio 0
	s_barrier
	s_add_i32 s52, 0, 0x18000
	s_add_i32 s53, 0, 0x1c000
	v_add_u32_e32 v160, s52, v166
	v_add_u32_e32 v164, s53, v166
	ds_read_b128 v[148:151], v160
	ds_read_b128 v[152:155], v160 offset:1024
	ds_read_b128 v[156:159], v160 offset:2048
	ds_read_b128 v[160:163], v160 offset:3072
	ds_read_b128 v[172:175], v164
	ds_read_b128 v[176:179], v164 offset:1024
	ds_read_b128 v[180:183], v164 offset:2048
	ds_read_b128 v[184:187], v164 offset:3072
	s_add_u32 s0, s30, 0x40000
	s_addc_u32 s1, s31, 0
	s_mov_b32 m0, s38
	v_lshl_add_u64 v[228:229], s[0:1], 0, v[130:131]
	ds_read_b128 v[188:191], v169 offset:32768
	ds_read_b128 v[192:195], v169 offset:33792
	ds_read_b128 v[196:199], v169 offset:34816
	ds_read_b128 v[200:203], v169 offset:35840
	ds_read_b128 v[204:207], v169 offset:36864
	ds_read_b128 v[208:211], v169 offset:37888
	ds_read_b128 v[212:215], v169 offset:38912
	ds_read_b128 v[216:219], v169 offset:39936
	global_load_lds_dwordx4 v[228:229], off
	v_lshl_add_u64 v[228:229], s[0:1], 0, v[134:135]
	s_mov_b32 m0, s39
	s_nop 0
	global_load_lds_dwordx4 v[228:229], off
	s_waitcnt vmcnt(8)
	s_waitcnt lgkmcnt(0)
	s_barrier
	s_setprio 1
	v_mfma_f32_16x16x32_bf16 v[126:129], v[148:151], v[188:191], v[126:129]
	v_mfma_f32_16x16x32_bf16 v[126:129], v[152:155], v[192:195], v[126:129]
	v_mfma_f32_16x16x32_bf16 v[118:121], v[156:159], v[188:191], v[118:121]
	v_mfma_f32_16x16x32_bf16 v[118:121], v[160:163], v[192:195], v[118:121]
	v_mfma_f32_16x16x32_bf16 v[110:113], v[148:151], v[196:199], v[110:113]
	v_mfma_f32_16x16x32_bf16 v[110:113], v[152:155], v[200:203], v[110:113]
	v_mfma_f32_16x16x32_bf16 v[106:109], v[156:159], v[196:199], v[106:109]
	v_mfma_f32_16x16x32_bf16 v[106:109], v[160:163], v[200:203], v[106:109]
	v_mfma_f32_16x16x32_bf16 v[94:97], v[148:151], v[204:207], v[94:97]
	v_mfma_f32_16x16x32_bf16 v[94:97], v[152:155], v[208:211], v[94:97]
	v_mfma_f32_16x16x32_bf16 v[90:93], v[156:159], v[204:207], v[90:93]
	v_mfma_f32_16x16x32_bf16 v[90:93], v[160:163], v[208:211], v[90:93]
	v_mfma_f32_16x16x32_bf16 v[78:81], v[148:151], v[212:215], v[78:81]
	v_mfma_f32_16x16x32_bf16 v[78:81], v[152:155], v[216:219], v[78:81]
	v_mfma_f32_16x16x32_bf16 v[74:77], v[156:159], v[212:215], v[74:77]
	v_mfma_f32_16x16x32_bf16 v[74:77], v[160:163], v[216:219], v[74:77]
	s_setprio 0
	s_setprio 1
	v_mfma_f32_16x16x32_bf16 v[122:125], v[172:175], v[188:191], v[122:125]
	v_mfma_f32_16x16x32_bf16 v[122:125], v[176:179], v[192:195], v[122:125]
	v_mfma_f32_16x16x32_bf16 v[114:117], v[180:183], v[188:191], v[114:117]
	v_mfma_f32_16x16x32_bf16 v[114:117], v[184:187], v[192:195], v[114:117]
	v_mfma_f32_16x16x32_bf16 v[102:105], v[172:175], v[196:199], v[102:105]
	v_mfma_f32_16x16x32_bf16 v[102:105], v[176:179], v[200:203], v[102:105]
	v_mfma_f32_16x16x32_bf16 v[98:101], v[180:183], v[196:199], v[98:101]
	v_mfma_f32_16x16x32_bf16 v[98:101], v[184:187], v[200:203], v[98:101]
	v_mfma_f32_16x16x32_bf16 v[86:89], v[172:175], v[204:207], v[86:89]
	v_mfma_f32_16x16x32_bf16 v[86:89], v[176:179], v[208:211], v[86:89]
	v_mfma_f32_16x16x32_bf16 v[82:85], v[180:183], v[204:207], v[82:85]
	v_mfma_f32_16x16x32_bf16 v[82:85], v[184:187], v[208:211], v[82:85]
	v_mfma_f32_16x16x32_bf16 v[70:73], v[172:175], v[212:215], v[70:73]
	v_mfma_f32_16x16x32_bf16 v[70:73], v[176:179], v[216:219], v[70:73]
	v_mfma_f32_16x16x32_bf16 v[66:69], v[180:183], v[212:215], v[66:69]
	v_mfma_f32_16x16x32_bf16 v[66:69], v[184:187], v[216:219], v[66:69]
	s_setprio 0
	s_barrier
	s_add_i32 s0, s52, s36
	v_lshl_add_u64 v[220:221], v[220:221], 0, s[14:15]
	s_mov_b32 m0, s0
	ds_read_b128 v[188:191], v169 offset:49152
	ds_read_b128 v[192:195], v169 offset:50176
	ds_read_b128 v[196:199], v169 offset:51200
	ds_read_b128 v[200:203], v169 offset:52224
	ds_read_b128 v[204:207], v169 offset:53248
	ds_read_b128 v[208:211], v169 offset:54272
	ds_read_b128 v[212:215], v169 offset:55296
	ds_read_b128 v[216:219], v169 offset:56320
	global_load_lds_dwordx4 v[220:221], off
	s_add_i32 m0, s0, 0x2000
	s_add_u32 s0, s2, 0x40080
	v_lshl_add_u64 v[220:221], v[222:223], 0, s[14:15]
	s_addc_u32 s1, s3, 0
	s_add_i32 s2, s53, s36
	global_load_lds_dwordx4 v[220:221], off
	v_lshl_add_u64 v[220:221], s[0:1], 0, v[132:133]
	s_mov_b32 m0, s2
	s_nop 0
	global_load_lds_dwordx4 v[220:221], off
	v_lshl_add_u64 v[220:221], s[0:1], 0, v[136:137]
	s_add_i32 m0, s2, 0x2000
	s_nop 0
	global_load_lds_dwordx4 v[220:221], off
	v_lshl_add_u64 v[220:221], v[224:225], 0, s[14:15]
	s_mov_b32 m0, s40
	s_nop 0
	global_load_lds_dwordx4 v[220:221], off
	v_lshl_add_u64 v[220:221], v[226:227], 0, s[14:15]
	s_mov_b32 m0, s41
	s_nop 0
	global_load_lds_dwordx4 v[220:221], off
	s_waitcnt vmcnt(8)
	s_waitcnt lgkmcnt(0)
	s_barrier
	s_setprio 1
	v_mfma_f32_16x16x32_bf16 v[62:65], v[148:151], v[188:191], v[62:65]
	v_mfma_f32_16x16x32_bf16 v[62:65], v[152:155], v[192:195], v[62:65]
	v_mfma_f32_16x16x32_bf16 v[58:61], v[156:159], v[188:191], v[58:61]
	v_mfma_f32_16x16x32_bf16 v[58:61], v[160:163], v[192:195], v[58:61]
	v_mfma_f32_16x16x32_bf16 v[46:49], v[148:151], v[196:199], v[46:49]
	v_mfma_f32_16x16x32_bf16 v[46:49], v[152:155], v[200:203], v[46:49]
	v_mfma_f32_16x16x32_bf16 v[42:45], v[156:159], v[196:199], v[42:45]
	v_mfma_f32_16x16x32_bf16 v[42:45], v[160:163], v[200:203], v[42:45]
	v_mfma_f32_16x16x32_bf16 v[30:33], v[148:151], v[204:207], v[30:33]
	v_mfma_f32_16x16x32_bf16 v[30:33], v[152:155], v[208:211], v[30:33]
	v_mfma_f32_16x16x32_bf16 v[26:29], v[156:159], v[204:207], v[26:29]
	v_mfma_f32_16x16x32_bf16 v[26:29], v[160:163], v[208:211], v[26:29]
	v_mfma_f32_16x16x32_bf16 v[14:17], v[148:151], v[212:215], v[14:17]
	v_mfma_f32_16x16x32_bf16 v[14:17], v[152:155], v[216:219], v[14:17]
	v_mfma_f32_16x16x32_bf16 v[10:13], v[156:159], v[212:215], v[10:13]
	v_mfma_f32_16x16x32_bf16 v[10:13], v[160:163], v[216:219], v[10:13]
	s_setprio 0
	s_setprio 1
	v_mfma_f32_16x16x32_bf16 v[54:57], v[172:175], v[188:191], v[54:57]
	v_mfma_f32_16x16x32_bf16 v[54:57], v[176:179], v[192:195], v[54:57]
	v_mfma_f32_16x16x32_bf16 v[50:53], v[180:183], v[188:191], v[50:53]
	v_mfma_f32_16x16x32_bf16 v[50:53], v[184:187], v[192:195], v[50:53]
	v_mfma_f32_16x16x32_bf16 v[38:41], v[172:175], v[196:199], v[38:41]
	v_mfma_f32_16x16x32_bf16 v[38:41], v[176:179], v[200:203], v[38:41]
	v_mfma_f32_16x16x32_bf16 v[34:37], v[180:183], v[196:199], v[34:37]
	v_mfma_f32_16x16x32_bf16 v[34:37], v[184:187], v[200:203], v[34:37]
	v_mfma_f32_16x16x32_bf16 v[22:25], v[172:175], v[204:207], v[22:25]
	v_mfma_f32_16x16x32_bf16 v[22:25], v[176:179], v[208:211], v[22:25]
	v_mfma_f32_16x16x32_bf16 v[18:21], v[180:183], v[204:207], v[18:21]
	v_mfma_f32_16x16x32_bf16 v[18:21], v[184:187], v[208:211], v[18:21]
	v_mfma_f32_16x16x32_bf16 v[6:9], v[172:175], v[212:215], v[6:9]
	v_mfma_f32_16x16x32_bf16 v[6:9], v[176:179], v[216:219], v[6:9]
	v_mfma_f32_16x16x32_bf16 v[2:5], v[180:183], v[212:215], v[2:5]
	v_mfma_f32_16x16x32_bf16 v[2:5], v[184:187], v[216:219], v[2:5]
	s_setprio 0
	s_barrier
	s_add_i32 s51, s51, 2
	s_add_u32 s28, s28, 0x100
	s_addc_u32 s29, s29, 0
	s_add_u32 s49, s49, 0x100
	s_addc_u32 s50, s50, 0
	s_cmp_gt_u32 s51, 13
	s_cbranch_scc0 .LBB0_202
	s_and_b64 vcc, exec, s[16:17]
	s_cbranch_vccz .LBB0_205
	s_barrier

.LBB0_283:
	ds_read_b128 v[114:117], v228
	ds_read_b128 v[118:121], v228 offset:1024
	ds_read_b128 v[122:125], v228 offset:2048
	ds_read_b128 v[126:129], v228 offset:3072
	ds_read_b128 v[146:149], v229
	ds_read_b128 v[150:153], v229 offset:1024
	ds_read_b128 v[154:157], v229 offset:2048
	ds_read_b128 v[158:161], v229 offset:3072
	s_add_u32 s0, s10, 0xfffc0080
	s_addc_u32 s1, s11, -1
	s_cmp_eq_u32 s51, 12
	s_cselect_b32 s13, s7, s1
	s_cselect_b32 s12, s9, s0
	s_cselect_b32 s3, s27, s37
	s_cselect_b32 s2, s29, s36
	v_lshl_add_u64 v[212:213], s[10:11], 0, v[180:181]
	s_add_i32 m0, s40, 0xc000
	ds_read_b128 v[162:165], v230
	ds_read_b128 v[166:169], v230 offset:1024
	ds_read_b128 v[188:191], v230 offset:2048
	ds_read_b128 v[192:195], v230 offset:3072
	ds_read_b128 v[196:199], v230 offset:4096
	ds_read_b128 v[200:203], v230 offset:5120
	ds_read_b128 v[204:207], v230 offset:6144
	ds_read_b128 v[208:211], v230 offset:7168
	global_load_lds_dwordx4 v[212:213], off
	v_lshl_add_u64 v[212:213], s[10:11], 0, v[182:183]
	s_add_i32 m0, s40, 0xe000
	s_nop 0
	global_load_lds_dwordx4 v[212:213], off
	s_waitcnt vmcnt(8)
	s_waitcnt lgkmcnt(0)
	s_barrier
	s_setprio 1
	v_mfma_f32_16x16x32_bf16 v[142:145], v[114:117], v[162:165], v[142:145]
	v_mfma_f32_16x16x32_bf16 v[142:145], v[118:121], v[166:169], v[142:145]
	v_mfma_f32_16x16x32_bf16 v[138:141], v[122:125], v[162:165], v[138:141]
	v_mfma_f32_16x16x32_bf16 v[138:141], v[126:129], v[166:169], v[138:141]
	v_mfma_f32_16x16x32_bf16 v[134:137], v[114:117], v[188:191], v[134:137]
	v_mfma_f32_16x16x32_bf16 v[134:137], v[118:121], v[192:195], v[134:137]
	v_mfma_f32_16x16x32_bf16 v[130:133], v[122:125], v[188:191], v[130:133]
	v_mfma_f32_16x16x32_bf16 v[130:133], v[126:129], v[192:195], v[130:133]
	v_mfma_f32_16x16x32_bf16 v[110:113], v[114:117], v[196:199], v[110:113]
	v_mfma_f32_16x16x32_bf16 v[110:113], v[118:121], v[200:203], v[110:113]
	v_mfma_f32_16x16x32_bf16 v[106:109], v[122:125], v[196:199], v[106:109]
	v_mfma_f32_16x16x32_bf16 v[106:109], v[126:129], v[200:203], v[106:109]
	v_mfma_f32_16x16x32_bf16 v[102:105], v[114:117], v[204:207], v[102:105]
	v_mfma_f32_16x16x32_bf16 v[102:105], v[118:121], v[208:211], v[102:105]
	v_mfma_f32_16x16x32_bf16 v[98:101], v[122:125], v[204:207], v[98:101]
	v_mfma_f32_16x16x32_bf16 v[98:101], v[126:129], v[208:211], v[98:101]
	s_setprio 0
	s_setprio 1
	v_mfma_f32_16x16x32_bf16 v[62:65], v[146:149], v[162:165], v[62:65]
	v_mfma_f32_16x16x32_bf16 v[62:65], v[150:153], v[166:169], v[62:65]
	v_mfma_f32_16x16x32_bf16 v[58:61], v[154:157], v[162:165], v[58:61]
	v_mfma_f32_16x16x32_bf16 v[58:61], v[158:161], v[166:169], v[58:61]
	v_mfma_f32_16x16x32_bf16 v[54:57], v[146:149], v[188:191], v[54:57]
	v_mfma_f32_16x16x32_bf16 v[54:57], v[150:153], v[192:195], v[54:57]
	v_mfma_f32_16x16x32_bf16 v[50:53], v[154:157], v[188:191], v[50:53]
	v_mfma_f32_16x16x32_bf16 v[50:53], v[158:161], v[192:195], v[50:53]
	v_mfma_f32_16x16x32_bf16 v[46:49], v[146:149], v[196:199], v[46:49]
	v_mfma_f32_16x16x32_bf16 v[46:49], v[150:153], v[200:203], v[46:49]
	v_mfma_f32_16x16x32_bf16 v[42:45], v[154:157], v[196:199], v[42:45]
	v_mfma_f32_16x16x32_bf16 v[42:45], v[158:161], v[200:203], v[42:45]
	v_mfma_f32_16x16x32_bf16 v[38:41], v[146:149], v[204:207], v[38:41]
	v_mfma_f32_16x16x32_bf16 v[38:41], v[150:153], v[208:211], v[38:41]
	v_mfma_f32_16x16x32_bf16 v[34:37], v[154:157], v[204:207], v[34:37]
	v_mfma_f32_16x16x32_bf16 v[34:37], v[158:161], v[208:211], v[34:37]
	s_setprio 0
	s_barrier
	s_add_i32 s0, s49, s39
	v_lshl_add_u64 v[212:213], s[2:3], 0, v[172:173]
	s_mov_b32 m0, s0
	ds_read_b128 v[162:165], v230 offset:16384
	ds_read_b128 v[166:169], v230 offset:17408
	ds_read_b128 v[188:191], v230 offset:18432
	ds_read_b128 v[192:195], v230 offset:19456
	ds_read_b128 v[196:199], v230 offset:20480
	ds_read_b128 v[200:203], v230 offset:21504
	ds_read_b128 v[204:207], v230 offset:22528
	ds_read_b128 v[208:211], v230 offset:23552
	global_load_lds_dwordx4 v[212:213], off
	s_add_i32 m0, s0, 0x2000
	s_add_u32 s0, s2, 0x40000
	v_lshl_add_u64 v[214:215], s[2:3], 0, v[176:177]
	s_addc_u32 s1, s3, 0
	s_add_i32 s52, s50, s39
	global_load_lds_dwordx4 v[214:215], off
	v_lshl_add_u64 v[216:217], s[0:1], 0, v[172:173]
	s_mov_b32 m0, s52
	v_lshl_add_u64 v[218:219], s[12:13], 0, v[174:175]
	global_load_lds_dwordx4 v[216:217], off
	v_lshl_add_u64 v[216:217], s[0:1], 0, v[176:177]
	s_add_i32 m0, s52, 0x2000
	s_nop 0
	global_load_lds_dwordx4 v[216:217], off
	v_lshl_add_u64 v[216:217], s[12:13], 0, v[170:171]
	s_mov_b32 m0, s40
	s_nop 0
	global_load_lds_dwordx4 v[216:217], off
	s_mov_b32 m0, s41
	s_nop 0
	global_load_lds_dwordx4 v[218:219], off
	s_waitcnt vmcnt(8)
	s_waitcnt lgkmcnt(0)
	s_barrier
	s_setprio 1
	v_mfma_f32_16x16x32_bf16 v[94:97], v[114:117], v[162:165], v[94:97]
	v_mfma_f32_16x16x32_bf16 v[94:97], v[118:121], v[166:169], v[94:97]
	v_mfma_f32_16x16x32_bf16 v[90:93], v[122:125], v[162:165], v[90:93]
	v_mfma_f32_16x16x32_bf16 v[90:93], v[126:129], v[166:169], v[90:93]
	v_mfma_f32_16x16x32_bf16 v[86:89], v[114:117], v[188:191], v[86:89]
	v_mfma_f32_16x16x32_bf16 v[86:89], v[118:121], v[192:195], v[86:89]
	v_mfma_f32_16x16x32_bf16 v[82:85], v[122:125], v[188:191], v[82:85]
	v_mfma_f32_16x16x32_bf16 v[82:85], v[126:129], v[192:195], v[82:85]
	v_mfma_f32_16x16x32_bf16 v[78:81], v[114:117], v[196:199], v[78:81]
	v_mfma_f32_16x16x32_bf16 v[78:81], v[118:121], v[200:203], v[78:81]
	v_mfma_f32_16x16x32_bf16 v[74:77], v[122:125], v[196:199], v[74:77]
	v_mfma_f32_16x16x32_bf16 v[74:77], v[126:129], v[200:203], v[74:77]
	v_mfma_f32_16x16x32_bf16 v[70:73], v[114:117], v[204:207], v[70:73]
	v_mfma_f32_16x16x32_bf16 v[70:73], v[118:121], v[208:211], v[70:73]
	v_mfma_f32_16x16x32_bf16 v[66:69], v[122:125], v[204:207], v[66:69]
	v_mfma_f32_16x16x32_bf16 v[66:69], v[126:129], v[208:211], v[66:69]
	s_setprio 0
	s_setprio 1
	v_mfma_f32_16x16x32_bf16 v[30:33], v[146:149], v[162:165], v[30:33]
	v_mfma_f32_16x16x32_bf16 v[30:33], v[150:153], v[166:169], v[30:33]
	v_mfma_f32_16x16x32_bf16 v[26:29], v[154:157], v[162:165], v[26:29]
	v_mfma_f32_16x16x32_bf16 v[26:29], v[158:161], v[166:169], v[26:29]
	v_mfma_f32_16x16x32_bf16 v[22:25], v[146:149], v[188:191], v[22:25]
	v_mfma_f32_16x16x32_bf16 v[22:25], v[150:153], v[192:195], v[22:25]
	v_mfma_f32_16x16x32_bf16 v[18:21], v[154:157], v[188:191], v[18:21]
	v_mfma_f32_16x16x32_bf16 v[18:21], v[158:161], v[192:195], v[18:21]
	v_mfma_f32_16x16x32_bf16 v[14:17], v[146:149], v[196:199], v[14:17]
	v_mfma_f32_16x16x32_bf16 v[14:17], v[150:153], v[200:203], v[14:17]
	v_mfma_f32_16x16x32_bf16 v[10:13], v[154:157], v[196:199], v[10:13]
	v_mfma_f32_16x16x32_bf16 v[10:13], v[158:161], v[200:203], v[10:13]
	v_mfma_f32_16x16x32_bf16 v[6:9], v[146:149], v[204:207], v[6:9]
	v_mfma_f32_16x16x32_bf16 v[6:9], v[150:153], v[208:211], v[6:9]
	v_mfma_f32_16x16x32_bf16 v[2:5], v[154:157], v[204:207], v[2:5]
	v_mfma_f32_16x16x32_bf16 v[2:5], v[158:161], v[208:211], v[2:5]
	s_setprio 0
	s_barrier
	s_add_i32 s52, 0, 0x18000
	s_add_i32 s53, 0, 0x1c000
	v_add_u32_e32 v126, s52, v223
	v_add_u32_e32 v158, s53, v223
	ds_read_b128 v[114:117], v126
	ds_read_b128 v[118:121], v126 offset:1024
	ds_read_b128 v[122:125], v126 offset:2048
	ds_read_b128 v[126:129], v126 offset:3072
	ds_read_b128 v[146:149], v158
	ds_read_b128 v[150:153], v158 offset:1024
	ds_read_b128 v[154:157], v158 offset:2048
	ds_read_b128 v[158:161], v158 offset:3072
	s_add_u32 s0, s12, 0x40000
	s_addc_u32 s1, s13, 0
	s_mov_b32 m0, s42
	v_lshl_add_u64 v[220:221], s[0:1], 0, v[170:171]
	ds_read_b128 v[162:165], v230 offset:32768
	ds_read_b128 v[166:169], v230 offset:33792
	ds_read_b128 v[188:191], v230 offset:34816
	ds_read_b128 v[192:195], v230 offset:35840
	ds_read_b128 v[196:199], v230 offset:36864
	ds_read_b128 v[200:203], v230 offset:37888
	ds_read_b128 v[204:207], v230 offset:38912
	ds_read_b128 v[208:211], v230 offset:39936
	global_load_lds_dwordx4 v[220:221], off
	v_lshl_add_u64 v[220:221], s[0:1], 0, v[174:175]
	s_mov_b32 m0, s43
	s_nop 0
	global_load_lds_dwordx4 v[220:221], off
	s_waitcnt vmcnt(8)
	s_waitcnt lgkmcnt(0)
	s_barrier
	s_setprio 1
	v_mfma_f32_16x16x32_bf16 v[142:145], v[114:117], v[162:165], v[142:145]
	v_mfma_f32_16x16x32_bf16 v[142:145], v[118:121], v[166:169], v[142:145]
	v_mfma_f32_16x16x32_bf16 v[138:141], v[122:125], v[162:165], v[138:141]
	v_mfma_f32_16x16x32_bf16 v[138:141], v[126:129], v[166:169], v[138:141]
	v_mfma_f32_16x16x32_bf16 v[134:137], v[114:117], v[188:191], v[134:137]
	v_mfma_f32_16x16x32_bf16 v[134:137], v[118:121], v[192:195], v[134:137]
	v_mfma_f32_16x16x32_bf16 v[130:133], v[122:125], v[188:191], v[130:133]
	v_mfma_f32_16x16x32_bf16 v[130:133], v[126:129], v[192:195], v[130:133]
	v_mfma_f32_16x16x32_bf16 v[110:113], v[114:117], v[196:199], v[110:113]
	v_mfma_f32_16x16x32_bf16 v[110:113], v[118:121], v[200:203], v[110:113]
	v_mfma_f32_16x16x32_bf16 v[106:109], v[122:125], v[196:199], v[106:109]
	v_mfma_f32_16x16x32_bf16 v[106:109], v[126:129], v[200:203], v[106:109]
	v_mfma_f32_16x16x32_bf16 v[102:105], v[114:117], v[204:207], v[102:105]
	v_mfma_f32_16x16x32_bf16 v[102:105], v[118:121], v[208:211], v[102:105]
	v_mfma_f32_16x16x32_bf16 v[98:101], v[122:125], v[204:207], v[98:101]
	v_mfma_f32_16x16x32_bf16 v[98:101], v[126:129], v[208:211], v[98:101]
	s_setprio 0
	s_setprio 1
	v_mfma_f32_16x16x32_bf16 v[62:65], v[146:149], v[162:165], v[62:65]
	v_mfma_f32_16x16x32_bf16 v[62:65], v[150:153], v[166:169], v[62:65]
	v_mfma_f32_16x16x32_bf16 v[58:61], v[154:157], v[162:165], v[58:61]
	v_mfma_f32_16x16x32_bf16 v[58:61], v[158:161], v[166:169], v[58:61]
	v_mfma_f32_16x16x32_bf16 v[54:57], v[146:149], v[188:191], v[54:57]
	v_mfma_f32_16x16x32_bf16 v[54:57], v[150:153], v[192:195], v[54:57]
	v_mfma_f32_16x16x32_bf16 v[50:53], v[154:157], v[188:191], v[50:53]
	v_mfma_f32_16x16x32_bf16 v[50:53], v[158:161], v[192:195], v[50:53]
	v_mfma_f32_16x16x32_bf16 v[46:49], v[146:149], v[196:199], v[46:49]
	v_mfma_f32_16x16x32_bf16 v[46:49], v[150:153], v[200:203], v[46:49]
	v_mfma_f32_16x16x32_bf16 v[42:45], v[154:157], v[196:199], v[42:45]
	v_mfma_f32_16x16x32_bf16 v[42:45], v[158:161], v[200:203], v[42:45]
	v_mfma_f32_16x16x32_bf16 v[38:41], v[146:149], v[204:207], v[38:41]
	v_mfma_f32_16x16x32_bf16 v[38:41], v[150:153], v[208:211], v[38:41]
	v_mfma_f32_16x16x32_bf16 v[34:37], v[154:157], v[204:207], v[34:37]
	v_mfma_f32_16x16x32_bf16 v[34:37], v[158:161], v[208:211], v[34:37]
	s_setprio 0
	s_barrier
	s_add_i32 s0, s52, s39
	v_lshl_add_u64 v[212:213], v[212:213], 0, s[22:23]
	s_mov_b32 m0, s0
	ds_read_b128 v[162:165], v230 offset:49152
	ds_read_b128 v[166:169], v230 offset:50176
	ds_read_b128 v[188:191], v230 offset:51200
	ds_read_b128 v[192:195], v230 offset:52224
	ds_read_b128 v[196:199], v230 offset:53248
	ds_read_b128 v[200:203], v230 offset:54272
	ds_read_b128 v[204:207], v230 offset:55296
	ds_read_b128 v[208:211], v230 offset:56320
	global_load_lds_dwordx4 v[212:213], off
	s_add_i32 m0, s0, 0x2000
	s_add_u32 s0, s2, 0x40080
	v_lshl_add_u64 v[212:213], v[214:215], 0, s[22:23]
	s_addc_u32 s1, s3, 0
	s_add_i32 s2, s53, s39
	global_load_lds_dwordx4 v[212:213], off
	v_lshl_add_u64 v[212:213], s[0:1], 0, v[172:173]
	s_mov_b32 m0, s2
	s_nop 0
	global_load_lds_dwordx4 v[212:213], off
	v_lshl_add_u64 v[212:213], s[0:1], 0, v[176:177]
	s_add_i32 m0, s2, 0x2000
	s_nop 0
	global_load_lds_dwordx4 v[212:213], off
	v_lshl_add_u64 v[212:213], v[216:217], 0, s[22:23]
	s_mov_b32 m0, s45
	s_nop 0
	global_load_lds_dwordx4 v[212:213], off
	v_lshl_add_u64 v[212:213], v[218:219], 0, s[22:23]
	s_mov_b32 m0, s46
	s_nop 0
	global_load_lds_dwordx4 v[212:213], off
	s_waitcnt vmcnt(8)
	s_waitcnt lgkmcnt(0)
	s_barrier
	s_setprio 1
	v_mfma_f32_16x16x32_bf16 v[94:97], v[114:117], v[162:165], v[94:97]
	v_mfma_f32_16x16x32_bf16 v[94:97], v[118:121], v[166:169], v[94:97]
	v_mfma_f32_16x16x32_bf16 v[90:93], v[122:125], v[162:165], v[90:93]
	v_mfma_f32_16x16x32_bf16 v[90:93], v[126:129], v[166:169], v[90:93]
	v_mfma_f32_16x16x32_bf16 v[86:89], v[114:117], v[188:191], v[86:89]
	v_mfma_f32_16x16x32_bf16 v[86:89], v[118:121], v[192:195], v[86:89]
	v_mfma_f32_16x16x32_bf16 v[82:85], v[122:125], v[188:191], v[82:85]
	v_mfma_f32_16x16x32_bf16 v[82:85], v[126:129], v[192:195], v[82:85]
	v_mfma_f32_16x16x32_bf16 v[78:81], v[114:117], v[196:199], v[78:81]
	v_mfma_f32_16x16x32_bf16 v[78:81], v[118:121], v[200:203], v[78:81]
	v_mfma_f32_16x16x32_bf16 v[74:77], v[122:125], v[196:199], v[74:77]
	v_mfma_f32_16x16x32_bf16 v[74:77], v[126:129], v[200:203], v[74:77]
	v_mfma_f32_16x16x32_bf16 v[70:73], v[114:117], v[204:207], v[70:73]
	v_mfma_f32_16x16x32_bf16 v[70:73], v[118:121], v[208:211], v[70:73]
	v_mfma_f32_16x16x32_bf16 v[66:69], v[122:125], v[204:207], v[66:69]
	v_mfma_f32_16x16x32_bf16 v[66:69], v[126:129], v[208:211], v[66:69]
	s_setprio 0
	s_setprio 1
	v_mfma_f32_16x16x32_bf16 v[30:33], v[146:149], v[162:165], v[30:33]
	v_mfma_f32_16x16x32_bf16 v[30:33], v[150:153], v[166:169], v[30:33]
	v_mfma_f32_16x16x32_bf16 v[26:29], v[154:157], v[162:165], v[26:29]
	v_mfma_f32_16x16x32_bf16 v[26:29], v[158:161], v[166:169], v[26:29]
	v_mfma_f32_16x16x32_bf16 v[22:25], v[146:149], v[188:191], v[22:25]
	v_mfma_f32_16x16x32_bf16 v[22:25], v[150:153], v[192:195], v[22:25]
	v_mfma_f32_16x16x32_bf16 v[18:21], v[154:157], v[188:191], v[18:21]
	v_mfma_f32_16x16x32_bf16 v[18:21], v[158:161], v[192:195], v[18:21]
	v_mfma_f32_16x16x32_bf16 v[14:17], v[146:149], v[196:199], v[14:17]
	v_mfma_f32_16x16x32_bf16 v[14:17], v[150:153], v[200:203], v[14:17]
	v_mfma_f32_16x16x32_bf16 v[10:13], v[154:157], v[196:199], v[10:13]
	v_mfma_f32_16x16x32_bf16 v[10:13], v[158:161], v[200:203], v[10:13]
	v_mfma_f32_16x16x32_bf16 v[6:9], v[146:149], v[204:207], v[6:9]
	v_mfma_f32_16x16x32_bf16 v[6:9], v[150:153], v[208:211], v[6:9]
	v_mfma_f32_16x16x32_bf16 v[2:5], v[154:157], v[204:207], v[2:5]
	v_mfma_f32_16x16x32_bf16 v[2:5], v[158:161], v[208:211], v[2:5]
	s_setprio 0
	s_barrier
	s_add_i32 s51, s51, 2
	s_add_u32 s10, s10, 0x100
	s_addc_u32 s11, s11, 0
	s_add_u32 s36, s36, 0x100
	s_addc_u32 s37, s37, 0
	s_cmp_gt_u32 s51, 13
	s_cbranch_scc0 .LBB0_283
	s_and_b64 vcc, exec, s[24:25]
	s_cbranch_vccz .LBB0_286
	s_barrier

.LBB0_381:
	s_ashr_i32 s21, s20, 31
	s_lshl_b64 s[0:1], s[20:21], 19
	s_add_u32 s22, s33, s0
	s_addc_u32 s23, s34, s1
	s_and_b64 s[0:1], s[6:7], exec
	s_cselect_b32 s11, s23, s29
	s_cselect_b32 s21, s22, s28
	s_ashr_i32 s19, s18, 31
	s_lshl_b64 s[0:1], s[18:19], 19
	s_add_u32 s24, s35, s0
	s_addc_u32 s25, s36, s1
	s_and_b64 s[0:1], s[6:7], exec
	s_cselect_b32 s19, s25, s3
	s_cselect_b32 s48, s24, s2
	s_add_u32 s28, s28, 0x40080
	s_addc_u32 s29, s29, 0
	s_add_u32 s49, s2, 0x100
	v_mov_b32_e32 v2, 0
	s_addc_u32 s50, s3, 0
	s_mov_b32 s51, -2
	s_waitcnt lgkmcnt(0)
	v_mov_b32_e32 v3, v2
	v_mov_b32_e32 v4, v2
	v_mov_b32_e32 v5, v2
	v_mov_b32_e32 v6, v2
	v_mov_b32_e32 v7, v2
	v_mov_b32_e32 v8, v2
	v_mov_b32_e32 v9, v2
	v_mov_b32_e32 v18, v2
	v_mov_b32_e32 v19, v2
	v_mov_b32_e32 v20, v2
	v_mov_b32_e32 v21, v2
	v_mov_b32_e32 v22, v2
	v_mov_b32_e32 v23, v2
	v_mov_b32_e32 v24, v2
	v_mov_b32_e32 v25, v2
	v_mov_b32_e32 v34, v2
	v_mov_b32_e32 v35, v2
	v_mov_b32_e32 v36, v2
	v_mov_b32_e32 v37, v2
	v_mov_b32_e32 v38, v2
	v_mov_b32_e32 v39, v2
	v_mov_b32_e32 v40, v2
	v_mov_b32_e32 v41, v2
	v_mov_b32_e32 v50, v2
	v_mov_b32_e32 v51, v2
	v_mov_b32_e32 v52, v2
	v_mov_b32_e32 v53, v2
	v_mov_b32_e32 v54, v2
	v_mov_b32_e32 v55, v2
	v_mov_b32_e32 v56, v2
	v_mov_b32_e32 v57, v2
	v_mov_b32_e32 v10, v2
	v_mov_b32_e32 v11, v2
	v_mov_b32_e32 v12, v2
	v_mov_b32_e32 v13, v2
	v_mov_b32_e32 v14, v2
	v_mov_b32_e32 v15, v2
	v_mov_b32_e32 v16, v2
	v_mov_b32_e32 v17, v2
	v_mov_b32_e32 v26, v2
	v_mov_b32_e32 v27, v2
	v_mov_b32_e32 v28, v2
	v_mov_b32_e32 v29, v2
	v_mov_b32_e32 v30, v2
	v_mov_b32_e32 v31, v2
	v_mov_b32_e32 v32, v2
	v_mov_b32_e32 v33, v2
	v_mov_b32_e32 v42, v2
	v_mov_b32_e32 v43, v2
	v_mov_b32_e32 v44, v2
	v_mov_b32_e32 v45, v2
	v_mov_b32_e32 v46, v2
	v_mov_b32_e32 v47, v2
	v_mov_b32_e32 v48, v2
	v_mov_b32_e32 v49, v2
	v_mov_b32_e32 v58, v2
	v_mov_b32_e32 v59, v2
	v_mov_b32_e32 v60, v2
	v_mov_b32_e32 v61, v2
	v_mov_b32_e32 v62, v2
	v_mov_b32_e32 v63, v2
	v_mov_b32_e32 v64, v2
	v_mov_b32_e32 v65, v2
	v_mov_b32_e32 v66, v2
	v_mov_b32_e32 v67, v2
	v_mov_b32_e32 v68, v2
	v_mov_b32_e32 v69, v2
	v_mov_b32_e32 v70, v2
	v_mov_b32_e32 v71, v2
	v_mov_b32_e32 v72, v2
	v_mov_b32_e32 v73, v2
	v_mov_b32_e32 v82, v2
	v_mov_b32_e32 v83, v2
	v_mov_b32_e32 v84, v2
	v_mov_b32_e32 v85, v2
	v_mov_b32_e32 v86, v2
	v_mov_b32_e32 v87, v2
	v_mov_b32_e32 v88, v2
	v_mov_b32_e32 v89, v2
	v_mov_b32_e32 v98, v2
	v_mov_b32_e32 v99, v2
	v_mov_b32_e32 v100, v2
	v_mov_b32_e32 v101, v2
	v_mov_b32_e32 v102, v2
	v_mov_b32_e32 v103, v2
	v_mov_b32_e32 v104, v2
	v_mov_b32_e32 v105, v2
	v_mov_b32_e32 v114, v2
	v_mov_b32_e32 v115, v2
	v_mov_b32_e32 v116, v2
	v_mov_b32_e32 v117, v2
	v_mov_b32_e32 v118, v2
	v_mov_b32_e32 v119, v2
	v_mov_b32_e32 v120, v2
	v_mov_b32_e32 v121, v2
	v_mov_b32_e32 v74, v2
	v_mov_b32_e32 v75, v2
	v_mov_b32_e32 v76, v2
	v_mov_b32_e32 v77, v2
	v_mov_b32_e32 v78, v2
	v_mov_b32_e32 v79, v2
	v_mov_b32_e32 v80, v2
	v_mov_b32_e32 v81, v2
	v_mov_b32_e32 v90, v2
	v_mov_b32_e32 v91, v2
	v_mov_b32_e32 v92, v2
	v_mov_b32_e32 v93, v2
	v_mov_b32_e32 v94, v2
	v_mov_b32_e32 v95, v2
	v_mov_b32_e32 v96, v2
	v_mov_b32_e32 v97, v2
	v_mov_b32_e32 v106, v2
	v_mov_b32_e32 v107, v2
	v_mov_b32_e32 v108, v2
	v_mov_b32_e32 v109, v2
	v_mov_b32_e32 v110, v2
	v_mov_b32_e32 v111, v2
	v_mov_b32_e32 v112, v2
	v_mov_b32_e32 v113, v2
	v_mov_b32_e32 v122, v2
	v_mov_b32_e32 v123, v2
	v_mov_b32_e32 v124, v2
	v_mov_b32_e32 v125, v2
	v_mov_b32_e32 v126, v2
	v_mov_b32_e32 v127, v2
	v_mov_b32_e32 v128, v2
	v_mov_b32_e32 v129, v2
	s_nop 0
	s_nop 0
	s_nop 0
	s_nop 0
	s_nop 0
	s_nop 0
	s_nop 0
	s_nop 0
	s_nop 0
	s_nop 0
	s_nop 0
	s_nop 0
	s_nop 0
	s_nop 0
.LBB0_382:
	ds_read_b128 v[130:133], v211
	ds_read_b128 v[134:137], v211 offset:1024
	ds_read_b128 v[138:141], v211 offset:2048
	ds_read_b128 v[142:145], v211 offset:3072
	ds_read_b128 v[146:149], v212
	ds_read_b128 v[150:153], v212 offset:1024
	ds_read_b128 v[154:157], v212 offset:2048
	ds_read_b128 v[158:161], v212 offset:3072
	s_add_u32 s0, s28, 0xfffc0080
	s_addc_u32 s1, s29, -1
	s_cmp_eq_u32 s51, 12
	s_cselect_b32 s31, s11, s1
	s_cselect_b32 s30, s21, s0
	s_cselect_b32 s3, s19, s50
	s_cselect_b32 s2, s48, s49
	v_lshl_add_u64 v[220:221], s[28:29], 0, v[186:187]
	s_add_i32 m0, s27, 0xc000
	ds_read_b128 v[162:165], v213
	ds_read_b128 v[166:169], v213 offset:1024
	ds_read_b128 v[170:173], v213 offset:2048
	ds_read_b128 v[174:177], v213 offset:3072
	ds_read_b128 v[194:197], v213 offset:4096
	ds_read_b128 v[198:201], v213 offset:5120
	ds_read_b128 v[202:205], v213 offset:6144
	ds_read_b128 v[216:219], v213 offset:7168
	global_load_lds_dwordx4 v[220:221], off
	v_lshl_add_u64 v[220:221], s[28:29], 0, v[188:189]
	s_add_i32 m0, s27, 0xe000
	s_nop 0
	global_load_lds_dwordx4 v[220:221], off
	s_waitcnt vmcnt(8)
	s_waitcnt lgkmcnt(0)
	s_barrier
	s_setprio 1
	v_mfma_f32_16x16x32_bf16 v[126:129], v[130:133], v[162:165], v[126:129]
	v_mfma_f32_16x16x32_bf16 v[126:129], v[134:137], v[166:169], v[126:129]
	v_mfma_f32_16x16x32_bf16 v[122:125], v[138:141], v[162:165], v[122:125]
	v_mfma_f32_16x16x32_bf16 v[122:125], v[142:145], v[166:169], v[122:125]
	v_mfma_f32_16x16x32_bf16 v[110:113], v[130:133], v[170:173], v[110:113]
	v_mfma_f32_16x16x32_bf16 v[110:113], v[134:137], v[174:177], v[110:113]
	v_mfma_f32_16x16x32_bf16 v[106:109], v[138:141], v[170:173], v[106:109]
	v_mfma_f32_16x16x32_bf16 v[106:109], v[142:145], v[174:177], v[106:109]
	v_mfma_f32_16x16x32_bf16 v[94:97], v[130:133], v[194:197], v[94:97]
	v_mfma_f32_16x16x32_bf16 v[94:97], v[134:137], v[198:201], v[94:97]
	v_mfma_f32_16x16x32_bf16 v[90:93], v[138:141], v[194:197], v[90:93]
	v_mfma_f32_16x16x32_bf16 v[90:93], v[142:145], v[198:201], v[90:93]
	v_mfma_f32_16x16x32_bf16 v[78:81], v[130:133], v[202:205], v[78:81]
	v_mfma_f32_16x16x32_bf16 v[78:81], v[134:137], v[216:219], v[78:81]
	v_mfma_f32_16x16x32_bf16 v[74:77], v[138:141], v[202:205], v[74:77]
	v_mfma_f32_16x16x32_bf16 v[74:77], v[142:145], v[216:219], v[74:77]
	s_setprio 0
	s_setprio 1
	v_mfma_f32_16x16x32_bf16 v[118:121], v[146:149], v[162:165], v[118:121]
	v_mfma_f32_16x16x32_bf16 v[118:121], v[150:153], v[166:169], v[118:121]
	v_mfma_f32_16x16x32_bf16 v[114:117], v[154:157], v[162:165], v[114:117]
	v_mfma_f32_16x16x32_bf16 v[114:117], v[158:161], v[166:169], v[114:117]
	v_mfma_f32_16x16x32_bf16 v[102:105], v[146:149], v[170:173], v[102:105]
	v_mfma_f32_16x16x32_bf16 v[102:105], v[150:153], v[174:177], v[102:105]
	v_mfma_f32_16x16x32_bf16 v[98:101], v[154:157], v[170:173], v[98:101]
	v_mfma_f32_16x16x32_bf16 v[98:101], v[158:161], v[174:177], v[98:101]
	v_mfma_f32_16x16x32_bf16 v[86:89], v[146:149], v[194:197], v[86:89]
	v_mfma_f32_16x16x32_bf16 v[86:89], v[150:153], v[198:201], v[86:89]
	v_mfma_f32_16x16x32_bf16 v[82:85], v[154:157], v[194:197], v[82:85]
	v_mfma_f32_16x16x32_bf16 v[82:85], v[158:161], v[198:201], v[82:85]
	v_mfma_f32_16x16x32_bf16 v[70:73], v[146:149], v[202:205], v[70:73]
	v_mfma_f32_16x16x32_bf16 v[70:73], v[150:153], v[216:219], v[70:73]
	v_mfma_f32_16x16x32_bf16 v[66:69], v[154:157], v[202:205], v[66:69]
	v_mfma_f32_16x16x32_bf16 v[66:69], v[158:161], v[216:219], v[66:69]
	s_setprio 0
	s_barrier
	s_add_i32 s0, s46, s37
	v_lshl_add_u64 v[220:221], s[2:3], 0, v[180:181]
	s_mov_b32 m0, s0
	ds_read_b128 v[162:165], v213 offset:16384
	ds_read_b128 v[166:169], v213 offset:17408
	ds_read_b128 v[170:173], v213 offset:18432
	ds_read_b128 v[174:177], v213 offset:19456
	ds_read_b128 v[194:197], v213 offset:20480
	ds_read_b128 v[198:201], v213 offset:21504
	ds_read_b128 v[202:205], v213 offset:22528
	ds_read_b128 v[216:219], v213 offset:23552
	global_load_lds_dwordx4 v[220:221], off
	s_add_i32 m0, s0, 0x2000
	s_add_u32 s0, s2, 0x40000
	v_lshl_add_u64 v[222:223], s[2:3], 0, v[184:185]
	s_addc_u32 s1, s3, 0
	s_add_i32 s52, s47, s37
	global_load_lds_dwordx4 v[222:223], off
	v_lshl_add_u64 v[224:225], s[0:1], 0, v[180:181]
	s_mov_b32 m0, s52
	v_lshl_add_u64 v[226:227], s[30:31], 0, v[182:183]
	global_load_lds_dwordx4 v[224:225], off
	v_lshl_add_u64 v[224:225], s[0:1], 0, v[184:185]
	s_add_i32 m0, s52, 0x2000
	s_nop 0
	global_load_lds_dwordx4 v[224:225], off
	v_lshl_add_u64 v[224:225], s[30:31], 0, v[178:179]
	s_mov_b32 m0, s27
	s_nop 0
	global_load_lds_dwordx4 v[224:225], off
	s_mov_b32 m0, s38
	s_nop 0
	global_load_lds_dwordx4 v[226:227], off
	s_waitcnt vmcnt(8)
	s_waitcnt lgkmcnt(0)
	s_barrier
	s_setprio 1
	v_mfma_f32_16x16x32_bf16 v[62:65], v[130:133], v[162:165], v[62:65]
	v_mfma_f32_16x16x32_bf16 v[62:65], v[134:137], v[166:169], v[62:65]
	v_mfma_f32_16x16x32_bf16 v[58:61], v[138:141], v[162:165], v[58:61]
	v_mfma_f32_16x16x32_bf16 v[58:61], v[142:145], v[166:169], v[58:61]
	v_mfma_f32_16x16x32_bf16 v[46:49], v[130:133], v[170:173], v[46:49]
	v_mfma_f32_16x16x32_bf16 v[46:49], v[134:137], v[174:177], v[46:49]
	v_mfma_f32_16x16x32_bf16 v[42:45], v[138:141], v[170:173], v[42:45]
	v_mfma_f32_16x16x32_bf16 v[42:45], v[142:145], v[174:177], v[42:45]
	v_mfma_f32_16x16x32_bf16 v[30:33], v[130:133], v[194:197], v[30:33]
	v_mfma_f32_16x16x32_bf16 v[30:33], v[134:137], v[198:201], v[30:33]
	v_mfma_f32_16x16x32_bf16 v[26:29], v[138:141], v[194:197], v[26:29]
	v_mfma_f32_16x16x32_bf16 v[26:29], v[142:145], v[198:201], v[26:29]
	v_mfma_f32_16x16x32_bf16 v[14:17], v[130:133], v[202:205], v[14:17]
	v_mfma_f32_16x16x32_bf16 v[14:17], v[134:137], v[216:219], v[14:17]
	v_mfma_f32_16x16x32_bf16 v[10:13], v[138:141], v[202:205], v[10:13]
	v_mfma_f32_16x16x32_bf16 v[10:13], v[142:145], v[216:219], v[10:13]
	s_setprio 0
	s_setprio 1
	v_mfma_f32_16x16x32_bf16 v[54:57], v[146:149], v[162:165], v[54:57]
	v_mfma_f32_16x16x32_bf16 v[54:57], v[150:153], v[166:169], v[54:57]
	v_mfma_f32_16x16x32_bf16 v[50:53], v[154:157], v[162:165], v[50:53]
	v_mfma_f32_16x16x32_bf16 v[50:53], v[158:161], v[166:169], v[50:53]
	v_mfma_f32_16x16x32_bf16 v[38:41], v[146:149], v[170:173], v[38:41]
	v_mfma_f32_16x16x32_bf16 v[38:41], v[150:153], v[174:177], v[38:41]
	v_mfma_f32_16x16x32_bf16 v[34:37], v[154:157], v[170:173], v[34:37]
	v_mfma_f32_16x16x32_bf16 v[34:37], v[158:161], v[174:177], v[34:37]
	v_mfma_f32_16x16x32_bf16 v[22:25], v[146:149], v[194:197], v[22:25]
	v_mfma_f32_16x16x32_bf16 v[22:25], v[150:153], v[198:201], v[22:25]
	v_mfma_f32_16x16x32_bf16 v[18:21], v[154:157], v[194:197], v[18:21]
	v_mfma_f32_16x16x32_bf16 v[18:21], v[158:161], v[198:201], v[18:21]
	v_mfma_f32_16x16x32_bf16 v[6:9], v[146:149], v[202:205], v[6:9]
	v_mfma_f32_16x16x32_bf16 v[6:9], v[150:153], v[216:219], v[6:9]
	v_mfma_f32_16x16x32_bf16 v[2:5], v[154:157], v[202:205], v[2:5]
	v_mfma_f32_16x16x32_bf16 v[2:5], v[158:161], v[216:219], v[2:5]
	s_setprio 0
	s_barrier
	s_add_i32 s52, 0, 0x18000
	s_add_i32 s53, 0, 0x1c000
	v_add_u32_e32 v142, s52, v207
	v_add_u32_e32 v158, s53, v207
	ds_read_b128 v[130:133], v142
	ds_read_b128 v[134:137], v142 offset:1024
	ds_read_b128 v[138:141], v142 offset:2048
	ds_read_b128 v[142:145], v142 offset:3072
	ds_read_b128 v[146:149], v158
	ds_read_b128 v[150:153], v158 offset:1024
	ds_read_b128 v[154:157], v158 offset:2048
	ds_read_b128 v[158:161], v158 offset:3072
	s_add_u32 s0, s30, 0x40000
	s_addc_u32 s1, s31, 0
	s_mov_b32 m0, s39
	v_lshl_add_u64 v[228:229], s[0:1], 0, v[178:179]
	ds_read_b128 v[162:165], v213 offset:32768
	ds_read_b128 v[166:169], v213 offset:33792
	ds_read_b128 v[170:173], v213 offset:34816
	ds_read_b128 v[174:177], v213 offset:35840
	ds_read_b128 v[194:197], v213 offset:36864
	ds_read_b128 v[198:201], v213 offset:37888
	ds_read_b128 v[202:205], v213 offset:38912
	ds_read_b128 v[216:219], v213 offset:39936
	global_load_lds_dwordx4 v[228:229], off
	v_lshl_add_u64 v[228:229], s[0:1], 0, v[182:183]
	s_mov_b32 m0, s40
	s_nop 0
	global_load_lds_dwordx4 v[228:229], off
	s_waitcnt vmcnt(8)
	s_waitcnt lgkmcnt(0)
	s_barrier
	s_setprio 1
	v_mfma_f32_16x16x32_bf16 v[126:129], v[130:133], v[162:165], v[126:129]
	v_mfma_f32_16x16x32_bf16 v[126:129], v[134:137], v[166:169], v[126:129]
	v_mfma_f32_16x16x32_bf16 v[122:125], v[138:141], v[162:165], v[122:125]
	v_mfma_f32_16x16x32_bf16 v[122:125], v[142:145], v[166:169], v[122:125]
	v_mfma_f32_16x16x32_bf16 v[110:113], v[130:133], v[170:173], v[110:113]
	v_mfma_f32_16x16x32_bf16 v[110:113], v[134:137], v[174:177], v[110:113]
	v_mfma_f32_16x16x32_bf16 v[106:109], v[138:141], v[170:173], v[106:109]
	v_mfma_f32_16x16x32_bf16 v[106:109], v[142:145], v[174:177], v[106:109]
	v_mfma_f32_16x16x32_bf16 v[94:97], v[130:133], v[194:197], v[94:97]
	v_mfma_f32_16x16x32_bf16 v[94:97], v[134:137], v[198:201], v[94:97]
	v_mfma_f32_16x16x32_bf16 v[90:93], v[138:141], v[194:197], v[90:93]
	v_mfma_f32_16x16x32_bf16 v[90:93], v[142:145], v[198:201], v[90:93]
	v_mfma_f32_16x16x32_bf16 v[78:81], v[130:133], v[202:205], v[78:81]
	v_mfma_f32_16x16x32_bf16 v[78:81], v[134:137], v[216:219], v[78:81]
	v_mfma_f32_16x16x32_bf16 v[74:77], v[138:141], v[202:205], v[74:77]
	v_mfma_f32_16x16x32_bf16 v[74:77], v[142:145], v[216:219], v[74:77]
	s_setprio 0
	s_setprio 1
	v_mfma_f32_16x16x32_bf16 v[118:121], v[146:149], v[162:165], v[118:121]
	v_mfma_f32_16x16x32_bf16 v[118:121], v[150:153], v[166:169], v[118:121]
	v_mfma_f32_16x16x32_bf16 v[114:117], v[154:157], v[162:165], v[114:117]
	v_mfma_f32_16x16x32_bf16 v[114:117], v[158:161], v[166:169], v[114:117]
	v_mfma_f32_16x16x32_bf16 v[102:105], v[146:149], v[170:173], v[102:105]
	v_mfma_f32_16x16x32_bf16 v[102:105], v[150:153], v[174:177], v[102:105]
	v_mfma_f32_16x16x32_bf16 v[98:101], v[154:157], v[170:173], v[98:101]
	v_mfma_f32_16x16x32_bf16 v[98:101], v[158:161], v[174:177], v[98:101]
	v_mfma_f32_16x16x32_bf16 v[86:89], v[146:149], v[194:197], v[86:89]
	v_mfma_f32_16x16x32_bf16 v[86:89], v[150:153], v[198:201], v[86:89]
	v_mfma_f32_16x16x32_bf16 v[82:85], v[154:157], v[194:197], v[82:85]
	v_mfma_f32_16x16x32_bf16 v[82:85], v[158:161], v[198:201], v[82:85]
	v_mfma_f32_16x16x32_bf16 v[70:73], v[146:149], v[202:205], v[70:73]
	v_mfma_f32_16x16x32_bf16 v[70:73], v[150:153], v[216:219], v[70:73]
	v_mfma_f32_16x16x32_bf16 v[66:69], v[154:157], v[202:205], v[66:69]
	v_mfma_f32_16x16x32_bf16 v[66:69], v[158:161], v[216:219], v[66:69]
	s_setprio 0
	s_barrier
	s_add_i32 s0, s52, s37
	v_lshl_add_u64 v[220:221], v[220:221], 0, s[14:15]
	s_mov_b32 m0, s0
	ds_read_b128 v[162:165], v213 offset:49152
	ds_read_b128 v[166:169], v213 offset:50176
	ds_read_b128 v[170:173], v213 offset:51200
	ds_read_b128 v[174:177], v213 offset:52224
	ds_read_b128 v[194:197], v213 offset:53248
	ds_read_b128 v[198:201], v213 offset:54272
	ds_read_b128 v[202:205], v213 offset:55296
	ds_read_b128 v[216:219], v213 offset:56320
	global_load_lds_dwordx4 v[220:221], off
	s_add_i32 m0, s0, 0x2000
	s_add_u32 s0, s2, 0x40080
	v_lshl_add_u64 v[220:221], v[222:223], 0, s[14:15]
	s_addc_u32 s1, s3, 0
	s_add_i32 s2, s53, s37
	global_load_lds_dwordx4 v[220:221], off
	v_lshl_add_u64 v[220:221], s[0:1], 0, v[180:181]
	s_mov_b32 m0, s2
	s_nop 0
	global_load_lds_dwordx4 v[220:221], off
	v_lshl_add_u64 v[220:221], s[0:1], 0, v[184:185]
	s_add_i32 m0, s2, 0x2000
	s_nop 0
	global_load_lds_dwordx4 v[220:221], off
	v_lshl_add_u64 v[220:221], v[224:225], 0, s[14:15]
	s_mov_b32 m0, s42
	s_nop 0
	global_load_lds_dwordx4 v[220:221], off
	v_lshl_add_u64 v[220:221], v[226:227], 0, s[14:15]
	s_mov_b32 m0, s43
	s_nop 0
	global_load_lds_dwordx4 v[220:221], off
	s_waitcnt vmcnt(8)
	s_waitcnt lgkmcnt(0)
	s_barrier
	s_setprio 1
	v_mfma_f32_16x16x32_bf16 v[62:65], v[130:133], v[162:165], v[62:65]
	v_mfma_f32_16x16x32_bf16 v[62:65], v[134:137], v[166:169], v[62:65]
	v_mfma_f32_16x16x32_bf16 v[58:61], v[138:141], v[162:165], v[58:61]
	v_mfma_f32_16x16x32_bf16 v[58:61], v[142:145], v[166:169], v[58:61]
	v_mfma_f32_16x16x32_bf16 v[46:49], v[130:133], v[170:173], v[46:49]
	v_mfma_f32_16x16x32_bf16 v[46:49], v[134:137], v[174:177], v[46:49]
	v_mfma_f32_16x16x32_bf16 v[42:45], v[138:141], v[170:173], v[42:45]
	v_mfma_f32_16x16x32_bf16 v[42:45], v[142:145], v[174:177], v[42:45]
	v_mfma_f32_16x16x32_bf16 v[30:33], v[130:133], v[194:197], v[30:33]
	v_mfma_f32_16x16x32_bf16 v[30:33], v[134:137], v[198:201], v[30:33]
	v_mfma_f32_16x16x32_bf16 v[26:29], v[138:141], v[194:197], v[26:29]
	v_mfma_f32_16x16x32_bf16 v[26:29], v[142:145], v[198:201], v[26:29]
	v_mfma_f32_16x16x32_bf16 v[14:17], v[130:133], v[202:205], v[14:17]
	v_mfma_f32_16x16x32_bf16 v[14:17], v[134:137], v[216:219], v[14:17]
	v_mfma_f32_16x16x32_bf16 v[10:13], v[138:141], v[202:205], v[10:13]
	v_mfma_f32_16x16x32_bf16 v[10:13], v[142:145], v[216:219], v[10:13]
	s_setprio 0
	s_setprio 1
	v_mfma_f32_16x16x32_bf16 v[54:57], v[146:149], v[162:165], v[54:57]
	v_mfma_f32_16x16x32_bf16 v[54:57], v[150:153], v[166:169], v[54:57]
	v_mfma_f32_16x16x32_bf16 v[50:53], v[154:157], v[162:165], v[50:53]
	v_mfma_f32_16x16x32_bf16 v[50:53], v[158:161], v[166:169], v[50:53]
	v_mfma_f32_16x16x32_bf16 v[38:41], v[146:149], v[170:173], v[38:41]
	v_mfma_f32_16x16x32_bf16 v[38:41], v[150:153], v[174:177], v[38:41]
	v_mfma_f32_16x16x32_bf16 v[34:37], v[154:157], v[170:173], v[34:37]
	v_mfma_f32_16x16x32_bf16 v[34:37], v[158:161], v[174:177], v[34:37]
	v_mfma_f32_16x16x32_bf16 v[22:25], v[146:149], v[194:197], v[22:25]
	v_mfma_f32_16x16x32_bf16 v[22:25], v[150:153], v[198:201], v[22:25]
	v_mfma_f32_16x16x32_bf16 v[18:21], v[154:157], v[194:197], v[18:21]
	v_mfma_f32_16x16x32_bf16 v[18:21], v[158:161], v[198:201], v[18:21]
	v_mfma_f32_16x16x32_bf16 v[6:9], v[146:149], v[202:205], v[6:9]
	v_mfma_f32_16x16x32_bf16 v[6:9], v[150:153], v[216:219], v[6:9]
	v_mfma_f32_16x16x32_bf16 v[2:5], v[154:157], v[202:205], v[2:5]
	v_mfma_f32_16x16x32_bf16 v[2:5], v[158:161], v[216:219], v[2:5]
	s_setprio 0
	s_barrier
	s_add_i32 s51, s51, 2
	s_add_u32 s28, s28, 0x100
	s_addc_u32 s29, s29, 0
	s_add_u32 s49, s49, 0x100
	s_addc_u32 s50, s50, 0
	s_cmp_gt_u32 s51, 13
	s_cbranch_scc0 .LBB0_382
	s_and_b64 vcc, exec, s[16:17]
	s_cbranch_vccz .LBB0_385
	s_barrier

.LBB0_470:
	s_and_b32 s99, s48, 1
	s_lshl_b32 s99, s99, 12
	v_readfirstlane_b32 s100, v0
	s_and_b32 s100, s100, 0xc0
	s_lshl_b32 s100, s100, 4
	s_add_i32 s99, s99, s100
	s_add_i32 m0, s99, 0x21000
	s_lshl_b32 s99, s26, 12
	s_add_u32 s100, s76, s99
	s_addc_u32 s101, s77, 0
	v_and_b32_e32 v129, 0xff, v0
	v_lshlrev_b32_e32 v129, 4, v129
	global_load_lds_dwordx4 v129, s[100:101]
	s_ashr_i32 s21, s20, 31
	s_lshl_b64 s[0:1], s[20:21], 19
	s_add_u32 s22, s78, s0
	s_addc_u32 s23, s79, s1
	s_and_b64 s[0:1], s[4:5], exec
	s_cselect_b32 s21, s23, s29
	s_cselect_b32 s49, s22, s28
	s_ashr_i32 s19, s18, 31
	s_lshl_b64 s[0:1], s[18:19], 19
	s_add_u32 s24, s33, s0
	s_addc_u32 s25, s34, s1
	s_and_b64 s[0:1], s[4:5], exec
	s_cselect_b32 s19, s25, s3
	s_cselect_b32 s50, s24, s2
	s_add_u32 s28, s28, 0x40080
	s_addc_u32 s29, s29, 0
	s_add_u32 s51, s2, 0x100
	v_mov_b32_e32 v2, 0
	s_addc_u32 s52, s3, 0
	s_mov_b32 s53, -2
	v_mov_b32_e32 v3, v2
	v_mov_b32_e32 v4, v2
	v_mov_b32_e32 v5, v2
	v_mov_b32_e32 v10, v2
	v_mov_b32_e32 v11, v2
	v_mov_b32_e32 v12, v2
	v_mov_b32_e32 v13, v2
	v_mov_b32_e32 v18, v2
	v_mov_b32_e32 v19, v2
	v_mov_b32_e32 v20, v2
	v_mov_b32_e32 v21, v2
	v_mov_b32_e32 v26, v2
	v_mov_b32_e32 v27, v2
	v_mov_b32_e32 v28, v2
	v_mov_b32_e32 v29, v2
	v_mov_b32_e32 v34, v2
	v_mov_b32_e32 v35, v2
	v_mov_b32_e32 v36, v2
	v_mov_b32_e32 v37, v2
	v_mov_b32_e32 v42, v2
	v_mov_b32_e32 v43, v2
	v_mov_b32_e32 v44, v2
	v_mov_b32_e32 v45, v2
	v_mov_b32_e32 v50, v2
	v_mov_b32_e32 v51, v2
	v_mov_b32_e32 v52, v2
	v_mov_b32_e32 v53, v2
	v_mov_b32_e32 v58, v2
	v_mov_b32_e32 v59, v2
	v_mov_b32_e32 v60, v2
	v_mov_b32_e32 v61, v2
	v_mov_b32_e32 v6, v2
	v_mov_b32_e32 v7, v2
	v_mov_b32_e32 v8, v2
	v_mov_b32_e32 v9, v2
	v_mov_b32_e32 v14, v2
	v_mov_b32_e32 v15, v2
	v_mov_b32_e32 v16, v2
	v_mov_b32_e32 v17, v2
	v_mov_b32_e32 v22, v2
	v_mov_b32_e32 v23, v2
	v_mov_b32_e32 v24, v2
	v_mov_b32_e32 v25, v2
	v_mov_b32_e32 v30, v2
	v_mov_b32_e32 v31, v2
	v_mov_b32_e32 v32, v2
	v_mov_b32_e32 v33, v2
	v_mov_b32_e32 v38, v2
	v_mov_b32_e32 v39, v2
	v_mov_b32_e32 v40, v2
	v_mov_b32_e32 v41, v2
	v_mov_b32_e32 v46, v2
	v_mov_b32_e32 v47, v2
	v_mov_b32_e32 v48, v2
	v_mov_b32_e32 v49, v2
	v_mov_b32_e32 v54, v2
	v_mov_b32_e32 v55, v2
	v_mov_b32_e32 v56, v2
	v_mov_b32_e32 v57, v2
	v_mov_b32_e32 v62, v2
	v_mov_b32_e32 v63, v2
	v_mov_b32_e32 v64, v2
	v_mov_b32_e32 v65, v2
	v_mov_b32_e32 v66, v2
	v_mov_b32_e32 v67, v2
	v_mov_b32_e32 v68, v2
	v_mov_b32_e32 v69, v2
	v_mov_b32_e32 v74, v2
	v_mov_b32_e32 v75, v2
	v_mov_b32_e32 v76, v2
	v_mov_b32_e32 v77, v2
	v_mov_b32_e32 v82, v2
	v_mov_b32_e32 v83, v2
	v_mov_b32_e32 v84, v2
	v_mov_b32_e32 v85, v2
	v_mov_b32_e32 v90, v2
	v_mov_b32_e32 v91, v2
	v_mov_b32_e32 v92, v2
	v_mov_b32_e32 v93, v2
	v_mov_b32_e32 v98, v2
	v_mov_b32_e32 v99, v2
	v_mov_b32_e32 v100, v2
	v_mov_b32_e32 v101, v2
	v_mov_b32_e32 v106, v2
	v_mov_b32_e32 v107, v2
	v_mov_b32_e32 v108, v2
	v_mov_b32_e32 v109, v2
	v_mov_b32_e32 v114, v2
	v_mov_b32_e32 v115, v2
	v_mov_b32_e32 v116, v2
	v_mov_b32_e32 v117, v2
	v_mov_b32_e32 v122, v2
	v_mov_b32_e32 v123, v2
	v_mov_b32_e32 v124, v2
	v_mov_b32_e32 v125, v2
	v_mov_b32_e32 v70, v2
	v_mov_b32_e32 v71, v2
	v_mov_b32_e32 v72, v2
	v_mov_b32_e32 v73, v2
	v_mov_b32_e32 v78, v2
	v_mov_b32_e32 v79, v2
	v_mov_b32_e32 v80, v2
	v_mov_b32_e32 v81, v2
	v_mov_b32_e32 v86, v2
	v_mov_b32_e32 v87, v2
	v_mov_b32_e32 v88, v2
	v_mov_b32_e32 v89, v2
	v_mov_b32_e32 v94, v2
	v_mov_b32_e32 v95, v2
	v_mov_b32_e32 v96, v2
	v_mov_b32_e32 v97, v2
	v_mov_b32_e32 v102, v2
	v_mov_b32_e32 v103, v2
	v_mov_b32_e32 v104, v2
	v_mov_b32_e32 v105, v2
	v_mov_b32_e32 v110, v2
	v_mov_b32_e32 v111, v2
	v_mov_b32_e32 v112, v2
	v_mov_b32_e32 v113, v2
	v_mov_b32_e32 v118, v2
	v_mov_b32_e32 v119, v2
	v_mov_b32_e32 v120, v2
	v_mov_b32_e32 v121, v2
	v_mov_b32_e32 v126, v2
	v_mov_b32_e32 v127, v2
	v_mov_b32_e32 v128, v2
	v_mov_b32_e32 v129, v2
	s_nop 0
	s_nop 0
	s_nop 0
	s_nop 0
	s_nop 0
	s_nop 0
	s_nop 0
	s_nop 0
	s_nop 0
	s_nop 0
	s_nop 0
	s_nop 0
	s_nop 0
	s_nop 0
	s_nop 0
.LBB0_471:
	ds_read_b128 v[148:151], v167
	ds_read_b128 v[152:155], v167 offset:1024
	ds_read_b128 v[156:159], v167 offset:2048
	ds_read_b128 v[160:163], v167 offset:3072
	ds_read_b128 v[172:175], v168
	ds_read_b128 v[176:179], v168 offset:1024
	ds_read_b128 v[180:183], v168 offset:2048
	ds_read_b128 v[184:187], v168 offset:3072
	s_add_u32 s0, s28, 0xfffc0080
	s_addc_u32 s1, s29, -1
	s_cmp_eq_u32 s53, 12
	s_cselect_b32 s31, s21, s1
	s_cselect_b32 s30, s49, s0
	s_cselect_b32 s3, s19, s52
	s_cselect_b32 s2, s50, s51
	v_lshl_add_u64 v[220:221], s[28:29], 0, v[140:141]
	s_add_i32 m0, s38, 0xc000
	ds_read_b128 v[188:191], v169
	ds_read_b128 v[192:195], v169 offset:1024
	ds_read_b128 v[196:199], v169 offset:2048
	ds_read_b128 v[200:203], v169 offset:3072
	ds_read_b128 v[204:207], v169 offset:4096
	ds_read_b128 v[208:211], v169 offset:5120
	ds_read_b128 v[212:215], v169 offset:6144
	ds_read_b128 v[216:219], v169 offset:7168
	global_load_lds_dwordx4 v[220:221], off
	v_lshl_add_u64 v[220:221], s[28:29], 0, v[142:143]
	s_add_i32 m0, s38, 0xe000
	s_nop 0
	global_load_lds_dwordx4 v[220:221], off
	s_waitcnt vmcnt(8)
	s_waitcnt lgkmcnt(0)
	s_barrier
	s_setprio 1
	v_mfma_f32_16x16x32_bf16 v[126:129], v[148:151], v[188:191], v[126:129]
	v_mfma_f32_16x16x32_bf16 v[126:129], v[152:155], v[192:195], v[126:129]
	v_mfma_f32_16x16x32_bf16 v[118:121], v[156:159], v[188:191], v[118:121]
	v_mfma_f32_16x16x32_bf16 v[118:121], v[160:163], v[192:195], v[118:121]
	v_mfma_f32_16x16x32_bf16 v[110:113], v[148:151], v[196:199], v[110:113]
	v_mfma_f32_16x16x32_bf16 v[110:113], v[152:155], v[200:203], v[110:113]
	v_mfma_f32_16x16x32_bf16 v[102:105], v[156:159], v[196:199], v[102:105]
	v_mfma_f32_16x16x32_bf16 v[102:105], v[160:163], v[200:203], v[102:105]
	v_mfma_f32_16x16x32_bf16 v[94:97], v[148:151], v[204:207], v[94:97]
	v_mfma_f32_16x16x32_bf16 v[94:97], v[152:155], v[208:211], v[94:97]
	v_mfma_f32_16x16x32_bf16 v[86:89], v[156:159], v[204:207], v[86:89]
	v_mfma_f32_16x16x32_bf16 v[86:89], v[160:163], v[208:211], v[86:89]
	v_mfma_f32_16x16x32_bf16 v[78:81], v[148:151], v[212:215], v[78:81]
	v_mfma_f32_16x16x32_bf16 v[78:81], v[152:155], v[216:219], v[78:81]
	v_mfma_f32_16x16x32_bf16 v[70:73], v[156:159], v[212:215], v[70:73]
	v_mfma_f32_16x16x32_bf16 v[70:73], v[160:163], v[216:219], v[70:73]
	s_setprio 0
	s_setprio 1
	v_mfma_f32_16x16x32_bf16 v[122:125], v[172:175], v[188:191], v[122:125]
	v_mfma_f32_16x16x32_bf16 v[122:125], v[176:179], v[192:195], v[122:125]
	v_mfma_f32_16x16x32_bf16 v[114:117], v[180:183], v[188:191], v[114:117]
	v_mfma_f32_16x16x32_bf16 v[114:117], v[184:187], v[192:195], v[114:117]
	v_mfma_f32_16x16x32_bf16 v[106:109], v[172:175], v[196:199], v[106:109]
	v_mfma_f32_16x16x32_bf16 v[106:109], v[176:179], v[200:203], v[106:109]
	v_mfma_f32_16x16x32_bf16 v[98:101], v[180:183], v[196:199], v[98:101]
	v_mfma_f32_16x16x32_bf16 v[98:101], v[184:187], v[200:203], v[98:101]
	v_mfma_f32_16x16x32_bf16 v[90:93], v[172:175], v[204:207], v[90:93]
	v_mfma_f32_16x16x32_bf16 v[90:93], v[176:179], v[208:211], v[90:93]
	v_mfma_f32_16x16x32_bf16 v[82:85], v[180:183], v[204:207], v[82:85]
	v_mfma_f32_16x16x32_bf16 v[82:85], v[184:187], v[208:211], v[82:85]
	v_mfma_f32_16x16x32_bf16 v[74:77], v[172:175], v[212:215], v[74:77]
	v_mfma_f32_16x16x32_bf16 v[74:77], v[176:179], v[216:219], v[74:77]
	v_mfma_f32_16x16x32_bf16 v[66:69], v[180:183], v[212:215], v[66:69]
	v_mfma_f32_16x16x32_bf16 v[66:69], v[184:187], v[216:219], v[66:69]
	s_setprio 0
	s_barrier
	s_add_i32 s0, s45, s35
	v_lshl_add_u64 v[220:221], s[2:3], 0, v[134:135]
	s_mov_b32 m0, s0
	ds_read_b128 v[188:191], v169 offset:16384
	ds_read_b128 v[192:195], v169 offset:17408
	ds_read_b128 v[196:199], v169 offset:18432
	ds_read_b128 v[200:203], v169 offset:19456
	ds_read_b128 v[204:207], v169 offset:20480
	ds_read_b128 v[208:211], v169 offset:21504
	ds_read_b128 v[212:215], v169 offset:22528
	ds_read_b128 v[216:219], v169 offset:23552
	global_load_lds_dwordx4 v[220:221], off
	s_add_i32 m0, s0, 0x2000
	s_add_u32 s0, s2, 0x40000
	v_lshl_add_u64 v[222:223], s[2:3], 0, v[130:131]
	s_addc_u32 s1, s3, 0
	s_add_i32 s54, s46, s35
	global_load_lds_dwordx4 v[222:223], off
	v_lshl_add_u64 v[224:225], s[0:1], 0, v[134:135]
	s_mov_b32 m0, s54
	v_lshl_add_u64 v[226:227], s[30:31], 0, v[132:133]
	global_load_lds_dwordx4 v[224:225], off
	v_lshl_add_u64 v[224:225], s[0:1], 0, v[130:131]
	s_add_i32 m0, s54, 0x2000
	s_nop 0
	global_load_lds_dwordx4 v[224:225], off
	v_lshl_add_u64 v[224:225], s[30:31], 0, v[136:137]
	s_mov_b32 m0, s38
	s_nop 0
	global_load_lds_dwordx4 v[224:225], off
	s_mov_b32 m0, s39
	s_nop 0
	global_load_lds_dwordx4 v[226:227], off
	s_waitcnt vmcnt(8)
	s_waitcnt lgkmcnt(0)
	s_barrier
	s_setprio 1
	v_mfma_f32_16x16x32_bf16 v[62:65], v[148:151], v[188:191], v[62:65]
	v_mfma_f32_16x16x32_bf16 v[62:65], v[152:155], v[192:195], v[62:65]
	v_mfma_f32_16x16x32_bf16 v[54:57], v[156:159], v[188:191], v[54:57]
	v_mfma_f32_16x16x32_bf16 v[54:57], v[160:163], v[192:195], v[54:57]
	v_mfma_f32_16x16x32_bf16 v[46:49], v[148:151], v[196:199], v[46:49]
	v_mfma_f32_16x16x32_bf16 v[46:49], v[152:155], v[200:203], v[46:49]
	v_mfma_f32_16x16x32_bf16 v[38:41], v[156:159], v[196:199], v[38:41]
	v_mfma_f32_16x16x32_bf16 v[38:41], v[160:163], v[200:203], v[38:41]
	v_mfma_f32_16x16x32_bf16 v[30:33], v[148:151], v[204:207], v[30:33]
	v_mfma_f32_16x16x32_bf16 v[30:33], v[152:155], v[208:211], v[30:33]
	v_mfma_f32_16x16x32_bf16 v[22:25], v[156:159], v[204:207], v[22:25]
	v_mfma_f32_16x16x32_bf16 v[22:25], v[160:163], v[208:211], v[22:25]
	v_mfma_f32_16x16x32_bf16 v[14:17], v[148:151], v[212:215], v[14:17]
	v_mfma_f32_16x16x32_bf16 v[14:17], v[152:155], v[216:219], v[14:17]
	v_mfma_f32_16x16x32_bf16 v[6:9], v[156:159], v[212:215], v[6:9]
	v_mfma_f32_16x16x32_bf16 v[6:9], v[160:163], v[216:219], v[6:9]
	s_setprio 0
	s_setprio 1
	v_mfma_f32_16x16x32_bf16 v[58:61], v[172:175], v[188:191], v[58:61]
	v_mfma_f32_16x16x32_bf16 v[58:61], v[176:179], v[192:195], v[58:61]
	v_mfma_f32_16x16x32_bf16 v[50:53], v[180:183], v[188:191], v[50:53]
	v_mfma_f32_16x16x32_bf16 v[50:53], v[184:187], v[192:195], v[50:53]
	v_mfma_f32_16x16x32_bf16 v[42:45], v[172:175], v[196:199], v[42:45]
	v_mfma_f32_16x16x32_bf16 v[42:45], v[176:179], v[200:203], v[42:45]
	v_mfma_f32_16x16x32_bf16 v[34:37], v[180:183], v[196:199], v[34:37]
	v_mfma_f32_16x16x32_bf16 v[34:37], v[184:187], v[200:203], v[34:37]
	v_mfma_f32_16x16x32_bf16 v[26:29], v[172:175], v[204:207], v[26:29]
	v_mfma_f32_16x16x32_bf16 v[26:29], v[176:179], v[208:211], v[26:29]
	v_mfma_f32_16x16x32_bf16 v[18:21], v[180:183], v[204:207], v[18:21]
	v_mfma_f32_16x16x32_bf16 v[18:21], v[184:187], v[208:211], v[18:21]
	v_mfma_f32_16x16x32_bf16 v[10:13], v[172:175], v[212:215], v[10:13]
	v_mfma_f32_16x16x32_bf16 v[10:13], v[176:179], v[216:219], v[10:13]
	v_mfma_f32_16x16x32_bf16 v[2:5], v[180:183], v[212:215], v[2:5]
	v_mfma_f32_16x16x32_bf16 v[2:5], v[184:187], v[216:219], v[2:5]
	s_setprio 0
	s_barrier
	s_add_i32 s54, 0, 0x18000
	s_add_i32 s55, 0, 0x1c000
	v_add_u32_e32 v160, s54, v166
	v_add_u32_e32 v171, s55, v166
	ds_read_b128 v[148:151], v160
	ds_read_b128 v[152:155], v160 offset:1024
	ds_read_b128 v[156:159], v160 offset:2048
	ds_read_b128 v[160:163], v160 offset:3072
	ds_read_b128 v[172:175], v171
	ds_read_b128 v[176:179], v171 offset:1024
	ds_read_b128 v[180:183], v171 offset:2048
	ds_read_b128 v[184:187], v171 offset:3072
	s_add_u32 s0, s30, 0x40000
	s_addc_u32 s1, s31, 0
	s_mov_b32 m0, s40
	v_lshl_add_u64 v[228:229], s[0:1], 0, v[136:137]
	ds_read_b128 v[188:191], v169 offset:32768
	ds_read_b128 v[192:195], v169 offset:33792
	ds_read_b128 v[196:199], v169 offset:34816
	ds_read_b128 v[200:203], v169 offset:35840
	ds_read_b128 v[204:207], v169 offset:36864
	ds_read_b128 v[208:211], v169 offset:37888
	ds_read_b128 v[212:215], v169 offset:38912
	ds_read_b128 v[216:219], v169 offset:39936
	global_load_lds_dwordx4 v[228:229], off
	v_lshl_add_u64 v[228:229], s[0:1], 0, v[132:133]
	s_mov_b32 m0, s41
	s_nop 0
	global_load_lds_dwordx4 v[228:229], off
	s_waitcnt vmcnt(8)
	s_waitcnt lgkmcnt(0)
	s_barrier
	s_setprio 1
	v_mfma_f32_16x16x32_bf16 v[126:129], v[148:151], v[188:191], v[126:129]
	v_mfma_f32_16x16x32_bf16 v[126:129], v[152:155], v[192:195], v[126:129]
	v_mfma_f32_16x16x32_bf16 v[118:121], v[156:159], v[188:191], v[118:121]
	v_mfma_f32_16x16x32_bf16 v[118:121], v[160:163], v[192:195], v[118:121]
	v_mfma_f32_16x16x32_bf16 v[110:113], v[148:151], v[196:199], v[110:113]
	v_mfma_f32_16x16x32_bf16 v[110:113], v[152:155], v[200:203], v[110:113]
	v_mfma_f32_16x16x32_bf16 v[102:105], v[156:159], v[196:199], v[102:105]
	v_mfma_f32_16x16x32_bf16 v[102:105], v[160:163], v[200:203], v[102:105]
	v_mfma_f32_16x16x32_bf16 v[94:97], v[148:151], v[204:207], v[94:97]
	v_mfma_f32_16x16x32_bf16 v[94:97], v[152:155], v[208:211], v[94:97]
	v_mfma_f32_16x16x32_bf16 v[86:89], v[156:159], v[204:207], v[86:89]
	v_mfma_f32_16x16x32_bf16 v[86:89], v[160:163], v[208:211], v[86:89]
	v_mfma_f32_16x16x32_bf16 v[78:81], v[148:151], v[212:215], v[78:81]
	v_mfma_f32_16x16x32_bf16 v[78:81], v[152:155], v[216:219], v[78:81]
	v_mfma_f32_16x16x32_bf16 v[70:73], v[156:159], v[212:215], v[70:73]
	v_mfma_f32_16x16x32_bf16 v[70:73], v[160:163], v[216:219], v[70:73]
	s_setprio 0
	s_setprio 1
	v_mfma_f32_16x16x32_bf16 v[122:125], v[172:175], v[188:191], v[122:125]
	v_mfma_f32_16x16x32_bf16 v[122:125], v[176:179], v[192:195], v[122:125]
	v_mfma_f32_16x16x32_bf16 v[114:117], v[180:183], v[188:191], v[114:117]
	v_mfma_f32_16x16x32_bf16 v[114:117], v[184:187], v[192:195], v[114:117]
	v_mfma_f32_16x16x32_bf16 v[106:109], v[172:175], v[196:199], v[106:109]
	v_mfma_f32_16x16x32_bf16 v[106:109], v[176:179], v[200:203], v[106:109]
	v_mfma_f32_16x16x32_bf16 v[98:101], v[180:183], v[196:199], v[98:101]
	v_mfma_f32_16x16x32_bf16 v[98:101], v[184:187], v[200:203], v[98:101]
	v_mfma_f32_16x16x32_bf16 v[90:93], v[172:175], v[204:207], v[90:93]
	v_mfma_f32_16x16x32_bf16 v[90:93], v[176:179], v[208:211], v[90:93]
	v_mfma_f32_16x16x32_bf16 v[82:85], v[180:183], v[204:207], v[82:85]
	v_mfma_f32_16x16x32_bf16 v[82:85], v[184:187], v[208:211], v[82:85]
	v_mfma_f32_16x16x32_bf16 v[74:77], v[172:175], v[212:215], v[74:77]
	v_mfma_f32_16x16x32_bf16 v[74:77], v[176:179], v[216:219], v[74:77]
	v_mfma_f32_16x16x32_bf16 v[66:69], v[180:183], v[212:215], v[66:69]
	v_mfma_f32_16x16x32_bf16 v[66:69], v[184:187], v[216:219], v[66:69]
	s_setprio 0
	s_barrier
	s_add_i32 s0, s54, s35
	v_lshl_add_u64 v[220:221], v[220:221], 0, s[14:15]
	s_mov_b32 m0, s0
	ds_read_b128 v[188:191], v169 offset:49152
	ds_read_b128 v[192:195], v169 offset:50176
	ds_read_b128 v[196:199], v169 offset:51200
	ds_read_b128 v[200:203], v169 offset:52224
	ds_read_b128 v[204:207], v169 offset:53248
	ds_read_b128 v[208:211], v169 offset:54272
	ds_read_b128 v[212:215], v169 offset:55296
	ds_read_b128 v[216:219], v169 offset:56320
	global_load_lds_dwordx4 v[220:221], off
	s_add_i32 m0, s0, 0x2000
	s_add_u32 s0, s2, 0x40080
	v_lshl_add_u64 v[220:221], v[222:223], 0, s[14:15]
	s_addc_u32 s1, s3, 0
	s_add_i32 s2, s55, s35
	global_load_lds_dwordx4 v[220:221], off
	v_lshl_add_u64 v[220:221], s[0:1], 0, v[134:135]
	s_mov_b32 m0, s2
	s_nop 0
	global_load_lds_dwordx4 v[220:221], off
	v_lshl_add_u64 v[220:221], s[0:1], 0, v[130:131]
	s_add_i32 m0, s2, 0x2000
	s_nop 0
	global_load_lds_dwordx4 v[220:221], off
	v_lshl_add_u64 v[220:221], v[224:225], 0, s[14:15]
	s_mov_b32 m0, s42
	s_nop 0
	global_load_lds_dwordx4 v[220:221], off
	v_lshl_add_u64 v[220:221], v[226:227], 0, s[14:15]
	s_mov_b32 m0, s43
	s_nop 0
	global_load_lds_dwordx4 v[220:221], off
	s_waitcnt vmcnt(8)
	s_waitcnt lgkmcnt(0)
	s_barrier
	s_setprio 1
	v_mfma_f32_16x16x32_bf16 v[62:65], v[148:151], v[188:191], v[62:65]
	v_mfma_f32_16x16x32_bf16 v[62:65], v[152:155], v[192:195], v[62:65]
	v_mfma_f32_16x16x32_bf16 v[54:57], v[156:159], v[188:191], v[54:57]
	v_mfma_f32_16x16x32_bf16 v[54:57], v[160:163], v[192:195], v[54:57]
	v_mfma_f32_16x16x32_bf16 v[46:49], v[148:151], v[196:199], v[46:49]
	v_mfma_f32_16x16x32_bf16 v[46:49], v[152:155], v[200:203], v[46:49]
	v_mfma_f32_16x16x32_bf16 v[38:41], v[156:159], v[196:199], v[38:41]
	v_mfma_f32_16x16x32_bf16 v[38:41], v[160:163], v[200:203], v[38:41]
	v_mfma_f32_16x16x32_bf16 v[30:33], v[148:151], v[204:207], v[30:33]
	v_mfma_f32_16x16x32_bf16 v[30:33], v[152:155], v[208:211], v[30:33]
	v_mfma_f32_16x16x32_bf16 v[22:25], v[156:159], v[204:207], v[22:25]
	v_mfma_f32_16x16x32_bf16 v[22:25], v[160:163], v[208:211], v[22:25]
	v_mfma_f32_16x16x32_bf16 v[14:17], v[148:151], v[212:215], v[14:17]
	v_mfma_f32_16x16x32_bf16 v[14:17], v[152:155], v[216:219], v[14:17]
	v_mfma_f32_16x16x32_bf16 v[6:9], v[156:159], v[212:215], v[6:9]
	v_mfma_f32_16x16x32_bf16 v[6:9], v[160:163], v[216:219], v[6:9]
	s_setprio 0
	s_setprio 1
	v_mfma_f32_16x16x32_bf16 v[58:61], v[172:175], v[188:191], v[58:61]
	v_mfma_f32_16x16x32_bf16 v[58:61], v[176:179], v[192:195], v[58:61]
	v_mfma_f32_16x16x32_bf16 v[50:53], v[180:183], v[188:191], v[50:53]
	v_mfma_f32_16x16x32_bf16 v[50:53], v[184:187], v[192:195], v[50:53]
	v_mfma_f32_16x16x32_bf16 v[42:45], v[172:175], v[196:199], v[42:45]
	v_mfma_f32_16x16x32_bf16 v[42:45], v[176:179], v[200:203], v[42:45]
	v_mfma_f32_16x16x32_bf16 v[34:37], v[180:183], v[196:199], v[34:37]
	v_mfma_f32_16x16x32_bf16 v[34:37], v[184:187], v[200:203], v[34:37]
	v_mfma_f32_16x16x32_bf16 v[26:29], v[172:175], v[204:207], v[26:29]
	v_mfma_f32_16x16x32_bf16 v[26:29], v[176:179], v[208:211], v[26:29]
	v_mfma_f32_16x16x32_bf16 v[18:21], v[180:183], v[204:207], v[18:21]
	v_mfma_f32_16x16x32_bf16 v[18:21], v[184:187], v[208:211], v[18:21]
	v_mfma_f32_16x16x32_bf16 v[10:13], v[172:175], v[212:215], v[10:13]
	v_mfma_f32_16x16x32_bf16 v[10:13], v[176:179], v[216:219], v[10:13]
	v_mfma_f32_16x16x32_bf16 v[2:5], v[180:183], v[212:215], v[2:5]
	v_mfma_f32_16x16x32_bf16 v[2:5], v[184:187], v[216:219], v[2:5]
	s_setprio 0
	s_barrier
	s_add_i32 s53, s53, 2
	s_add_u32 s28, s28, 0x100
	s_addc_u32 s29, s29, 0
	s_add_u32 s51, s51, 0x100
	s_addc_u32 s52, s52, 0
	s_cmp_gt_u32 s53, 13
	s_cbranch_scc0 .LBB0_471
	s_and_b64 vcc, exec, s[16:17]
	s_cbranch_vccz .LBB0_474
	s_barrier

.LBB0_583:
	s_add_u32 s22, s22, 0xb0080
	s_addc_u32 s23, s23, 0
	s_add_u32 s45, s2, 0x100
	v_mov_b32_e32 v2, 0
	s_addc_u32 s46, s3, 0
	s_mov_b32 s47, -2
	s_waitcnt lgkmcnt(0)
	v_mov_b32_e32 v3, v2
	v_mov_b32_e32 v4, v2
	v_mov_b32_e32 v5, v2
	v_mov_b32_e32 v6, v2
	v_mov_b32_e32 v7, v2
	v_mov_b32_e32 v8, v2
	v_mov_b32_e32 v9, v2
	v_mov_b32_e32 v18, v2
	v_mov_b32_e32 v19, v2
	v_mov_b32_e32 v20, v2
	v_mov_b32_e32 v21, v2
	v_mov_b32_e32 v22, v2
	v_mov_b32_e32 v23, v2
	v_mov_b32_e32 v24, v2
	v_mov_b32_e32 v25, v2
	v_mov_b32_e32 v34, v2
	v_mov_b32_e32 v35, v2
	v_mov_b32_e32 v36, v2
	v_mov_b32_e32 v37, v2
	v_mov_b32_e32 v38, v2
	v_mov_b32_e32 v39, v2
	v_mov_b32_e32 v40, v2
	v_mov_b32_e32 v41, v2
	v_mov_b32_e32 v50, v2
	v_mov_b32_e32 v51, v2
	v_mov_b32_e32 v52, v2
	v_mov_b32_e32 v53, v2
	v_mov_b32_e32 v54, v2
	v_mov_b32_e32 v55, v2
	v_mov_b32_e32 v56, v2
	v_mov_b32_e32 v57, v2
	v_mov_b32_e32 v10, v2
	v_mov_b32_e32 v11, v2
	v_mov_b32_e32 v12, v2
	v_mov_b32_e32 v13, v2
	v_mov_b32_e32 v14, v2
	v_mov_b32_e32 v15, v2
	v_mov_b32_e32 v16, v2
	v_mov_b32_e32 v17, v2
	v_mov_b32_e32 v26, v2
	v_mov_b32_e32 v27, v2
	v_mov_b32_e32 v28, v2
	v_mov_b32_e32 v29, v2
	v_mov_b32_e32 v30, v2
	v_mov_b32_e32 v31, v2
	v_mov_b32_e32 v32, v2
	v_mov_b32_e32 v33, v2
	v_mov_b32_e32 v42, v2
	v_mov_b32_e32 v43, v2
	v_mov_b32_e32 v44, v2
	v_mov_b32_e32 v45, v2
	v_mov_b32_e32 v46, v2
	v_mov_b32_e32 v47, v2
	v_mov_b32_e32 v48, v2
	v_mov_b32_e32 v49, v2
	v_mov_b32_e32 v58, v2
	v_mov_b32_e32 v59, v2
	v_mov_b32_e32 v60, v2
	v_mov_b32_e32 v61, v2
	v_mov_b32_e32 v62, v2
	v_mov_b32_e32 v63, v2
	v_mov_b32_e32 v64, v2
	v_mov_b32_e32 v65, v2
	v_mov_b32_e32 v66, v2
	v_mov_b32_e32 v67, v2
	v_mov_b32_e32 v68, v2
	v_mov_b32_e32 v69, v2
	v_mov_b32_e32 v70, v2
	v_mov_b32_e32 v71, v2
	v_mov_b32_e32 v72, v2
	v_mov_b32_e32 v73, v2
	v_mov_b32_e32 v82, v2
	v_mov_b32_e32 v83, v2
	v_mov_b32_e32 v84, v2
	v_mov_b32_e32 v85, v2
	v_mov_b32_e32 v86, v2
	v_mov_b32_e32 v87, v2
	v_mov_b32_e32 v88, v2
	v_mov_b32_e32 v89, v2
	v_mov_b32_e32 v98, v2
	v_mov_b32_e32 v99, v2
	v_mov_b32_e32 v100, v2
	v_mov_b32_e32 v101, v2
	v_mov_b32_e32 v102, v2
	v_mov_b32_e32 v103, v2
	v_mov_b32_e32 v104, v2
	v_mov_b32_e32 v105, v2
	v_mov_b32_e32 v114, v2
	v_mov_b32_e32 v115, v2
	v_mov_b32_e32 v116, v2
	v_mov_b32_e32 v117, v2
	v_mov_b32_e32 v118, v2
	v_mov_b32_e32 v119, v2
	v_mov_b32_e32 v120, v2
	v_mov_b32_e32 v121, v2
	v_mov_b32_e32 v74, v2
	v_mov_b32_e32 v75, v2
	v_mov_b32_e32 v76, v2
	v_mov_b32_e32 v77, v2
	v_mov_b32_e32 v78, v2
	v_mov_b32_e32 v79, v2
	v_mov_b32_e32 v80, v2
	v_mov_b32_e32 v81, v2
	v_mov_b32_e32 v90, v2
	v_mov_b32_e32 v91, v2
	v_mov_b32_e32 v92, v2
	v_mov_b32_e32 v93, v2
	v_mov_b32_e32 v94, v2
	v_mov_b32_e32 v95, v2
	v_mov_b32_e32 v96, v2
	v_mov_b32_e32 v97, v2
	v_mov_b32_e32 v106, v2
	v_mov_b32_e32 v107, v2
	v_mov_b32_e32 v108, v2
	v_mov_b32_e32 v109, v2
	v_mov_b32_e32 v110, v2
	v_mov_b32_e32 v111, v2
	v_mov_b32_e32 v112, v2
	v_mov_b32_e32 v113, v2
	v_mov_b32_e32 v122, v2
	v_mov_b32_e32 v123, v2
	v_mov_b32_e32 v124, v2
	v_mov_b32_e32 v125, v2
	v_mov_b32_e32 v126, v2
	v_mov_b32_e32 v127, v2
	v_mov_b32_e32 v128, v2
	v_mov_b32_e32 v129, v2
	s_nop 0
	s_nop 0
	s_nop 0
	s_nop 0
	s_nop 0
	s_nop 0
	s_nop 0
	s_nop 0
	s_nop 0
	s_nop 0
	s_nop 0
	s_nop 0
	s_nop 0
	s_nop 0
.LBB0_584:
	ds_read_b128 v[130:133], v187
	ds_read_b128 v[134:137], v187 offset:1024
	ds_read_b128 v[138:141], v187 offset:2048
	ds_read_b128 v[142:145], v187 offset:3072
	ds_read_b128 v[146:149], v188
	ds_read_b128 v[150:153], v188 offset:1024
	ds_read_b128 v[170:173], v188 offset:2048
	ds_read_b128 v[174:177], v188 offset:3072
	s_add_u32 s0, s22, 0xfff50080
	s_addc_u32 s1, s23, -1
	s_cmp_eq_u32 s47, 40
	s_cselect_b32 s25, s9, s1
	s_cselect_b32 s24, s8, s0
	s_cselect_b32 s3, s21, s46
	s_cselect_b32 s2, s20, s45
	v_lshl_add_u64 v[220:221], s[22:23], 0, v[162:163]
	s_add_i32 m0, s31, 0xc000
	ds_read_b128 v[178:181], v189
	ds_read_b128 v[192:195], v189 offset:1024
	ds_read_b128 v[196:199], v189 offset:2048
	ds_read_b128 v[200:203], v189 offset:3072
	ds_read_b128 v[204:207], v189 offset:4096
	ds_read_b128 v[208:211], v189 offset:5120
	ds_read_b128 v[212:215], v189 offset:6144
	ds_read_b128 v[216:219], v189 offset:7168
	global_load_lds_dwordx4 v[220:221], off
	v_lshl_add_u64 v[220:221], s[22:23], 0, v[164:165]
	s_add_i32 m0, s31, 0xe000
	s_nop 0
	global_load_lds_dwordx4 v[220:221], off
	s_waitcnt vmcnt(8)
	s_waitcnt lgkmcnt(0)
	s_barrier
	s_setprio 1
	v_mfma_f32_16x16x32_bf16 v[126:129], v[130:133], v[178:181], v[126:129]
	v_mfma_f32_16x16x32_bf16 v[126:129], v[134:137], v[192:195], v[126:129]
	v_mfma_f32_16x16x32_bf16 v[122:125], v[138:141], v[178:181], v[122:125]
	v_mfma_f32_16x16x32_bf16 v[122:125], v[142:145], v[192:195], v[122:125]
	v_mfma_f32_16x16x32_bf16 v[110:113], v[130:133], v[196:199], v[110:113]
	v_mfma_f32_16x16x32_bf16 v[110:113], v[134:137], v[200:203], v[110:113]
	v_mfma_f32_16x16x32_bf16 v[106:109], v[138:141], v[196:199], v[106:109]
	v_mfma_f32_16x16x32_bf16 v[106:109], v[142:145], v[200:203], v[106:109]
	v_mfma_f32_16x16x32_bf16 v[94:97], v[130:133], v[204:207], v[94:97]
	v_mfma_f32_16x16x32_bf16 v[94:97], v[134:137], v[208:211], v[94:97]
	v_mfma_f32_16x16x32_bf16 v[90:93], v[138:141], v[204:207], v[90:93]
	v_mfma_f32_16x16x32_bf16 v[90:93], v[142:145], v[208:211], v[90:93]
	v_mfma_f32_16x16x32_bf16 v[78:81], v[130:133], v[212:215], v[78:81]
	v_mfma_f32_16x16x32_bf16 v[78:81], v[134:137], v[216:219], v[78:81]
	v_mfma_f32_16x16x32_bf16 v[74:77], v[138:141], v[212:215], v[74:77]
	v_mfma_f32_16x16x32_bf16 v[74:77], v[142:145], v[216:219], v[74:77]
	s_setprio 0
	s_setprio 1
	v_mfma_f32_16x16x32_bf16 v[118:121], v[146:149], v[178:181], v[118:121]
	v_mfma_f32_16x16x32_bf16 v[118:121], v[150:153], v[192:195], v[118:121]
	v_mfma_f32_16x16x32_bf16 v[114:117], v[170:173], v[178:181], v[114:117]
	v_mfma_f32_16x16x32_bf16 v[114:117], v[174:177], v[192:195], v[114:117]
	v_mfma_f32_16x16x32_bf16 v[102:105], v[146:149], v[196:199], v[102:105]
	v_mfma_f32_16x16x32_bf16 v[102:105], v[150:153], v[200:203], v[102:105]
	v_mfma_f32_16x16x32_bf16 v[98:101], v[170:173], v[196:199], v[98:101]
	v_mfma_f32_16x16x32_bf16 v[98:101], v[174:177], v[200:203], v[98:101]
	v_mfma_f32_16x16x32_bf16 v[86:89], v[146:149], v[204:207], v[86:89]
	v_mfma_f32_16x16x32_bf16 v[86:89], v[150:153], v[208:211], v[86:89]
	v_mfma_f32_16x16x32_bf16 v[82:85], v[170:173], v[204:207], v[82:85]
	v_mfma_f32_16x16x32_bf16 v[82:85], v[174:177], v[208:211], v[82:85]
	v_mfma_f32_16x16x32_bf16 v[70:73], v[146:149], v[212:215], v[70:73]
	v_mfma_f32_16x16x32_bf16 v[70:73], v[150:153], v[216:219], v[70:73]
	v_mfma_f32_16x16x32_bf16 v[66:69], v[170:173], v[212:215], v[66:69]
	v_mfma_f32_16x16x32_bf16 v[66:69], v[174:177], v[216:219], v[66:69]
	s_setprio 0
	s_barrier
	s_add_i32 s0, s41, s30
	v_lshl_add_u64 v[220:221], s[2:3], 0, v[156:157]
	s_mov_b32 m0, s0
	ds_read_b128 v[178:181], v189 offset:16384
	ds_read_b128 v[192:195], v189 offset:17408
	ds_read_b128 v[196:199], v189 offset:18432
	ds_read_b128 v[200:203], v189 offset:19456
	ds_read_b128 v[204:207], v189 offset:20480
	ds_read_b128 v[208:211], v189 offset:21504
	ds_read_b128 v[212:215], v189 offset:22528
	ds_read_b128 v[216:219], v189 offset:23552
	global_load_lds_dwordx4 v[220:221], off
	s_add_i32 m0, s0, 0x2000
	s_add_u32 s0, s2, 0xb0000
	v_lshl_add_u64 v[222:223], s[2:3], 0, v[160:161]
	s_addc_u32 s1, s3, 0
	s_add_i32 s48, s42, s30
	global_load_lds_dwordx4 v[222:223], off
	v_lshl_add_u64 v[224:225], s[0:1], 0, v[156:157]
	s_mov_b32 m0, s48
	v_lshl_add_u64 v[226:227], s[24:25], 0, v[158:159]
	global_load_lds_dwordx4 v[224:225], off
	v_lshl_add_u64 v[224:225], s[0:1], 0, v[160:161]
	s_add_i32 m0, s48, 0x2000
	s_nop 0
	global_load_lds_dwordx4 v[224:225], off
	v_lshl_add_u64 v[224:225], s[24:25], 0, v[154:155]
	s_mov_b32 m0, s31
	s_nop 0
	global_load_lds_dwordx4 v[224:225], off
	s_mov_b32 m0, s33
	s_nop 0
	global_load_lds_dwordx4 v[226:227], off
	s_waitcnt vmcnt(8)
	s_waitcnt lgkmcnt(0)
	s_barrier
	s_setprio 1
	v_mfma_f32_16x16x32_bf16 v[62:65], v[130:133], v[178:181], v[62:65]
	v_mfma_f32_16x16x32_bf16 v[62:65], v[134:137], v[192:195], v[62:65]
	v_mfma_f32_16x16x32_bf16 v[58:61], v[138:141], v[178:181], v[58:61]
	v_mfma_f32_16x16x32_bf16 v[58:61], v[142:145], v[192:195], v[58:61]
	v_mfma_f32_16x16x32_bf16 v[46:49], v[130:133], v[196:199], v[46:49]
	v_mfma_f32_16x16x32_bf16 v[46:49], v[134:137], v[200:203], v[46:49]
	v_mfma_f32_16x16x32_bf16 v[42:45], v[138:141], v[196:199], v[42:45]
	v_mfma_f32_16x16x32_bf16 v[42:45], v[142:145], v[200:203], v[42:45]
	v_mfma_f32_16x16x32_bf16 v[30:33], v[130:133], v[204:207], v[30:33]
	v_mfma_f32_16x16x32_bf16 v[30:33], v[134:137], v[208:211], v[30:33]
	v_mfma_f32_16x16x32_bf16 v[26:29], v[138:141], v[204:207], v[26:29]
	v_mfma_f32_16x16x32_bf16 v[26:29], v[142:145], v[208:211], v[26:29]
	v_mfma_f32_16x16x32_bf16 v[14:17], v[130:133], v[212:215], v[14:17]
	v_mfma_f32_16x16x32_bf16 v[14:17], v[134:137], v[216:219], v[14:17]
	v_mfma_f32_16x16x32_bf16 v[10:13], v[138:141], v[212:215], v[10:13]
	v_mfma_f32_16x16x32_bf16 v[10:13], v[142:145], v[216:219], v[10:13]
	s_setprio 0
	s_setprio 1
	v_mfma_f32_16x16x32_bf16 v[54:57], v[146:149], v[178:181], v[54:57]
	v_mfma_f32_16x16x32_bf16 v[54:57], v[150:153], v[192:195], v[54:57]
	v_mfma_f32_16x16x32_bf16 v[50:53], v[170:173], v[178:181], v[50:53]
	v_mfma_f32_16x16x32_bf16 v[50:53], v[174:177], v[192:195], v[50:53]
	v_mfma_f32_16x16x32_bf16 v[38:41], v[146:149], v[196:199], v[38:41]
	v_mfma_f32_16x16x32_bf16 v[38:41], v[150:153], v[200:203], v[38:41]
	v_mfma_f32_16x16x32_bf16 v[34:37], v[170:173], v[196:199], v[34:37]
	v_mfma_f32_16x16x32_bf16 v[34:37], v[174:177], v[200:203], v[34:37]
	v_mfma_f32_16x16x32_bf16 v[22:25], v[146:149], v[204:207], v[22:25]
	v_mfma_f32_16x16x32_bf16 v[22:25], v[150:153], v[208:211], v[22:25]
	v_mfma_f32_16x16x32_bf16 v[18:21], v[170:173], v[204:207], v[18:21]
	v_mfma_f32_16x16x32_bf16 v[18:21], v[174:177], v[208:211], v[18:21]
	v_mfma_f32_16x16x32_bf16 v[6:9], v[146:149], v[212:215], v[6:9]
	v_mfma_f32_16x16x32_bf16 v[6:9], v[150:153], v[216:219], v[6:9]
	v_mfma_f32_16x16x32_bf16 v[2:5], v[170:173], v[212:215], v[2:5]
	v_mfma_f32_16x16x32_bf16 v[2:5], v[174:177], v[216:219], v[2:5]
	s_setprio 0
	s_barrier
	s_add_i32 s48, 0, 0x18000
	s_add_i32 s49, 0, 0x1c000
	v_add_u32_e32 v142, s48, v183
	v_add_u32_e32 v174, s49, v183
	ds_read_b128 v[130:133], v142
	ds_read_b128 v[134:137], v142 offset:1024
	ds_read_b128 v[138:141], v142 offset:2048
	ds_read_b128 v[142:145], v142 offset:3072
	ds_read_b128 v[146:149], v174
	ds_read_b128 v[150:153], v174 offset:1024
	ds_read_b128 v[170:173], v174 offset:2048
	ds_read_b128 v[174:177], v174 offset:3072
	s_add_u32 s0, s24, 0xb0000
	s_addc_u32 s1, s25, 0
	s_mov_b32 m0, s34
	v_lshl_add_u64 v[228:229], s[0:1], 0, v[154:155]
	ds_read_b128 v[178:181], v189 offset:32768
	ds_read_b128 v[192:195], v189 offset:33792
	ds_read_b128 v[196:199], v189 offset:34816
	ds_read_b128 v[200:203], v189 offset:35840
	ds_read_b128 v[204:207], v189 offset:36864
	ds_read_b128 v[208:211], v189 offset:37888
	ds_read_b128 v[212:215], v189 offset:38912
	ds_read_b128 v[216:219], v189 offset:39936
	global_load_lds_dwordx4 v[228:229], off
	v_lshl_add_u64 v[228:229], s[0:1], 0, v[158:159]
	s_mov_b32 m0, s35
	s_nop 0
	global_load_lds_dwordx4 v[228:229], off
	s_waitcnt vmcnt(8)
	s_waitcnt lgkmcnt(0)
	s_barrier
	s_setprio 1
	v_mfma_f32_16x16x32_bf16 v[126:129], v[130:133], v[178:181], v[126:129]
	v_mfma_f32_16x16x32_bf16 v[126:129], v[134:137], v[192:195], v[126:129]
	v_mfma_f32_16x16x32_bf16 v[122:125], v[138:141], v[178:181], v[122:125]
	v_mfma_f32_16x16x32_bf16 v[122:125], v[142:145], v[192:195], v[122:125]
	v_mfma_f32_16x16x32_bf16 v[110:113], v[130:133], v[196:199], v[110:113]
	v_mfma_f32_16x16x32_bf16 v[110:113], v[134:137], v[200:203], v[110:113]
	v_mfma_f32_16x16x32_bf16 v[106:109], v[138:141], v[196:199], v[106:109]
	v_mfma_f32_16x16x32_bf16 v[106:109], v[142:145], v[200:203], v[106:109]
	v_mfma_f32_16x16x32_bf16 v[94:97], v[130:133], v[204:207], v[94:97]
	v_mfma_f32_16x16x32_bf16 v[94:97], v[134:137], v[208:211], v[94:97]
	v_mfma_f32_16x16x32_bf16 v[90:93], v[138:141], v[204:207], v[90:93]
	v_mfma_f32_16x16x32_bf16 v[90:93], v[142:145], v[208:211], v[90:93]
	v_mfma_f32_16x16x32_bf16 v[78:81], v[130:133], v[212:215], v[78:81]
	v_mfma_f32_16x16x32_bf16 v[78:81], v[134:137], v[216:219], v[78:81]
	v_mfma_f32_16x16x32_bf16 v[74:77], v[138:141], v[212:215], v[74:77]
	v_mfma_f32_16x16x32_bf16 v[74:77], v[142:145], v[216:219], v[74:77]
	s_setprio 0
	s_setprio 1
	v_mfma_f32_16x16x32_bf16 v[118:121], v[146:149], v[178:181], v[118:121]
	v_mfma_f32_16x16x32_bf16 v[118:121], v[150:153], v[192:195], v[118:121]
	v_mfma_f32_16x16x32_bf16 v[114:117], v[170:173], v[178:181], v[114:117]
	v_mfma_f32_16x16x32_bf16 v[114:117], v[174:177], v[192:195], v[114:117]
	v_mfma_f32_16x16x32_bf16 v[102:105], v[146:149], v[196:199], v[102:105]
	v_mfma_f32_16x16x32_bf16 v[102:105], v[150:153], v[200:203], v[102:105]
	v_mfma_f32_16x16x32_bf16 v[98:101], v[170:173], v[196:199], v[98:101]
	v_mfma_f32_16x16x32_bf16 v[98:101], v[174:177], v[200:203], v[98:101]
	v_mfma_f32_16x16x32_bf16 v[86:89], v[146:149], v[204:207], v[86:89]
	v_mfma_f32_16x16x32_bf16 v[86:89], v[150:153], v[208:211], v[86:89]
	v_mfma_f32_16x16x32_bf16 v[82:85], v[170:173], v[204:207], v[82:85]
	v_mfma_f32_16x16x32_bf16 v[82:85], v[174:177], v[208:211], v[82:85]
	v_mfma_f32_16x16x32_bf16 v[70:73], v[146:149], v[212:215], v[70:73]
	v_mfma_f32_16x16x32_bf16 v[70:73], v[150:153], v[216:219], v[70:73]
	v_mfma_f32_16x16x32_bf16 v[66:69], v[170:173], v[212:215], v[66:69]
	v_mfma_f32_16x16x32_bf16 v[66:69], v[174:177], v[216:219], v[66:69]
	s_setprio 0
	s_barrier
	s_add_i32 s0, s48, s30
	v_lshl_add_u64 v[220:221], v[220:221], 0, s[16:17]
	s_mov_b32 m0, s0
	ds_read_b128 v[178:181], v189 offset:49152
	ds_read_b128 v[192:195], v189 offset:50176
	ds_read_b128 v[196:199], v189 offset:51200
	ds_read_b128 v[200:203], v189 offset:52224
	ds_read_b128 v[204:207], v189 offset:53248
	ds_read_b128 v[208:211], v189 offset:54272
	ds_read_b128 v[212:215], v189 offset:55296
	ds_read_b128 v[216:219], v189 offset:56320
	global_load_lds_dwordx4 v[220:221], off
	s_add_i32 m0, s0, 0x2000
	s_add_u32 s0, s2, 0xb0080
	v_lshl_add_u64 v[220:221], v[222:223], 0, s[16:17]
	s_addc_u32 s1, s3, 0
	s_add_i32 s2, s49, s30
	global_load_lds_dwordx4 v[220:221], off
	v_lshl_add_u64 v[220:221], s[0:1], 0, v[156:157]
	s_mov_b32 m0, s2
	s_nop 0
	global_load_lds_dwordx4 v[220:221], off
	v_lshl_add_u64 v[220:221], s[0:1], 0, v[160:161]
	s_add_i32 m0, s2, 0x2000
	s_nop 0
	global_load_lds_dwordx4 v[220:221], off
	v_lshl_add_u64 v[220:221], v[224:225], 0, s[16:17]
	s_mov_b32 m0, s37
	s_nop 0
	global_load_lds_dwordx4 v[220:221], off
	v_lshl_add_u64 v[220:221], v[226:227], 0, s[16:17]
	s_mov_b32 m0, s38
	s_nop 0
	global_load_lds_dwordx4 v[220:221], off
	s_waitcnt vmcnt(8)
	s_waitcnt lgkmcnt(0)
	s_barrier
	s_setprio 1
	v_mfma_f32_16x16x32_bf16 v[62:65], v[130:133], v[178:181], v[62:65]
	v_mfma_f32_16x16x32_bf16 v[62:65], v[134:137], v[192:195], v[62:65]
	v_mfma_f32_16x16x32_bf16 v[58:61], v[138:141], v[178:181], v[58:61]
	v_mfma_f32_16x16x32_bf16 v[58:61], v[142:145], v[192:195], v[58:61]
	v_mfma_f32_16x16x32_bf16 v[46:49], v[130:133], v[196:199], v[46:49]
	v_mfma_f32_16x16x32_bf16 v[46:49], v[134:137], v[200:203], v[46:49]
	v_mfma_f32_16x16x32_bf16 v[42:45], v[138:141], v[196:199], v[42:45]
	v_mfma_f32_16x16x32_bf16 v[42:45], v[142:145], v[200:203], v[42:45]
	v_mfma_f32_16x16x32_bf16 v[30:33], v[130:133], v[204:207], v[30:33]
	v_mfma_f32_16x16x32_bf16 v[30:33], v[134:137], v[208:211], v[30:33]
	v_mfma_f32_16x16x32_bf16 v[26:29], v[138:141], v[204:207], v[26:29]
	v_mfma_f32_16x16x32_bf16 v[26:29], v[142:145], v[208:211], v[26:29]
	v_mfma_f32_16x16x32_bf16 v[14:17], v[130:133], v[212:215], v[14:17]
	v_mfma_f32_16x16x32_bf16 v[14:17], v[134:137], v[216:219], v[14:17]
	v_mfma_f32_16x16x32_bf16 v[10:13], v[138:141], v[212:215], v[10:13]
	v_mfma_f32_16x16x32_bf16 v[10:13], v[142:145], v[216:219], v[10:13]
	s_setprio 0
	s_setprio 1
	v_mfma_f32_16x16x32_bf16 v[54:57], v[146:149], v[178:181], v[54:57]
	v_mfma_f32_16x16x32_bf16 v[54:57], v[150:153], v[192:195], v[54:57]
	v_mfma_f32_16x16x32_bf16 v[50:53], v[170:173], v[178:181], v[50:53]
	v_mfma_f32_16x16x32_bf16 v[50:53], v[174:177], v[192:195], v[50:53]
	v_mfma_f32_16x16x32_bf16 v[38:41], v[146:149], v[196:199], v[38:41]
	v_mfma_f32_16x16x32_bf16 v[38:41], v[150:153], v[200:203], v[38:41]
	v_mfma_f32_16x16x32_bf16 v[34:37], v[170:173], v[196:199], v[34:37]
	v_mfma_f32_16x16x32_bf16 v[34:37], v[174:177], v[200:203], v[34:37]
	v_mfma_f32_16x16x32_bf16 v[22:25], v[146:149], v[204:207], v[22:25]
	v_mfma_f32_16x16x32_bf16 v[22:25], v[150:153], v[208:211], v[22:25]
	v_mfma_f32_16x16x32_bf16 v[18:21], v[170:173], v[204:207], v[18:21]
	v_mfma_f32_16x16x32_bf16 v[18:21], v[174:177], v[208:211], v[18:21]
	v_mfma_f32_16x16x32_bf16 v[6:9], v[146:149], v[212:215], v[6:9]
	v_mfma_f32_16x16x32_bf16 v[6:9], v[150:153], v[216:219], v[6:9]
	v_mfma_f32_16x16x32_bf16 v[2:5], v[170:173], v[212:215], v[2:5]
	v_mfma_f32_16x16x32_bf16 v[2:5], v[174:177], v[216:219], v[2:5]
	s_setprio 0
	s_barrier
	s_add_i32 s47, s47, 2
	s_add_u32 s22, s22, 0x100
	s_addc_u32 s23, s23, 0
	s_add_u32 s45, s45, 0x100
	s_addc_u32 s46, s46, 0
	s_cmp_gt_u32 s47, 41
	s_cbranch_scc0 .LBB0_584
	s_and_b64 vcc, exec, s[18:19]
	s_cbranch_vccz .LBB0_587
	s_barrier

.LBB0_675:
	ds_read_b128 v[82:85], v219
	ds_read_b128 v[86:89], v219 offset:1024
	ds_read_b128 v[94:97], v219 offset:2048
	ds_read_b128 v[102:105], v219 offset:3072
	ds_read_b128 v[110:113], v220
	ds_read_b128 v[118:121], v220 offset:1024
	ds_read_b128 v[138:141], v220 offset:2048
	ds_read_b128 v[158:161], v220 offset:3072
	s_add_u32 s0, s8, 0xfffc0080
	s_addc_u32 s1, s9, -1
	s_cmp_eq_u32 s51, 12
	s_cselect_b32 s31, s7, s1
	s_cselect_b32 s30, s23, s0
	s_cselect_b32 s3, s21, s50
	s_cselect_b32 s2, s34, s35
	v_lshl_add_u64 v[224:225], s[8:9], 0, v[190:191]
	s_add_i32 m0, s29, 0xc000
	ds_read_b128 v[162:165], v221
	ds_read_b128 v[166:169], v221 offset:1024
	ds_read_b128 v[170:173], v221 offset:2048
	ds_read_b128 v[174:177], v221 offset:3072
	ds_read_b128 v[198:201], v221 offset:4096
	ds_read_b128 v[202:205], v221 offset:5120
	ds_read_b128 v[206:209], v221 offset:6144
	ds_read_b128 v[210:213], v221 offset:7168
	global_load_lds_dwordx4 v[224:225], off
	v_lshl_add_u64 v[224:225], s[8:9], 0, v[192:193]
	s_add_i32 m0, s29, 0xe000
	s_nop 0
	global_load_lds_dwordx4 v[224:225], off
	s_waitcnt vmcnt(8)
	s_waitcnt lgkmcnt(0)
	s_barrier
	s_setprio 1
	v_mfma_f32_16x16x32_bf16 v[154:157], v[82:85], v[162:165], v[154:157]
	v_mfma_f32_16x16x32_bf16 v[154:157], v[86:89], v[166:169], v[154:157]
	v_mfma_f32_16x16x32_bf16 v[150:153], v[94:97], v[162:165], v[150:153]
	v_mfma_f32_16x16x32_bf16 v[150:153], v[102:105], v[166:169], v[150:153]
	v_mfma_f32_16x16x32_bf16 v[134:137], v[82:85], v[170:173], v[134:137]
	v_mfma_f32_16x16x32_bf16 v[134:137], v[86:89], v[174:177], v[134:137]
	v_mfma_f32_16x16x32_bf16 v[130:133], v[94:97], v[170:173], v[130:133]
	v_mfma_f32_16x16x32_bf16 v[130:133], v[102:105], v[174:177], v[130:133]
	v_mfma_f32_16x16x32_bf16 v[114:117], v[82:85], v[198:201], v[114:117]
	v_mfma_f32_16x16x32_bf16 v[114:117], v[86:89], v[202:205], v[114:117]
	v_mfma_f32_16x16x32_bf16 v[106:109], v[94:97], v[198:201], v[106:109]
	v_mfma_f32_16x16x32_bf16 v[106:109], v[102:105], v[202:205], v[106:109]
	v_mfma_f32_16x16x32_bf16 v[78:81], v[82:85], v[206:209], v[78:81]
	v_mfma_f32_16x16x32_bf16 v[78:81], v[86:89], v[210:213], v[78:81]
	v_mfma_f32_16x16x32_bf16 v[74:77], v[94:97], v[206:209], v[74:77]
	v_mfma_f32_16x16x32_bf16 v[74:77], v[102:105], v[210:213], v[74:77]
	s_setprio 0
	s_setprio 1
	v_mfma_f32_16x16x32_bf16 v[146:149], v[110:113], v[162:165], v[146:149]
	v_mfma_f32_16x16x32_bf16 v[146:149], v[118:121], v[166:169], v[146:149]
	v_mfma_f32_16x16x32_bf16 v[142:145], v[138:141], v[162:165], v[142:145]
	v_mfma_f32_16x16x32_bf16 v[142:145], v[158:161], v[166:169], v[142:145]
	v_mfma_f32_16x16x32_bf16 v[126:129], v[110:113], v[170:173], v[126:129]
	v_mfma_f32_16x16x32_bf16 v[126:129], v[118:121], v[174:177], v[126:129]
	v_mfma_f32_16x16x32_bf16 v[122:125], v[138:141], v[170:173], v[122:125]
	v_mfma_f32_16x16x32_bf16 v[122:125], v[158:161], v[174:177], v[122:125]
	v_mfma_f32_16x16x32_bf16 v[98:101], v[110:113], v[198:201], v[98:101]
	v_mfma_f32_16x16x32_bf16 v[98:101], v[118:121], v[202:205], v[98:101]
	v_mfma_f32_16x16x32_bf16 v[90:93], v[138:141], v[198:201], v[90:93]
	v_mfma_f32_16x16x32_bf16 v[90:93], v[158:161], v[202:205], v[90:93]
	v_mfma_f32_16x16x32_bf16 v[70:73], v[110:113], v[206:209], v[70:73]
	v_mfma_f32_16x16x32_bf16 v[70:73], v[118:121], v[210:213], v[70:73]
	v_mfma_f32_16x16x32_bf16 v[66:69], v[138:141], v[206:209], v[66:69]
	v_mfma_f32_16x16x32_bf16 v[66:69], v[158:161], v[210:213], v[66:69]
	s_setprio 0
	s_barrier
	s_add_i32 s0, s48, s36
	v_lshl_add_u64 v[224:225], s[2:3], 0, v[182:183]
	s_mov_b32 m0, s0
	ds_read_b128 v[162:165], v221 offset:16384
	ds_read_b128 v[166:169], v221 offset:17408
	ds_read_b128 v[170:173], v221 offset:18432
	ds_read_b128 v[174:177], v221 offset:19456
	ds_read_b128 v[198:201], v221 offset:20480
	ds_read_b128 v[202:205], v221 offset:21504
	ds_read_b128 v[206:209], v221 offset:22528
	ds_read_b128 v[210:213], v221 offset:23552
	global_load_lds_dwordx4 v[224:225], off
	s_add_i32 m0, s0, 0x2000
	s_add_u32 s0, s2, 0x40000
	v_lshl_add_u64 v[226:227], s[2:3], 0, v[186:187]
	s_addc_u32 s1, s3, 0
	s_add_i32 s52, s49, s36
	global_load_lds_dwordx4 v[226:227], off
	v_lshl_add_u64 v[228:229], s[0:1], 0, v[182:183]
	s_mov_b32 m0, s52
	v_lshl_add_u64 v[230:231], s[30:31], 0, v[184:185]
	global_load_lds_dwordx4 v[228:229], off
	v_lshl_add_u64 v[228:229], s[0:1], 0, v[186:187]
	s_add_i32 m0, s52, 0x2000
	s_nop 0
	global_load_lds_dwordx4 v[228:229], off
	v_lshl_add_u64 v[228:229], s[30:31], 0, v[180:181]
	s_mov_b32 m0, s29
	s_nop 0
	global_load_lds_dwordx4 v[228:229], off
	s_mov_b32 m0, s37
	s_nop 0
	global_load_lds_dwordx4 v[230:231], off
	s_waitcnt vmcnt(8)
	s_waitcnt lgkmcnt(0)
	s_barrier
	s_setprio 1
	v_mfma_f32_16x16x32_bf16 v[62:65], v[82:85], v[162:165], v[62:65]
	v_mfma_f32_16x16x32_bf16 v[62:65], v[86:89], v[166:169], v[62:65]
	v_mfma_f32_16x16x32_bf16 v[58:61], v[94:97], v[162:165], v[58:61]
	v_mfma_f32_16x16x32_bf16 v[58:61], v[102:105], v[166:169], v[58:61]
	v_mfma_f32_16x16x32_bf16 v[46:49], v[82:85], v[170:173], v[46:49]
	v_mfma_f32_16x16x32_bf16 v[46:49], v[86:89], v[174:177], v[46:49]
	v_mfma_f32_16x16x32_bf16 v[42:45], v[94:97], v[170:173], v[42:45]
	v_mfma_f32_16x16x32_bf16 v[42:45], v[102:105], v[174:177], v[42:45]
	v_mfma_f32_16x16x32_bf16 v[30:33], v[82:85], v[198:201], v[30:33]
	v_mfma_f32_16x16x32_bf16 v[30:33], v[86:89], v[202:205], v[30:33]
	v_mfma_f32_16x16x32_bf16 v[26:29], v[94:97], v[198:201], v[26:29]
	v_mfma_f32_16x16x32_bf16 v[26:29], v[102:105], v[202:205], v[26:29]
	v_mfma_f32_16x16x32_bf16 v[14:17], v[82:85], v[206:209], v[14:17]
	v_mfma_f32_16x16x32_bf16 v[14:17], v[86:89], v[210:213], v[14:17]
	v_mfma_f32_16x16x32_bf16 v[10:13], v[94:97], v[206:209], v[10:13]
	v_mfma_f32_16x16x32_bf16 v[10:13], v[102:105], v[210:213], v[10:13]
	s_setprio 0
	s_setprio 1
	v_mfma_f32_16x16x32_bf16 v[54:57], v[110:113], v[162:165], v[54:57]
	v_mfma_f32_16x16x32_bf16 v[54:57], v[118:121], v[166:169], v[54:57]
	v_mfma_f32_16x16x32_bf16 v[50:53], v[138:141], v[162:165], v[50:53]
	v_mfma_f32_16x16x32_bf16 v[50:53], v[158:161], v[166:169], v[50:53]
	v_mfma_f32_16x16x32_bf16 v[38:41], v[110:113], v[170:173], v[38:41]
	v_mfma_f32_16x16x32_bf16 v[38:41], v[118:121], v[174:177], v[38:41]
	v_mfma_f32_16x16x32_bf16 v[34:37], v[138:141], v[170:173], v[34:37]
	v_mfma_f32_16x16x32_bf16 v[34:37], v[158:161], v[174:177], v[34:37]
	v_mfma_f32_16x16x32_bf16 v[22:25], v[110:113], v[198:201], v[22:25]
	v_mfma_f32_16x16x32_bf16 v[22:25], v[118:121], v[202:205], v[22:25]
	v_mfma_f32_16x16x32_bf16 v[18:21], v[138:141], v[198:201], v[18:21]
	v_mfma_f32_16x16x32_bf16 v[18:21], v[158:161], v[202:205], v[18:21]
	v_mfma_f32_16x16x32_bf16 v[6:9], v[110:113], v[206:209], v[6:9]
	v_mfma_f32_16x16x32_bf16 v[6:9], v[118:121], v[210:213], v[6:9]
	v_mfma_f32_16x16x32_bf16 v[2:5], v[138:141], v[206:209], v[2:5]
	v_mfma_f32_16x16x32_bf16 v[2:5], v[158:161], v[210:213], v[2:5]
	s_setprio 0
	s_barrier
	s_add_i32 s52, 0, 0x18000
	s_add_i32 s53, 0, 0x1c000
	v_add_u32_e32 v102, s52, v218
	v_add_u32_e32 v158, s53, v218
	ds_read_b128 v[82:85], v102
	ds_read_b128 v[86:89], v102 offset:1024
	ds_read_b128 v[94:97], v102 offset:2048
	ds_read_b128 v[102:105], v102 offset:3072
	ds_read_b128 v[110:113], v158
	ds_read_b128 v[118:121], v158 offset:1024
	ds_read_b128 v[138:141], v158 offset:2048
	ds_read_b128 v[158:161], v158 offset:3072
	s_add_u32 s0, s30, 0x40000
	s_addc_u32 s1, s31, 0
	s_mov_b32 m0, s38
	v_lshl_add_u64 v[232:233], s[0:1], 0, v[180:181]
	ds_read_b128 v[162:165], v221 offset:32768
	ds_read_b128 v[166:169], v221 offset:33792
	ds_read_b128 v[170:173], v221 offset:34816
	ds_read_b128 v[174:177], v221 offset:35840
	ds_read_b128 v[198:201], v221 offset:36864
	ds_read_b128 v[202:205], v221 offset:37888
	ds_read_b128 v[206:209], v221 offset:38912
	ds_read_b128 v[210:213], v221 offset:39936
	global_load_lds_dwordx4 v[232:233], off
	v_lshl_add_u64 v[232:233], s[0:1], 0, v[184:185]
	s_mov_b32 m0, s39
	s_nop 0
	global_load_lds_dwordx4 v[232:233], off
	s_waitcnt vmcnt(8)
	s_waitcnt lgkmcnt(0)
	s_barrier
	s_setprio 1
	v_mfma_f32_16x16x32_bf16 v[154:157], v[82:85], v[162:165], v[154:157]
	v_mfma_f32_16x16x32_bf16 v[154:157], v[86:89], v[166:169], v[154:157]
	v_mfma_f32_16x16x32_bf16 v[150:153], v[94:97], v[162:165], v[150:153]
	v_mfma_f32_16x16x32_bf16 v[150:153], v[102:105], v[166:169], v[150:153]
	v_mfma_f32_16x16x32_bf16 v[134:137], v[82:85], v[170:173], v[134:137]
	v_mfma_f32_16x16x32_bf16 v[134:137], v[86:89], v[174:177], v[134:137]
	v_mfma_f32_16x16x32_bf16 v[130:133], v[94:97], v[170:173], v[130:133]
	v_mfma_f32_16x16x32_bf16 v[130:133], v[102:105], v[174:177], v[130:133]
	v_mfma_f32_16x16x32_bf16 v[114:117], v[82:85], v[198:201], v[114:117]
	v_mfma_f32_16x16x32_bf16 v[114:117], v[86:89], v[202:205], v[114:117]
	v_mfma_f32_16x16x32_bf16 v[106:109], v[94:97], v[198:201], v[106:109]
	v_mfma_f32_16x16x32_bf16 v[106:109], v[102:105], v[202:205], v[106:109]
	v_mfma_f32_16x16x32_bf16 v[78:81], v[82:85], v[206:209], v[78:81]
	v_mfma_f32_16x16x32_bf16 v[78:81], v[86:89], v[210:213], v[78:81]
	v_mfma_f32_16x16x32_bf16 v[74:77], v[94:97], v[206:209], v[74:77]
	v_mfma_f32_16x16x32_bf16 v[74:77], v[102:105], v[210:213], v[74:77]
	s_setprio 0
	s_setprio 1
	v_mfma_f32_16x16x32_bf16 v[146:149], v[110:113], v[162:165], v[146:149]
	v_mfma_f32_16x16x32_bf16 v[146:149], v[118:121], v[166:169], v[146:149]
	v_mfma_f32_16x16x32_bf16 v[142:145], v[138:141], v[162:165], v[142:145]
	v_mfma_f32_16x16x32_bf16 v[142:145], v[158:161], v[166:169], v[142:145]
	v_mfma_f32_16x16x32_bf16 v[126:129], v[110:113], v[170:173], v[126:129]
	v_mfma_f32_16x16x32_bf16 v[126:129], v[118:121], v[174:177], v[126:129]
	v_mfma_f32_16x16x32_bf16 v[122:125], v[138:141], v[170:173], v[122:125]
	v_mfma_f32_16x16x32_bf16 v[122:125], v[158:161], v[174:177], v[122:125]
	v_mfma_f32_16x16x32_bf16 v[98:101], v[110:113], v[198:201], v[98:101]
	v_mfma_f32_16x16x32_bf16 v[98:101], v[118:121], v[202:205], v[98:101]
	v_mfma_f32_16x16x32_bf16 v[90:93], v[138:141], v[198:201], v[90:93]
	v_mfma_f32_16x16x32_bf16 v[90:93], v[158:161], v[202:205], v[90:93]
	v_mfma_f32_16x16x32_bf16 v[70:73], v[110:113], v[206:209], v[70:73]
	v_mfma_f32_16x16x32_bf16 v[70:73], v[118:121], v[210:213], v[70:73]
	v_mfma_f32_16x16x32_bf16 v[66:69], v[138:141], v[206:209], v[66:69]
	v_mfma_f32_16x16x32_bf16 v[66:69], v[158:161], v[210:213], v[66:69]
	s_setprio 0
	s_barrier
	s_add_i32 s0, s52, s36
	v_lshl_add_u64 v[224:225], v[224:225], 0, s[12:13]
	s_mov_b32 m0, s0
	ds_read_b128 v[162:165], v221 offset:49152
	ds_read_b128 v[166:169], v221 offset:50176
	ds_read_b128 v[170:173], v221 offset:51200
	ds_read_b128 v[174:177], v221 offset:52224
	ds_read_b128 v[198:201], v221 offset:53248
	ds_read_b128 v[202:205], v221 offset:54272
	ds_read_b128 v[206:209], v221 offset:55296
	ds_read_b128 v[210:213], v221 offset:56320
	global_load_lds_dwordx4 v[224:225], off
	s_add_i32 m0, s0, 0x2000
	s_add_u32 s0, s2, 0x40080
	v_lshl_add_u64 v[224:225], v[226:227], 0, s[12:13]
	s_addc_u32 s1, s3, 0
	s_add_i32 s2, s53, s36
	global_load_lds_dwordx4 v[224:225], off
	v_lshl_add_u64 v[224:225], s[0:1], 0, v[182:183]
	s_mov_b32 m0, s2
	s_nop 0
	global_load_lds_dwordx4 v[224:225], off
	v_lshl_add_u64 v[224:225], s[0:1], 0, v[186:187]
	s_add_i32 m0, s2, 0x2000
	s_nop 0
	global_load_lds_dwordx4 v[224:225], off
	v_lshl_add_u64 v[224:225], v[228:229], 0, s[12:13]
	s_mov_b32 m0, s44
	s_nop 0
	global_load_lds_dwordx4 v[224:225], off
	v_lshl_add_u64 v[224:225], v[230:231], 0, s[12:13]
	s_mov_b32 m0, s45
	s_nop 0
	global_load_lds_dwordx4 v[224:225], off
	s_waitcnt vmcnt(8)
	s_waitcnt lgkmcnt(0)
	s_barrier
	s_setprio 1
	v_mfma_f32_16x16x32_bf16 v[62:65], v[82:85], v[162:165], v[62:65]
	v_mfma_f32_16x16x32_bf16 v[62:65], v[86:89], v[166:169], v[62:65]
	v_mfma_f32_16x16x32_bf16 v[58:61], v[94:97], v[162:165], v[58:61]
	v_mfma_f32_16x16x32_bf16 v[58:61], v[102:105], v[166:169], v[58:61]
	v_mfma_f32_16x16x32_bf16 v[46:49], v[82:85], v[170:173], v[46:49]
	v_mfma_f32_16x16x32_bf16 v[46:49], v[86:89], v[174:177], v[46:49]
	v_mfma_f32_16x16x32_bf16 v[42:45], v[94:97], v[170:173], v[42:45]
	v_mfma_f32_16x16x32_bf16 v[42:45], v[102:105], v[174:177], v[42:45]
	v_mfma_f32_16x16x32_bf16 v[30:33], v[82:85], v[198:201], v[30:33]
	v_mfma_f32_16x16x32_bf16 v[30:33], v[86:89], v[202:205], v[30:33]
	v_mfma_f32_16x16x32_bf16 v[26:29], v[94:97], v[198:201], v[26:29]
	v_mfma_f32_16x16x32_bf16 v[26:29], v[102:105], v[202:205], v[26:29]
	v_mfma_f32_16x16x32_bf16 v[14:17], v[82:85], v[206:209], v[14:17]
	v_mfma_f32_16x16x32_bf16 v[14:17], v[86:89], v[210:213], v[14:17]
	v_mfma_f32_16x16x32_bf16 v[10:13], v[94:97], v[206:209], v[10:13]
	v_mfma_f32_16x16x32_bf16 v[10:13], v[102:105], v[210:213], v[10:13]
	s_setprio 0
	s_setprio 1
	v_mfma_f32_16x16x32_bf16 v[54:57], v[110:113], v[162:165], v[54:57]
	v_mfma_f32_16x16x32_bf16 v[54:57], v[118:121], v[166:169], v[54:57]
	v_mfma_f32_16x16x32_bf16 v[50:53], v[138:141], v[162:165], v[50:53]
	v_mfma_f32_16x16x32_bf16 v[50:53], v[158:161], v[166:169], v[50:53]
	v_mfma_f32_16x16x32_bf16 v[38:41], v[110:113], v[170:173], v[38:41]
	v_mfma_f32_16x16x32_bf16 v[38:41], v[118:121], v[174:177], v[38:41]
	v_mfma_f32_16x16x32_bf16 v[34:37], v[138:141], v[170:173], v[34:37]
	v_mfma_f32_16x16x32_bf16 v[34:37], v[158:161], v[174:177], v[34:37]
	v_mfma_f32_16x16x32_bf16 v[22:25], v[110:113], v[198:201], v[22:25]
	v_mfma_f32_16x16x32_bf16 v[22:25], v[118:121], v[202:205], v[22:25]
	v_mfma_f32_16x16x32_bf16 v[18:21], v[138:141], v[198:201], v[18:21]
	v_mfma_f32_16x16x32_bf16 v[18:21], v[158:161], v[202:205], v[18:21]
	v_mfma_f32_16x16x32_bf16 v[6:9], v[110:113], v[206:209], v[6:9]
	v_mfma_f32_16x16x32_bf16 v[6:9], v[118:121], v[210:213], v[6:9]
	v_mfma_f32_16x16x32_bf16 v[2:5], v[138:141], v[206:209], v[2:5]
	v_mfma_f32_16x16x32_bf16 v[2:5], v[158:161], v[210:213], v[2:5]
	s_setprio 0
	s_barrier
	s_add_i32 s51, s51, 2
	s_add_u32 s8, s8, 0x100
	s_addc_u32 s9, s9, 0
	s_add_u32 s35, s35, 0x100
	s_addc_u32 s50, s50, 0
	s_cmp_gt_u32 s51, 13
	s_cbranch_scc0 .LBB0_675
	s_and_b64 vcc, exec, s[14:15]
	s_cbranch_vccz .LBB0_678
	s_barrier

.LBB0_920:
	ds_read_b128 v[130:133], v187
	ds_read_b128 v[134:137], v187 offset:1024
	ds_read_b128 v[138:141], v187 offset:2048
	ds_read_b128 v[142:145], v187 offset:3072
	ds_read_b128 v[146:149], v188
	ds_read_b128 v[150:153], v188 offset:1024
	ds_read_b128 v[170:173], v188 offset:2048
	ds_read_b128 v[174:177], v188 offset:3072
	s_add_u32 s0, s28, 0xfffc0080
	s_addc_u32 s1, s29, -1
	s_cmp_eq_u32 s51, 12
	s_cselect_b32 s31, s11, s1
	s_cselect_b32 s30, s21, s0
	s_cselect_b32 s3, s19, s50
	s_cselect_b32 s2, s48, s49
	v_lshl_add_u64 v[220:221], s[28:29], 0, v[162:163]
	s_add_i32 m0, s27, 0xc000
	ds_read_b128 v[178:181], v189
	ds_read_b128 v[192:195], v189 offset:1024
	ds_read_b128 v[196:199], v189 offset:2048
	ds_read_b128 v[200:203], v189 offset:3072
	ds_read_b128 v[204:207], v189 offset:4096
	ds_read_b128 v[208:211], v189 offset:5120
	ds_read_b128 v[212:215], v189 offset:6144
	ds_read_b128 v[216:219], v189 offset:7168
	global_load_lds_dwordx4 v[220:221], off
	v_lshl_add_u64 v[220:221], s[28:29], 0, v[164:165]
	s_add_i32 m0, s27, 0xe000
	s_nop 0
	global_load_lds_dwordx4 v[220:221], off
	s_waitcnt vmcnt(8)
	s_waitcnt lgkmcnt(0)
	s_barrier
	s_setprio 1
	v_mfma_f32_16x16x32_bf16 v[126:129], v[130:133], v[178:181], v[126:129]
	v_mfma_f32_16x16x32_bf16 v[126:129], v[134:137], v[192:195], v[126:129]
	v_mfma_f32_16x16x32_bf16 v[122:125], v[138:141], v[178:181], v[122:125]
	v_mfma_f32_16x16x32_bf16 v[122:125], v[142:145], v[192:195], v[122:125]
	v_mfma_f32_16x16x32_bf16 v[110:113], v[130:133], v[196:199], v[110:113]
	v_mfma_f32_16x16x32_bf16 v[110:113], v[134:137], v[200:203], v[110:113]
	v_mfma_f32_16x16x32_bf16 v[106:109], v[138:141], v[196:199], v[106:109]
	v_mfma_f32_16x16x32_bf16 v[106:109], v[142:145], v[200:203], v[106:109]
	v_mfma_f32_16x16x32_bf16 v[94:97], v[130:133], v[204:207], v[94:97]
	v_mfma_f32_16x16x32_bf16 v[94:97], v[134:137], v[208:211], v[94:97]
	v_mfma_f32_16x16x32_bf16 v[90:93], v[138:141], v[204:207], v[90:93]
	v_mfma_f32_16x16x32_bf16 v[90:93], v[142:145], v[208:211], v[90:93]
	v_mfma_f32_16x16x32_bf16 v[78:81], v[130:133], v[212:215], v[78:81]
	v_mfma_f32_16x16x32_bf16 v[78:81], v[134:137], v[216:219], v[78:81]
	v_mfma_f32_16x16x32_bf16 v[74:77], v[138:141], v[212:215], v[74:77]
	v_mfma_f32_16x16x32_bf16 v[74:77], v[142:145], v[216:219], v[74:77]
	s_setprio 0
	s_setprio 1
	v_mfma_f32_16x16x32_bf16 v[118:121], v[146:149], v[178:181], v[118:121]
	v_mfma_f32_16x16x32_bf16 v[118:121], v[150:153], v[192:195], v[118:121]
	v_mfma_f32_16x16x32_bf16 v[114:117], v[170:173], v[178:181], v[114:117]
	v_mfma_f32_16x16x32_bf16 v[114:117], v[174:177], v[192:195], v[114:117]
	v_mfma_f32_16x16x32_bf16 v[102:105], v[146:149], v[196:199], v[102:105]
	v_mfma_f32_16x16x32_bf16 v[102:105], v[150:153], v[200:203], v[102:105]
	v_mfma_f32_16x16x32_bf16 v[98:101], v[170:173], v[196:199], v[98:101]
	v_mfma_f32_16x16x32_bf16 v[98:101], v[174:177], v[200:203], v[98:101]
	v_mfma_f32_16x16x32_bf16 v[86:89], v[146:149], v[204:207], v[86:89]
	v_mfma_f32_16x16x32_bf16 v[86:89], v[150:153], v[208:211], v[86:89]
	v_mfma_f32_16x16x32_bf16 v[82:85], v[170:173], v[204:207], v[82:85]
	v_mfma_f32_16x16x32_bf16 v[82:85], v[174:177], v[208:211], v[82:85]
	v_mfma_f32_16x16x32_bf16 v[70:73], v[146:149], v[212:215], v[70:73]
	v_mfma_f32_16x16x32_bf16 v[70:73], v[150:153], v[216:219], v[70:73]
	v_mfma_f32_16x16x32_bf16 v[66:69], v[170:173], v[212:215], v[66:69]
	v_mfma_f32_16x16x32_bf16 v[66:69], v[174:177], v[216:219], v[66:69]
	s_setprio 0
	s_barrier
	s_add_i32 s0, s46, s37
	v_lshl_add_u64 v[220:221], s[2:3], 0, v[156:157]
	s_mov_b32 m0, s0
	ds_read_b128 v[178:181], v189 offset:16384
	ds_read_b128 v[192:195], v189 offset:17408
	ds_read_b128 v[196:199], v189 offset:18432
	ds_read_b128 v[200:203], v189 offset:19456
	ds_read_b128 v[204:207], v189 offset:20480
	ds_read_b128 v[208:211], v189 offset:21504
	ds_read_b128 v[212:215], v189 offset:22528
	ds_read_b128 v[216:219], v189 offset:23552
	global_load_lds_dwordx4 v[220:221], off
	s_add_i32 m0, s0, 0x2000
	s_add_u32 s0, s2, 0x40000
	v_lshl_add_u64 v[222:223], s[2:3], 0, v[160:161]
	s_addc_u32 s1, s3, 0
	s_add_i32 s52, s47, s37
	global_load_lds_dwordx4 v[222:223], off
	v_lshl_add_u64 v[224:225], s[0:1], 0, v[156:157]
	s_mov_b32 m0, s52
	v_lshl_add_u64 v[226:227], s[30:31], 0, v[158:159]
	global_load_lds_dwordx4 v[224:225], off
	v_lshl_add_u64 v[224:225], s[0:1], 0, v[160:161]
	s_add_i32 m0, s52, 0x2000
	s_nop 0
	global_load_lds_dwordx4 v[224:225], off
	v_lshl_add_u64 v[224:225], s[30:31], 0, v[154:155]
	s_mov_b32 m0, s27
	s_nop 0
	global_load_lds_dwordx4 v[224:225], off
	s_mov_b32 m0, s38
	s_nop 0
	global_load_lds_dwordx4 v[226:227], off
	s_waitcnt vmcnt(8)
	s_waitcnt lgkmcnt(0)
	s_barrier
	s_setprio 1
	v_mfma_f32_16x16x32_bf16 v[62:65], v[130:133], v[178:181], v[62:65]
	v_mfma_f32_16x16x32_bf16 v[62:65], v[134:137], v[192:195], v[62:65]
	v_mfma_f32_16x16x32_bf16 v[58:61], v[138:141], v[178:181], v[58:61]
	v_mfma_f32_16x16x32_bf16 v[58:61], v[142:145], v[192:195], v[58:61]
	v_mfma_f32_16x16x32_bf16 v[46:49], v[130:133], v[196:199], v[46:49]
	v_mfma_f32_16x16x32_bf16 v[46:49], v[134:137], v[200:203], v[46:49]
	v_mfma_f32_16x16x32_bf16 v[42:45], v[138:141], v[196:199], v[42:45]
	v_mfma_f32_16x16x32_bf16 v[42:45], v[142:145], v[200:203], v[42:45]
	v_mfma_f32_16x16x32_bf16 v[30:33], v[130:133], v[204:207], v[30:33]
	v_mfma_f32_16x16x32_bf16 v[30:33], v[134:137], v[208:211], v[30:33]
	v_mfma_f32_16x16x32_bf16 v[26:29], v[138:141], v[204:207], v[26:29]
	v_mfma_f32_16x16x32_bf16 v[26:29], v[142:145], v[208:211], v[26:29]
	v_mfma_f32_16x16x32_bf16 v[14:17], v[130:133], v[212:215], v[14:17]
	v_mfma_f32_16x16x32_bf16 v[14:17], v[134:137], v[216:219], v[14:17]
	v_mfma_f32_16x16x32_bf16 v[10:13], v[138:141], v[212:215], v[10:13]
	v_mfma_f32_16x16x32_bf16 v[10:13], v[142:145], v[216:219], v[10:13]
	s_setprio 0
	s_setprio 1
	v_mfma_f32_16x16x32_bf16 v[54:57], v[146:149], v[178:181], v[54:57]
	v_mfma_f32_16x16x32_bf16 v[54:57], v[150:153], v[192:195], v[54:57]
	v_mfma_f32_16x16x32_bf16 v[50:53], v[170:173], v[178:181], v[50:53]
	v_mfma_f32_16x16x32_bf16 v[50:53], v[174:177], v[192:195], v[50:53]
	v_mfma_f32_16x16x32_bf16 v[38:41], v[146:149], v[196:199], v[38:41]
	v_mfma_f32_16x16x32_bf16 v[38:41], v[150:153], v[200:203], v[38:41]
	v_mfma_f32_16x16x32_bf16 v[34:37], v[170:173], v[196:199], v[34:37]
	v_mfma_f32_16x16x32_bf16 v[34:37], v[174:177], v[200:203], v[34:37]
	v_mfma_f32_16x16x32_bf16 v[22:25], v[146:149], v[204:207], v[22:25]
	v_mfma_f32_16x16x32_bf16 v[22:25], v[150:153], v[208:211], v[22:25]
	v_mfma_f32_16x16x32_bf16 v[18:21], v[170:173], v[204:207], v[18:21]
	v_mfma_f32_16x16x32_bf16 v[18:21], v[174:177], v[208:211], v[18:21]
	v_mfma_f32_16x16x32_bf16 v[6:9], v[146:149], v[212:215], v[6:9]
	v_mfma_f32_16x16x32_bf16 v[6:9], v[150:153], v[216:219], v[6:9]
	v_mfma_f32_16x16x32_bf16 v[2:5], v[170:173], v[212:215], v[2:5]
	v_mfma_f32_16x16x32_bf16 v[2:5], v[174:177], v[216:219], v[2:5]
	s_setprio 0
	s_barrier
	s_add_i32 s52, 0, 0x18000
	s_add_i32 s53, 0, 0x1c000
	v_add_u32_e32 v142, s52, v183
	v_add_u32_e32 v174, s53, v183
	ds_read_b128 v[130:133], v142
	ds_read_b128 v[134:137], v142 offset:1024
	ds_read_b128 v[138:141], v142 offset:2048
	ds_read_b128 v[142:145], v142 offset:3072
	ds_read_b128 v[146:149], v174
	ds_read_b128 v[150:153], v174 offset:1024
	ds_read_b128 v[170:173], v174 offset:2048
	ds_read_b128 v[174:177], v174 offset:3072
	s_add_u32 s0, s30, 0x40000
	s_addc_u32 s1, s31, 0
	s_mov_b32 m0, s39
	v_lshl_add_u64 v[228:229], s[0:1], 0, v[154:155]
	ds_read_b128 v[178:181], v189 offset:32768
	ds_read_b128 v[192:195], v189 offset:33792
	ds_read_b128 v[196:199], v189 offset:34816
	ds_read_b128 v[200:203], v189 offset:35840
	ds_read_b128 v[204:207], v189 offset:36864
	ds_read_b128 v[208:211], v189 offset:37888
	ds_read_b128 v[212:215], v189 offset:38912
	ds_read_b128 v[216:219], v189 offset:39936
	global_load_lds_dwordx4 v[228:229], off
	v_lshl_add_u64 v[228:229], s[0:1], 0, v[158:159]
	s_mov_b32 m0, s40
	s_nop 0
	global_load_lds_dwordx4 v[228:229], off
	s_waitcnt vmcnt(8)
	s_waitcnt lgkmcnt(0)
	s_barrier
	s_setprio 1
	v_mfma_f32_16x16x32_bf16 v[126:129], v[130:133], v[178:181], v[126:129]
	v_mfma_f32_16x16x32_bf16 v[126:129], v[134:137], v[192:195], v[126:129]
	v_mfma_f32_16x16x32_bf16 v[122:125], v[138:141], v[178:181], v[122:125]
	v_mfma_f32_16x16x32_bf16 v[122:125], v[142:145], v[192:195], v[122:125]
	v_mfma_f32_16x16x32_bf16 v[110:113], v[130:133], v[196:199], v[110:113]
	v_mfma_f32_16x16x32_bf16 v[110:113], v[134:137], v[200:203], v[110:113]
	v_mfma_f32_16x16x32_bf16 v[106:109], v[138:141], v[196:199], v[106:109]
	v_mfma_f32_16x16x32_bf16 v[106:109], v[142:145], v[200:203], v[106:109]
	v_mfma_f32_16x16x32_bf16 v[94:97], v[130:133], v[204:207], v[94:97]
	v_mfma_f32_16x16x32_bf16 v[94:97], v[134:137], v[208:211], v[94:97]
	v_mfma_f32_16x16x32_bf16 v[90:93], v[138:141], v[204:207], v[90:93]
	v_mfma_f32_16x16x32_bf16 v[90:93], v[142:145], v[208:211], v[90:93]
	v_mfma_f32_16x16x32_bf16 v[78:81], v[130:133], v[212:215], v[78:81]
	v_mfma_f32_16x16x32_bf16 v[78:81], v[134:137], v[216:219], v[78:81]
	v_mfma_f32_16x16x32_bf16 v[74:77], v[138:141], v[212:215], v[74:77]
	v_mfma_f32_16x16x32_bf16 v[74:77], v[142:145], v[216:219], v[74:77]
	s_setprio 0
	s_setprio 1
	v_mfma_f32_16x16x32_bf16 v[118:121], v[146:149], v[178:181], v[118:121]
	v_mfma_f32_16x16x32_bf16 v[118:121], v[150:153], v[192:195], v[118:121]
	v_mfma_f32_16x16x32_bf16 v[114:117], v[170:173], v[178:181], v[114:117]
	v_mfma_f32_16x16x32_bf16 v[114:117], v[174:177], v[192:195], v[114:117]
	v_mfma_f32_16x16x32_bf16 v[102:105], v[146:149], v[196:199], v[102:105]
	v_mfma_f32_16x16x32_bf16 v[102:105], v[150:153], v[200:203], v[102:105]
	v_mfma_f32_16x16x32_bf16 v[98:101], v[170:173], v[196:199], v[98:101]
	v_mfma_f32_16x16x32_bf16 v[98:101], v[174:177], v[200:203], v[98:101]
	v_mfma_f32_16x16x32_bf16 v[86:89], v[146:149], v[204:207], v[86:89]
	v_mfma_f32_16x16x32_bf16 v[86:89], v[150:153], v[208:211], v[86:89]
	v_mfma_f32_16x16x32_bf16 v[82:85], v[170:173], v[204:207], v[82:85]
	v_mfma_f32_16x16x32_bf16 v[82:85], v[174:177], v[208:211], v[82:85]
	v_mfma_f32_16x16x32_bf16 v[70:73], v[146:149], v[212:215], v[70:73]
	v_mfma_f32_16x16x32_bf16 v[70:73], v[150:153], v[216:219], v[70:73]
	v_mfma_f32_16x16x32_bf16 v[66:69], v[170:173], v[212:215], v[66:69]
	v_mfma_f32_16x16x32_bf16 v[66:69], v[174:177], v[216:219], v[66:69]
	s_setprio 0
	s_barrier
	s_add_i32 s0, s52, s37
	v_lshl_add_u64 v[220:221], v[220:221], 0, s[14:15]
	s_mov_b32 m0, s0
	ds_read_b128 v[178:181], v189 offset:49152
	ds_read_b128 v[192:195], v189 offset:50176
	ds_read_b128 v[196:199], v189 offset:51200
	ds_read_b128 v[200:203], v189 offset:52224
	ds_read_b128 v[204:207], v189 offset:53248
	ds_read_b128 v[208:211], v189 offset:54272
	ds_read_b128 v[212:215], v189 offset:55296
	ds_read_b128 v[216:219], v189 offset:56320
	global_load_lds_dwordx4 v[220:221], off
	s_add_i32 m0, s0, 0x2000
	s_add_u32 s0, s2, 0x40080
	v_lshl_add_u64 v[220:221], v[222:223], 0, s[14:15]
	s_addc_u32 s1, s3, 0
	s_add_i32 s2, s53, s37
	global_load_lds_dwordx4 v[220:221], off
	v_lshl_add_u64 v[220:221], s[0:1], 0, v[156:157]
	s_mov_b32 m0, s2
	s_nop 0
	global_load_lds_dwordx4 v[220:221], off
	v_lshl_add_u64 v[220:221], s[0:1], 0, v[160:161]
	s_add_i32 m0, s2, 0x2000
	s_nop 0
	global_load_lds_dwordx4 v[220:221], off
	v_lshl_add_u64 v[220:221], v[224:225], 0, s[14:15]
	s_mov_b32 m0, s42
	s_nop 0
	global_load_lds_dwordx4 v[220:221], off
	v_lshl_add_u64 v[220:221], v[226:227], 0, s[14:15]
	s_mov_b32 m0, s43
	s_nop 0
	global_load_lds_dwordx4 v[220:221], off
	s_waitcnt vmcnt(8)
	s_waitcnt lgkmcnt(0)
	s_barrier
	s_setprio 1
	v_mfma_f32_16x16x32_bf16 v[62:65], v[130:133], v[178:181], v[62:65]
	v_mfma_f32_16x16x32_bf16 v[62:65], v[134:137], v[192:195], v[62:65]
	v_mfma_f32_16x16x32_bf16 v[58:61], v[138:141], v[178:181], v[58:61]
	v_mfma_f32_16x16x32_bf16 v[58:61], v[142:145], v[192:195], v[58:61]
	v_mfma_f32_16x16x32_bf16 v[46:49], v[130:133], v[196:199], v[46:49]
	v_mfma_f32_16x16x32_bf16 v[46:49], v[134:137], v[200:203], v[46:49]
	v_mfma_f32_16x16x32_bf16 v[42:45], v[138:141], v[196:199], v[42:45]
	v_mfma_f32_16x16x32_bf16 v[42:45], v[142:145], v[200:203], v[42:45]
	v_mfma_f32_16x16x32_bf16 v[30:33], v[130:133], v[204:207], v[30:33]
	v_mfma_f32_16x16x32_bf16 v[30:33], v[134:137], v[208:211], v[30:33]
	v_mfma_f32_16x16x32_bf16 v[26:29], v[138:141], v[204:207], v[26:29]
	v_mfma_f32_16x16x32_bf16 v[26:29], v[142:145], v[208:211], v[26:29]
	v_mfma_f32_16x16x32_bf16 v[14:17], v[130:133], v[212:215], v[14:17]
	v_mfma_f32_16x16x32_bf16 v[14:17], v[134:137], v[216:219], v[14:17]
	v_mfma_f32_16x16x32_bf16 v[10:13], v[138:141], v[212:215], v[10:13]
	v_mfma_f32_16x16x32_bf16 v[10:13], v[142:145], v[216:219], v[10:13]
	s_setprio 0
	s_setprio 1
	v_mfma_f32_16x16x32_bf16 v[54:57], v[146:149], v[178:181], v[54:57]
	v_mfma_f32_16x16x32_bf16 v[54:57], v[150:153], v[192:195], v[54:57]
	v_mfma_f32_16x16x32_bf16 v[50:53], v[170:173], v[178:181], v[50:53]
	v_mfma_f32_16x16x32_bf16 v[50:53], v[174:177], v[192:195], v[50:53]
	v_mfma_f32_16x16x32_bf16 v[38:41], v[146:149], v[196:199], v[38:41]
	v_mfma_f32_16x16x32_bf16 v[38:41], v[150:153], v[200:203], v[38:41]
	v_mfma_f32_16x16x32_bf16 v[34:37], v[170:173], v[196:199], v[34:37]
	v_mfma_f32_16x16x32_bf16 v[34:37], v[174:177], v[200:203], v[34:37]
	v_mfma_f32_16x16x32_bf16 v[22:25], v[146:149], v[204:207], v[22:25]
	v_mfma_f32_16x16x32_bf16 v[22:25], v[150:153], v[208:211], v[22:25]
	v_mfma_f32_16x16x32_bf16 v[18:21], v[170:173], v[204:207], v[18:21]
	v_mfma_f32_16x16x32_bf16 v[18:21], v[174:177], v[208:211], v[18:21]
	v_mfma_f32_16x16x32_bf16 v[6:9], v[146:149], v[212:215], v[6:9]
	v_mfma_f32_16x16x32_bf16 v[6:9], v[150:153], v[216:219], v[6:9]
	v_mfma_f32_16x16x32_bf16 v[2:5], v[170:173], v[212:215], v[2:5]
	v_mfma_f32_16x16x32_bf16 v[2:5], v[174:177], v[216:219], v[2:5]
	s_setprio 0
	s_barrier
	s_add_i32 s51, s51, 2
	s_add_u32 s28, s28, 0x100
	s_addc_u32 s29, s29, 0
	s_add_u32 s49, s49, 0x100
	s_addc_u32 s50, s50, 0
	s_cmp_gt_u32 s51, 13
	s_cbranch_scc0 .LBB0_920
	s_and_b64 vcc, exec, s[16:17]
	s_cbranch_vccz .LBB0_923
	s_barrier

.LBB0_1009:
	ds_read_b128 v[148:151], v167
	ds_read_b128 v[152:155], v167 offset:1024
	ds_read_b128 v[156:159], v167 offset:2048
	ds_read_b128 v[160:163], v167 offset:3072
	ds_read_b128 v[172:175], v168
	ds_read_b128 v[176:179], v168 offset:1024
	ds_read_b128 v[180:183], v168 offset:2048
	ds_read_b128 v[184:187], v168 offset:3072
	s_add_u32 s0, s28, 0xfffc0080
	s_addc_u32 s1, s29, -1
	s_cmp_eq_u32 s53, 12
	s_cselect_b32 s31, s21, s1
	s_cselect_b32 s30, s49, s0
	s_cselect_b32 s3, s19, s52
	s_cselect_b32 s2, s50, s51
	v_lshl_add_u64 v[220:221], s[28:29], 0, v[140:141]
	s_add_i32 m0, s27, 0xc000
	ds_read_b128 v[188:191], v169
	ds_read_b128 v[192:195], v169 offset:1024
	ds_read_b128 v[196:199], v169 offset:2048
	ds_read_b128 v[200:203], v169 offset:3072
	ds_read_b128 v[204:207], v169 offset:4096
	ds_read_b128 v[208:211], v169 offset:5120
	ds_read_b128 v[212:215], v169 offset:6144
	ds_read_b128 v[216:219], v169 offset:7168
	global_load_lds_dwordx4 v[220:221], off
	v_lshl_add_u64 v[220:221], s[28:29], 0, v[142:143]
	s_add_i32 m0, s27, 0xe000
	s_nop 0
	global_load_lds_dwordx4 v[220:221], off
	s_waitcnt vmcnt(8)
	s_waitcnt lgkmcnt(0)
	s_barrier
	s_setprio 1
	v_mfma_f32_16x16x32_bf16 v[126:129], v[148:151], v[188:191], v[126:129]
	v_mfma_f32_16x16x32_bf16 v[126:129], v[152:155], v[192:195], v[126:129]
	v_mfma_f32_16x16x32_bf16 v[118:121], v[156:159], v[188:191], v[118:121]
	v_mfma_f32_16x16x32_bf16 v[118:121], v[160:163], v[192:195], v[118:121]
	v_mfma_f32_16x16x32_bf16 v[110:113], v[148:151], v[196:199], v[110:113]
	v_mfma_f32_16x16x32_bf16 v[110:113], v[152:155], v[200:203], v[110:113]
	v_mfma_f32_16x16x32_bf16 v[102:105], v[156:159], v[196:199], v[102:105]
	v_mfma_f32_16x16x32_bf16 v[102:105], v[160:163], v[200:203], v[102:105]
	v_mfma_f32_16x16x32_bf16 v[94:97], v[148:151], v[204:207], v[94:97]
	v_mfma_f32_16x16x32_bf16 v[94:97], v[152:155], v[208:211], v[94:97]
	v_mfma_f32_16x16x32_bf16 v[86:89], v[156:159], v[204:207], v[86:89]
	v_mfma_f32_16x16x32_bf16 v[86:89], v[160:163], v[208:211], v[86:89]
	v_mfma_f32_16x16x32_bf16 v[78:81], v[148:151], v[212:215], v[78:81]
	v_mfma_f32_16x16x32_bf16 v[78:81], v[152:155], v[216:219], v[78:81]
	v_mfma_f32_16x16x32_bf16 v[70:73], v[156:159], v[212:215], v[70:73]
	v_mfma_f32_16x16x32_bf16 v[70:73], v[160:163], v[216:219], v[70:73]
	s_setprio 0
	s_setprio 1
	v_mfma_f32_16x16x32_bf16 v[122:125], v[172:175], v[188:191], v[122:125]
	v_mfma_f32_16x16x32_bf16 v[122:125], v[176:179], v[192:195], v[122:125]
	v_mfma_f32_16x16x32_bf16 v[114:117], v[180:183], v[188:191], v[114:117]
	v_mfma_f32_16x16x32_bf16 v[114:117], v[184:187], v[192:195], v[114:117]
	v_mfma_f32_16x16x32_bf16 v[106:109], v[172:175], v[196:199], v[106:109]
	v_mfma_f32_16x16x32_bf16 v[106:109], v[176:179], v[200:203], v[106:109]
	v_mfma_f32_16x16x32_bf16 v[98:101], v[180:183], v[196:199], v[98:101]
	v_mfma_f32_16x16x32_bf16 v[98:101], v[184:187], v[200:203], v[98:101]
	v_mfma_f32_16x16x32_bf16 v[90:93], v[172:175], v[204:207], v[90:93]
	v_mfma_f32_16x16x32_bf16 v[90:93], v[176:179], v[208:211], v[90:93]
	v_mfma_f32_16x16x32_bf16 v[82:85], v[180:183], v[204:207], v[82:85]
	v_mfma_f32_16x16x32_bf16 v[82:85], v[184:187], v[208:211], v[82:85]
	v_mfma_f32_16x16x32_bf16 v[74:77], v[172:175], v[212:215], v[74:77]
	v_mfma_f32_16x16x32_bf16 v[74:77], v[176:179], v[216:219], v[74:77]
	v_mfma_f32_16x16x32_bf16 v[66:69], v[180:183], v[212:215], v[66:69]
	v_mfma_f32_16x16x32_bf16 v[66:69], v[184:187], v[216:219], v[66:69]
	s_setprio 0
	s_barrier
	s_add_i32 s0, s44, s35
	v_lshl_add_u64 v[220:221], s[2:3], 0, v[134:135]
	s_mov_b32 m0, s0
	ds_read_b128 v[188:191], v169 offset:16384
	ds_read_b128 v[192:195], v169 offset:17408
	ds_read_b128 v[196:199], v169 offset:18432
	ds_read_b128 v[200:203], v169 offset:19456
	ds_read_b128 v[204:207], v169 offset:20480
	ds_read_b128 v[208:211], v169 offset:21504
	ds_read_b128 v[212:215], v169 offset:22528
	ds_read_b128 v[216:219], v169 offset:23552
	global_load_lds_dwordx4 v[220:221], off
	s_add_i32 m0, s0, 0x2000
	s_add_u32 s0, s2, 0x40000
	v_lshl_add_u64 v[222:223], s[2:3], 0, v[130:131]
	s_addc_u32 s1, s3, 0
	s_add_i32 s54, s45, s35
	global_load_lds_dwordx4 v[222:223], off
	v_lshl_add_u64 v[224:225], s[0:1], 0, v[134:135]
	s_mov_b32 m0, s54
	v_lshl_add_u64 v[226:227], s[30:31], 0, v[132:133]
	global_load_lds_dwordx4 v[224:225], off
	v_lshl_add_u64 v[224:225], s[0:1], 0, v[130:131]
	s_add_i32 m0, s54, 0x2000
	s_nop 0
	global_load_lds_dwordx4 v[224:225], off
	v_lshl_add_u64 v[224:225], s[30:31], 0, v[136:137]
	s_mov_b32 m0, s27
	s_nop 0
	global_load_lds_dwordx4 v[224:225], off
	s_mov_b32 m0, s38
	s_nop 0
	global_load_lds_dwordx4 v[226:227], off
	s_waitcnt vmcnt(8)
	s_waitcnt lgkmcnt(0)
	s_barrier
	s_setprio 1
	v_mfma_f32_16x16x32_bf16 v[62:65], v[148:151], v[188:191], v[62:65]
	v_mfma_f32_16x16x32_bf16 v[62:65], v[152:155], v[192:195], v[62:65]
	v_mfma_f32_16x16x32_bf16 v[54:57], v[156:159], v[188:191], v[54:57]
	v_mfma_f32_16x16x32_bf16 v[54:57], v[160:163], v[192:195], v[54:57]
	v_mfma_f32_16x16x32_bf16 v[46:49], v[148:151], v[196:199], v[46:49]
	v_mfma_f32_16x16x32_bf16 v[46:49], v[152:155], v[200:203], v[46:49]
	v_mfma_f32_16x16x32_bf16 v[38:41], v[156:159], v[196:199], v[38:41]
	v_mfma_f32_16x16x32_bf16 v[38:41], v[160:163], v[200:203], v[38:41]
	v_mfma_f32_16x16x32_bf16 v[30:33], v[148:151], v[204:207], v[30:33]
	v_mfma_f32_16x16x32_bf16 v[30:33], v[152:155], v[208:211], v[30:33]
	v_mfma_f32_16x16x32_bf16 v[22:25], v[156:159], v[204:207], v[22:25]
	v_mfma_f32_16x16x32_bf16 v[22:25], v[160:163], v[208:211], v[22:25]
	v_mfma_f32_16x16x32_bf16 v[14:17], v[148:151], v[212:215], v[14:17]
	v_mfma_f32_16x16x32_bf16 v[14:17], v[152:155], v[216:219], v[14:17]
	v_mfma_f32_16x16x32_bf16 v[6:9], v[156:159], v[212:215], v[6:9]
	v_mfma_f32_16x16x32_bf16 v[6:9], v[160:163], v[216:219], v[6:9]
	s_setprio 0
	s_setprio 1
	v_mfma_f32_16x16x32_bf16 v[58:61], v[172:175], v[188:191], v[58:61]
	v_mfma_f32_16x16x32_bf16 v[58:61], v[176:179], v[192:195], v[58:61]
	v_mfma_f32_16x16x32_bf16 v[50:53], v[180:183], v[188:191], v[50:53]
	v_mfma_f32_16x16x32_bf16 v[50:53], v[184:187], v[192:195], v[50:53]
	v_mfma_f32_16x16x32_bf16 v[42:45], v[172:175], v[196:199], v[42:45]
	v_mfma_f32_16x16x32_bf16 v[42:45], v[176:179], v[200:203], v[42:45]
	v_mfma_f32_16x16x32_bf16 v[34:37], v[180:183], v[196:199], v[34:37]
	v_mfma_f32_16x16x32_bf16 v[34:37], v[184:187], v[200:203], v[34:37]
	v_mfma_f32_16x16x32_bf16 v[26:29], v[172:175], v[204:207], v[26:29]
	v_mfma_f32_16x16x32_bf16 v[26:29], v[176:179], v[208:211], v[26:29]
	v_mfma_f32_16x16x32_bf16 v[18:21], v[180:183], v[204:207], v[18:21]
	v_mfma_f32_16x16x32_bf16 v[18:21], v[184:187], v[208:211], v[18:21]
	v_mfma_f32_16x16x32_bf16 v[10:13], v[172:175], v[212:215], v[10:13]
	v_mfma_f32_16x16x32_bf16 v[10:13], v[176:179], v[216:219], v[10:13]
	v_mfma_f32_16x16x32_bf16 v[2:5], v[180:183], v[212:215], v[2:5]
	v_mfma_f32_16x16x32_bf16 v[2:5], v[184:187], v[216:219], v[2:5]
	s_setprio 0
	s_barrier
	s_add_i32 s54, 0, 0x18000
	s_add_i32 s55, 0, 0x1c000
	v_add_u32_e32 v160, s54, v166
	v_add_u32_e32 v171, s55, v166
	ds_read_b128 v[148:151], v160
	ds_read_b128 v[152:155], v160 offset:1024
	ds_read_b128 v[156:159], v160 offset:2048
	ds_read_b128 v[160:163], v160 offset:3072
	ds_read_b128 v[172:175], v171
	ds_read_b128 v[176:179], v171 offset:1024
	ds_read_b128 v[180:183], v171 offset:2048
	ds_read_b128 v[184:187], v171 offset:3072
	s_add_u32 s0, s30, 0x40000
	s_addc_u32 s1, s31, 0
	s_mov_b32 m0, s39
	v_lshl_add_u64 v[228:229], s[0:1], 0, v[136:137]
	ds_read_b128 v[188:191], v169 offset:32768
	ds_read_b128 v[192:195], v169 offset:33792
	ds_read_b128 v[196:199], v169 offset:34816
	ds_read_b128 v[200:203], v169 offset:35840
	ds_read_b128 v[204:207], v169 offset:36864
	ds_read_b128 v[208:211], v169 offset:37888
	ds_read_b128 v[212:215], v169 offset:38912
	ds_read_b128 v[216:219], v169 offset:39936
	global_load_lds_dwordx4 v[228:229], off
	v_lshl_add_u64 v[228:229], s[0:1], 0, v[132:133]
	s_mov_b32 m0, s40
	s_nop 0
	global_load_lds_dwordx4 v[228:229], off
	s_waitcnt vmcnt(8)
	s_waitcnt lgkmcnt(0)
	s_barrier
	s_setprio 1
	v_mfma_f32_16x16x32_bf16 v[126:129], v[148:151], v[188:191], v[126:129]
	v_mfma_f32_16x16x32_bf16 v[126:129], v[152:155], v[192:195], v[126:129]
	v_mfma_f32_16x16x32_bf16 v[118:121], v[156:159], v[188:191], v[118:121]
	v_mfma_f32_16x16x32_bf16 v[118:121], v[160:163], v[192:195], v[118:121]
	v_mfma_f32_16x16x32_bf16 v[110:113], v[148:151], v[196:199], v[110:113]
	v_mfma_f32_16x16x32_bf16 v[110:113], v[152:155], v[200:203], v[110:113]
	v_mfma_f32_16x16x32_bf16 v[102:105], v[156:159], v[196:199], v[102:105]
	v_mfma_f32_16x16x32_bf16 v[102:105], v[160:163], v[200:203], v[102:105]
	v_mfma_f32_16x16x32_bf16 v[94:97], v[148:151], v[204:207], v[94:97]
	v_mfma_f32_16x16x32_bf16 v[94:97], v[152:155], v[208:211], v[94:97]
	v_mfma_f32_16x16x32_bf16 v[86:89], v[156:159], v[204:207], v[86:89]
	v_mfma_f32_16x16x32_bf16 v[86:89], v[160:163], v[208:211], v[86:89]
	v_mfma_f32_16x16x32_bf16 v[78:81], v[148:151], v[212:215], v[78:81]
	v_mfma_f32_16x16x32_bf16 v[78:81], v[152:155], v[216:219], v[78:81]
	v_mfma_f32_16x16x32_bf16 v[70:73], v[156:159], v[212:215], v[70:73]
	v_mfma_f32_16x16x32_bf16 v[70:73], v[160:163], v[216:219], v[70:73]
	s_setprio 0
	s_setprio 1
	v_mfma_f32_16x16x32_bf16 v[122:125], v[172:175], v[188:191], v[122:125]
	v_mfma_f32_16x16x32_bf16 v[122:125], v[176:179], v[192:195], v[122:125]
	v_mfma_f32_16x16x32_bf16 v[114:117], v[180:183], v[188:191], v[114:117]
	v_mfma_f32_16x16x32_bf16 v[114:117], v[184:187], v[192:195], v[114:117]
	v_mfma_f32_16x16x32_bf16 v[106:109], v[172:175], v[196:199], v[106:109]
	v_mfma_f32_16x16x32_bf16 v[106:109], v[176:179], v[200:203], v[106:109]
	v_mfma_f32_16x16x32_bf16 v[98:101], v[180:183], v[196:199], v[98:101]
	v_mfma_f32_16x16x32_bf16 v[98:101], v[184:187], v[200:203], v[98:101]
	v_mfma_f32_16x16x32_bf16 v[90:93], v[172:175], v[204:207], v[90:93]
	v_mfma_f32_16x16x32_bf16 v[90:93], v[176:179], v[208:211], v[90:93]
	v_mfma_f32_16x16x32_bf16 v[82:85], v[180:183], v[204:207], v[82:85]
	v_mfma_f32_16x16x32_bf16 v[82:85], v[184:187], v[208:211], v[82:85]
	v_mfma_f32_16x16x32_bf16 v[74:77], v[172:175], v[212:215], v[74:77]
	v_mfma_f32_16x16x32_bf16 v[74:77], v[176:179], v[216:219], v[74:77]
	v_mfma_f32_16x16x32_bf16 v[66:69], v[180:183], v[212:215], v[66:69]
	v_mfma_f32_16x16x32_bf16 v[66:69], v[184:187], v[216:219], v[66:69]
	s_setprio 0
	s_barrier
	s_add_i32 s0, s54, s35
	v_lshl_add_u64 v[220:221], v[220:221], 0, s[14:15]
	s_mov_b32 m0, s0
	ds_read_b128 v[188:191], v169 offset:49152
	ds_read_b128 v[192:195], v169 offset:50176
	ds_read_b128 v[196:199], v169 offset:51200
	ds_read_b128 v[200:203], v169 offset:52224
	ds_read_b128 v[204:207], v169 offset:53248
	ds_read_b128 v[208:211], v169 offset:54272
	ds_read_b128 v[212:215], v169 offset:55296
	ds_read_b128 v[216:219], v169 offset:56320
	global_load_lds_dwordx4 v[220:221], off
	s_add_i32 m0, s0, 0x2000
	s_add_u32 s0, s2, 0x40080
	v_lshl_add_u64 v[220:221], v[222:223], 0, s[14:15]
	s_addc_u32 s1, s3, 0
	s_add_i32 s2, s55, s35
	global_load_lds_dwordx4 v[220:221], off
	v_lshl_add_u64 v[220:221], s[0:1], 0, v[134:135]
	s_mov_b32 m0, s2
	s_nop 0
	global_load_lds_dwordx4 v[220:221], off
	v_lshl_add_u64 v[220:221], s[0:1], 0, v[130:131]
	s_add_i32 m0, s2, 0x2000
	s_nop 0
	global_load_lds_dwordx4 v[220:221], off
	v_lshl_add_u64 v[220:221], v[224:225], 0, s[14:15]
	s_mov_b32 m0, s41
	s_nop 0
	global_load_lds_dwordx4 v[220:221], off
	v_lshl_add_u64 v[220:221], v[226:227], 0, s[14:15]
	s_mov_b32 m0, s42
	s_nop 0
	global_load_lds_dwordx4 v[220:221], off
	s_waitcnt vmcnt(8)
	s_waitcnt lgkmcnt(0)
	s_barrier
	s_setprio 1
	v_mfma_f32_16x16x32_bf16 v[62:65], v[148:151], v[188:191], v[62:65]
	v_mfma_f32_16x16x32_bf16 v[62:65], v[152:155], v[192:195], v[62:65]
	v_mfma_f32_16x16x32_bf16 v[54:57], v[156:159], v[188:191], v[54:57]
	v_mfma_f32_16x16x32_bf16 v[54:57], v[160:163], v[192:195], v[54:57]
	v_mfma_f32_16x16x32_bf16 v[46:49], v[148:151], v[196:199], v[46:49]
	v_mfma_f32_16x16x32_bf16 v[46:49], v[152:155], v[200:203], v[46:49]
	v_mfma_f32_16x16x32_bf16 v[38:41], v[156:159], v[196:199], v[38:41]
	v_mfma_f32_16x16x32_bf16 v[38:41], v[160:163], v[200:203], v[38:41]
	v_mfma_f32_16x16x32_bf16 v[30:33], v[148:151], v[204:207], v[30:33]
	v_mfma_f32_16x16x32_bf16 v[30:33], v[152:155], v[208:211], v[30:33]
	v_mfma_f32_16x16x32_bf16 v[22:25], v[156:159], v[204:207], v[22:25]
	v_mfma_f32_16x16x32_bf16 v[22:25], v[160:163], v[208:211], v[22:25]
	v_mfma_f32_16x16x32_bf16 v[14:17], v[148:151], v[212:215], v[14:17]
	v_mfma_f32_16x16x32_bf16 v[14:17], v[152:155], v[216:219], v[14:17]
	v_mfma_f32_16x16x32_bf16 v[6:9], v[156:159], v[212:215], v[6:9]
	v_mfma_f32_16x16x32_bf16 v[6:9], v[160:163], v[216:219], v[6:9]
	s_setprio 0
	s_setprio 1
	v_mfma_f32_16x16x32_bf16 v[58:61], v[172:175], v[188:191], v[58:61]
	v_mfma_f32_16x16x32_bf16 v[58:61], v[176:179], v[192:195], v[58:61]
	v_mfma_f32_16x16x32_bf16 v[50:53], v[180:183], v[188:191], v[50:53]
	v_mfma_f32_16x16x32_bf16 v[50:53], v[184:187], v[192:195], v[50:53]
	v_mfma_f32_16x16x32_bf16 v[42:45], v[172:175], v[196:199], v[42:45]
	v_mfma_f32_16x16x32_bf16 v[42:45], v[176:179], v[200:203], v[42:45]
	v_mfma_f32_16x16x32_bf16 v[34:37], v[180:183], v[196:199], v[34:37]
	v_mfma_f32_16x16x32_bf16 v[34:37], v[184:187], v[200:203], v[34:37]
	v_mfma_f32_16x16x32_bf16 v[26:29], v[172:175], v[204:207], v[26:29]
	v_mfma_f32_16x16x32_bf16 v[26:29], v[176:179], v[208:211], v[26:29]
	v_mfma_f32_16x16x32_bf16 v[18:21], v[180:183], v[204:207], v[18:21]
	v_mfma_f32_16x16x32_bf16 v[18:21], v[184:187], v[208:211], v[18:21]
	v_mfma_f32_16x16x32_bf16 v[10:13], v[172:175], v[212:215], v[10:13]
	v_mfma_f32_16x16x32_bf16 v[10:13], v[176:179], v[216:219], v[10:13]
	v_mfma_f32_16x16x32_bf16 v[2:5], v[180:183], v[212:215], v[2:5]
	v_mfma_f32_16x16x32_bf16 v[2:5], v[184:187], v[216:219], v[2:5]
	s_setprio 0
	s_barrier
	s_add_i32 s53, s53, 2
	s_add_u32 s28, s28, 0x100
	s_addc_u32 s29, s29, 0
	s_add_u32 s51, s51, 0x100
	s_addc_u32 s52, s52, 0
	s_cmp_gt_u32 s53, 13
	s_cbranch_scc0 .LBB0_1009
	s_and_b64 vcc, exec, s[16:17]
	s_cbranch_vccz .LBB0_1012
	s_barrier

.LBB0_1122:
	s_add_u32 s24, s24, 0xb0080
	s_addc_u32 s25, s25, 0
	s_add_u32 s47, s2, 0x100
	v_mov_b32_e32 v2, 0
	s_addc_u32 s48, s3, 0
	s_mov_b32 s49, -2
	s_waitcnt lgkmcnt(0)
	v_mov_b32_e32 v3, v2
	v_mov_b32_e32 v4, v2
	v_mov_b32_e32 v5, v2
	v_mov_b32_e32 v6, v2
	v_mov_b32_e32 v7, v2
	v_mov_b32_e32 v8, v2
	v_mov_b32_e32 v9, v2
	v_mov_b32_e32 v18, v2
	v_mov_b32_e32 v19, v2
	v_mov_b32_e32 v20, v2
	v_mov_b32_e32 v21, v2
	v_mov_b32_e32 v22, v2
	v_mov_b32_e32 v23, v2
	v_mov_b32_e32 v24, v2
	v_mov_b32_e32 v25, v2
	v_mov_b32_e32 v34, v2
	v_mov_b32_e32 v35, v2
	v_mov_b32_e32 v36, v2
	v_mov_b32_e32 v37, v2
	v_mov_b32_e32 v38, v2
	v_mov_b32_e32 v39, v2
	v_mov_b32_e32 v40, v2
	v_mov_b32_e32 v41, v2
	v_mov_b32_e32 v50, v2
	v_mov_b32_e32 v51, v2
	v_mov_b32_e32 v52, v2
	v_mov_b32_e32 v53, v2
	v_mov_b32_e32 v54, v2
	v_mov_b32_e32 v55, v2
	v_mov_b32_e32 v56, v2
	v_mov_b32_e32 v57, v2
	v_mov_b32_e32 v10, v2
	v_mov_b32_e32 v11, v2
	v_mov_b32_e32 v12, v2
	v_mov_b32_e32 v13, v2
	v_mov_b32_e32 v14, v2
	v_mov_b32_e32 v15, v2
	v_mov_b32_e32 v16, v2
	v_mov_b32_e32 v17, v2
	v_mov_b32_e32 v26, v2
	v_mov_b32_e32 v27, v2
	v_mov_b32_e32 v28, v2
	v_mov_b32_e32 v29, v2
	v_mov_b32_e32 v30, v2
	v_mov_b32_e32 v31, v2
	v_mov_b32_e32 v32, v2
	v_mov_b32_e32 v33, v2
	v_mov_b32_e32 v42, v2
	v_mov_b32_e32 v43, v2
	v_mov_b32_e32 v44, v2
	v_mov_b32_e32 v45, v2
	v_mov_b32_e32 v46, v2
	v_mov_b32_e32 v47, v2
	v_mov_b32_e32 v48, v2
	v_mov_b32_e32 v49, v2
	v_mov_b32_e32 v58, v2
	v_mov_b32_e32 v59, v2
	v_mov_b32_e32 v60, v2
	v_mov_b32_e32 v61, v2
	v_mov_b32_e32 v62, v2
	v_mov_b32_e32 v63, v2
	v_mov_b32_e32 v64, v2
	v_mov_b32_e32 v65, v2
	v_mov_b32_e32 v66, v2
	v_mov_b32_e32 v67, v2
	v_mov_b32_e32 v68, v2
	v_mov_b32_e32 v69, v2
	v_mov_b32_e32 v70, v2
	v_mov_b32_e32 v71, v2
	v_mov_b32_e32 v72, v2
	v_mov_b32_e32 v73, v2
	v_mov_b32_e32 v82, v2
	v_mov_b32_e32 v83, v2
	v_mov_b32_e32 v84, v2
	v_mov_b32_e32 v85, v2
	v_mov_b32_e32 v86, v2
	v_mov_b32_e32 v87, v2
	v_mov_b32_e32 v88, v2
	v_mov_b32_e32 v89, v2
	v_mov_b32_e32 v98, v2
	v_mov_b32_e32 v99, v2
	v_mov_b32_e32 v100, v2
	v_mov_b32_e32 v101, v2
	v_mov_b32_e32 v102, v2
	v_mov_b32_e32 v103, v2
	v_mov_b32_e32 v104, v2
	v_mov_b32_e32 v105, v2
	v_mov_b32_e32 v114, v2
	v_mov_b32_e32 v115, v2
	v_mov_b32_e32 v116, v2
	v_mov_b32_e32 v117, v2
	v_mov_b32_e32 v118, v2
	v_mov_b32_e32 v119, v2
	v_mov_b32_e32 v120, v2
	v_mov_b32_e32 v121, v2
	v_mov_b32_e32 v74, v2
	v_mov_b32_e32 v75, v2
	v_mov_b32_e32 v76, v2
	v_mov_b32_e32 v77, v2
	v_mov_b32_e32 v78, v2
	v_mov_b32_e32 v79, v2
	v_mov_b32_e32 v80, v2
	v_mov_b32_e32 v81, v2
	v_mov_b32_e32 v90, v2
	v_mov_b32_e32 v91, v2
	v_mov_b32_e32 v92, v2
	v_mov_b32_e32 v93, v2
	v_mov_b32_e32 v94, v2
	v_mov_b32_e32 v95, v2
	v_mov_b32_e32 v96, v2
	v_mov_b32_e32 v97, v2
	v_mov_b32_e32 v106, v2
	v_mov_b32_e32 v107, v2
	v_mov_b32_e32 v108, v2
	v_mov_b32_e32 v109, v2
	v_mov_b32_e32 v110, v2
	v_mov_b32_e32 v111, v2
	v_mov_b32_e32 v112, v2
	v_mov_b32_e32 v113, v2
	v_mov_b32_e32 v122, v2
	v_mov_b32_e32 v123, v2
	v_mov_b32_e32 v124, v2
	v_mov_b32_e32 v125, v2
	v_mov_b32_e32 v126, v2
	v_mov_b32_e32 v127, v2
	v_mov_b32_e32 v128, v2
	v_mov_b32_e32 v129, v2
	s_nop 0
	s_nop 0
	s_nop 0
	s_nop 0
.LBB0_1123:
	ds_read_b128 v[130:133], v187
	ds_read_b128 v[134:137], v187 offset:1024
	ds_read_b128 v[138:141], v187 offset:2048
	ds_read_b128 v[142:145], v187 offset:3072
	ds_read_b128 v[146:149], v188
	ds_read_b128 v[150:153], v188 offset:1024
	ds_read_b128 v[170:173], v188 offset:2048
	ds_read_b128 v[174:177], v188 offset:3072
	s_add_u32 s0, s24, 0xfff50080
	s_addc_u32 s1, s25, -1
	s_cmp_eq_u32 s49, 40
	s_cselect_b32 s27, s9, s1
	s_cselect_b32 s26, s8, s0
	s_cselect_b32 s3, s23, s48
	s_cselect_b32 s2, s22, s47
	v_lshl_add_u64 v[220:221], s[24:25], 0, v[162:163]
	s_add_i32 m0, s34, 0xc000
	ds_read_b128 v[178:181], v189
	ds_read_b128 v[192:195], v189 offset:1024
	ds_read_b128 v[196:199], v189 offset:2048
	ds_read_b128 v[200:203], v189 offset:3072
	ds_read_b128 v[204:207], v189 offset:4096
	ds_read_b128 v[208:211], v189 offset:5120
	ds_read_b128 v[212:215], v189 offset:6144
	ds_read_b128 v[216:219], v189 offset:7168
	global_load_lds_dwordx4 v[220:221], off
	v_lshl_add_u64 v[220:221], s[24:25], 0, v[164:165]
	s_add_i32 m0, s34, 0xe000
	s_nop 0
	global_load_lds_dwordx4 v[220:221], off
	s_waitcnt vmcnt(8)
	s_waitcnt lgkmcnt(0)
	s_barrier
	s_setprio 1
	v_mfma_f32_16x16x32_bf16 v[126:129], v[130:133], v[178:181], v[126:129]
	v_mfma_f32_16x16x32_bf16 v[126:129], v[134:137], v[192:195], v[126:129]
	v_mfma_f32_16x16x32_bf16 v[122:125], v[138:141], v[178:181], v[122:125]
	v_mfma_f32_16x16x32_bf16 v[122:125], v[142:145], v[192:195], v[122:125]
	v_mfma_f32_16x16x32_bf16 v[110:113], v[130:133], v[196:199], v[110:113]
	v_mfma_f32_16x16x32_bf16 v[110:113], v[134:137], v[200:203], v[110:113]
	v_mfma_f32_16x16x32_bf16 v[106:109], v[138:141], v[196:199], v[106:109]
	v_mfma_f32_16x16x32_bf16 v[106:109], v[142:145], v[200:203], v[106:109]
	v_mfma_f32_16x16x32_bf16 v[94:97], v[130:133], v[204:207], v[94:97]
	v_mfma_f32_16x16x32_bf16 v[94:97], v[134:137], v[208:211], v[94:97]
	v_mfma_f32_16x16x32_bf16 v[90:93], v[138:141], v[204:207], v[90:93]
	v_mfma_f32_16x16x32_bf16 v[90:93], v[142:145], v[208:211], v[90:93]
	v_mfma_f32_16x16x32_bf16 v[78:81], v[130:133], v[212:215], v[78:81]
	v_mfma_f32_16x16x32_bf16 v[78:81], v[134:137], v[216:219], v[78:81]
	v_mfma_f32_16x16x32_bf16 v[74:77], v[138:141], v[212:215], v[74:77]
	v_mfma_f32_16x16x32_bf16 v[74:77], v[142:145], v[216:219], v[74:77]
	s_setprio 0
	s_setprio 1
	v_mfma_f32_16x16x32_bf16 v[118:121], v[146:149], v[178:181], v[118:121]
	v_mfma_f32_16x16x32_bf16 v[118:121], v[150:153], v[192:195], v[118:121]
	v_mfma_f32_16x16x32_bf16 v[114:117], v[170:173], v[178:181], v[114:117]
	v_mfma_f32_16x16x32_bf16 v[114:117], v[174:177], v[192:195], v[114:117]
	v_mfma_f32_16x16x32_bf16 v[102:105], v[146:149], v[196:199], v[102:105]
	v_mfma_f32_16x16x32_bf16 v[102:105], v[150:153], v[200:203], v[102:105]
	v_mfma_f32_16x16x32_bf16 v[98:101], v[170:173], v[196:199], v[98:101]
	v_mfma_f32_16x16x32_bf16 v[98:101], v[174:177], v[200:203], v[98:101]
	v_mfma_f32_16x16x32_bf16 v[86:89], v[146:149], v[204:207], v[86:89]
	v_mfma_f32_16x16x32_bf16 v[86:89], v[150:153], v[208:211], v[86:89]
	v_mfma_f32_16x16x32_bf16 v[82:85], v[170:173], v[204:207], v[82:85]
	v_mfma_f32_16x16x32_bf16 v[82:85], v[174:177], v[208:211], v[82:85]
	v_mfma_f32_16x16x32_bf16 v[70:73], v[146:149], v[212:215], v[70:73]
	v_mfma_f32_16x16x32_bf16 v[70:73], v[150:153], v[216:219], v[70:73]
	v_mfma_f32_16x16x32_bf16 v[66:69], v[170:173], v[212:215], v[66:69]
	v_mfma_f32_16x16x32_bf16 v[66:69], v[174:177], v[216:219], v[66:69]
	s_setprio 0
	s_barrier
	s_add_i32 s0, s43, s33
	v_lshl_add_u64 v[220:221], s[2:3], 0, v[156:157]
	s_mov_b32 m0, s0
	ds_read_b128 v[178:181], v189 offset:16384
	ds_read_b128 v[192:195], v189 offset:17408
	ds_read_b128 v[196:199], v189 offset:18432
	ds_read_b128 v[200:203], v189 offset:19456
	ds_read_b128 v[204:207], v189 offset:20480
	ds_read_b128 v[208:211], v189 offset:21504
	ds_read_b128 v[212:215], v189 offset:22528
	ds_read_b128 v[216:219], v189 offset:23552
	global_load_lds_dwordx4 v[220:221], off
	s_add_i32 m0, s0, 0x2000
	s_add_u32 s0, s2, 0xb0000
	v_lshl_add_u64 v[222:223], s[2:3], 0, v[160:161]
	s_addc_u32 s1, s3, 0
	s_add_i32 s50, s44, s33
	global_load_lds_dwordx4 v[222:223], off
	v_lshl_add_u64 v[224:225], s[0:1], 0, v[156:157]
	s_mov_b32 m0, s50
	v_lshl_add_u64 v[226:227], s[26:27], 0, v[158:159]
	global_load_lds_dwordx4 v[224:225], off
	v_lshl_add_u64 v[224:225], s[0:1], 0, v[160:161]
	s_add_i32 m0, s50, 0x2000
	s_nop 0
	global_load_lds_dwordx4 v[224:225], off
	v_lshl_add_u64 v[224:225], s[26:27], 0, v[154:155]
	s_mov_b32 m0, s34
	s_nop 0
	global_load_lds_dwordx4 v[224:225], off
	s_mov_b32 m0, s35
	s_nop 0
	global_load_lds_dwordx4 v[226:227], off
	s_waitcnt vmcnt(8)
	s_waitcnt lgkmcnt(0)
	s_barrier
	s_setprio 1
	v_mfma_f32_16x16x32_bf16 v[62:65], v[130:133], v[178:181], v[62:65]
	v_mfma_f32_16x16x32_bf16 v[62:65], v[134:137], v[192:195], v[62:65]
	v_mfma_f32_16x16x32_bf16 v[58:61], v[138:141], v[178:181], v[58:61]
	v_mfma_f32_16x16x32_bf16 v[58:61], v[142:145], v[192:195], v[58:61]
	v_mfma_f32_16x16x32_bf16 v[46:49], v[130:133], v[196:199], v[46:49]
	v_mfma_f32_16x16x32_bf16 v[46:49], v[134:137], v[200:203], v[46:49]
	v_mfma_f32_16x16x32_bf16 v[42:45], v[138:141], v[196:199], v[42:45]
	v_mfma_f32_16x16x32_bf16 v[42:45], v[142:145], v[200:203], v[42:45]
	v_mfma_f32_16x16x32_bf16 v[30:33], v[130:133], v[204:207], v[30:33]
	v_mfma_f32_16x16x32_bf16 v[30:33], v[134:137], v[208:211], v[30:33]
	v_mfma_f32_16x16x32_bf16 v[26:29], v[138:141], v[204:207], v[26:29]
	v_mfma_f32_16x16x32_bf16 v[26:29], v[142:145], v[208:211], v[26:29]
	v_mfma_f32_16x16x32_bf16 v[14:17], v[130:133], v[212:215], v[14:17]
	v_mfma_f32_16x16x32_bf16 v[14:17], v[134:137], v[216:219], v[14:17]
	v_mfma_f32_16x16x32_bf16 v[10:13], v[138:141], v[212:215], v[10:13]
	v_mfma_f32_16x16x32_bf16 v[10:13], v[142:145], v[216:219], v[10:13]
	s_setprio 0
	s_setprio 1
	v_mfma_f32_16x16x32_bf16 v[54:57], v[146:149], v[178:181], v[54:57]
	v_mfma_f32_16x16x32_bf16 v[54:57], v[150:153], v[192:195], v[54:57]
	v_mfma_f32_16x16x32_bf16 v[50:53], v[170:173], v[178:181], v[50:53]
	v_mfma_f32_16x16x32_bf16 v[50:53], v[174:177], v[192:195], v[50:53]
	v_mfma_f32_16x16x32_bf16 v[38:41], v[146:149], v[196:199], v[38:41]
	v_mfma_f32_16x16x32_bf16 v[38:41], v[150:153], v[200:203], v[38:41]
	v_mfma_f32_16x16x32_bf16 v[34:37], v[170:173], v[196:199], v[34:37]
	v_mfma_f32_16x16x32_bf16 v[34:37], v[174:177], v[200:203], v[34:37]
	v_mfma_f32_16x16x32_bf16 v[22:25], v[146:149], v[204:207], v[22:25]
	v_mfma_f32_16x16x32_bf16 v[22:25], v[150:153], v[208:211], v[22:25]
	v_mfma_f32_16x16x32_bf16 v[18:21], v[170:173], v[204:207], v[18:21]
	v_mfma_f32_16x16x32_bf16 v[18:21], v[174:177], v[208:211], v[18:21]
	v_mfma_f32_16x16x32_bf16 v[6:9], v[146:149], v[212:215], v[6:9]
	v_mfma_f32_16x16x32_bf16 v[6:9], v[150:153], v[216:219], v[6:9]
	v_mfma_f32_16x16x32_bf16 v[2:5], v[170:173], v[212:215], v[2:5]
	v_mfma_f32_16x16x32_bf16 v[2:5], v[174:177], v[216:219], v[2:5]
	s_setprio 0
	s_barrier
	s_add_i32 s50, 0, 0x18000
	s_add_i32 s51, 0, 0x1c000
	v_add_u32_e32 v142, s50, v183
	v_add_u32_e32 v174, s51, v183
	ds_read_b128 v[130:133], v142
	ds_read_b128 v[134:137], v142 offset:1024
	ds_read_b128 v[138:141], v142 offset:2048
	ds_read_b128 v[142:145], v142 offset:3072
	ds_read_b128 v[146:149], v174
	ds_read_b128 v[150:153], v174 offset:1024
	ds_read_b128 v[170:173], v174 offset:2048
	ds_read_b128 v[174:177], v174 offset:3072
	s_add_u32 s0, s26, 0xb0000
	s_addc_u32 s1, s27, 0
	s_mov_b32 m0, s36
	v_lshl_add_u64 v[228:229], s[0:1], 0, v[154:155]
	ds_read_b128 v[178:181], v189 offset:32768
	ds_read_b128 v[192:195], v189 offset:33792
	ds_read_b128 v[196:199], v189 offset:34816
	ds_read_b128 v[200:203], v189 offset:35840
	ds_read_b128 v[204:207], v189 offset:36864
	ds_read_b128 v[208:211], v189 offset:37888
	ds_read_b128 v[212:215], v189 offset:38912
	ds_read_b128 v[216:219], v189 offset:39936
	global_load_lds_dwordx4 v[228:229], off
	v_lshl_add_u64 v[228:229], s[0:1], 0, v[158:159]
	s_mov_b32 m0, s37
	s_nop 0
	global_load_lds_dwordx4 v[228:229], off
	s_waitcnt vmcnt(8)
	s_waitcnt lgkmcnt(0)
	s_barrier
	s_setprio 1
	v_mfma_f32_16x16x32_bf16 v[126:129], v[130:133], v[178:181], v[126:129]
	v_mfma_f32_16x16x32_bf16 v[126:129], v[134:137], v[192:195], v[126:129]
	v_mfma_f32_16x16x32_bf16 v[122:125], v[138:141], v[178:181], v[122:125]
	v_mfma_f32_16x16x32_bf16 v[122:125], v[142:145], v[192:195], v[122:125]
	v_mfma_f32_16x16x32_bf16 v[110:113], v[130:133], v[196:199], v[110:113]
	v_mfma_f32_16x16x32_bf16 v[110:113], v[134:137], v[200:203], v[110:113]
	v_mfma_f32_16x16x32_bf16 v[106:109], v[138:141], v[196:199], v[106:109]
	v_mfma_f32_16x16x32_bf16 v[106:109], v[142:145], v[200:203], v[106:109]
	v_mfma_f32_16x16x32_bf16 v[94:97], v[130:133], v[204:207], v[94:97]
	v_mfma_f32_16x16x32_bf16 v[94:97], v[134:137], v[208:211], v[94:97]
	v_mfma_f32_16x16x32_bf16 v[90:93], v[138:141], v[204:207], v[90:93]
	v_mfma_f32_16x16x32_bf16 v[90:93], v[142:145], v[208:211], v[90:93]
	v_mfma_f32_16x16x32_bf16 v[78:81], v[130:133], v[212:215], v[78:81]
	v_mfma_f32_16x16x32_bf16 v[78:81], v[134:137], v[216:219], v[78:81]
	v_mfma_f32_16x16x32_bf16 v[74:77], v[138:141], v[212:215], v[74:77]
	v_mfma_f32_16x16x32_bf16 v[74:77], v[142:145], v[216:219], v[74:77]
	s_setprio 0
	s_setprio 1
	v_mfma_f32_16x16x32_bf16 v[118:121], v[146:149], v[178:181], v[118:121]
	v_mfma_f32_16x16x32_bf16 v[118:121], v[150:153], v[192:195], v[118:121]
	v_mfma_f32_16x16x32_bf16 v[114:117], v[170:173], v[178:181], v[114:117]
	v_mfma_f32_16x16x32_bf16 v[114:117], v[174:177], v[192:195], v[114:117]
	v_mfma_f32_16x16x32_bf16 v[102:105], v[146:149], v[196:199], v[102:105]
	v_mfma_f32_16x16x32_bf16 v[102:105], v[150:153], v[200:203], v[102:105]
	v_mfma_f32_16x16x32_bf16 v[98:101], v[170:173], v[196:199], v[98:101]
	v_mfma_f32_16x16x32_bf16 v[98:101], v[174:177], v[200:203], v[98:101]
	v_mfma_f32_16x16x32_bf16 v[86:89], v[146:149], v[204:207], v[86:89]
	v_mfma_f32_16x16x32_bf16 v[86:89], v[150:153], v[208:211], v[86:89]
	v_mfma_f32_16x16x32_bf16 v[82:85], v[170:173], v[204:207], v[82:85]
	v_mfma_f32_16x16x32_bf16 v[82:85], v[174:177], v[208:211], v[82:85]
	v_mfma_f32_16x16x32_bf16 v[70:73], v[146:149], v[212:215], v[70:73]
	v_mfma_f32_16x16x32_bf16 v[70:73], v[150:153], v[216:219], v[70:73]
	v_mfma_f32_16x16x32_bf16 v[66:69], v[170:173], v[212:215], v[66:69]
	v_mfma_f32_16x16x32_bf16 v[66:69], v[174:177], v[216:219], v[66:69]
	s_setprio 0
	s_barrier
	s_add_i32 s0, s50, s33
	v_lshl_add_u64 v[220:221], v[220:221], 0, s[16:17]
	s_mov_b32 m0, s0
	ds_read_b128 v[178:181], v189 offset:49152
	ds_read_b128 v[192:195], v189 offset:50176
	ds_read_b128 v[196:199], v189 offset:51200
	ds_read_b128 v[200:203], v189 offset:52224
	ds_read_b128 v[204:207], v189 offset:53248
	ds_read_b128 v[208:211], v189 offset:54272
	ds_read_b128 v[212:215], v189 offset:55296
	ds_read_b128 v[216:219], v189 offset:56320
	global_load_lds_dwordx4 v[220:221], off
	s_add_i32 m0, s0, 0x2000
	s_add_u32 s0, s2, 0xb0080
	v_lshl_add_u64 v[220:221], v[222:223], 0, s[16:17]
	s_addc_u32 s1, s3, 0
	s_add_i32 s2, s51, s33
	global_load_lds_dwordx4 v[220:221], off
	v_lshl_add_u64 v[220:221], s[0:1], 0, v[156:157]
	s_mov_b32 m0, s2
	s_nop 0
	global_load_lds_dwordx4 v[220:221], off
	v_lshl_add_u64 v[220:221], s[0:1], 0, v[160:161]
	s_add_i32 m0, s2, 0x2000
	s_nop 0
	global_load_lds_dwordx4 v[220:221], off
	v_lshl_add_u64 v[220:221], v[224:225], 0, s[16:17]
	s_mov_b32 m0, s39
	s_nop 0
	global_load_lds_dwordx4 v[220:221], off
	v_lshl_add_u64 v[220:221], v[226:227], 0, s[16:17]
	s_mov_b32 m0, s40
	s_nop 0
	global_load_lds_dwordx4 v[220:221], off
	s_waitcnt vmcnt(8)
	s_waitcnt lgkmcnt(0)
	s_barrier
	s_setprio 1
	v_mfma_f32_16x16x32_bf16 v[62:65], v[130:133], v[178:181], v[62:65]
	v_mfma_f32_16x16x32_bf16 v[62:65], v[134:137], v[192:195], v[62:65]
	v_mfma_f32_16x16x32_bf16 v[58:61], v[138:141], v[178:181], v[58:61]
	v_mfma_f32_16x16x32_bf16 v[58:61], v[142:145], v[192:195], v[58:61]
	v_mfma_f32_16x16x32_bf16 v[46:49], v[130:133], v[196:199], v[46:49]
	v_mfma_f32_16x16x32_bf16 v[46:49], v[134:137], v[200:203], v[46:49]
	v_mfma_f32_16x16x32_bf16 v[42:45], v[138:141], v[196:199], v[42:45]
	v_mfma_f32_16x16x32_bf16 v[42:45], v[142:145], v[200:203], v[42:45]
	v_mfma_f32_16x16x32_bf16 v[30:33], v[130:133], v[204:207], v[30:33]
	v_mfma_f32_16x16x32_bf16 v[30:33], v[134:137], v[208:211], v[30:33]
	v_mfma_f32_16x16x32_bf16 v[26:29], v[138:141], v[204:207], v[26:29]
	v_mfma_f32_16x16x32_bf16 v[26:29], v[142:145], v[208:211], v[26:29]
	v_mfma_f32_16x16x32_bf16 v[14:17], v[130:133], v[212:215], v[14:17]
	v_mfma_f32_16x16x32_bf16 v[14:17], v[134:137], v[216:219], v[14:17]
	v_mfma_f32_16x16x32_bf16 v[10:13], v[138:141], v[212:215], v[10:13]
	v_mfma_f32_16x16x32_bf16 v[10:13], v[142:145], v[216:219], v[10:13]
	s_setprio 0
	s_setprio 1
	v_mfma_f32_16x16x32_bf16 v[54:57], v[146:149], v[178:181], v[54:57]
	v_mfma_f32_16x16x32_bf16 v[54:57], v[150:153], v[192:195], v[54:57]
	v_mfma_f32_16x16x32_bf16 v[50:53], v[170:173], v[178:181], v[50:53]
	v_mfma_f32_16x16x32_bf16 v[50:53], v[174:177], v[192:195], v[50:53]
	v_mfma_f32_16x16x32_bf16 v[38:41], v[146:149], v[196:199], v[38:41]
	v_mfma_f32_16x16x32_bf16 v[38:41], v[150:153], v[200:203], v[38:41]
	v_mfma_f32_16x16x32_bf16 v[34:37], v[170:173], v[196:199], v[34:37]
	v_mfma_f32_16x16x32_bf16 v[34:37], v[174:177], v[200:203], v[34:37]
	v_mfma_f32_16x16x32_bf16 v[22:25], v[146:149], v[204:207], v[22:25]
	v_mfma_f32_16x16x32_bf16 v[22:25], v[150:153], v[208:211], v[22:25]
	v_mfma_f32_16x16x32_bf16 v[18:21], v[170:173], v[204:207], v[18:21]
	v_mfma_f32_16x16x32_bf16 v[18:21], v[174:177], v[208:211], v[18:21]
	v_mfma_f32_16x16x32_bf16 v[6:9], v[146:149], v[212:215], v[6:9]
	v_mfma_f32_16x16x32_bf16 v[6:9], v[150:153], v[216:219], v[6:9]
	v_mfma_f32_16x16x32_bf16 v[2:5], v[170:173], v[212:215], v[2:5]
	v_mfma_f32_16x16x32_bf16 v[2:5], v[174:177], v[216:219], v[2:5]
	s_setprio 0
	s_barrier
	s_add_i32 s49, s49, 2
	s_add_u32 s24, s24, 0x100
	s_addc_u32 s25, s25, 0
	s_add_u32 s47, s47, 0x100
	s_addc_u32 s48, s48, 0
	s_cmp_gt_u32 s49, 41
	s_cbranch_scc0 .LBB0_1123
	s_and_b64 vcc, exec, s[18:19]
	s_cbranch_vccz .LBB0_1126
	s_barrier

.LBB0_1213:
	s_and_b32 s99, s56, 1
	s_lshl_b32 s99, s99, 12
	v_readfirstlane_b32 s100, v0
	s_and_b32 s100, s100, 0xc0
	s_lshl_b32 s100, s100, 4
	s_add_i32 s99, s99, s100
	s_add_i32 m0, s99, 0x21000
	s_lshl_b32 s99, s8, 12
	s_add_u32 s100, s76, s99
	s_addc_u32 s101, s77, 0
	v_and_b32_e32 v149, 0xff, v0
	v_lshlrev_b32_e32 v149, 4, v149
	global_load_lds_dwordx4 v149, s[100:101]
	s_ashr_i32 s31, s30, 31
	s_lshl_b64 s[0:1], s[30:31], 19
	s_add_u32 s34, s78, s0
	s_addc_u32 s35, s79, s1
	s_and_b64 s[0:1], s[4:5], exec
	s_cselect_b32 s7, s35, s39
	s_cselect_b32 s9, s34, s38
	s_ashr_i32 s29, s28, 31
	s_lshl_b64 s[0:1], s[28:29], 19
	s_add_u32 s36, s27, s0
	s_addc_u32 s37, s33, s1
	s_and_b64 s[0:1], s[4:5], exec
	s_cselect_b32 s10, s37, s3
	s_cselect_b32 s29, s36, s2
	s_add_u32 s38, s38, 0x40080
	s_addc_u32 s39, s39, 0
	s_add_u32 s31, s2, 0x100
	v_mov_b32_e32 v2, 0
	s_addc_u32 s57, s3, 0
	s_mov_b32 s58, -2
	v_mov_b32_e32 v3, v2
	v_mov_b32_e32 v4, v2
	v_mov_b32_e32 v5, v2
	v_mov_b32_e32 v6, v2
	v_mov_b32_e32 v7, v2
	v_mov_b32_e32 v8, v2
	v_mov_b32_e32 v9, v2
	v_mov_b32_e32 v18, v2
	v_mov_b32_e32 v19, v2
	v_mov_b32_e32 v20, v2
	v_mov_b32_e32 v21, v2
	v_mov_b32_e32 v22, v2
	v_mov_b32_e32 v23, v2
	v_mov_b32_e32 v24, v2
	v_mov_b32_e32 v25, v2
	v_mov_b32_e32 v34, v2
	v_mov_b32_e32 v35, v2
	v_mov_b32_e32 v36, v2
	v_mov_b32_e32 v37, v2
	v_mov_b32_e32 v38, v2
	v_mov_b32_e32 v39, v2
	v_mov_b32_e32 v40, v2
	v_mov_b32_e32 v41, v2
	v_mov_b32_e32 v50, v2
	v_mov_b32_e32 v51, v2
	v_mov_b32_e32 v52, v2
	v_mov_b32_e32 v53, v2
	v_mov_b32_e32 v54, v2
	v_mov_b32_e32 v55, v2
	v_mov_b32_e32 v56, v2
	v_mov_b32_e32 v57, v2
	v_mov_b32_e32 v10, v2
	v_mov_b32_e32 v11, v2
	v_mov_b32_e32 v12, v2
	v_mov_b32_e32 v13, v2
	v_mov_b32_e32 v14, v2
	v_mov_b32_e32 v15, v2
	v_mov_b32_e32 v16, v2
	v_mov_b32_e32 v17, v2
	v_mov_b32_e32 v26, v2
	v_mov_b32_e32 v27, v2
	v_mov_b32_e32 v28, v2
	v_mov_b32_e32 v29, v2
	v_mov_b32_e32 v30, v2
	v_mov_b32_e32 v31, v2
	v_mov_b32_e32 v32, v2
	v_mov_b32_e32 v33, v2
	v_mov_b32_e32 v42, v2
	v_mov_b32_e32 v43, v2
	v_mov_b32_e32 v44, v2
	v_mov_b32_e32 v45, v2
	v_mov_b32_e32 v46, v2
	v_mov_b32_e32 v47, v2
	v_mov_b32_e32 v48, v2
	v_mov_b32_e32 v49, v2
	v_mov_b32_e32 v58, v2
	v_mov_b32_e32 v59, v2
	v_mov_b32_e32 v60, v2
	v_mov_b32_e32 v61, v2
	v_mov_b32_e32 v66, v2
	v_mov_b32_e32 v67, v2
	v_mov_b32_e32 v68, v2
	v_mov_b32_e32 v69, v2
	v_mov_b32_e32 v70, v2
	v_mov_b32_e32 v71, v2
	v_mov_b32_e32 v72, v2
	v_mov_b32_e32 v73, v2
	v_mov_b32_e32 v74, v2
	v_mov_b32_e32 v75, v2
	v_mov_b32_e32 v76, v2
	v_mov_b32_e32 v77, v2
	v_mov_b32_e32 v90, v2
	v_mov_b32_e32 v91, v2
	v_mov_b32_e32 v92, v2
	v_mov_b32_e32 v93, v2
	v_mov_b32_e32 v94, v2
	v_mov_b32_e32 v95, v2
	v_mov_b32_e32 v96, v2
	v_mov_b32_e32 v97, v2
	v_mov_b32_e32 v110, v2
	v_mov_b32_e32 v111, v2
	v_mov_b32_e32 v112, v2
	v_mov_b32_e32 v113, v2
	v_mov_b32_e32 v114, v2
	v_mov_b32_e32 v115, v2
	v_mov_b32_e32 v116, v2
	v_mov_b32_e32 v117, v2
	v_mov_b32_e32 v130, v2
	v_mov_b32_e32 v131, v2
	v_mov_b32_e32 v132, v2
	v_mov_b32_e32 v133, v2
	v_mov_b32_e32 v134, v2
	v_mov_b32_e32 v135, v2
	v_mov_b32_e32 v136, v2
	v_mov_b32_e32 v137, v2
	v_mov_b32_e32 v82, v2
	v_mov_b32_e32 v83, v2
	v_mov_b32_e32 v84, v2
	v_mov_b32_e32 v85, v2
	v_mov_b32_e32 v86, v2
	v_mov_b32_e32 v87, v2
	v_mov_b32_e32 v88, v2
	v_mov_b32_e32 v89, v2
	v_mov_b32_e32 v102, v2
	v_mov_b32_e32 v103, v2
	v_mov_b32_e32 v104, v2
	v_mov_b32_e32 v105, v2
	v_mov_b32_e32 v106, v2
	v_mov_b32_e32 v107, v2
	v_mov_b32_e32 v108, v2
	v_mov_b32_e32 v109, v2
	v_mov_b32_e32 v122, v2
	v_mov_b32_e32 v123, v2
	v_mov_b32_e32 v124, v2
	v_mov_b32_e32 v125, v2
	v_mov_b32_e32 v126, v2
	v_mov_b32_e32 v127, v2
	v_mov_b32_e32 v128, v2
	v_mov_b32_e32 v129, v2
	v_mov_b32_e32 v142, v2
	v_mov_b32_e32 v143, v2
	v_mov_b32_e32 v144, v2
	v_mov_b32_e32 v145, v2
	v_mov_b32_e32 v146, v2
	v_mov_b32_e32 v147, v2
	v_mov_b32_e32 v148, v2
	v_mov_b32_e32 v149, v2
	s_nop 0
	s_nop 0
	s_nop 0
	s_nop 0
	s_nop 0
	s_nop 0
	s_nop 0
	s_nop 0
	s_nop 0
	s_nop 0
.LBB0_1214:
	ds_read_b128 v[62:65], v208
	ds_read_b128 v[78:81], v208 offset:1024
	ds_read_b128 v[98:101], v208 offset:2048
	ds_read_b128 v[118:121], v208 offset:3072
	ds_read_b128 v[138:141], v209
	ds_read_b128 v[150:153], v209 offset:1024
	ds_read_b128 v[154:157], v209 offset:2048
	ds_read_b128 v[178:181], v209 offset:3072
	s_add_u32 s0, s38, 0xfffc0080
	s_addc_u32 s1, s39, -1
	s_cmp_eq_u32 s58, 12
	s_cselect_b32 s41, s7, s1
	s_cselect_b32 s40, s9, s0
	s_cselect_b32 s3, s10, s57
	s_cselect_b32 s2, s29, s31
	v_lshl_add_u64 v[202:203], s[38:39], 0, v[170:171]
	s_add_i32 m0, s43, 0xc000
	ds_read_b128 v[182:185], v210
	ds_read_b128 v[186:189], v210 offset:1024
	ds_read_b128 v[190:193], v210 offset:2048
	ds_read_b128 v[194:197], v210 offset:3072
	ds_read_b128 v[198:201], v210 offset:4096
	ds_read_b128 v[212:215], v210 offset:5120
	ds_read_b128 v[216:219], v210 offset:6144
	ds_read_b128 v[220:223], v210 offset:7168
	global_load_lds_dwordx4 v[202:203], off
	v_lshl_add_u64 v[202:203], s[38:39], 0, v[172:173]
	s_add_i32 m0, s43, 0xe000
	s_nop 0
	global_load_lds_dwordx4 v[202:203], off
	s_waitcnt vmcnt(8)
	s_waitcnt lgkmcnt(0)
	s_barrier
	s_setprio 1
	v_mfma_f32_16x16x32_bf16 v[146:149], v[62:65], v[182:185], v[146:149]
	v_mfma_f32_16x16x32_bf16 v[146:149], v[78:81], v[186:189], v[146:149]
	v_mfma_f32_16x16x32_bf16 v[142:145], v[98:101], v[182:185], v[142:145]
	v_mfma_f32_16x16x32_bf16 v[142:145], v[118:121], v[186:189], v[142:145]
	v_mfma_f32_16x16x32_bf16 v[126:129], v[62:65], v[190:193], v[126:129]
	v_mfma_f32_16x16x32_bf16 v[126:129], v[78:81], v[194:197], v[126:129]
	v_mfma_f32_16x16x32_bf16 v[122:125], v[98:101], v[190:193], v[122:125]
	v_mfma_f32_16x16x32_bf16 v[122:125], v[118:121], v[194:197], v[122:125]
	v_mfma_f32_16x16x32_bf16 v[106:109], v[62:65], v[198:201], v[106:109]
	v_mfma_f32_16x16x32_bf16 v[106:109], v[78:81], v[212:215], v[106:109]
	v_mfma_f32_16x16x32_bf16 v[102:105], v[98:101], v[198:201], v[102:105]
	v_mfma_f32_16x16x32_bf16 v[102:105], v[118:121], v[212:215], v[102:105]
	v_mfma_f32_16x16x32_bf16 v[86:89], v[62:65], v[216:219], v[86:89]
	v_mfma_f32_16x16x32_bf16 v[86:89], v[78:81], v[220:223], v[86:89]
	v_mfma_f32_16x16x32_bf16 v[82:85], v[98:101], v[216:219], v[82:85]
	v_mfma_f32_16x16x32_bf16 v[82:85], v[118:121], v[220:223], v[82:85]
	s_setprio 0
	s_setprio 1
	v_mfma_f32_16x16x32_bf16 v[134:137], v[138:141], v[182:185], v[134:137]
	v_mfma_f32_16x16x32_bf16 v[134:137], v[150:153], v[186:189], v[134:137]
	v_mfma_f32_16x16x32_bf16 v[130:133], v[154:157], v[182:185], v[130:133]
	v_mfma_f32_16x16x32_bf16 v[130:133], v[178:181], v[186:189], v[130:133]
	v_mfma_f32_16x16x32_bf16 v[114:117], v[138:141], v[190:193], v[114:117]
	v_mfma_f32_16x16x32_bf16 v[114:117], v[150:153], v[194:197], v[114:117]
	v_mfma_f32_16x16x32_bf16 v[110:113], v[154:157], v[190:193], v[110:113]
	v_mfma_f32_16x16x32_bf16 v[110:113], v[178:181], v[194:197], v[110:113]
	v_mfma_f32_16x16x32_bf16 v[94:97], v[138:141], v[198:201], v[94:97]
	v_mfma_f32_16x16x32_bf16 v[94:97], v[150:153], v[212:215], v[94:97]
	v_mfma_f32_16x16x32_bf16 v[90:93], v[154:157], v[198:201], v[90:93]
	v_mfma_f32_16x16x32_bf16 v[90:93], v[178:181], v[212:215], v[90:93]
	v_mfma_f32_16x16x32_bf16 v[74:77], v[138:141], v[216:219], v[74:77]
	v_mfma_f32_16x16x32_bf16 v[74:77], v[150:153], v[220:223], v[74:77]
	v_mfma_f32_16x16x32_bf16 v[70:73], v[154:157], v[216:219], v[70:73]
	v_mfma_f32_16x16x32_bf16 v[70:73], v[178:181], v[220:223], v[70:73]
	s_setprio 0
	s_barrier
	s_add_i32 s0, s53, s42
	v_lshl_add_u64 v[202:203], s[2:3], 0, v[162:163]
	s_mov_b32 m0, s0
	ds_read_b128 v[182:185], v210 offset:16384
	ds_read_b128 v[186:189], v210 offset:17408
	ds_read_b128 v[190:193], v210 offset:18432
	ds_read_b128 v[194:197], v210 offset:19456
	ds_read_b128 v[198:201], v210 offset:20480
	ds_read_b128 v[212:215], v210 offset:21504
	ds_read_b128 v[216:219], v210 offset:22528
	ds_read_b128 v[220:223], v210 offset:23552
	global_load_lds_dwordx4 v[202:203], off
	s_add_i32 m0, s0, 0x2000
	s_add_u32 s0, s2, 0x40000
	v_lshl_add_u64 v[224:225], s[2:3], 0, v[166:167]
	s_addc_u32 s1, s3, 0
	s_add_i32 s59, s54, s42
	global_load_lds_dwordx4 v[224:225], off
	v_lshl_add_u64 v[226:227], s[0:1], 0, v[162:163]
	s_mov_b32 m0, s59
	v_lshl_add_u64 v[228:229], s[40:41], 0, v[164:165]
	global_load_lds_dwordx4 v[226:227], off
	v_lshl_add_u64 v[226:227], s[0:1], 0, v[166:167]
	s_add_i32 m0, s59, 0x2000
	s_nop 0
	global_load_lds_dwordx4 v[226:227], off
	v_lshl_add_u64 v[226:227], s[40:41], 0, v[160:161]
	s_mov_b32 m0, s43
	s_nop 0
	global_load_lds_dwordx4 v[226:227], off
	s_mov_b32 m0, s44
	s_nop 0
	global_load_lds_dwordx4 v[228:229], off
	s_waitcnt vmcnt(8)
	s_waitcnt lgkmcnt(0)
	s_barrier
	s_setprio 1
	v_mfma_f32_16x16x32_bf16 v[66:69], v[62:65], v[182:185], v[66:69]
	v_mfma_f32_16x16x32_bf16 v[66:69], v[78:81], v[186:189], v[66:69]
	v_mfma_f32_16x16x32_bf16 v[58:61], v[98:101], v[182:185], v[58:61]
	v_mfma_f32_16x16x32_bf16 v[58:61], v[118:121], v[186:189], v[58:61]
	v_mfma_f32_16x16x32_bf16 v[46:49], v[62:65], v[190:193], v[46:49]
	v_mfma_f32_16x16x32_bf16 v[46:49], v[78:81], v[194:197], v[46:49]
	v_mfma_f32_16x16x32_bf16 v[42:45], v[98:101], v[190:193], v[42:45]
	v_mfma_f32_16x16x32_bf16 v[42:45], v[118:121], v[194:197], v[42:45]
	v_mfma_f32_16x16x32_bf16 v[30:33], v[62:65], v[198:201], v[30:33]
	v_mfma_f32_16x16x32_bf16 v[30:33], v[78:81], v[212:215], v[30:33]
	v_mfma_f32_16x16x32_bf16 v[26:29], v[98:101], v[198:201], v[26:29]
	v_mfma_f32_16x16x32_bf16 v[26:29], v[118:121], v[212:215], v[26:29]
	v_mfma_f32_16x16x32_bf16 v[14:17], v[62:65], v[216:219], v[14:17]
	v_mfma_f32_16x16x32_bf16 v[14:17], v[78:81], v[220:223], v[14:17]
	v_mfma_f32_16x16x32_bf16 v[10:13], v[98:101], v[216:219], v[10:13]
	v_mfma_f32_16x16x32_bf16 v[10:13], v[118:121], v[220:223], v[10:13]
	s_setprio 0
	s_setprio 1
	v_mfma_f32_16x16x32_bf16 v[54:57], v[138:141], v[182:185], v[54:57]
	v_mfma_f32_16x16x32_bf16 v[54:57], v[150:153], v[186:189], v[54:57]
	v_mfma_f32_16x16x32_bf16 v[50:53], v[154:157], v[182:185], v[50:53]
	v_mfma_f32_16x16x32_bf16 v[50:53], v[178:181], v[186:189], v[50:53]
	v_mfma_f32_16x16x32_bf16 v[38:41], v[138:141], v[190:193], v[38:41]
	v_mfma_f32_16x16x32_bf16 v[38:41], v[150:153], v[194:197], v[38:41]
	v_mfma_f32_16x16x32_bf16 v[34:37], v[154:157], v[190:193], v[34:37]
	v_mfma_f32_16x16x32_bf16 v[34:37], v[178:181], v[194:197], v[34:37]
	v_mfma_f32_16x16x32_bf16 v[22:25], v[138:141], v[198:201], v[22:25]
	v_mfma_f32_16x16x32_bf16 v[22:25], v[150:153], v[212:215], v[22:25]
	v_mfma_f32_16x16x32_bf16 v[18:21], v[154:157], v[198:201], v[18:21]
	v_mfma_f32_16x16x32_bf16 v[18:21], v[178:181], v[212:215], v[18:21]
	v_mfma_f32_16x16x32_bf16 v[6:9], v[138:141], v[216:219], v[6:9]
	v_mfma_f32_16x16x32_bf16 v[6:9], v[150:153], v[220:223], v[6:9]
	v_mfma_f32_16x16x32_bf16 v[2:5], v[154:157], v[216:219], v[2:5]
	v_mfma_f32_16x16x32_bf16 v[2:5], v[178:181], v[220:223], v[2:5]
	s_setprio 0
	s_barrier
	s_add_i32 s59, 0, 0x18000
	s_add_i32 s60, 0, 0x1c000
	v_add_u32_e32 v118, s59, v206
	v_add_u32_e32 v168, s60, v206
	ds_read_b128 v[62:65], v118
	ds_read_b128 v[78:81], v118 offset:1024
	ds_read_b128 v[98:101], v118 offset:2048
	ds_read_b128 v[118:121], v118 offset:3072
	ds_read_b128 v[138:141], v168
	ds_read_b128 v[150:153], v168 offset:1024
	ds_read_b128 v[154:157], v168 offset:2048
	ds_read_b128 v[178:181], v168 offset:3072
	s_add_u32 s0, s40, 0x40000
	s_addc_u32 s1, s41, 0
	s_mov_b32 m0, s45
	v_lshl_add_u64 v[230:231], s[0:1], 0, v[160:161]
	ds_read_b128 v[182:185], v210 offset:32768
	ds_read_b128 v[186:189], v210 offset:33792
	ds_read_b128 v[190:193], v210 offset:34816
	ds_read_b128 v[194:197], v210 offset:35840
	ds_read_b128 v[198:201], v210 offset:36864
	ds_read_b128 v[212:215], v210 offset:37888
	ds_read_b128 v[216:219], v210 offset:38912
	ds_read_b128 v[220:223], v210 offset:39936
	global_load_lds_dwordx4 v[230:231], off
	v_lshl_add_u64 v[230:231], s[0:1], 0, v[164:165]
	s_mov_b32 m0, s46
	s_nop 0
	global_load_lds_dwordx4 v[230:231], off
	s_waitcnt vmcnt(8)
	s_waitcnt lgkmcnt(0)
	s_barrier
	s_setprio 1
	v_mfma_f32_16x16x32_bf16 v[146:149], v[62:65], v[182:185], v[146:149]
	v_mfma_f32_16x16x32_bf16 v[146:149], v[78:81], v[186:189], v[146:149]
	v_mfma_f32_16x16x32_bf16 v[142:145], v[98:101], v[182:185], v[142:145]
	v_mfma_f32_16x16x32_bf16 v[142:145], v[118:121], v[186:189], v[142:145]
	v_mfma_f32_16x16x32_bf16 v[126:129], v[62:65], v[190:193], v[126:129]
	v_mfma_f32_16x16x32_bf16 v[126:129], v[78:81], v[194:197], v[126:129]
	v_mfma_f32_16x16x32_bf16 v[122:125], v[98:101], v[190:193], v[122:125]
	v_mfma_f32_16x16x32_bf16 v[122:125], v[118:121], v[194:197], v[122:125]
	v_mfma_f32_16x16x32_bf16 v[106:109], v[62:65], v[198:201], v[106:109]
	v_mfma_f32_16x16x32_bf16 v[106:109], v[78:81], v[212:215], v[106:109]
	v_mfma_f32_16x16x32_bf16 v[102:105], v[98:101], v[198:201], v[102:105]
	v_mfma_f32_16x16x32_bf16 v[102:105], v[118:121], v[212:215], v[102:105]
	v_mfma_f32_16x16x32_bf16 v[86:89], v[62:65], v[216:219], v[86:89]
	v_mfma_f32_16x16x32_bf16 v[86:89], v[78:81], v[220:223], v[86:89]
	v_mfma_f32_16x16x32_bf16 v[82:85], v[98:101], v[216:219], v[82:85]
	v_mfma_f32_16x16x32_bf16 v[82:85], v[118:121], v[220:223], v[82:85]
	s_setprio 0
	s_setprio 1
	v_mfma_f32_16x16x32_bf16 v[134:137], v[138:141], v[182:185], v[134:137]
	v_mfma_f32_16x16x32_bf16 v[134:137], v[150:153], v[186:189], v[134:137]
	v_mfma_f32_16x16x32_bf16 v[130:133], v[154:157], v[182:185], v[130:133]
	v_mfma_f32_16x16x32_bf16 v[130:133], v[178:181], v[186:189], v[130:133]
	v_mfma_f32_16x16x32_bf16 v[114:117], v[138:141], v[190:193], v[114:117]
	v_mfma_f32_16x16x32_bf16 v[114:117], v[150:153], v[194:197], v[114:117]
	v_mfma_f32_16x16x32_bf16 v[110:113], v[154:157], v[190:193], v[110:113]
	v_mfma_f32_16x16x32_bf16 v[110:113], v[178:181], v[194:197], v[110:113]
	v_mfma_f32_16x16x32_bf16 v[94:97], v[138:141], v[198:201], v[94:97]
	v_mfma_f32_16x16x32_bf16 v[94:97], v[150:153], v[212:215], v[94:97]
	v_mfma_f32_16x16x32_bf16 v[90:93], v[154:157], v[198:201], v[90:93]
	v_mfma_f32_16x16x32_bf16 v[90:93], v[178:181], v[212:215], v[90:93]
	v_mfma_f32_16x16x32_bf16 v[74:77], v[138:141], v[216:219], v[74:77]
	v_mfma_f32_16x16x32_bf16 v[74:77], v[150:153], v[220:223], v[74:77]
	v_mfma_f32_16x16x32_bf16 v[70:73], v[154:157], v[216:219], v[70:73]
	v_mfma_f32_16x16x32_bf16 v[70:73], v[178:181], v[220:223], v[70:73]
	s_setprio 0
	s_barrier
	s_add_i32 s0, s59, s42
	v_lshl_add_u64 v[202:203], v[202:203], 0, s[22:23]
	s_mov_b32 m0, s0
	ds_read_b128 v[182:185], v210 offset:49152
	ds_read_b128 v[186:189], v210 offset:50176
	ds_read_b128 v[190:193], v210 offset:51200
	ds_read_b128 v[194:197], v210 offset:52224
	ds_read_b128 v[198:201], v210 offset:53248
	ds_read_b128 v[212:215], v210 offset:54272
	ds_read_b128 v[216:219], v210 offset:55296
	ds_read_b128 v[220:223], v210 offset:56320
	global_load_lds_dwordx4 v[202:203], off
	s_add_i32 m0, s0, 0x2000
	s_add_u32 s0, s2, 0x40080
	v_lshl_add_u64 v[202:203], v[224:225], 0, s[22:23]
	s_addc_u32 s1, s3, 0
	s_add_i32 s2, s60, s42
	global_load_lds_dwordx4 v[202:203], off
	v_lshl_add_u64 v[202:203], s[0:1], 0, v[162:163]
	s_mov_b32 m0, s2
	s_nop 0
	global_load_lds_dwordx4 v[202:203], off
	v_lshl_add_u64 v[202:203], s[0:1], 0, v[166:167]
	s_add_i32 m0, s2, 0x2000
	s_nop 0
	global_load_lds_dwordx4 v[202:203], off
	v_lshl_add_u64 v[202:203], v[226:227], 0, s[22:23]
	s_mov_b32 m0, s49
	s_nop 0
	global_load_lds_dwordx4 v[202:203], off
	v_lshl_add_u64 v[202:203], v[228:229], 0, s[22:23]
	s_mov_b32 m0, s50
	s_nop 0
	global_load_lds_dwordx4 v[202:203], off
	s_waitcnt vmcnt(8)
	s_waitcnt lgkmcnt(0)
	s_barrier
	s_setprio 1
	v_mfma_f32_16x16x32_bf16 v[66:69], v[62:65], v[182:185], v[66:69]
	v_mfma_f32_16x16x32_bf16 v[66:69], v[78:81], v[186:189], v[66:69]
	v_mfma_f32_16x16x32_bf16 v[58:61], v[98:101], v[182:185], v[58:61]
	v_mfma_f32_16x16x32_bf16 v[58:61], v[118:121], v[186:189], v[58:61]
	v_mfma_f32_16x16x32_bf16 v[46:49], v[62:65], v[190:193], v[46:49]
	v_mfma_f32_16x16x32_bf16 v[46:49], v[78:81], v[194:197], v[46:49]
	v_mfma_f32_16x16x32_bf16 v[42:45], v[98:101], v[190:193], v[42:45]
	v_mfma_f32_16x16x32_bf16 v[42:45], v[118:121], v[194:197], v[42:45]
	v_mfma_f32_16x16x32_bf16 v[30:33], v[62:65], v[198:201], v[30:33]
	v_mfma_f32_16x16x32_bf16 v[30:33], v[78:81], v[212:215], v[30:33]
	v_mfma_f32_16x16x32_bf16 v[26:29], v[98:101], v[198:201], v[26:29]
	v_mfma_f32_16x16x32_bf16 v[26:29], v[118:121], v[212:215], v[26:29]
	v_mfma_f32_16x16x32_bf16 v[14:17], v[62:65], v[216:219], v[14:17]
	v_mfma_f32_16x16x32_bf16 v[14:17], v[78:81], v[220:223], v[14:17]
	v_mfma_f32_16x16x32_bf16 v[10:13], v[98:101], v[216:219], v[10:13]
	v_mfma_f32_16x16x32_bf16 v[10:13], v[118:121], v[220:223], v[10:13]
	s_setprio 0
	s_setprio 1
	v_mfma_f32_16x16x32_bf16 v[54:57], v[138:141], v[182:185], v[54:57]
	v_mfma_f32_16x16x32_bf16 v[54:57], v[150:153], v[186:189], v[54:57]
	v_mfma_f32_16x16x32_bf16 v[50:53], v[154:157], v[182:185], v[50:53]
	v_mfma_f32_16x16x32_bf16 v[50:53], v[178:181], v[186:189], v[50:53]
	v_mfma_f32_16x16x32_bf16 v[38:41], v[138:141], v[190:193], v[38:41]
	v_mfma_f32_16x16x32_bf16 v[38:41], v[150:153], v[194:197], v[38:41]
	v_mfma_f32_16x16x32_bf16 v[34:37], v[154:157], v[190:193], v[34:37]
	v_mfma_f32_16x16x32_bf16 v[34:37], v[178:181], v[194:197], v[34:37]
	v_mfma_f32_16x16x32_bf16 v[22:25], v[138:141], v[198:201], v[22:25]
	v_mfma_f32_16x16x32_bf16 v[22:25], v[150:153], v[212:215], v[22:25]
	v_mfma_f32_16x16x32_bf16 v[18:21], v[154:157], v[198:201], v[18:21]
	v_mfma_f32_16x16x32_bf16 v[18:21], v[178:181], v[212:215], v[18:21]
	v_mfma_f32_16x16x32_bf16 v[6:9], v[138:141], v[216:219], v[6:9]
	v_mfma_f32_16x16x32_bf16 v[6:9], v[150:153], v[220:223], v[6:9]
	v_mfma_f32_16x16x32_bf16 v[2:5], v[154:157], v[216:219], v[2:5]
	v_mfma_f32_16x16x32_bf16 v[2:5], v[178:181], v[220:223], v[2:5]
	s_setprio 0
	s_barrier
	s_add_i32 s58, s58, 2
	s_add_u32 s38, s38, 0x100
	s_addc_u32 s39, s39, 0
	s_add_u32 s31, s31, 0x100
	s_addc_u32 s57, s57, 0
	s_cmp_gt_u32 s58, 13
	s_cbranch_scc0 .LBB0_1214
	s_and_b64 vcc, exec, s[24:25]
	s_cbranch_vccz .LBB0_1217
	s_barrier

.LBB0_1625:
	s_ashr_i32 s29, s28, 31
	s_lshl_b64 s[0:1], s[28:29], 20
	s_add_u32 s30, s33, s0
	s_addc_u32 s31, s42, s1
	s_and_b64 s[0:1], s[6:7], exec
	s_cselect_b32 s11, s31, s39
	s_cselect_b32 s29, s30, s38
	s_ashr_i32 s27, s26, 31
	s_lshl_b64 s[0:1], s[26:27], 20
	s_add_u32 s34, s43, s0
	s_addc_u32 s35, s44, s1
	s_and_b64 s[0:1], s[6:7], exec
	s_cselect_b32 s27, s35, s3
	s_cselect_b32 s56, s34, s2
	s_add_u32 s38, s38, 0x80080
	s_addc_u32 s39, s39, 0
	s_add_u32 s57, s2, 0x100
	v_mov_b32_e32 v2, 0
	s_addc_u32 s58, s3, 0
	s_mov_b32 s59, -2
	s_waitcnt lgkmcnt(0)
	v_mov_b32_e32 v3, v2
	v_mov_b32_e32 v4, v2
	v_mov_b32_e32 v5, v2
	v_mov_b32_e32 v6, v2
	v_mov_b32_e32 v7, v2
	v_mov_b32_e32 v8, v2
	v_mov_b32_e32 v9, v2
	v_mov_b32_e32 v18, v2
	v_mov_b32_e32 v19, v2
	v_mov_b32_e32 v20, v2
	v_mov_b32_e32 v21, v2
	v_mov_b32_e32 v22, v2
	v_mov_b32_e32 v23, v2
	v_mov_b32_e32 v24, v2
	v_mov_b32_e32 v25, v2
	v_mov_b32_e32 v34, v2
	v_mov_b32_e32 v35, v2
	v_mov_b32_e32 v36, v2
	v_mov_b32_e32 v37, v2
	v_mov_b32_e32 v38, v2
	v_mov_b32_e32 v39, v2
	v_mov_b32_e32 v40, v2
	v_mov_b32_e32 v41, v2
	v_mov_b32_e32 v50, v2
	v_mov_b32_e32 v51, v2
	v_mov_b32_e32 v52, v2
	v_mov_b32_e32 v53, v2
	v_mov_b32_e32 v54, v2
	v_mov_b32_e32 v55, v2
	v_mov_b32_e32 v56, v2
	v_mov_b32_e32 v57, v2
	v_mov_b32_e32 v10, v2
	v_mov_b32_e32 v11, v2
	v_mov_b32_e32 v12, v2
	v_mov_b32_e32 v13, v2
	v_mov_b32_e32 v14, v2
	v_mov_b32_e32 v15, v2
	v_mov_b32_e32 v16, v2
	v_mov_b32_e32 v17, v2
	v_mov_b32_e32 v26, v2
	v_mov_b32_e32 v27, v2
	v_mov_b32_e32 v28, v2
	v_mov_b32_e32 v29, v2
	v_mov_b32_e32 v30, v2
	v_mov_b32_e32 v31, v2
	v_mov_b32_e32 v32, v2
	v_mov_b32_e32 v33, v2
	v_mov_b32_e32 v42, v2
	v_mov_b32_e32 v43, v2
	v_mov_b32_e32 v44, v2
	v_mov_b32_e32 v45, v2
	v_mov_b32_e32 v46, v2
	v_mov_b32_e32 v47, v2
	v_mov_b32_e32 v48, v2
	v_mov_b32_e32 v49, v2
	v_mov_b32_e32 v58, v2
	v_mov_b32_e32 v59, v2
	v_mov_b32_e32 v60, v2
	v_mov_b32_e32 v61, v2
	v_mov_b32_e32 v62, v2
	v_mov_b32_e32 v63, v2
	v_mov_b32_e32 v64, v2
	v_mov_b32_e32 v65, v2
	v_mov_b32_e32 v66, v2
	v_mov_b32_e32 v67, v2
	v_mov_b32_e32 v68, v2
	v_mov_b32_e32 v69, v2
	v_mov_b32_e32 v70, v2
	v_mov_b32_e32 v71, v2
	v_mov_b32_e32 v72, v2
	v_mov_b32_e32 v73, v2
	v_mov_b32_e32 v82, v2
	v_mov_b32_e32 v83, v2
	v_mov_b32_e32 v84, v2
	v_mov_b32_e32 v85, v2
	v_mov_b32_e32 v86, v2
	v_mov_b32_e32 v87, v2
	v_mov_b32_e32 v88, v2
	v_mov_b32_e32 v89, v2
	v_mov_b32_e32 v98, v2
	v_mov_b32_e32 v99, v2
	v_mov_b32_e32 v100, v2
	v_mov_b32_e32 v101, v2
	v_mov_b32_e32 v102, v2
	v_mov_b32_e32 v103, v2
	v_mov_b32_e32 v104, v2
	v_mov_b32_e32 v105, v2
	v_mov_b32_e32 v114, v2
	v_mov_b32_e32 v115, v2
	v_mov_b32_e32 v116, v2
	v_mov_b32_e32 v117, v2
	v_mov_b32_e32 v118, v2
	v_mov_b32_e32 v119, v2
	v_mov_b32_e32 v120, v2
	v_mov_b32_e32 v121, v2
	v_mov_b32_e32 v74, v2
	v_mov_b32_e32 v75, v2
	v_mov_b32_e32 v76, v2
	v_mov_b32_e32 v77, v2
	v_mov_b32_e32 v78, v2
	v_mov_b32_e32 v79, v2
	v_mov_b32_e32 v80, v2
	v_mov_b32_e32 v81, v2
	v_mov_b32_e32 v90, v2
	v_mov_b32_e32 v91, v2
	v_mov_b32_e32 v92, v2
	v_mov_b32_e32 v93, v2
	v_mov_b32_e32 v94, v2
	v_mov_b32_e32 v95, v2
	v_mov_b32_e32 v96, v2
	v_mov_b32_e32 v97, v2
	v_mov_b32_e32 v106, v2
	v_mov_b32_e32 v107, v2
	v_mov_b32_e32 v108, v2
	v_mov_b32_e32 v109, v2
	v_mov_b32_e32 v110, v2
	v_mov_b32_e32 v111, v2
	v_mov_b32_e32 v112, v2
	v_mov_b32_e32 v113, v2
	v_mov_b32_e32 v122, v2
	v_mov_b32_e32 v123, v2
	v_mov_b32_e32 v124, v2
	v_mov_b32_e32 v125, v2
	v_mov_b32_e32 v126, v2
	v_mov_b32_e32 v127, v2
	v_mov_b32_e32 v128, v2
	v_mov_b32_e32 v129, v2
	s_nop 0
	s_nop 0
	s_nop 0
	s_nop 0
	s_nop 0
	s_nop 0
	s_nop 0
	s_nop 0
	s_nop 0
.LBB0_1626:
	ds_read_b128 v[130:133], v186
	ds_read_b128 v[134:137], v186 offset:1024
	ds_read_b128 v[138:141], v186 offset:2048
	ds_read_b128 v[142:145], v186 offset:3072
	ds_read_b128 v[146:149], v187
	ds_read_b128 v[150:153], v187 offset:1024
	ds_read_b128 v[170:173], v187 offset:2048
	ds_read_b128 v[174:177], v187 offset:3072
	s_add_u32 s0, s38, 0xfff80080
	s_addc_u32 s1, s39, -1
	s_cmp_eq_u32 s59, 28
	s_cselect_b32 s41, s11, s1
	s_cselect_b32 s40, s29, s0
	s_cselect_b32 s3, s27, s58
	s_cselect_b32 s2, s56, s57
	v_lshl_add_u64 v[218:219], s[38:39], 0, v[162:163]
	s_add_i32 m0, s37, 0xc000
	ds_read_b128 v[178:181], v188
	ds_read_b128 v[190:193], v188 offset:1024
	ds_read_b128 v[194:197], v188 offset:2048
	ds_read_b128 v[198:201], v188 offset:3072
	ds_read_b128 v[202:205], v188 offset:4096
	ds_read_b128 v[206:209], v188 offset:5120
	ds_read_b128 v[210:213], v188 offset:6144
	ds_read_b128 v[214:217], v188 offset:7168
	global_load_lds_dwordx4 v[218:219], off
	v_lshl_add_u64 v[218:219], s[38:39], 0, v[164:165]
	s_add_i32 m0, s37, 0xe000
	s_nop 0
	global_load_lds_dwordx4 v[218:219], off
	s_waitcnt vmcnt(8)
	s_waitcnt lgkmcnt(0)
	s_barrier
	s_setprio 1
	v_mfma_f32_16x16x32_bf16 v[126:129], v[130:133], v[178:181], v[126:129]
	v_mfma_f32_16x16x32_bf16 v[126:129], v[134:137], v[190:193], v[126:129]
	v_mfma_f32_16x16x32_bf16 v[122:125], v[138:141], v[178:181], v[122:125]
	v_mfma_f32_16x16x32_bf16 v[122:125], v[142:145], v[190:193], v[122:125]
	v_mfma_f32_16x16x32_bf16 v[110:113], v[130:133], v[194:197], v[110:113]
	v_mfma_f32_16x16x32_bf16 v[110:113], v[134:137], v[198:201], v[110:113]
	v_mfma_f32_16x16x32_bf16 v[106:109], v[138:141], v[194:197], v[106:109]
	v_mfma_f32_16x16x32_bf16 v[106:109], v[142:145], v[198:201], v[106:109]
	v_mfma_f32_16x16x32_bf16 v[94:97], v[130:133], v[202:205], v[94:97]
	v_mfma_f32_16x16x32_bf16 v[94:97], v[134:137], v[206:209], v[94:97]
	v_mfma_f32_16x16x32_bf16 v[90:93], v[138:141], v[202:205], v[90:93]
	v_mfma_f32_16x16x32_bf16 v[90:93], v[142:145], v[206:209], v[90:93]
	v_mfma_f32_16x16x32_bf16 v[78:81], v[130:133], v[210:213], v[78:81]
	v_mfma_f32_16x16x32_bf16 v[78:81], v[134:137], v[214:217], v[78:81]
	v_mfma_f32_16x16x32_bf16 v[74:77], v[138:141], v[210:213], v[74:77]
	v_mfma_f32_16x16x32_bf16 v[74:77], v[142:145], v[214:217], v[74:77]
	s_setprio 0
	s_setprio 1
	v_mfma_f32_16x16x32_bf16 v[118:121], v[146:149], v[178:181], v[118:121]
	v_mfma_f32_16x16x32_bf16 v[118:121], v[150:153], v[190:193], v[118:121]
	v_mfma_f32_16x16x32_bf16 v[114:117], v[170:173], v[178:181], v[114:117]
	v_mfma_f32_16x16x32_bf16 v[114:117], v[174:177], v[190:193], v[114:117]
	v_mfma_f32_16x16x32_bf16 v[102:105], v[146:149], v[194:197], v[102:105]
	v_mfma_f32_16x16x32_bf16 v[102:105], v[150:153], v[198:201], v[102:105]
	v_mfma_f32_16x16x32_bf16 v[98:101], v[170:173], v[194:197], v[98:101]
	v_mfma_f32_16x16x32_bf16 v[98:101], v[174:177], v[198:201], v[98:101]
	v_mfma_f32_16x16x32_bf16 v[86:89], v[146:149], v[202:205], v[86:89]
	v_mfma_f32_16x16x32_bf16 v[86:89], v[150:153], v[206:209], v[86:89]
	v_mfma_f32_16x16x32_bf16 v[82:85], v[170:173], v[202:205], v[82:85]
	v_mfma_f32_16x16x32_bf16 v[82:85], v[174:177], v[206:209], v[82:85]
	v_mfma_f32_16x16x32_bf16 v[70:73], v[146:149], v[210:213], v[70:73]
	v_mfma_f32_16x16x32_bf16 v[70:73], v[150:153], v[214:217], v[70:73]
	v_mfma_f32_16x16x32_bf16 v[66:69], v[170:173], v[210:213], v[66:69]
	v_mfma_f32_16x16x32_bf16 v[66:69], v[174:177], v[214:217], v[66:69]
	s_setprio 0
	s_barrier
	s_add_i32 s0, s54, s45
	v_lshl_add_u64 v[218:219], s[2:3], 0, v[156:157]
	s_mov_b32 m0, s0
	ds_read_b128 v[178:181], v188 offset:16384
	ds_read_b128 v[190:193], v188 offset:17408
	ds_read_b128 v[194:197], v188 offset:18432
	ds_read_b128 v[198:201], v188 offset:19456
	ds_read_b128 v[202:205], v188 offset:20480
	ds_read_b128 v[206:209], v188 offset:21504
	ds_read_b128 v[210:213], v188 offset:22528
	ds_read_b128 v[214:217], v188 offset:23552
	global_load_lds_dwordx4 v[218:219], off
	s_add_i32 m0, s0, 0x2000
	s_add_u32 s0, s2, 0x80000
	v_lshl_add_u64 v[220:221], s[2:3], 0, v[160:161]
	s_addc_u32 s1, s3, 0
	s_add_i32 s60, s55, s45
	global_load_lds_dwordx4 v[220:221], off
	v_lshl_add_u64 v[222:223], s[0:1], 0, v[156:157]
	s_mov_b32 m0, s60
	v_lshl_add_u64 v[224:225], s[40:41], 0, v[158:159]
	global_load_lds_dwordx4 v[222:223], off
	v_lshl_add_u64 v[222:223], s[0:1], 0, v[160:161]
	s_add_i32 m0, s60, 0x2000
	s_nop 0
	global_load_lds_dwordx4 v[222:223], off
	v_lshl_add_u64 v[222:223], s[40:41], 0, v[154:155]
	s_mov_b32 m0, s37
	s_nop 0
	global_load_lds_dwordx4 v[222:223], off
	s_mov_b32 m0, s46
	s_nop 0
	global_load_lds_dwordx4 v[224:225], off
	s_waitcnt vmcnt(8)
	s_waitcnt lgkmcnt(0)
	s_barrier
	s_setprio 1
	v_mfma_f32_16x16x32_bf16 v[62:65], v[130:133], v[178:181], v[62:65]
	v_mfma_f32_16x16x32_bf16 v[62:65], v[134:137], v[190:193], v[62:65]
	v_mfma_f32_16x16x32_bf16 v[58:61], v[138:141], v[178:181], v[58:61]
	v_mfma_f32_16x16x32_bf16 v[58:61], v[142:145], v[190:193], v[58:61]
	v_mfma_f32_16x16x32_bf16 v[46:49], v[130:133], v[194:197], v[46:49]
	v_mfma_f32_16x16x32_bf16 v[46:49], v[134:137], v[198:201], v[46:49]
	v_mfma_f32_16x16x32_bf16 v[42:45], v[138:141], v[194:197], v[42:45]
	v_mfma_f32_16x16x32_bf16 v[42:45], v[142:145], v[198:201], v[42:45]
	v_mfma_f32_16x16x32_bf16 v[30:33], v[130:133], v[202:205], v[30:33]
	v_mfma_f32_16x16x32_bf16 v[30:33], v[134:137], v[206:209], v[30:33]
	v_mfma_f32_16x16x32_bf16 v[26:29], v[138:141], v[202:205], v[26:29]
	v_mfma_f32_16x16x32_bf16 v[26:29], v[142:145], v[206:209], v[26:29]
	v_mfma_f32_16x16x32_bf16 v[14:17], v[130:133], v[210:213], v[14:17]
	v_mfma_f32_16x16x32_bf16 v[14:17], v[134:137], v[214:217], v[14:17]
	v_mfma_f32_16x16x32_bf16 v[10:13], v[138:141], v[210:213], v[10:13]
	v_mfma_f32_16x16x32_bf16 v[10:13], v[142:145], v[214:217], v[10:13]
	s_setprio 0
	s_setprio 1
	v_mfma_f32_16x16x32_bf16 v[54:57], v[146:149], v[178:181], v[54:57]
	v_mfma_f32_16x16x32_bf16 v[54:57], v[150:153], v[190:193], v[54:57]
	v_mfma_f32_16x16x32_bf16 v[50:53], v[170:173], v[178:181], v[50:53]
	v_mfma_f32_16x16x32_bf16 v[50:53], v[174:177], v[190:193], v[50:53]
	v_mfma_f32_16x16x32_bf16 v[38:41], v[146:149], v[194:197], v[38:41]
	v_mfma_f32_16x16x32_bf16 v[38:41], v[150:153], v[198:201], v[38:41]
	v_mfma_f32_16x16x32_bf16 v[34:37], v[170:173], v[194:197], v[34:37]
	v_mfma_f32_16x16x32_bf16 v[34:37], v[174:177], v[198:201], v[34:37]
	v_mfma_f32_16x16x32_bf16 v[22:25], v[146:149], v[202:205], v[22:25]
	v_mfma_f32_16x16x32_bf16 v[22:25], v[150:153], v[206:209], v[22:25]
	v_mfma_f32_16x16x32_bf16 v[18:21], v[170:173], v[202:205], v[18:21]
	v_mfma_f32_16x16x32_bf16 v[18:21], v[174:177], v[206:209], v[18:21]
	v_mfma_f32_16x16x32_bf16 v[6:9], v[146:149], v[210:213], v[6:9]
	v_mfma_f32_16x16x32_bf16 v[6:9], v[150:153], v[214:217], v[6:9]
	v_mfma_f32_16x16x32_bf16 v[2:5], v[170:173], v[210:213], v[2:5]
	v_mfma_f32_16x16x32_bf16 v[2:5], v[174:177], v[214:217], v[2:5]
	s_setprio 0
	s_barrier
	s_add_i32 s60, 0, 0x18000
	s_add_i32 s61, 0, 0x1c000
	v_add_u32_e32 v142, s60, v182
	v_add_u32_e32 v174, s61, v182
	ds_read_b128 v[130:133], v142
	ds_read_b128 v[134:137], v142 offset:1024
	ds_read_b128 v[138:141], v142 offset:2048
	ds_read_b128 v[142:145], v142 offset:3072
	ds_read_b128 v[146:149], v174
	ds_read_b128 v[150:153], v174 offset:1024
	ds_read_b128 v[170:173], v174 offset:2048
	ds_read_b128 v[174:177], v174 offset:3072
	s_add_u32 s0, s40, 0x80000
	s_addc_u32 s1, s41, 0
	s_mov_b32 m0, s47
	v_lshl_add_u64 v[226:227], s[0:1], 0, v[154:155]
	ds_read_b128 v[178:181], v188 offset:32768
	ds_read_b128 v[190:193], v188 offset:33792
	ds_read_b128 v[194:197], v188 offset:34816
	ds_read_b128 v[198:201], v188 offset:35840
	ds_read_b128 v[202:205], v188 offset:36864
	ds_read_b128 v[206:209], v188 offset:37888
	ds_read_b128 v[210:213], v188 offset:38912
	ds_read_b128 v[214:217], v188 offset:39936
	global_load_lds_dwordx4 v[226:227], off
	v_lshl_add_u64 v[226:227], s[0:1], 0, v[158:159]
	s_mov_b32 m0, s48
	s_nop 0
	global_load_lds_dwordx4 v[226:227], off
	s_waitcnt vmcnt(8)
	s_waitcnt lgkmcnt(0)
	s_barrier
	s_setprio 1
	v_mfma_f32_16x16x32_bf16 v[126:129], v[130:133], v[178:181], v[126:129]
	v_mfma_f32_16x16x32_bf16 v[126:129], v[134:137], v[190:193], v[126:129]
	v_mfma_f32_16x16x32_bf16 v[122:125], v[138:141], v[178:181], v[122:125]
	v_mfma_f32_16x16x32_bf16 v[122:125], v[142:145], v[190:193], v[122:125]
	v_mfma_f32_16x16x32_bf16 v[110:113], v[130:133], v[194:197], v[110:113]
	v_mfma_f32_16x16x32_bf16 v[110:113], v[134:137], v[198:201], v[110:113]
	v_mfma_f32_16x16x32_bf16 v[106:109], v[138:141], v[194:197], v[106:109]
	v_mfma_f32_16x16x32_bf16 v[106:109], v[142:145], v[198:201], v[106:109]
	v_mfma_f32_16x16x32_bf16 v[94:97], v[130:133], v[202:205], v[94:97]
	v_mfma_f32_16x16x32_bf16 v[94:97], v[134:137], v[206:209], v[94:97]
	v_mfma_f32_16x16x32_bf16 v[90:93], v[138:141], v[202:205], v[90:93]
	v_mfma_f32_16x16x32_bf16 v[90:93], v[142:145], v[206:209], v[90:93]
	v_mfma_f32_16x16x32_bf16 v[78:81], v[130:133], v[210:213], v[78:81]
	v_mfma_f32_16x16x32_bf16 v[78:81], v[134:137], v[214:217], v[78:81]
	v_mfma_f32_16x16x32_bf16 v[74:77], v[138:141], v[210:213], v[74:77]
	v_mfma_f32_16x16x32_bf16 v[74:77], v[142:145], v[214:217], v[74:77]
	s_setprio 0
	s_setprio 1
	v_mfma_f32_16x16x32_bf16 v[118:121], v[146:149], v[178:181], v[118:121]
	v_mfma_f32_16x16x32_bf16 v[118:121], v[150:153], v[190:193], v[118:121]
	v_mfma_f32_16x16x32_bf16 v[114:117], v[170:173], v[178:181], v[114:117]
	v_mfma_f32_16x16x32_bf16 v[114:117], v[174:177], v[190:193], v[114:117]
	v_mfma_f32_16x16x32_bf16 v[102:105], v[146:149], v[194:197], v[102:105]
	v_mfma_f32_16x16x32_bf16 v[102:105], v[150:153], v[198:201], v[102:105]
	v_mfma_f32_16x16x32_bf16 v[98:101], v[170:173], v[194:197], v[98:101]
	v_mfma_f32_16x16x32_bf16 v[98:101], v[174:177], v[198:201], v[98:101]
	v_mfma_f32_16x16x32_bf16 v[86:89], v[146:149], v[202:205], v[86:89]
	v_mfma_f32_16x16x32_bf16 v[86:89], v[150:153], v[206:209], v[86:89]
	v_mfma_f32_16x16x32_bf16 v[82:85], v[170:173], v[202:205], v[82:85]
	v_mfma_f32_16x16x32_bf16 v[82:85], v[174:177], v[206:209], v[82:85]
	v_mfma_f32_16x16x32_bf16 v[70:73], v[146:149], v[210:213], v[70:73]
	v_mfma_f32_16x16x32_bf16 v[70:73], v[150:153], v[214:217], v[70:73]
	v_mfma_f32_16x16x32_bf16 v[66:69], v[170:173], v[210:213], v[66:69]
	v_mfma_f32_16x16x32_bf16 v[66:69], v[174:177], v[214:217], v[66:69]
	s_setprio 0
	s_barrier
	s_add_i32 s0, s60, s45
	v_lshl_add_u64 v[218:219], v[218:219], 0, s[14:15]
	s_mov_b32 m0, s0
	ds_read_b128 v[178:181], v188 offset:49152
	ds_read_b128 v[190:193], v188 offset:50176
	ds_read_b128 v[194:197], v188 offset:51200
	ds_read_b128 v[198:201], v188 offset:52224
	ds_read_b128 v[202:205], v188 offset:53248
	ds_read_b128 v[206:209], v188 offset:54272
	ds_read_b128 v[210:213], v188 offset:55296
	ds_read_b128 v[214:217], v188 offset:56320
	global_load_lds_dwordx4 v[218:219], off
	s_add_i32 m0, s0, 0x2000
	s_add_u32 s0, s2, 0x80080
	v_lshl_add_u64 v[218:219], v[220:221], 0, s[14:15]
	s_addc_u32 s1, s3, 0
	s_add_i32 s2, s61, s45
	global_load_lds_dwordx4 v[218:219], off
	v_lshl_add_u64 v[218:219], s[0:1], 0, v[156:157]
	s_mov_b32 m0, s2
	s_nop 0
	global_load_lds_dwordx4 v[218:219], off
	v_lshl_add_u64 v[218:219], s[0:1], 0, v[160:161]
	s_add_i32 m0, s2, 0x2000
	s_nop 0
	global_load_lds_dwordx4 v[218:219], off
	v_lshl_add_u64 v[218:219], v[222:223], 0, s[14:15]
	s_mov_b32 m0, s50
	s_nop 0
	global_load_lds_dwordx4 v[218:219], off
	v_lshl_add_u64 v[218:219], v[224:225], 0, s[14:15]
	s_mov_b32 m0, s51
	s_nop 0
	global_load_lds_dwordx4 v[218:219], off
	s_waitcnt vmcnt(8)
	s_waitcnt lgkmcnt(0)
	s_barrier
	s_setprio 1
	v_mfma_f32_16x16x32_bf16 v[62:65], v[130:133], v[178:181], v[62:65]
	v_mfma_f32_16x16x32_bf16 v[62:65], v[134:137], v[190:193], v[62:65]
	v_mfma_f32_16x16x32_bf16 v[58:61], v[138:141], v[178:181], v[58:61]
	v_mfma_f32_16x16x32_bf16 v[58:61], v[142:145], v[190:193], v[58:61]
	v_mfma_f32_16x16x32_bf16 v[46:49], v[130:133], v[194:197], v[46:49]
	v_mfma_f32_16x16x32_bf16 v[46:49], v[134:137], v[198:201], v[46:49]
	v_mfma_f32_16x16x32_bf16 v[42:45], v[138:141], v[194:197], v[42:45]
	v_mfma_f32_16x16x32_bf16 v[42:45], v[142:145], v[198:201], v[42:45]
	v_mfma_f32_16x16x32_bf16 v[30:33], v[130:133], v[202:205], v[30:33]
	v_mfma_f32_16x16x32_bf16 v[30:33], v[134:137], v[206:209], v[30:33]
	v_mfma_f32_16x16x32_bf16 v[26:29], v[138:141], v[202:205], v[26:29]
	v_mfma_f32_16x16x32_bf16 v[26:29], v[142:145], v[206:209], v[26:29]
	v_mfma_f32_16x16x32_bf16 v[14:17], v[130:133], v[210:213], v[14:17]
	v_mfma_f32_16x16x32_bf16 v[14:17], v[134:137], v[214:217], v[14:17]
	v_mfma_f32_16x16x32_bf16 v[10:13], v[138:141], v[210:213], v[10:13]
	v_mfma_f32_16x16x32_bf16 v[10:13], v[142:145], v[214:217], v[10:13]
	s_setprio 0
	s_setprio 1
	v_mfma_f32_16x16x32_bf16 v[54:57], v[146:149], v[178:181], v[54:57]
	v_mfma_f32_16x16x32_bf16 v[54:57], v[150:153], v[190:193], v[54:57]
	v_mfma_f32_16x16x32_bf16 v[50:53], v[170:173], v[178:181], v[50:53]
	v_mfma_f32_16x16x32_bf16 v[50:53], v[174:177], v[190:193], v[50:53]
	v_mfma_f32_16x16x32_bf16 v[38:41], v[146:149], v[194:197], v[38:41]
	v_mfma_f32_16x16x32_bf16 v[38:41], v[150:153], v[198:201], v[38:41]
	v_mfma_f32_16x16x32_bf16 v[34:37], v[170:173], v[194:197], v[34:37]
	v_mfma_f32_16x16x32_bf16 v[34:37], v[174:177], v[198:201], v[34:37]
	v_mfma_f32_16x16x32_bf16 v[22:25], v[146:149], v[202:205], v[22:25]
	v_mfma_f32_16x16x32_bf16 v[22:25], v[150:153], v[206:209], v[22:25]
	v_mfma_f32_16x16x32_bf16 v[18:21], v[170:173], v[202:205], v[18:21]
	v_mfma_f32_16x16x32_bf16 v[18:21], v[174:177], v[206:209], v[18:21]
	v_mfma_f32_16x16x32_bf16 v[6:9], v[146:149], v[210:213], v[6:9]
	v_mfma_f32_16x16x32_bf16 v[6:9], v[150:153], v[214:217], v[6:9]
	v_mfma_f32_16x16x32_bf16 v[2:5], v[170:173], v[210:213], v[2:5]
	v_mfma_f32_16x16x32_bf16 v[2:5], v[174:177], v[214:217], v[2:5]
	s_setprio 0
	s_barrier
	s_add_i32 s59, s59, 2
	s_add_u32 s38, s38, 0x100
	s_addc_u32 s39, s39, 0
	s_add_u32 s57, s57, 0x100
	s_addc_u32 s58, s58, 0
	s_cmp_gt_u32 s59, 29
	s_cbranch_scc0 .LBB0_1626
	s_and_b64 vcc, exec, s[16:17]
	s_cbranch_vccz .LBB0_1629
	s_barrier

.LBB0_1714:
	s_and_b32 s99, s47, 1
	s_lshl_b32 s99, s99, 12
	v_readfirstlane_b32 s100, v0
	s_and_b32 s100, s100, 0xc0
	s_lshl_b32 s100, s100, 4
	s_add_i32 s99, s99, s100
	s_add_i32 m0, s99, 0x21000
	s_lshl_b32 s99, s26, 12
	s_add_u32 s100, s76, s99
	s_addc_u32 s101, s77, 0
	v_and_b32_e32 v129, 0xff, v0
	v_lshlrev_b32_e32 v129, 4, v129
	global_load_lds_dwordx4 v129, s[100:101]
	s_ashr_i32 s21, s20, 31
	s_lshl_b64 s[0:1], s[20:21], 19
	s_add_u32 s22, s78, s0
	s_addc_u32 s23, s79, s1
	s_and_b64 s[0:1], s[4:5], exec
	s_cselect_b32 s21, s23, s29
	s_cselect_b32 s49, s22, s28
	s_ashr_i32 s19, s18, 31
	s_lshl_b64 s[0:1], s[18:19], 19
	s_add_u32 s24, s33, s0
	s_addc_u32 s25, s34, s1
	s_and_b64 s[0:1], s[4:5], exec
	s_cselect_b32 s19, s25, s3
	s_cselect_b32 s50, s24, s2
	s_add_u32 s28, s28, 0x40080
	s_addc_u32 s29, s29, 0
	s_add_u32 s51, s2, 0x100
	v_mov_b32_e32 v2, 0
	s_addc_u32 s52, s3, 0
	s_mov_b32 s53, -2
	v_mov_b32_e32 v3, v2
	v_mov_b32_e32 v4, v2
	v_mov_b32_e32 v5, v2
	v_mov_b32_e32 v10, v2
	v_mov_b32_e32 v11, v2
	v_mov_b32_e32 v12, v2
	v_mov_b32_e32 v13, v2
	v_mov_b32_e32 v18, v2
	v_mov_b32_e32 v19, v2
	v_mov_b32_e32 v20, v2
	v_mov_b32_e32 v21, v2
	v_mov_b32_e32 v26, v2
	v_mov_b32_e32 v27, v2
	v_mov_b32_e32 v28, v2
	v_mov_b32_e32 v29, v2
	v_mov_b32_e32 v34, v2
	v_mov_b32_e32 v35, v2
	v_mov_b32_e32 v36, v2
	v_mov_b32_e32 v37, v2
	v_mov_b32_e32 v42, v2
	v_mov_b32_e32 v43, v2
	v_mov_b32_e32 v44, v2
	v_mov_b32_e32 v45, v2
	v_mov_b32_e32 v50, v2
	v_mov_b32_e32 v51, v2
	v_mov_b32_e32 v52, v2
	v_mov_b32_e32 v53, v2
	v_mov_b32_e32 v58, v2
	v_mov_b32_e32 v59, v2
	v_mov_b32_e32 v60, v2
	v_mov_b32_e32 v61, v2
	v_mov_b32_e32 v6, v2
	v_mov_b32_e32 v7, v2
	v_mov_b32_e32 v8, v2
	v_mov_b32_e32 v9, v2
	v_mov_b32_e32 v14, v2
	v_mov_b32_e32 v15, v2
	v_mov_b32_e32 v16, v2
	v_mov_b32_e32 v17, v2
	v_mov_b32_e32 v22, v2
	v_mov_b32_e32 v23, v2
	v_mov_b32_e32 v24, v2
	v_mov_b32_e32 v25, v2
	v_mov_b32_e32 v30, v2
	v_mov_b32_e32 v31, v2
	v_mov_b32_e32 v32, v2
	v_mov_b32_e32 v33, v2
	v_mov_b32_e32 v38, v2
	v_mov_b32_e32 v39, v2
	v_mov_b32_e32 v40, v2
	v_mov_b32_e32 v41, v2
	v_mov_b32_e32 v46, v2
	v_mov_b32_e32 v47, v2
	v_mov_b32_e32 v48, v2
	v_mov_b32_e32 v49, v2
	v_mov_b32_e32 v54, v2
	v_mov_b32_e32 v55, v2
	v_mov_b32_e32 v56, v2
	v_mov_b32_e32 v57, v2
	v_mov_b32_e32 v62, v2
	v_mov_b32_e32 v63, v2
	v_mov_b32_e32 v64, v2
	v_mov_b32_e32 v65, v2
	v_mov_b32_e32 v66, v2
	v_mov_b32_e32 v67, v2
	v_mov_b32_e32 v68, v2
	v_mov_b32_e32 v69, v2
	v_mov_b32_e32 v74, v2
	v_mov_b32_e32 v75, v2
	v_mov_b32_e32 v76, v2
	v_mov_b32_e32 v77, v2
	v_mov_b32_e32 v82, v2
	v_mov_b32_e32 v83, v2
	v_mov_b32_e32 v84, v2
	v_mov_b32_e32 v85, v2
	v_mov_b32_e32 v90, v2
	v_mov_b32_e32 v91, v2
	v_mov_b32_e32 v92, v2
	v_mov_b32_e32 v93, v2
	v_mov_b32_e32 v98, v2
	v_mov_b32_e32 v99, v2
	v_mov_b32_e32 v100, v2
	v_mov_b32_e32 v101, v2
	v_mov_b32_e32 v106, v2
	v_mov_b32_e32 v107, v2
	v_mov_b32_e32 v108, v2
	v_mov_b32_e32 v109, v2
	v_mov_b32_e32 v114, v2
	v_mov_b32_e32 v115, v2
	v_mov_b32_e32 v116, v2
	v_mov_b32_e32 v117, v2
	v_mov_b32_e32 v122, v2
	v_mov_b32_e32 v123, v2
	v_mov_b32_e32 v124, v2
	v_mov_b32_e32 v125, v2
	v_mov_b32_e32 v70, v2
	v_mov_b32_e32 v71, v2
	v_mov_b32_e32 v72, v2
	v_mov_b32_e32 v73, v2
	v_mov_b32_e32 v78, v2
	v_mov_b32_e32 v79, v2
	v_mov_b32_e32 v80, v2
	v_mov_b32_e32 v81, v2
	v_mov_b32_e32 v86, v2
	v_mov_b32_e32 v87, v2
	v_mov_b32_e32 v88, v2
	v_mov_b32_e32 v89, v2
	v_mov_b32_e32 v94, v2
	v_mov_b32_e32 v95, v2
	v_mov_b32_e32 v96, v2
	v_mov_b32_e32 v97, v2
	v_mov_b32_e32 v102, v2
	v_mov_b32_e32 v103, v2
	v_mov_b32_e32 v104, v2
	v_mov_b32_e32 v105, v2
	v_mov_b32_e32 v110, v2
	v_mov_b32_e32 v111, v2
	v_mov_b32_e32 v112, v2
	v_mov_b32_e32 v113, v2
	v_mov_b32_e32 v118, v2
	v_mov_b32_e32 v119, v2
	v_mov_b32_e32 v120, v2
	v_mov_b32_e32 v121, v2
	v_mov_b32_e32 v126, v2
	v_mov_b32_e32 v127, v2
	v_mov_b32_e32 v128, v2
	v_mov_b32_e32 v129, v2
	s_nop 0
	s_nop 0
	s_nop 0
	s_nop 0
	s_nop 0
	s_nop 0
	s_nop 0
	s_nop 0
	s_nop 0
	s_nop 0
	s_nop 0
	s_nop 0
	s_nop 0
	s_nop 0
.LBB0_1715:
	ds_read_b128 v[148:151], v166
	ds_read_b128 v[152:155], v166 offset:1024
	ds_read_b128 v[156:159], v166 offset:2048
	ds_read_b128 v[160:163], v166 offset:3072
	ds_read_b128 v[170:173], v167
	ds_read_b128 v[174:177], v167 offset:1024
	ds_read_b128 v[178:181], v167 offset:2048
	ds_read_b128 v[182:185], v167 offset:3072
	s_add_u32 s0, s28, 0xfffc0080
	s_addc_u32 s1, s29, -1
	s_cmp_eq_u32 s53, 12
	s_cselect_b32 s31, s21, s1
	s_cselect_b32 s30, s49, s0
	s_cselect_b32 s3, s19, s52
	s_cselect_b32 s2, s50, s51
	v_lshl_add_u64 v[218:219], s[28:29], 0, v[140:141]
	s_add_i32 m0, s27, 0xc000
	ds_read_b128 v[186:189], v168
	ds_read_b128 v[190:193], v168 offset:1024
	ds_read_b128 v[194:197], v168 offset:2048
	ds_read_b128 v[198:201], v168 offset:3072
	ds_read_b128 v[202:205], v168 offset:4096
	ds_read_b128 v[206:209], v168 offset:5120
	ds_read_b128 v[210:213], v168 offset:6144
	ds_read_b128 v[214:217], v168 offset:7168
	global_load_lds_dwordx4 v[218:219], off
	v_lshl_add_u64 v[218:219], s[28:29], 0, v[142:143]
	s_add_i32 m0, s27, 0xe000
	s_nop 0
	global_load_lds_dwordx4 v[218:219], off
	s_waitcnt vmcnt(8)
	s_waitcnt lgkmcnt(0)
	s_barrier
	s_setprio 1
	v_mfma_f32_16x16x32_bf16 v[126:129], v[148:151], v[186:189], v[126:129]
	v_mfma_f32_16x16x32_bf16 v[126:129], v[152:155], v[190:193], v[126:129]
	v_mfma_f32_16x16x32_bf16 v[118:121], v[156:159], v[186:189], v[118:121]
	v_mfma_f32_16x16x32_bf16 v[118:121], v[160:163], v[190:193], v[118:121]
	v_mfma_f32_16x16x32_bf16 v[110:113], v[148:151], v[194:197], v[110:113]
	v_mfma_f32_16x16x32_bf16 v[110:113], v[152:155], v[198:201], v[110:113]
	v_mfma_f32_16x16x32_bf16 v[102:105], v[156:159], v[194:197], v[102:105]
	v_mfma_f32_16x16x32_bf16 v[102:105], v[160:163], v[198:201], v[102:105]
	v_mfma_f32_16x16x32_bf16 v[94:97], v[148:151], v[202:205], v[94:97]
	v_mfma_f32_16x16x32_bf16 v[94:97], v[152:155], v[206:209], v[94:97]
	v_mfma_f32_16x16x32_bf16 v[86:89], v[156:159], v[202:205], v[86:89]
	v_mfma_f32_16x16x32_bf16 v[86:89], v[160:163], v[206:209], v[86:89]
	v_mfma_f32_16x16x32_bf16 v[78:81], v[148:151], v[210:213], v[78:81]
	v_mfma_f32_16x16x32_bf16 v[78:81], v[152:155], v[214:217], v[78:81]
	v_mfma_f32_16x16x32_bf16 v[70:73], v[156:159], v[210:213], v[70:73]
	v_mfma_f32_16x16x32_bf16 v[70:73], v[160:163], v[214:217], v[70:73]
	s_setprio 0
	s_setprio 1
	v_mfma_f32_16x16x32_bf16 v[122:125], v[170:173], v[186:189], v[122:125]
	v_mfma_f32_16x16x32_bf16 v[122:125], v[174:177], v[190:193], v[122:125]
	v_mfma_f32_16x16x32_bf16 v[114:117], v[178:181], v[186:189], v[114:117]
	v_mfma_f32_16x16x32_bf16 v[114:117], v[182:185], v[190:193], v[114:117]
	v_mfma_f32_16x16x32_bf16 v[106:109], v[170:173], v[194:197], v[106:109]
	v_mfma_f32_16x16x32_bf16 v[106:109], v[174:177], v[198:201], v[106:109]
	v_mfma_f32_16x16x32_bf16 v[98:101], v[178:181], v[194:197], v[98:101]
	v_mfma_f32_16x16x32_bf16 v[98:101], v[182:185], v[198:201], v[98:101]
	v_mfma_f32_16x16x32_bf16 v[90:93], v[170:173], v[202:205], v[90:93]
	v_mfma_f32_16x16x32_bf16 v[90:93], v[174:177], v[206:209], v[90:93]
	v_mfma_f32_16x16x32_bf16 v[82:85], v[178:181], v[202:205], v[82:85]
	v_mfma_f32_16x16x32_bf16 v[82:85], v[182:185], v[206:209], v[82:85]
	v_mfma_f32_16x16x32_bf16 v[74:77], v[170:173], v[210:213], v[74:77]
	v_mfma_f32_16x16x32_bf16 v[74:77], v[174:177], v[214:217], v[74:77]
	v_mfma_f32_16x16x32_bf16 v[66:69], v[178:181], v[210:213], v[66:69]
	v_mfma_f32_16x16x32_bf16 v[66:69], v[182:185], v[214:217], v[66:69]
	s_setprio 0
	s_barrier
	s_add_i32 s0, s44, s35
	v_lshl_add_u64 v[218:219], s[2:3], 0, v[134:135]
	s_mov_b32 m0, s0
	ds_read_b128 v[186:189], v168 offset:16384
	ds_read_b128 v[190:193], v168 offset:17408
	ds_read_b128 v[194:197], v168 offset:18432
	ds_read_b128 v[198:201], v168 offset:19456
	ds_read_b128 v[202:205], v168 offset:20480
	ds_read_b128 v[206:209], v168 offset:21504
	ds_read_b128 v[210:213], v168 offset:22528
	ds_read_b128 v[214:217], v168 offset:23552
	global_load_lds_dwordx4 v[218:219], off
	s_add_i32 m0, s0, 0x2000
	s_add_u32 s0, s2, 0x40000
	v_lshl_add_u64 v[220:221], s[2:3], 0, v[130:131]
	s_addc_u32 s1, s3, 0
	s_add_i32 s54, s45, s35
	global_load_lds_dwordx4 v[220:221], off
	v_lshl_add_u64 v[222:223], s[0:1], 0, v[134:135]
	s_mov_b32 m0, s54
	v_lshl_add_u64 v[224:225], s[30:31], 0, v[132:133]
	global_load_lds_dwordx4 v[222:223], off
	v_lshl_add_u64 v[222:223], s[0:1], 0, v[130:131]
	s_add_i32 m0, s54, 0x2000
	s_nop 0
	global_load_lds_dwordx4 v[222:223], off
	v_lshl_add_u64 v[222:223], s[30:31], 0, v[136:137]
	s_mov_b32 m0, s27
	s_nop 0
	global_load_lds_dwordx4 v[222:223], off
	s_mov_b32 m0, s38
	s_nop 0
	global_load_lds_dwordx4 v[224:225], off
	s_waitcnt vmcnt(8)
	s_waitcnt lgkmcnt(0)
	s_barrier
	s_setprio 1
	v_mfma_f32_16x16x32_bf16 v[62:65], v[148:151], v[186:189], v[62:65]
	v_mfma_f32_16x16x32_bf16 v[62:65], v[152:155], v[190:193], v[62:65]
	v_mfma_f32_16x16x32_bf16 v[54:57], v[156:159], v[186:189], v[54:57]
	v_mfma_f32_16x16x32_bf16 v[54:57], v[160:163], v[190:193], v[54:57]
	v_mfma_f32_16x16x32_bf16 v[46:49], v[148:151], v[194:197], v[46:49]
	v_mfma_f32_16x16x32_bf16 v[46:49], v[152:155], v[198:201], v[46:49]
	v_mfma_f32_16x16x32_bf16 v[38:41], v[156:159], v[194:197], v[38:41]
	v_mfma_f32_16x16x32_bf16 v[38:41], v[160:163], v[198:201], v[38:41]
	v_mfma_f32_16x16x32_bf16 v[30:33], v[148:151], v[202:205], v[30:33]
	v_mfma_f32_16x16x32_bf16 v[30:33], v[152:155], v[206:209], v[30:33]
	v_mfma_f32_16x16x32_bf16 v[22:25], v[156:159], v[202:205], v[22:25]
	v_mfma_f32_16x16x32_bf16 v[22:25], v[160:163], v[206:209], v[22:25]
	v_mfma_f32_16x16x32_bf16 v[14:17], v[148:151], v[210:213], v[14:17]
	v_mfma_f32_16x16x32_bf16 v[14:17], v[152:155], v[214:217], v[14:17]
	v_mfma_f32_16x16x32_bf16 v[6:9], v[156:159], v[210:213], v[6:9]
	v_mfma_f32_16x16x32_bf16 v[6:9], v[160:163], v[214:217], v[6:9]
	s_setprio 0
	s_setprio 1
	v_mfma_f32_16x16x32_bf16 v[58:61], v[170:173], v[186:189], v[58:61]
	v_mfma_f32_16x16x32_bf16 v[58:61], v[174:177], v[190:193], v[58:61]
	v_mfma_f32_16x16x32_bf16 v[50:53], v[178:181], v[186:189], v[50:53]
	v_mfma_f32_16x16x32_bf16 v[50:53], v[182:185], v[190:193], v[50:53]
	v_mfma_f32_16x16x32_bf16 v[42:45], v[170:173], v[194:197], v[42:45]
	v_mfma_f32_16x16x32_bf16 v[42:45], v[174:177], v[198:201], v[42:45]
	v_mfma_f32_16x16x32_bf16 v[34:37], v[178:181], v[194:197], v[34:37]
	v_mfma_f32_16x16x32_bf16 v[34:37], v[182:185], v[198:201], v[34:37]
	v_mfma_f32_16x16x32_bf16 v[26:29], v[170:173], v[202:205], v[26:29]
	v_mfma_f32_16x16x32_bf16 v[26:29], v[174:177], v[206:209], v[26:29]
	v_mfma_f32_16x16x32_bf16 v[18:21], v[178:181], v[202:205], v[18:21]
	v_mfma_f32_16x16x32_bf16 v[18:21], v[182:185], v[206:209], v[18:21]
	v_mfma_f32_16x16x32_bf16 v[10:13], v[170:173], v[210:213], v[10:13]
	v_mfma_f32_16x16x32_bf16 v[10:13], v[174:177], v[214:217], v[10:13]
	v_mfma_f32_16x16x32_bf16 v[2:5], v[178:181], v[210:213], v[2:5]
	v_mfma_f32_16x16x32_bf16 v[2:5], v[182:185], v[214:217], v[2:5]
	s_setprio 0
	s_barrier
	s_add_i32 s54, 0, 0x18000
	s_add_i32 s55, 0, 0x1c000
	v_add_u32_e32 v160, s54, v165
	v_add_u32_e32 v182, s55, v165
	ds_read_b128 v[148:151], v160
	ds_read_b128 v[152:155], v160 offset:1024
	ds_read_b128 v[156:159], v160 offset:2048
	ds_read_b128 v[160:163], v160 offset:3072
	ds_read_b128 v[170:173], v182
	ds_read_b128 v[174:177], v182 offset:1024
	ds_read_b128 v[178:181], v182 offset:2048
	ds_read_b128 v[182:185], v182 offset:3072
	s_add_u32 s0, s30, 0x40000
	s_addc_u32 s1, s31, 0
	s_mov_b32 m0, s39
	v_lshl_add_u64 v[226:227], s[0:1], 0, v[136:137]
	ds_read_b128 v[186:189], v168 offset:32768
	ds_read_b128 v[190:193], v168 offset:33792
	ds_read_b128 v[194:197], v168 offset:34816
	ds_read_b128 v[198:201], v168 offset:35840
	ds_read_b128 v[202:205], v168 offset:36864
	ds_read_b128 v[206:209], v168 offset:37888
	ds_read_b128 v[210:213], v168 offset:38912
	ds_read_b128 v[214:217], v168 offset:39936
	global_load_lds_dwordx4 v[226:227], off
	v_lshl_add_u64 v[226:227], s[0:1], 0, v[132:133]
	s_mov_b32 m0, s40
	s_nop 0
	global_load_lds_dwordx4 v[226:227], off
	s_waitcnt vmcnt(8)
	s_waitcnt lgkmcnt(0)
	s_barrier
	s_setprio 1
	v_mfma_f32_16x16x32_bf16 v[126:129], v[148:151], v[186:189], v[126:129]
	v_mfma_f32_16x16x32_bf16 v[126:129], v[152:155], v[190:193], v[126:129]
	v_mfma_f32_16x16x32_bf16 v[118:121], v[156:159], v[186:189], v[118:121]
	v_mfma_f32_16x16x32_bf16 v[118:121], v[160:163], v[190:193], v[118:121]
	v_mfma_f32_16x16x32_bf16 v[110:113], v[148:151], v[194:197], v[110:113]
	v_mfma_f32_16x16x32_bf16 v[110:113], v[152:155], v[198:201], v[110:113]
	v_mfma_f32_16x16x32_bf16 v[102:105], v[156:159], v[194:197], v[102:105]
	v_mfma_f32_16x16x32_bf16 v[102:105], v[160:163], v[198:201], v[102:105]
	v_mfma_f32_16x16x32_bf16 v[94:97], v[148:151], v[202:205], v[94:97]
	v_mfma_f32_16x16x32_bf16 v[94:97], v[152:155], v[206:209], v[94:97]
	v_mfma_f32_16x16x32_bf16 v[86:89], v[156:159], v[202:205], v[86:89]
	v_mfma_f32_16x16x32_bf16 v[86:89], v[160:163], v[206:209], v[86:89]
	v_mfma_f32_16x16x32_bf16 v[78:81], v[148:151], v[210:213], v[78:81]
	v_mfma_f32_16x16x32_bf16 v[78:81], v[152:155], v[214:217], v[78:81]
	v_mfma_f32_16x16x32_bf16 v[70:73], v[156:159], v[210:213], v[70:73]
	v_mfma_f32_16x16x32_bf16 v[70:73], v[160:163], v[214:217], v[70:73]
	s_setprio 0
	s_setprio 1
	v_mfma_f32_16x16x32_bf16 v[122:125], v[170:173], v[186:189], v[122:125]
	v_mfma_f32_16x16x32_bf16 v[122:125], v[174:177], v[190:193], v[122:125]
	v_mfma_f32_16x16x32_bf16 v[114:117], v[178:181], v[186:189], v[114:117]
	v_mfma_f32_16x16x32_bf16 v[114:117], v[182:185], v[190:193], v[114:117]
	v_mfma_f32_16x16x32_bf16 v[106:109], v[170:173], v[194:197], v[106:109]
	v_mfma_f32_16x16x32_bf16 v[106:109], v[174:177], v[198:201], v[106:109]
	v_mfma_f32_16x16x32_bf16 v[98:101], v[178:181], v[194:197], v[98:101]
	v_mfma_f32_16x16x32_bf16 v[98:101], v[182:185], v[198:201], v[98:101]
	v_mfma_f32_16x16x32_bf16 v[90:93], v[170:173], v[202:205], v[90:93]
	v_mfma_f32_16x16x32_bf16 v[90:93], v[174:177], v[206:209], v[90:93]
	v_mfma_f32_16x16x32_bf16 v[82:85], v[178:181], v[202:205], v[82:85]
	v_mfma_f32_16x16x32_bf16 v[82:85], v[182:185], v[206:209], v[82:85]
	v_mfma_f32_16x16x32_bf16 v[74:77], v[170:173], v[210:213], v[74:77]
	v_mfma_f32_16x16x32_bf16 v[74:77], v[174:177], v[214:217], v[74:77]
	v_mfma_f32_16x16x32_bf16 v[66:69], v[178:181], v[210:213], v[66:69]
	v_mfma_f32_16x16x32_bf16 v[66:69], v[182:185], v[214:217], v[66:69]
	s_setprio 0
	s_barrier
	s_add_i32 s0, s54, s35
	v_lshl_add_u64 v[218:219], v[218:219], 0, s[14:15]
	s_mov_b32 m0, s0
	ds_read_b128 v[186:189], v168 offset:49152
	ds_read_b128 v[190:193], v168 offset:50176
	ds_read_b128 v[194:197], v168 offset:51200
	ds_read_b128 v[198:201], v168 offset:52224
	ds_read_b128 v[202:205], v168 offset:53248
	ds_read_b128 v[206:209], v168 offset:54272
	ds_read_b128 v[210:213], v168 offset:55296
	ds_read_b128 v[214:217], v168 offset:56320
	global_load_lds_dwordx4 v[218:219], off
	s_add_i32 m0, s0, 0x2000
	s_add_u32 s0, s2, 0x40080
	v_lshl_add_u64 v[218:219], v[220:221], 0, s[14:15]
	s_addc_u32 s1, s3, 0
	s_add_i32 s2, s55, s35
	global_load_lds_dwordx4 v[218:219], off
	v_lshl_add_u64 v[218:219], s[0:1], 0, v[134:135]
	s_mov_b32 m0, s2
	s_nop 0
	global_load_lds_dwordx4 v[218:219], off
	v_lshl_add_u64 v[218:219], s[0:1], 0, v[130:131]
	s_add_i32 m0, s2, 0x2000
	s_nop 0
	global_load_lds_dwordx4 v[218:219], off
	v_lshl_add_u64 v[218:219], v[222:223], 0, s[14:15]
	s_mov_b32 m0, s41
	s_nop 0
	global_load_lds_dwordx4 v[218:219], off
	v_lshl_add_u64 v[218:219], v[224:225], 0, s[14:15]
	s_mov_b32 m0, s42
	s_nop 0
	global_load_lds_dwordx4 v[218:219], off
	s_waitcnt vmcnt(8)
	s_waitcnt lgkmcnt(0)
	s_barrier
	s_setprio 1
	v_mfma_f32_16x16x32_bf16 v[62:65], v[148:151], v[186:189], v[62:65]
	v_mfma_f32_16x16x32_bf16 v[62:65], v[152:155], v[190:193], v[62:65]
	v_mfma_f32_16x16x32_bf16 v[54:57], v[156:159], v[186:189], v[54:57]
	v_mfma_f32_16x16x32_bf16 v[54:57], v[160:163], v[190:193], v[54:57]
	v_mfma_f32_16x16x32_bf16 v[46:49], v[148:151], v[194:197], v[46:49]
	v_mfma_f32_16x16x32_bf16 v[46:49], v[152:155], v[198:201], v[46:49]
	v_mfma_f32_16x16x32_bf16 v[38:41], v[156:159], v[194:197], v[38:41]
	v_mfma_f32_16x16x32_bf16 v[38:41], v[160:163], v[198:201], v[38:41]
	v_mfma_f32_16x16x32_bf16 v[30:33], v[148:151], v[202:205], v[30:33]
	v_mfma_f32_16x16x32_bf16 v[30:33], v[152:155], v[206:209], v[30:33]
	v_mfma_f32_16x16x32_bf16 v[22:25], v[156:159], v[202:205], v[22:25]
	v_mfma_f32_16x16x32_bf16 v[22:25], v[160:163], v[206:209], v[22:25]
	v_mfma_f32_16x16x32_bf16 v[14:17], v[148:151], v[210:213], v[14:17]
	v_mfma_f32_16x16x32_bf16 v[14:17], v[152:155], v[214:217], v[14:17]
	v_mfma_f32_16x16x32_bf16 v[6:9], v[156:159], v[210:213], v[6:9]
	v_mfma_f32_16x16x32_bf16 v[6:9], v[160:163], v[214:217], v[6:9]
	s_setprio 0
	s_setprio 1
	v_mfma_f32_16x16x32_bf16 v[58:61], v[170:173], v[186:189], v[58:61]
	v_mfma_f32_16x16x32_bf16 v[58:61], v[174:177], v[190:193], v[58:61]
	v_mfma_f32_16x16x32_bf16 v[50:53], v[178:181], v[186:189], v[50:53]
	v_mfma_f32_16x16x32_bf16 v[50:53], v[182:185], v[190:193], v[50:53]
	v_mfma_f32_16x16x32_bf16 v[42:45], v[170:173], v[194:197], v[42:45]
	v_mfma_f32_16x16x32_bf16 v[42:45], v[174:177], v[198:201], v[42:45]
	v_mfma_f32_16x16x32_bf16 v[34:37], v[178:181], v[194:197], v[34:37]
	v_mfma_f32_16x16x32_bf16 v[34:37], v[182:185], v[198:201], v[34:37]
	v_mfma_f32_16x16x32_bf16 v[26:29], v[170:173], v[202:205], v[26:29]
	v_mfma_f32_16x16x32_bf16 v[26:29], v[174:177], v[206:209], v[26:29]
	v_mfma_f32_16x16x32_bf16 v[18:21], v[178:181], v[202:205], v[18:21]
	v_mfma_f32_16x16x32_bf16 v[18:21], v[182:185], v[206:209], v[18:21]
	v_mfma_f32_16x16x32_bf16 v[10:13], v[170:173], v[210:213], v[10:13]
	v_mfma_f32_16x16x32_bf16 v[10:13], v[174:177], v[214:217], v[10:13]
	v_mfma_f32_16x16x32_bf16 v[2:5], v[178:181], v[210:213], v[2:5]
	v_mfma_f32_16x16x32_bf16 v[2:5], v[182:185], v[214:217], v[2:5]
	s_setprio 0
	s_barrier
	s_add_i32 s53, s53, 2
	s_add_u32 s28, s28, 0x100
	s_addc_u32 s29, s29, 0
	s_add_u32 s51, s51, 0x100
	s_addc_u32 s52, s52, 0
	s_cmp_gt_u32 s53, 13
	s_cbranch_scc0 .LBB0_1715
	s_and_b64 vcc, exec, s[16:17]
	s_cbranch_vccz .LBB0_1718
	s_barrier

.LBB0_1840:
	s_add_u32 s30, s30, 0xb0080
	s_addc_u32 s31, s31, 0
	s_add_u32 s53, s2, 0x100
	v_mov_b32_e32 v2, 0
	s_addc_u32 s54, s3, 0
	s_mov_b32 s55, -2
	s_waitcnt lgkmcnt(0)
	v_mov_b32_e32 v3, v2
	v_mov_b32_e32 v4, v2
	v_mov_b32_e32 v5, v2
	v_mov_b32_e32 v6, v2
	v_mov_b32_e32 v7, v2
	v_mov_b32_e32 v8, v2
	v_mov_b32_e32 v9, v2
	v_mov_b32_e32 v18, v2
	v_mov_b32_e32 v19, v2
	v_mov_b32_e32 v20, v2
	v_mov_b32_e32 v21, v2
	v_mov_b32_e32 v22, v2
	v_mov_b32_e32 v23, v2
	v_mov_b32_e32 v24, v2
	v_mov_b32_e32 v25, v2
	v_mov_b32_e32 v34, v2
	v_mov_b32_e32 v35, v2
	v_mov_b32_e32 v36, v2
	v_mov_b32_e32 v37, v2
	v_mov_b32_e32 v38, v2
	v_mov_b32_e32 v39, v2
	v_mov_b32_e32 v40, v2
	v_mov_b32_e32 v41, v2
	v_mov_b32_e32 v50, v2
	v_mov_b32_e32 v51, v2
	v_mov_b32_e32 v52, v2
	v_mov_b32_e32 v53, v2
	v_mov_b32_e32 v54, v2
	v_mov_b32_e32 v55, v2
	v_mov_b32_e32 v56, v2
	v_mov_b32_e32 v57, v2
	v_mov_b32_e32 v10, v2
	v_mov_b32_e32 v11, v2
	v_mov_b32_e32 v12, v2
	v_mov_b32_e32 v13, v2
	v_mov_b32_e32 v14, v2
	v_mov_b32_e32 v15, v2
	v_mov_b32_e32 v16, v2
	v_mov_b32_e32 v17, v2
	v_mov_b32_e32 v26, v2
	v_mov_b32_e32 v27, v2
	v_mov_b32_e32 v28, v2
	v_mov_b32_e32 v29, v2
	v_mov_b32_e32 v30, v2
	v_mov_b32_e32 v31, v2
	v_mov_b32_e32 v32, v2
	v_mov_b32_e32 v33, v2
	v_mov_b32_e32 v42, v2
	v_mov_b32_e32 v43, v2
	v_mov_b32_e32 v44, v2
	v_mov_b32_e32 v45, v2
	v_mov_b32_e32 v46, v2
	v_mov_b32_e32 v47, v2
	v_mov_b32_e32 v48, v2
	v_mov_b32_e32 v49, v2
	v_mov_b32_e32 v58, v2
	v_mov_b32_e32 v59, v2
	v_mov_b32_e32 v60, v2
	v_mov_b32_e32 v61, v2
	v_mov_b32_e32 v62, v2
	v_mov_b32_e32 v63, v2
	v_mov_b32_e32 v64, v2
	v_mov_b32_e32 v65, v2
	v_mov_b32_e32 v66, v2
	v_mov_b32_e32 v67, v2
	v_mov_b32_e32 v68, v2
	v_mov_b32_e32 v69, v2
	v_mov_b32_e32 v70, v2
	v_mov_b32_e32 v71, v2
	v_mov_b32_e32 v72, v2
	v_mov_b32_e32 v73, v2
	v_mov_b32_e32 v82, v2
	v_mov_b32_e32 v83, v2
	v_mov_b32_e32 v84, v2
	v_mov_b32_e32 v85, v2
	v_mov_b32_e32 v86, v2
	v_mov_b32_e32 v87, v2
	v_mov_b32_e32 v88, v2
	v_mov_b32_e32 v89, v2
	v_mov_b32_e32 v98, v2
	v_mov_b32_e32 v99, v2
	v_mov_b32_e32 v100, v2
	v_mov_b32_e32 v101, v2
	v_mov_b32_e32 v102, v2
	v_mov_b32_e32 v103, v2
	v_mov_b32_e32 v104, v2
	v_mov_b32_e32 v105, v2
	v_mov_b32_e32 v114, v2
	v_mov_b32_e32 v115, v2
	v_mov_b32_e32 v116, v2
	v_mov_b32_e32 v117, v2
	v_mov_b32_e32 v118, v2
	v_mov_b32_e32 v119, v2
	v_mov_b32_e32 v120, v2
	v_mov_b32_e32 v121, v2
	v_mov_b32_e32 v74, v2
	v_mov_b32_e32 v75, v2
	v_mov_b32_e32 v76, v2
	v_mov_b32_e32 v77, v2
	v_mov_b32_e32 v78, v2
	v_mov_b32_e32 v79, v2
	v_mov_b32_e32 v80, v2
	v_mov_b32_e32 v81, v2
	v_mov_b32_e32 v90, v2
	v_mov_b32_e32 v91, v2
	v_mov_b32_e32 v92, v2
	v_mov_b32_e32 v93, v2
	v_mov_b32_e32 v94, v2
	v_mov_b32_e32 v95, v2
	v_mov_b32_e32 v96, v2
	v_mov_b32_e32 v97, v2
	v_mov_b32_e32 v106, v2
	v_mov_b32_e32 v107, v2
	v_mov_b32_e32 v108, v2
	v_mov_b32_e32 v109, v2
	v_mov_b32_e32 v110, v2
	v_mov_b32_e32 v111, v2
	v_mov_b32_e32 v112, v2
	v_mov_b32_e32 v113, v2
	v_mov_b32_e32 v122, v2
	v_mov_b32_e32 v123, v2
	v_mov_b32_e32 v124, v2
	v_mov_b32_e32 v125, v2
	v_mov_b32_e32 v126, v2
	v_mov_b32_e32 v127, v2
	v_mov_b32_e32 v128, v2
	v_mov_b32_e32 v129, v2
	s_nop 0
	s_nop 0
	s_nop 0
	s_nop 0
	s_nop 0
.LBB0_1841:
	ds_read_b128 v[130:133], v186
	ds_read_b128 v[134:137], v186 offset:1024
	ds_read_b128 v[138:141], v186 offset:2048
	ds_read_b128 v[142:145], v186 offset:3072
	ds_read_b128 v[146:149], v187
	ds_read_b128 v[150:153], v187 offset:1024
	ds_read_b128 v[170:173], v187 offset:2048
	ds_read_b128 v[174:177], v187 offset:3072
	s_add_u32 s0, s30, 0xfff50080
	s_addc_u32 s1, s31, -1
	s_cmp_eq_u32 s55, 40
	s_cselect_b32 s35, s9, s1
	s_cselect_b32 s34, s8, s0
	s_cselect_b32 s3, s29, s54
	s_cselect_b32 s2, s28, s53
	v_lshl_add_u64 v[218:219], s[30:31], 0, v[162:163]
	s_add_i32 m0, s40, 0xc000
	ds_read_b128 v[178:181], v188
	ds_read_b128 v[190:193], v188 offset:1024
	ds_read_b128 v[194:197], v188 offset:2048
	ds_read_b128 v[198:201], v188 offset:3072
	ds_read_b128 v[202:205], v188 offset:4096
	ds_read_b128 v[206:209], v188 offset:5120
	ds_read_b128 v[210:213], v188 offset:6144
	ds_read_b128 v[214:217], v188 offset:7168
	global_load_lds_dwordx4 v[218:219], off
	v_lshl_add_u64 v[218:219], s[30:31], 0, v[164:165]
	s_add_i32 m0, s40, 0xe000
	s_nop 0
	global_load_lds_dwordx4 v[218:219], off
	s_waitcnt vmcnt(8)
	s_waitcnt lgkmcnt(0)
	s_barrier
	s_setprio 1
	v_mfma_f32_16x16x32_bf16 v[126:129], v[130:133], v[178:181], v[126:129]
	v_mfma_f32_16x16x32_bf16 v[126:129], v[134:137], v[190:193], v[126:129]
	v_mfma_f32_16x16x32_bf16 v[122:125], v[138:141], v[178:181], v[122:125]
	v_mfma_f32_16x16x32_bf16 v[122:125], v[142:145], v[190:193], v[122:125]
	v_mfma_f32_16x16x32_bf16 v[110:113], v[130:133], v[194:197], v[110:113]
	v_mfma_f32_16x16x32_bf16 v[110:113], v[134:137], v[198:201], v[110:113]
	v_mfma_f32_16x16x32_bf16 v[106:109], v[138:141], v[194:197], v[106:109]
	v_mfma_f32_16x16x32_bf16 v[106:109], v[142:145], v[198:201], v[106:109]
	v_mfma_f32_16x16x32_bf16 v[94:97], v[130:133], v[202:205], v[94:97]
	v_mfma_f32_16x16x32_bf16 v[94:97], v[134:137], v[206:209], v[94:97]
	v_mfma_f32_16x16x32_bf16 v[90:93], v[138:141], v[202:205], v[90:93]
	v_mfma_f32_16x16x32_bf16 v[90:93], v[142:145], v[206:209], v[90:93]
	v_mfma_f32_16x16x32_bf16 v[78:81], v[130:133], v[210:213], v[78:81]
	v_mfma_f32_16x16x32_bf16 v[78:81], v[134:137], v[214:217], v[78:81]
	v_mfma_f32_16x16x32_bf16 v[74:77], v[138:141], v[210:213], v[74:77]
	v_mfma_f32_16x16x32_bf16 v[74:77], v[142:145], v[214:217], v[74:77]
	s_setprio 0
	s_setprio 1
	v_mfma_f32_16x16x32_bf16 v[118:121], v[146:149], v[178:181], v[118:121]
	v_mfma_f32_16x16x32_bf16 v[118:121], v[150:153], v[190:193], v[118:121]
	v_mfma_f32_16x16x32_bf16 v[114:117], v[170:173], v[178:181], v[114:117]
	v_mfma_f32_16x16x32_bf16 v[114:117], v[174:177], v[190:193], v[114:117]
	v_mfma_f32_16x16x32_bf16 v[102:105], v[146:149], v[194:197], v[102:105]
	v_mfma_f32_16x16x32_bf16 v[102:105], v[150:153], v[198:201], v[102:105]
	v_mfma_f32_16x16x32_bf16 v[98:101], v[170:173], v[194:197], v[98:101]
	v_mfma_f32_16x16x32_bf16 v[98:101], v[174:177], v[198:201], v[98:101]
	v_mfma_f32_16x16x32_bf16 v[86:89], v[146:149], v[202:205], v[86:89]
	v_mfma_f32_16x16x32_bf16 v[86:89], v[150:153], v[206:209], v[86:89]
	v_mfma_f32_16x16x32_bf16 v[82:85], v[170:173], v[202:205], v[82:85]
	v_mfma_f32_16x16x32_bf16 v[82:85], v[174:177], v[206:209], v[82:85]
	v_mfma_f32_16x16x32_bf16 v[70:73], v[146:149], v[210:213], v[70:73]
	v_mfma_f32_16x16x32_bf16 v[70:73], v[150:153], v[214:217], v[70:73]
	v_mfma_f32_16x16x32_bf16 v[66:69], v[170:173], v[210:213], v[66:69]
	v_mfma_f32_16x16x32_bf16 v[66:69], v[174:177], v[214:217], v[66:69]
	s_setprio 0
	s_barrier
	s_add_i32 s0, s49, s39
	v_lshl_add_u64 v[218:219], s[2:3], 0, v[156:157]
	s_mov_b32 m0, s0
	ds_read_b128 v[178:181], v188 offset:16384
	ds_read_b128 v[190:193], v188 offset:17408
	ds_read_b128 v[194:197], v188 offset:18432
	ds_read_b128 v[198:201], v188 offset:19456
	ds_read_b128 v[202:205], v188 offset:20480
	ds_read_b128 v[206:209], v188 offset:21504
	ds_read_b128 v[210:213], v188 offset:22528
	ds_read_b128 v[214:217], v188 offset:23552
	global_load_lds_dwordx4 v[218:219], off
	s_add_i32 m0, s0, 0x2000
	s_add_u32 s0, s2, 0xb0000
	v_lshl_add_u64 v[220:221], s[2:3], 0, v[160:161]
	s_addc_u32 s1, s3, 0
	s_add_i32 s56, s50, s39
	global_load_lds_dwordx4 v[220:221], off
	v_lshl_add_u64 v[222:223], s[0:1], 0, v[156:157]
	s_mov_b32 m0, s56
	v_lshl_add_u64 v[224:225], s[34:35], 0, v[158:159]
	global_load_lds_dwordx4 v[222:223], off
	v_lshl_add_u64 v[222:223], s[0:1], 0, v[160:161]
	s_add_i32 m0, s56, 0x2000
	s_nop 0
	global_load_lds_dwordx4 v[222:223], off
	v_lshl_add_u64 v[222:223], s[34:35], 0, v[154:155]
	s_mov_b32 m0, s40
	s_nop 0
	global_load_lds_dwordx4 v[222:223], off
	s_mov_b32 m0, s41
	s_nop 0
	global_load_lds_dwordx4 v[224:225], off
	s_waitcnt vmcnt(8)
	s_waitcnt lgkmcnt(0)
	s_barrier
	s_setprio 1
	v_mfma_f32_16x16x32_bf16 v[62:65], v[130:133], v[178:181], v[62:65]
	v_mfma_f32_16x16x32_bf16 v[62:65], v[134:137], v[190:193], v[62:65]
	v_mfma_f32_16x16x32_bf16 v[58:61], v[138:141], v[178:181], v[58:61]
	v_mfma_f32_16x16x32_bf16 v[58:61], v[142:145], v[190:193], v[58:61]
	v_mfma_f32_16x16x32_bf16 v[46:49], v[130:133], v[194:197], v[46:49]
	v_mfma_f32_16x16x32_bf16 v[46:49], v[134:137], v[198:201], v[46:49]
	v_mfma_f32_16x16x32_bf16 v[42:45], v[138:141], v[194:197], v[42:45]
	v_mfma_f32_16x16x32_bf16 v[42:45], v[142:145], v[198:201], v[42:45]
	v_mfma_f32_16x16x32_bf16 v[30:33], v[130:133], v[202:205], v[30:33]
	v_mfma_f32_16x16x32_bf16 v[30:33], v[134:137], v[206:209], v[30:33]
	v_mfma_f32_16x16x32_bf16 v[26:29], v[138:141], v[202:205], v[26:29]
	v_mfma_f32_16x16x32_bf16 v[26:29], v[142:145], v[206:209], v[26:29]
	v_mfma_f32_16x16x32_bf16 v[14:17], v[130:133], v[210:213], v[14:17]
	v_mfma_f32_16x16x32_bf16 v[14:17], v[134:137], v[214:217], v[14:17]
	v_mfma_f32_16x16x32_bf16 v[10:13], v[138:141], v[210:213], v[10:13]
	v_mfma_f32_16x16x32_bf16 v[10:13], v[142:145], v[214:217], v[10:13]
	s_setprio 0
	s_setprio 1
	v_mfma_f32_16x16x32_bf16 v[54:57], v[146:149], v[178:181], v[54:57]
	v_mfma_f32_16x16x32_bf16 v[54:57], v[150:153], v[190:193], v[54:57]
	v_mfma_f32_16x16x32_bf16 v[50:53], v[170:173], v[178:181], v[50:53]
	v_mfma_f32_16x16x32_bf16 v[50:53], v[174:177], v[190:193], v[50:53]
	v_mfma_f32_16x16x32_bf16 v[38:41], v[146:149], v[194:197], v[38:41]
	v_mfma_f32_16x16x32_bf16 v[38:41], v[150:153], v[198:201], v[38:41]
	v_mfma_f32_16x16x32_bf16 v[34:37], v[170:173], v[194:197], v[34:37]
	v_mfma_f32_16x16x32_bf16 v[34:37], v[174:177], v[198:201], v[34:37]
	v_mfma_f32_16x16x32_bf16 v[22:25], v[146:149], v[202:205], v[22:25]
	v_mfma_f32_16x16x32_bf16 v[22:25], v[150:153], v[206:209], v[22:25]
	v_mfma_f32_16x16x32_bf16 v[18:21], v[170:173], v[202:205], v[18:21]
	v_mfma_f32_16x16x32_bf16 v[18:21], v[174:177], v[206:209], v[18:21]
	v_mfma_f32_16x16x32_bf16 v[6:9], v[146:149], v[210:213], v[6:9]
	v_mfma_f32_16x16x32_bf16 v[6:9], v[150:153], v[214:217], v[6:9]
	v_mfma_f32_16x16x32_bf16 v[2:5], v[170:173], v[210:213], v[2:5]
	v_mfma_f32_16x16x32_bf16 v[2:5], v[174:177], v[214:217], v[2:5]
	s_setprio 0
	s_barrier
	s_add_i32 s56, 0, 0x18000
	s_add_i32 s57, 0, 0x1c000
	v_add_u32_e32 v142, s56, v182
	v_add_u32_e32 v174, s57, v182
	ds_read_b128 v[130:133], v142
	ds_read_b128 v[134:137], v142 offset:1024
	ds_read_b128 v[138:141], v142 offset:2048
	ds_read_b128 v[142:145], v142 offset:3072
	ds_read_b128 v[146:149], v174
	ds_read_b128 v[150:153], v174 offset:1024
	ds_read_b128 v[170:173], v174 offset:2048
	ds_read_b128 v[174:177], v174 offset:3072
	s_add_u32 s0, s34, 0xb0000
	s_addc_u32 s1, s35, 0
	s_mov_b32 m0, s42
	v_lshl_add_u64 v[226:227], s[0:1], 0, v[154:155]
	ds_read_b128 v[178:181], v188 offset:32768
	ds_read_b128 v[190:193], v188 offset:33792
	ds_read_b128 v[194:197], v188 offset:34816
	ds_read_b128 v[198:201], v188 offset:35840
	ds_read_b128 v[202:205], v188 offset:36864
	ds_read_b128 v[206:209], v188 offset:37888
	ds_read_b128 v[210:213], v188 offset:38912
	ds_read_b128 v[214:217], v188 offset:39936
	global_load_lds_dwordx4 v[226:227], off
	v_lshl_add_u64 v[226:227], s[0:1], 0, v[158:159]
	s_mov_b32 m0, s43
	s_nop 0
	global_load_lds_dwordx4 v[226:227], off
	s_waitcnt vmcnt(8)
	s_waitcnt lgkmcnt(0)
	s_barrier
	s_setprio 1
	v_mfma_f32_16x16x32_bf16 v[126:129], v[130:133], v[178:181], v[126:129]
	v_mfma_f32_16x16x32_bf16 v[126:129], v[134:137], v[190:193], v[126:129]
	v_mfma_f32_16x16x32_bf16 v[122:125], v[138:141], v[178:181], v[122:125]
	v_mfma_f32_16x16x32_bf16 v[122:125], v[142:145], v[190:193], v[122:125]
	v_mfma_f32_16x16x32_bf16 v[110:113], v[130:133], v[194:197], v[110:113]
	v_mfma_f32_16x16x32_bf16 v[110:113], v[134:137], v[198:201], v[110:113]
	v_mfma_f32_16x16x32_bf16 v[106:109], v[138:141], v[194:197], v[106:109]
	v_mfma_f32_16x16x32_bf16 v[106:109], v[142:145], v[198:201], v[106:109]
	v_mfma_f32_16x16x32_bf16 v[94:97], v[130:133], v[202:205], v[94:97]
	v_mfma_f32_16x16x32_bf16 v[94:97], v[134:137], v[206:209], v[94:97]
	v_mfma_f32_16x16x32_bf16 v[90:93], v[138:141], v[202:205], v[90:93]
	v_mfma_f32_16x16x32_bf16 v[90:93], v[142:145], v[206:209], v[90:93]
	v_mfma_f32_16x16x32_bf16 v[78:81], v[130:133], v[210:213], v[78:81]
	v_mfma_f32_16x16x32_bf16 v[78:81], v[134:137], v[214:217], v[78:81]
	v_mfma_f32_16x16x32_bf16 v[74:77], v[138:141], v[210:213], v[74:77]
	v_mfma_f32_16x16x32_bf16 v[74:77], v[142:145], v[214:217], v[74:77]
	s_setprio 0
	s_setprio 1
	v_mfma_f32_16x16x32_bf16 v[118:121], v[146:149], v[178:181], v[118:121]
	v_mfma_f32_16x16x32_bf16 v[118:121], v[150:153], v[190:193], v[118:121]
	v_mfma_f32_16x16x32_bf16 v[114:117], v[170:173], v[178:181], v[114:117]
	v_mfma_f32_16x16x32_bf16 v[114:117], v[174:177], v[190:193], v[114:117]
	v_mfma_f32_16x16x32_bf16 v[102:105], v[146:149], v[194:197], v[102:105]
	v_mfma_f32_16x16x32_bf16 v[102:105], v[150:153], v[198:201], v[102:105]
	v_mfma_f32_16x16x32_bf16 v[98:101], v[170:173], v[194:197], v[98:101]
	v_mfma_f32_16x16x32_bf16 v[98:101], v[174:177], v[198:201], v[98:101]
	v_mfma_f32_16x16x32_bf16 v[86:89], v[146:149], v[202:205], v[86:89]
	v_mfma_f32_16x16x32_bf16 v[86:89], v[150:153], v[206:209], v[86:89]
	v_mfma_f32_16x16x32_bf16 v[82:85], v[170:173], v[202:205], v[82:85]
	v_mfma_f32_16x16x32_bf16 v[82:85], v[174:177], v[206:209], v[82:85]
	v_mfma_f32_16x16x32_bf16 v[70:73], v[146:149], v[210:213], v[70:73]
	v_mfma_f32_16x16x32_bf16 v[70:73], v[150:153], v[214:217], v[70:73]
	v_mfma_f32_16x16x32_bf16 v[66:69], v[170:173], v[210:213], v[66:69]
	v_mfma_f32_16x16x32_bf16 v[66:69], v[174:177], v[214:217], v[66:69]
	s_setprio 0
	s_barrier
	s_add_i32 s0, s56, s39
	v_lshl_add_u64 v[218:219], v[218:219], 0, s[16:17]
	s_mov_b32 m0, s0
	ds_read_b128 v[178:181], v188 offset:49152
	ds_read_b128 v[190:193], v188 offset:50176
	ds_read_b128 v[194:197], v188 offset:51200
	ds_read_b128 v[198:201], v188 offset:52224
	ds_read_b128 v[202:205], v188 offset:53248
	ds_read_b128 v[206:209], v188 offset:54272
	ds_read_b128 v[210:213], v188 offset:55296
	ds_read_b128 v[214:217], v188 offset:56320
	global_load_lds_dwordx4 v[218:219], off
	s_add_i32 m0, s0, 0x2000
	s_add_u32 s0, s2, 0xb0080
	v_lshl_add_u64 v[218:219], v[220:221], 0, s[16:17]
	s_addc_u32 s1, s3, 0
	s_add_i32 s2, s57, s39
	global_load_lds_dwordx4 v[218:219], off
	v_lshl_add_u64 v[218:219], s[0:1], 0, v[156:157]
	s_mov_b32 m0, s2
	s_nop 0
	global_load_lds_dwordx4 v[218:219], off
	v_lshl_add_u64 v[218:219], s[0:1], 0, v[160:161]
	s_add_i32 m0, s2, 0x2000
	s_nop 0
	global_load_lds_dwordx4 v[218:219], off
	v_lshl_add_u64 v[218:219], v[222:223], 0, s[16:17]
	s_mov_b32 m0, s45
	s_nop 0
	global_load_lds_dwordx4 v[218:219], off
	v_lshl_add_u64 v[218:219], v[224:225], 0, s[16:17]
	s_mov_b32 m0, s46
	s_nop 0
	global_load_lds_dwordx4 v[218:219], off
	s_waitcnt vmcnt(8)
	s_waitcnt lgkmcnt(0)
	s_barrier
	s_setprio 1
	v_mfma_f32_16x16x32_bf16 v[62:65], v[130:133], v[178:181], v[62:65]
	v_mfma_f32_16x16x32_bf16 v[62:65], v[134:137], v[190:193], v[62:65]
	v_mfma_f32_16x16x32_bf16 v[58:61], v[138:141], v[178:181], v[58:61]
	v_mfma_f32_16x16x32_bf16 v[58:61], v[142:145], v[190:193], v[58:61]
	v_mfma_f32_16x16x32_bf16 v[46:49], v[130:133], v[194:197], v[46:49]
	v_mfma_f32_16x16x32_bf16 v[46:49], v[134:137], v[198:201], v[46:49]
	v_mfma_f32_16x16x32_bf16 v[42:45], v[138:141], v[194:197], v[42:45]
	v_mfma_f32_16x16x32_bf16 v[42:45], v[142:145], v[198:201], v[42:45]
	v_mfma_f32_16x16x32_bf16 v[30:33], v[130:133], v[202:205], v[30:33]
	v_mfma_f32_16x16x32_bf16 v[30:33], v[134:137], v[206:209], v[30:33]
	v_mfma_f32_16x16x32_bf16 v[26:29], v[138:141], v[202:205], v[26:29]
	v_mfma_f32_16x16x32_bf16 v[26:29], v[142:145], v[206:209], v[26:29]
	v_mfma_f32_16x16x32_bf16 v[14:17], v[130:133], v[210:213], v[14:17]
	v_mfma_f32_16x16x32_bf16 v[14:17], v[134:137], v[214:217], v[14:17]
	v_mfma_f32_16x16x32_bf16 v[10:13], v[138:141], v[210:213], v[10:13]
	v_mfma_f32_16x16x32_bf16 v[10:13], v[142:145], v[214:217], v[10:13]
	s_setprio 0
	s_setprio 1
	v_mfma_f32_16x16x32_bf16 v[54:57], v[146:149], v[178:181], v[54:57]
	v_mfma_f32_16x16x32_bf16 v[54:57], v[150:153], v[190:193], v[54:57]
	v_mfma_f32_16x16x32_bf16 v[50:53], v[170:173], v[178:181], v[50:53]
	v_mfma_f32_16x16x32_bf16 v[50:53], v[174:177], v[190:193], v[50:53]
	v_mfma_f32_16x16x32_bf16 v[38:41], v[146:149], v[194:197], v[38:41]
	v_mfma_f32_16x16x32_bf16 v[38:41], v[150:153], v[198:201], v[38:41]
	v_mfma_f32_16x16x32_bf16 v[34:37], v[170:173], v[194:197], v[34:37]
	v_mfma_f32_16x16x32_bf16 v[34:37], v[174:177], v[198:201], v[34:37]
	v_mfma_f32_16x16x32_bf16 v[22:25], v[146:149], v[202:205], v[22:25]
	v_mfma_f32_16x16x32_bf16 v[22:25], v[150:153], v[206:209], v[22:25]
	v_mfma_f32_16x16x32_bf16 v[18:21], v[170:173], v[202:205], v[18:21]
	v_mfma_f32_16x16x32_bf16 v[18:21], v[174:177], v[206:209], v[18:21]
	v_mfma_f32_16x16x32_bf16 v[6:9], v[146:149], v[210:213], v[6:9]
	v_mfma_f32_16x16x32_bf16 v[6:9], v[150:153], v[214:217], v[6:9]
	v_mfma_f32_16x16x32_bf16 v[2:5], v[170:173], v[210:213], v[2:5]
	v_mfma_f32_16x16x32_bf16 v[2:5], v[174:177], v[214:217], v[2:5]
	s_setprio 0
	s_barrier
	s_add_i32 s55, s55, 2
	s_add_u32 s30, s30, 0x100
	s_addc_u32 s31, s31, 0
	s_add_u32 s53, s53, 0x100
	s_addc_u32 s54, s54, 0
	s_cmp_gt_u32 s55, 41
	s_cbranch_scc0 .LBB0_1841
	s_and_b64 vcc, exec, s[18:19]
	s_cbranch_vccz .LBB0_1844
	s_barrier

.LBB0_1937:
	s_and_b32 s99, s45, 1
	s_lshl_b32 s99, s99, 12
	v_readfirstlane_b32 s100, v0
	s_and_b32 s100, s100, 0xc0
	s_lshl_b32 s100, s100, 4
	s_add_i32 s99, s99, s100
	s_add_i32 m0, s99, 0x21000
	s_lshl_b32 s99, s26, 12
	s_add_u32 s100, s76, s99
	s_addc_u32 s101, s77, 0
	v_and_b32_e32 v129, 0xff, v0
	v_lshlrev_b32_e32 v129, 4, v129
	global_load_lds_dwordx4 v129, s[100:101]
	s_ashr_i32 s21, s20, 31
	s_lshl_b64 s[0:1], s[20:21], 19
	s_add_u32 s22, s78, s0
	s_addc_u32 s23, s79, s1
	s_and_b64 s[0:1], s[4:5], exec
	s_cselect_b32 s21, s23, s29
	s_cselect_b32 s47, s22, s28
	s_ashr_i32 s19, s18, 31
	s_lshl_b64 s[0:1], s[18:19], 19
	s_add_u32 s24, s34, s0
	s_addc_u32 s25, s35, s1
	s_and_b64 s[0:1], s[4:5], exec
	s_cselect_b32 s19, s25, s3
	s_cselect_b32 s48, s24, s2
	s_add_u32 s28, s28, 0x40080
	s_addc_u32 s29, s29, 0
	s_add_u32 s49, s2, 0x100
	v_mov_b32_e32 v2, 0
	s_addc_u32 s50, s3, 0
	s_mov_b32 s51, -2
	v_mov_b32_e32 v3, v2
	v_mov_b32_e32 v4, v2
	v_mov_b32_e32 v5, v2
	v_mov_b32_e32 v6, v2
	v_mov_b32_e32 v7, v2
	v_mov_b32_e32 v8, v2
	v_mov_b32_e32 v9, v2
	v_mov_b32_e32 v18, v2
	v_mov_b32_e32 v19, v2
	v_mov_b32_e32 v20, v2
	v_mov_b32_e32 v21, v2
	v_mov_b32_e32 v22, v2
	v_mov_b32_e32 v23, v2
	v_mov_b32_e32 v24, v2
	v_mov_b32_e32 v25, v2
	v_mov_b32_e32 v34, v2
	v_mov_b32_e32 v35, v2
	v_mov_b32_e32 v36, v2
	v_mov_b32_e32 v37, v2
	v_mov_b32_e32 v38, v2
	v_mov_b32_e32 v39, v2
	v_mov_b32_e32 v40, v2
	v_mov_b32_e32 v41, v2
	v_mov_b32_e32 v50, v2
	v_mov_b32_e32 v51, v2
	v_mov_b32_e32 v52, v2
	v_mov_b32_e32 v53, v2
	v_mov_b32_e32 v54, v2
	v_mov_b32_e32 v55, v2
	v_mov_b32_e32 v56, v2
	v_mov_b32_e32 v57, v2
	v_mov_b32_e32 v10, v2
	v_mov_b32_e32 v11, v2
	v_mov_b32_e32 v12, v2
	v_mov_b32_e32 v13, v2
	v_mov_b32_e32 v14, v2
	v_mov_b32_e32 v15, v2
	v_mov_b32_e32 v16, v2
	v_mov_b32_e32 v17, v2
	v_mov_b32_e32 v26, v2
	v_mov_b32_e32 v27, v2
	v_mov_b32_e32 v28, v2
	v_mov_b32_e32 v29, v2
	v_mov_b32_e32 v30, v2
	v_mov_b32_e32 v31, v2
	v_mov_b32_e32 v32, v2
	v_mov_b32_e32 v33, v2
	v_mov_b32_e32 v42, v2
	v_mov_b32_e32 v43, v2
	v_mov_b32_e32 v44, v2
	v_mov_b32_e32 v45, v2
	v_mov_b32_e32 v46, v2
	v_mov_b32_e32 v47, v2
	v_mov_b32_e32 v48, v2
	v_mov_b32_e32 v49, v2
	v_mov_b32_e32 v58, v2
	v_mov_b32_e32 v59, v2
	v_mov_b32_e32 v60, v2
	v_mov_b32_e32 v61, v2
	v_mov_b32_e32 v62, v2
	v_mov_b32_e32 v63, v2
	v_mov_b32_e32 v64, v2
	v_mov_b32_e32 v65, v2
	v_mov_b32_e32 v66, v2
	v_mov_b32_e32 v67, v2
	v_mov_b32_e32 v68, v2
	v_mov_b32_e32 v69, v2
	v_mov_b32_e32 v70, v2
	v_mov_b32_e32 v71, v2
	v_mov_b32_e32 v72, v2
	v_mov_b32_e32 v73, v2
	v_mov_b32_e32 v82, v2
	v_mov_b32_e32 v83, v2
	v_mov_b32_e32 v84, v2
	v_mov_b32_e32 v85, v2
	v_mov_b32_e32 v86, v2
	v_mov_b32_e32 v87, v2
	v_mov_b32_e32 v88, v2
	v_mov_b32_e32 v89, v2
	v_mov_b32_e32 v98, v2
	v_mov_b32_e32 v99, v2
	v_mov_b32_e32 v100, v2
	v_mov_b32_e32 v101, v2
	v_mov_b32_e32 v102, v2
	v_mov_b32_e32 v103, v2
	v_mov_b32_e32 v104, v2
	v_mov_b32_e32 v105, v2
	v_mov_b32_e32 v114, v2
	v_mov_b32_e32 v115, v2
	v_mov_b32_e32 v116, v2
	v_mov_b32_e32 v117, v2
	v_mov_b32_e32 v122, v2
	v_mov_b32_e32 v123, v2
	v_mov_b32_e32 v124, v2
	v_mov_b32_e32 v125, v2
	v_mov_b32_e32 v74, v2
	v_mov_b32_e32 v75, v2
	v_mov_b32_e32 v76, v2
	v_mov_b32_e32 v77, v2
	v_mov_b32_e32 v78, v2
	v_mov_b32_e32 v79, v2
	v_mov_b32_e32 v80, v2
	v_mov_b32_e32 v81, v2
	v_mov_b32_e32 v90, v2
	v_mov_b32_e32 v91, v2
	v_mov_b32_e32 v92, v2
	v_mov_b32_e32 v93, v2
	v_mov_b32_e32 v94, v2
	v_mov_b32_e32 v95, v2
	v_mov_b32_e32 v96, v2
	v_mov_b32_e32 v97, v2
	v_mov_b32_e32 v106, v2
	v_mov_b32_e32 v107, v2
	v_mov_b32_e32 v108, v2
	v_mov_b32_e32 v109, v2
	v_mov_b32_e32 v110, v2
	v_mov_b32_e32 v111, v2
	v_mov_b32_e32 v112, v2
	v_mov_b32_e32 v113, v2
	v_mov_b32_e32 v118, v2
	v_mov_b32_e32 v119, v2
	v_mov_b32_e32 v120, v2
	v_mov_b32_e32 v121, v2
	v_mov_b32_e32 v126, v2
	v_mov_b32_e32 v127, v2
	v_mov_b32_e32 v128, v2
	v_mov_b32_e32 v129, v2
	s_nop 0
	s_nop 0
	s_nop 0
	s_nop 0
	s_nop 0
	s_nop 0
	s_nop 0
	s_nop 0
	s_nop 0
	s_nop 0
.LBB0_1938:
	ds_read_b128 v[148:151], v161
	ds_read_b128 v[152:155], v161 offset:1024
	ds_read_b128 v[156:159], v161 offset:2048
	ds_read_b128 v[166:169], v161 offset:3072
	ds_read_b128 v[170:173], v162
	ds_read_b128 v[174:177], v162 offset:1024
	ds_read_b128 v[178:181], v162 offset:2048
	ds_read_b128 v[182:185], v162 offset:3072
	s_add_u32 s0, s28, 0xfffc0080
	s_addc_u32 s1, s29, -1
	s_cmp_eq_u32 s51, 12
	s_cselect_b32 s31, s21, s1
	s_cselect_b32 s30, s47, s0
	s_cselect_b32 s3, s19, s50
	s_cselect_b32 s2, s48, s49
	v_lshl_add_u64 v[218:219], s[28:29], 0, v[140:141]
	s_add_i32 m0, s27, 0xc000
	ds_read_b128 v[186:189], v163
	ds_read_b128 v[190:193], v163 offset:1024
	ds_read_b128 v[194:197], v163 offset:2048
	ds_read_b128 v[198:201], v163 offset:3072
	ds_read_b128 v[202:205], v163 offset:4096
	ds_read_b128 v[206:209], v163 offset:5120
	ds_read_b128 v[210:213], v163 offset:6144
	ds_read_b128 v[214:217], v163 offset:7168
	global_load_lds_dwordx4 v[218:219], off
	v_lshl_add_u64 v[218:219], s[28:29], 0, v[142:143]
	s_add_i32 m0, s27, 0xe000
	s_nop 0
	global_load_lds_dwordx4 v[218:219], off
	s_waitcnt vmcnt(8)
	s_waitcnt lgkmcnt(0)
	s_barrier
	s_setprio 1
	v_mfma_f32_16x16x32_bf16 v[126:129], v[148:151], v[186:189], v[126:129]
	v_mfma_f32_16x16x32_bf16 v[126:129], v[152:155], v[190:193], v[126:129]
	v_mfma_f32_16x16x32_bf16 v[118:121], v[156:159], v[186:189], v[118:121]
	v_mfma_f32_16x16x32_bf16 v[118:121], v[166:169], v[190:193], v[118:121]
	v_mfma_f32_16x16x32_bf16 v[110:113], v[148:151], v[194:197], v[110:113]
	v_mfma_f32_16x16x32_bf16 v[110:113], v[152:155], v[198:201], v[110:113]
	v_mfma_f32_16x16x32_bf16 v[106:109], v[156:159], v[194:197], v[106:109]
	v_mfma_f32_16x16x32_bf16 v[106:109], v[166:169], v[198:201], v[106:109]
	v_mfma_f32_16x16x32_bf16 v[94:97], v[148:151], v[202:205], v[94:97]
	v_mfma_f32_16x16x32_bf16 v[94:97], v[152:155], v[206:209], v[94:97]
	v_mfma_f32_16x16x32_bf16 v[90:93], v[156:159], v[202:205], v[90:93]
	v_mfma_f32_16x16x32_bf16 v[90:93], v[166:169], v[206:209], v[90:93]
	v_mfma_f32_16x16x32_bf16 v[78:81], v[148:151], v[210:213], v[78:81]
	v_mfma_f32_16x16x32_bf16 v[78:81], v[152:155], v[214:217], v[78:81]
	v_mfma_f32_16x16x32_bf16 v[74:77], v[156:159], v[210:213], v[74:77]
	v_mfma_f32_16x16x32_bf16 v[74:77], v[166:169], v[214:217], v[74:77]
	s_setprio 0
	s_setprio 1
	v_mfma_f32_16x16x32_bf16 v[122:125], v[170:173], v[186:189], v[122:125]
	v_mfma_f32_16x16x32_bf16 v[122:125], v[174:177], v[190:193], v[122:125]
	v_mfma_f32_16x16x32_bf16 v[114:117], v[178:181], v[186:189], v[114:117]
	v_mfma_f32_16x16x32_bf16 v[114:117], v[182:185], v[190:193], v[114:117]
	v_mfma_f32_16x16x32_bf16 v[102:105], v[170:173], v[194:197], v[102:105]
	v_mfma_f32_16x16x32_bf16 v[102:105], v[174:177], v[198:201], v[102:105]
	v_mfma_f32_16x16x32_bf16 v[98:101], v[178:181], v[194:197], v[98:101]
	v_mfma_f32_16x16x32_bf16 v[98:101], v[182:185], v[198:201], v[98:101]
	v_mfma_f32_16x16x32_bf16 v[86:89], v[170:173], v[202:205], v[86:89]
	v_mfma_f32_16x16x32_bf16 v[86:89], v[174:177], v[206:209], v[86:89]
	v_mfma_f32_16x16x32_bf16 v[82:85], v[178:181], v[202:205], v[82:85]
	v_mfma_f32_16x16x32_bf16 v[82:85], v[182:185], v[206:209], v[82:85]
	v_mfma_f32_16x16x32_bf16 v[70:73], v[170:173], v[210:213], v[70:73]
	v_mfma_f32_16x16x32_bf16 v[70:73], v[174:177], v[214:217], v[70:73]
	v_mfma_f32_16x16x32_bf16 v[66:69], v[178:181], v[210:213], v[66:69]
	v_mfma_f32_16x16x32_bf16 v[66:69], v[182:185], v[214:217], v[66:69]
	s_setprio 0
	s_barrier
	s_add_i32 s0, s43, s36
	v_lshl_add_u64 v[218:219], s[2:3], 0, v[132:133]
	s_mov_b32 m0, s0
	ds_read_b128 v[186:189], v163 offset:16384
	ds_read_b128 v[190:193], v163 offset:17408
	ds_read_b128 v[194:197], v163 offset:18432
	ds_read_b128 v[198:201], v163 offset:19456
	ds_read_b128 v[202:205], v163 offset:20480
	ds_read_b128 v[206:209], v163 offset:21504
	ds_read_b128 v[210:213], v163 offset:22528
	ds_read_b128 v[214:217], v163 offset:23552
	global_load_lds_dwordx4 v[218:219], off
	s_add_i32 m0, s0, 0x2000
	s_add_u32 s0, s2, 0x40000
	v_lshl_add_u64 v[220:221], s[2:3], 0, v[136:137]
	s_addc_u32 s1, s3, 0
	s_add_i32 s52, s44, s36
	global_load_lds_dwordx4 v[220:221], off
	v_lshl_add_u64 v[222:223], s[0:1], 0, v[132:133]
	s_mov_b32 m0, s52
	v_lshl_add_u64 v[224:225], s[30:31], 0, v[134:135]
	global_load_lds_dwordx4 v[222:223], off
	v_lshl_add_u64 v[222:223], s[0:1], 0, v[136:137]
	s_add_i32 m0, s52, 0x2000
	s_nop 0
	global_load_lds_dwordx4 v[222:223], off
	v_lshl_add_u64 v[222:223], s[30:31], 0, v[130:131]
	s_mov_b32 m0, s27
	s_nop 0
	global_load_lds_dwordx4 v[222:223], off
	s_mov_b32 m0, s37
	s_nop 0
	global_load_lds_dwordx4 v[224:225], off
	s_waitcnt vmcnt(8)
	s_waitcnt lgkmcnt(0)
	s_barrier
	s_setprio 1
	v_mfma_f32_16x16x32_bf16 v[62:65], v[148:151], v[186:189], v[62:65]
	v_mfma_f32_16x16x32_bf16 v[62:65], v[152:155], v[190:193], v[62:65]
	v_mfma_f32_16x16x32_bf16 v[58:61], v[156:159], v[186:189], v[58:61]
	v_mfma_f32_16x16x32_bf16 v[58:61], v[166:169], v[190:193], v[58:61]
	v_mfma_f32_16x16x32_bf16 v[46:49], v[148:151], v[194:197], v[46:49]
	v_mfma_f32_16x16x32_bf16 v[46:49], v[152:155], v[198:201], v[46:49]
	v_mfma_f32_16x16x32_bf16 v[42:45], v[156:159], v[194:197], v[42:45]
	v_mfma_f32_16x16x32_bf16 v[42:45], v[166:169], v[198:201], v[42:45]
	v_mfma_f32_16x16x32_bf16 v[30:33], v[148:151], v[202:205], v[30:33]
	v_mfma_f32_16x16x32_bf16 v[30:33], v[152:155], v[206:209], v[30:33]
	v_mfma_f32_16x16x32_bf16 v[26:29], v[156:159], v[202:205], v[26:29]
	v_mfma_f32_16x16x32_bf16 v[26:29], v[166:169], v[206:209], v[26:29]
	v_mfma_f32_16x16x32_bf16 v[14:17], v[148:151], v[210:213], v[14:17]
	v_mfma_f32_16x16x32_bf16 v[14:17], v[152:155], v[214:217], v[14:17]
	v_mfma_f32_16x16x32_bf16 v[10:13], v[156:159], v[210:213], v[10:13]
	v_mfma_f32_16x16x32_bf16 v[10:13], v[166:169], v[214:217], v[10:13]
	s_setprio 0
	s_setprio 1
	v_mfma_f32_16x16x32_bf16 v[54:57], v[170:173], v[186:189], v[54:57]
	v_mfma_f32_16x16x32_bf16 v[54:57], v[174:177], v[190:193], v[54:57]
	v_mfma_f32_16x16x32_bf16 v[50:53], v[178:181], v[186:189], v[50:53]
	v_mfma_f32_16x16x32_bf16 v[50:53], v[182:185], v[190:193], v[50:53]
	v_mfma_f32_16x16x32_bf16 v[38:41], v[170:173], v[194:197], v[38:41]
	v_mfma_f32_16x16x32_bf16 v[38:41], v[174:177], v[198:201], v[38:41]
	v_mfma_f32_16x16x32_bf16 v[34:37], v[178:181], v[194:197], v[34:37]
	v_mfma_f32_16x16x32_bf16 v[34:37], v[182:185], v[198:201], v[34:37]
	v_mfma_f32_16x16x32_bf16 v[22:25], v[170:173], v[202:205], v[22:25]
	v_mfma_f32_16x16x32_bf16 v[22:25], v[174:177], v[206:209], v[22:25]
	v_mfma_f32_16x16x32_bf16 v[18:21], v[178:181], v[202:205], v[18:21]
	v_mfma_f32_16x16x32_bf16 v[18:21], v[182:185], v[206:209], v[18:21]
	v_mfma_f32_16x16x32_bf16 v[6:9], v[170:173], v[210:213], v[6:9]
	v_mfma_f32_16x16x32_bf16 v[6:9], v[174:177], v[214:217], v[6:9]
	v_mfma_f32_16x16x32_bf16 v[2:5], v[178:181], v[210:213], v[2:5]
	v_mfma_f32_16x16x32_bf16 v[2:5], v[182:185], v[214:217], v[2:5]
	s_setprio 0
	s_barrier
	s_add_i32 s52, 0, 0x18000
	v_add_u32_e32 v165, s52, v160
	s_add_i32 s53, 0, 0x1c000
	ds_read_b128 v[148:151], v165
	ds_read_b128 v[152:155], v165 offset:1024
	ds_read_b128 v[156:159], v165 offset:2048
	ds_read_b128 v[166:169], v165 offset:3072
	v_add_u32_e32 v165, s53, v160
	ds_read_b128 v[170:173], v165
	ds_read_b128 v[174:177], v165 offset:1024
	ds_read_b128 v[178:181], v165 offset:2048
	ds_read_b128 v[182:185], v165 offset:3072
	s_add_u32 s0, s30, 0x40000
	s_addc_u32 s1, s31, 0
	s_mov_b32 m0, s38
	v_lshl_add_u64 v[226:227], s[0:1], 0, v[130:131]
	ds_read_b128 v[186:189], v163 offset:32768
	ds_read_b128 v[190:193], v163 offset:33792
	ds_read_b128 v[194:197], v163 offset:34816
	ds_read_b128 v[198:201], v163 offset:35840
	ds_read_b128 v[202:205], v163 offset:36864
	ds_read_b128 v[206:209], v163 offset:37888
	ds_read_b128 v[210:213], v163 offset:38912
	ds_read_b128 v[214:217], v163 offset:39936
	global_load_lds_dwordx4 v[226:227], off
	v_lshl_add_u64 v[226:227], s[0:1], 0, v[134:135]
	s_mov_b32 m0, s39
	s_nop 0
	global_load_lds_dwordx4 v[226:227], off
	s_waitcnt vmcnt(8)
	s_waitcnt lgkmcnt(0)
	s_barrier
	s_setprio 1
	v_mfma_f32_16x16x32_bf16 v[126:129], v[148:151], v[186:189], v[126:129]
	v_mfma_f32_16x16x32_bf16 v[126:129], v[152:155], v[190:193], v[126:129]
	v_mfma_f32_16x16x32_bf16 v[118:121], v[156:159], v[186:189], v[118:121]
	v_mfma_f32_16x16x32_bf16 v[118:121], v[166:169], v[190:193], v[118:121]
	v_mfma_f32_16x16x32_bf16 v[110:113], v[148:151], v[194:197], v[110:113]
	v_mfma_f32_16x16x32_bf16 v[110:113], v[152:155], v[198:201], v[110:113]
	v_mfma_f32_16x16x32_bf16 v[106:109], v[156:159], v[194:197], v[106:109]
	v_mfma_f32_16x16x32_bf16 v[106:109], v[166:169], v[198:201], v[106:109]
	v_mfma_f32_16x16x32_bf16 v[94:97], v[148:151], v[202:205], v[94:97]
	v_mfma_f32_16x16x32_bf16 v[94:97], v[152:155], v[206:209], v[94:97]
	v_mfma_f32_16x16x32_bf16 v[90:93], v[156:159], v[202:205], v[90:93]
	v_mfma_f32_16x16x32_bf16 v[90:93], v[166:169], v[206:209], v[90:93]
	v_mfma_f32_16x16x32_bf16 v[78:81], v[148:151], v[210:213], v[78:81]
	v_mfma_f32_16x16x32_bf16 v[78:81], v[152:155], v[214:217], v[78:81]
	v_mfma_f32_16x16x32_bf16 v[74:77], v[156:159], v[210:213], v[74:77]
	v_mfma_f32_16x16x32_bf16 v[74:77], v[166:169], v[214:217], v[74:77]
	s_setprio 0
	s_setprio 1
	v_mfma_f32_16x16x32_bf16 v[122:125], v[170:173], v[186:189], v[122:125]
	v_mfma_f32_16x16x32_bf16 v[122:125], v[174:177], v[190:193], v[122:125]
	v_mfma_f32_16x16x32_bf16 v[114:117], v[178:181], v[186:189], v[114:117]
	v_mfma_f32_16x16x32_bf16 v[114:117], v[182:185], v[190:193], v[114:117]
	v_mfma_f32_16x16x32_bf16 v[102:105], v[170:173], v[194:197], v[102:105]
	v_mfma_f32_16x16x32_bf16 v[102:105], v[174:177], v[198:201], v[102:105]
	v_mfma_f32_16x16x32_bf16 v[98:101], v[178:181], v[194:197], v[98:101]
	v_mfma_f32_16x16x32_bf16 v[98:101], v[182:185], v[198:201], v[98:101]
	v_mfma_f32_16x16x32_bf16 v[86:89], v[170:173], v[202:205], v[86:89]
	v_mfma_f32_16x16x32_bf16 v[86:89], v[174:177], v[206:209], v[86:89]
	v_mfma_f32_16x16x32_bf16 v[82:85], v[178:181], v[202:205], v[82:85]
	v_mfma_f32_16x16x32_bf16 v[82:85], v[182:185], v[206:209], v[82:85]
	v_mfma_f32_16x16x32_bf16 v[70:73], v[170:173], v[210:213], v[70:73]
	v_mfma_f32_16x16x32_bf16 v[70:73], v[174:177], v[214:217], v[70:73]
	v_mfma_f32_16x16x32_bf16 v[66:69], v[178:181], v[210:213], v[66:69]
	v_mfma_f32_16x16x32_bf16 v[66:69], v[182:185], v[214:217], v[66:69]
	s_setprio 0
	s_barrier
	s_add_i32 s0, s52, s36
	v_lshl_add_u64 v[218:219], v[218:219], 0, s[14:15]
	s_mov_b32 m0, s0
	ds_read_b128 v[186:189], v163 offset:49152
	ds_read_b128 v[190:193], v163 offset:50176
	ds_read_b128 v[194:197], v163 offset:51200
	ds_read_b128 v[198:201], v163 offset:52224
	ds_read_b128 v[202:205], v163 offset:53248
	ds_read_b128 v[206:209], v163 offset:54272
	ds_read_b128 v[210:213], v163 offset:55296
	ds_read_b128 v[214:217], v163 offset:56320
	global_load_lds_dwordx4 v[218:219], off
	s_add_i32 m0, s0, 0x2000
	s_add_u32 s0, s2, 0x40080
	v_lshl_add_u64 v[218:219], v[220:221], 0, s[14:15]
	s_addc_u32 s1, s3, 0
	s_add_i32 s2, s53, s36
	global_load_lds_dwordx4 v[218:219], off
	v_lshl_add_u64 v[218:219], s[0:1], 0, v[132:133]
	s_mov_b32 m0, s2
	s_nop 0
	global_load_lds_dwordx4 v[218:219], off
	v_lshl_add_u64 v[218:219], s[0:1], 0, v[136:137]
	s_add_i32 m0, s2, 0x2000
	s_nop 0
	global_load_lds_dwordx4 v[218:219], off
	v_lshl_add_u64 v[218:219], v[222:223], 0, s[14:15]
	s_mov_b32 m0, s40
	s_nop 0
	global_load_lds_dwordx4 v[218:219], off
	v_lshl_add_u64 v[218:219], v[224:225], 0, s[14:15]
	s_mov_b32 m0, s41
	s_nop 0
	global_load_lds_dwordx4 v[218:219], off
	s_waitcnt vmcnt(8)
	s_waitcnt lgkmcnt(0)
	s_barrier
	s_setprio 1
	v_mfma_f32_16x16x32_bf16 v[62:65], v[148:151], v[186:189], v[62:65]
	v_mfma_f32_16x16x32_bf16 v[62:65], v[152:155], v[190:193], v[62:65]
	v_mfma_f32_16x16x32_bf16 v[58:61], v[156:159], v[186:189], v[58:61]
	v_mfma_f32_16x16x32_bf16 v[58:61], v[166:169], v[190:193], v[58:61]
	v_mfma_f32_16x16x32_bf16 v[46:49], v[148:151], v[194:197], v[46:49]
	v_mfma_f32_16x16x32_bf16 v[46:49], v[152:155], v[198:201], v[46:49]
	v_mfma_f32_16x16x32_bf16 v[42:45], v[156:159], v[194:197], v[42:45]
	v_mfma_f32_16x16x32_bf16 v[42:45], v[166:169], v[198:201], v[42:45]
	v_mfma_f32_16x16x32_bf16 v[30:33], v[148:151], v[202:205], v[30:33]
	v_mfma_f32_16x16x32_bf16 v[30:33], v[152:155], v[206:209], v[30:33]
	v_mfma_f32_16x16x32_bf16 v[26:29], v[156:159], v[202:205], v[26:29]
	v_mfma_f32_16x16x32_bf16 v[26:29], v[166:169], v[206:209], v[26:29]
	v_mfma_f32_16x16x32_bf16 v[14:17], v[148:151], v[210:213], v[14:17]
	v_mfma_f32_16x16x32_bf16 v[14:17], v[152:155], v[214:217], v[14:17]
	v_mfma_f32_16x16x32_bf16 v[10:13], v[156:159], v[210:213], v[10:13]
	v_mfma_f32_16x16x32_bf16 v[10:13], v[166:169], v[214:217], v[10:13]
	s_setprio 0
	s_setprio 1
	v_mfma_f32_16x16x32_bf16 v[54:57], v[170:173], v[186:189], v[54:57]
	v_mfma_f32_16x16x32_bf16 v[54:57], v[174:177], v[190:193], v[54:57]
	v_mfma_f32_16x16x32_bf16 v[50:53], v[178:181], v[186:189], v[50:53]
	v_mfma_f32_16x16x32_bf16 v[50:53], v[182:185], v[190:193], v[50:53]
	v_mfma_f32_16x16x32_bf16 v[38:41], v[170:173], v[194:197], v[38:41]
	v_mfma_f32_16x16x32_bf16 v[38:41], v[174:177], v[198:201], v[38:41]
	v_mfma_f32_16x16x32_bf16 v[34:37], v[178:181], v[194:197], v[34:37]
	v_mfma_f32_16x16x32_bf16 v[34:37], v[182:185], v[198:201], v[34:37]
	v_mfma_f32_16x16x32_bf16 v[22:25], v[170:173], v[202:205], v[22:25]
	v_mfma_f32_16x16x32_bf16 v[22:25], v[174:177], v[206:209], v[22:25]
	v_mfma_f32_16x16x32_bf16 v[18:21], v[178:181], v[202:205], v[18:21]
	v_mfma_f32_16x16x32_bf16 v[18:21], v[182:185], v[206:209], v[18:21]
	v_mfma_f32_16x16x32_bf16 v[6:9], v[170:173], v[210:213], v[6:9]
	v_mfma_f32_16x16x32_bf16 v[6:9], v[174:177], v[214:217], v[6:9]
	v_mfma_f32_16x16x32_bf16 v[2:5], v[178:181], v[210:213], v[2:5]
	v_mfma_f32_16x16x32_bf16 v[2:5], v[182:185], v[214:217], v[2:5]
	s_setprio 0
	s_barrier
	s_add_i32 s51, s51, 2
	s_add_u32 s28, s28, 0x100
	s_addc_u32 s29, s29, 0
	s_add_u32 s49, s49, 0x100
	s_addc_u32 s50, s50, 0
	s_cmp_gt_u32 s51, 13
	s_cbranch_scc0 .LBB0_1938
	s_and_b64 vcc, exec, s[16:17]
	s_cbranch_vccz .LBB0_1941
	s_barrier

.LBB0_2018:
	s_ashr_i32 s57, s56, 31
	s_lshl_b64 s[0:1], s[56:57], 19
	s_add_u32 s58, s78, s0
	s_addc_u32 s59, s79, s1
	s_and_b64 s[0:1], s[4:5], exec
	s_cselect_b32 s7, s59, s11
	s_cselect_b32 s9, s58, s10
	s_ashr_i32 s55, s54, 31
	s_lshl_b64 s[0:1], s[54:55], 19
	s_add_u32 s60, s33, s0
	s_addc_u32 s61, s64, s1
	s_and_b64 s[0:1], s[4:5], exec
	s_cselect_b32 s55, s61, s3
	s_cselect_b32 s57, s60, s2
	s_add_u32 s10, s10, 0x40080
	s_addc_u32 s11, s11, 0
	s_add_u32 s62, s2, 0x100
	v_mov_b32_e32 v2, 0
	s_addc_u32 s63, s3, 0
	s_mov_b32 s77, -2
	v_mov_b32_e32 v3, v2
	v_mov_b32_e32 v4, v2
	v_mov_b32_e32 v5, v2
	v_mov_b32_e32 v6, v2
	v_mov_b32_e32 v7, v2
	v_mov_b32_e32 v8, v2
	v_mov_b32_e32 v9, v2
	v_mov_b32_e32 v10, v2
	v_mov_b32_e32 v11, v2
	v_mov_b32_e32 v12, v2
	v_mov_b32_e32 v13, v2
	v_mov_b32_e32 v14, v2
	v_mov_b32_e32 v15, v2
	v_mov_b32_e32 v16, v2
	v_mov_b32_e32 v17, v2
	v_mov_b32_e32 v18, v2
	v_mov_b32_e32 v19, v2
	v_mov_b32_e32 v20, v2
	v_mov_b32_e32 v21, v2
	v_mov_b32_e32 v22, v2
	v_mov_b32_e32 v23, v2
	v_mov_b32_e32 v24, v2
	v_mov_b32_e32 v25, v2
	v_mov_b32_e32 v26, v2
	v_mov_b32_e32 v27, v2
	v_mov_b32_e32 v28, v2
	v_mov_b32_e32 v29, v2
	v_mov_b32_e32 v30, v2
	v_mov_b32_e32 v31, v2
	v_mov_b32_e32 v32, v2
	v_mov_b32_e32 v33, v2
	v_mov_b32_e32 v66, v2
	v_mov_b32_e32 v67, v2
	v_mov_b32_e32 v68, v2
	v_mov_b32_e32 v69, v2
	v_mov_b32_e32 v70, v2
	v_mov_b32_e32 v71, v2
	v_mov_b32_e32 v72, v2
	v_mov_b32_e32 v73, v2
	v_mov_b32_e32 v74, v2
	v_mov_b32_e32 v75, v2
	v_mov_b32_e32 v76, v2
	v_mov_b32_e32 v77, v2
	v_mov_b32_e32 v78, v2
	v_mov_b32_e32 v79, v2
	v_mov_b32_e32 v80, v2
	v_mov_b32_e32 v81, v2
	v_mov_b32_e32 v82, v2
	v_mov_b32_e32 v83, v2
	v_mov_b32_e32 v84, v2
	v_mov_b32_e32 v85, v2
	v_mov_b32_e32 v86, v2
	v_mov_b32_e32 v87, v2
	v_mov_b32_e32 v88, v2
	v_mov_b32_e32 v89, v2
	v_mov_b32_e32 v90, v2
	v_mov_b32_e32 v91, v2
	v_mov_b32_e32 v92, v2
	v_mov_b32_e32 v93, v2
	v_mov_b32_e32 v94, v2
	v_mov_b32_e32 v95, v2
	v_mov_b32_e32 v96, v2
	v_mov_b32_e32 v97, v2
	v_mov_b32_e32 v34, v2
	v_mov_b32_e32 v35, v2
	v_mov_b32_e32 v36, v2
	v_mov_b32_e32 v37, v2
	v_mov_b32_e32 v38, v2
	v_mov_b32_e32 v39, v2
	v_mov_b32_e32 v40, v2
	v_mov_b32_e32 v41, v2
	v_mov_b32_e32 v42, v2
	v_mov_b32_e32 v43, v2
	v_mov_b32_e32 v44, v2
	v_mov_b32_e32 v45, v2
	v_mov_b32_e32 v46, v2
	v_mov_b32_e32 v47, v2
	v_mov_b32_e32 v48, v2
	v_mov_b32_e32 v49, v2
	v_mov_b32_e32 v50, v2
	v_mov_b32_e32 v51, v2
	v_mov_b32_e32 v52, v2
	v_mov_b32_e32 v53, v2
	v_mov_b32_e32 v54, v2
	v_mov_b32_e32 v55, v2
	v_mov_b32_e32 v56, v2
	v_mov_b32_e32 v57, v2
	v_mov_b32_e32 v58, v2
	v_mov_b32_e32 v59, v2
	v_mov_b32_e32 v60, v2
	v_mov_b32_e32 v61, v2
	v_mov_b32_e32 v62, v2
	v_mov_b32_e32 v63, v2
	v_mov_b32_e32 v64, v2
	v_mov_b32_e32 v65, v2
	v_mov_b32_e32 v98, v2
	v_mov_b32_e32 v99, v2
	v_mov_b32_e32 v100, v2
	v_mov_b32_e32 v101, v2
	v_mov_b32_e32 v102, v2
	v_mov_b32_e32 v103, v2
	v_mov_b32_e32 v104, v2
	v_mov_b32_e32 v105, v2
	v_mov_b32_e32 v106, v2
	v_mov_b32_e32 v107, v2
	v_mov_b32_e32 v108, v2
	v_mov_b32_e32 v109, v2
	v_mov_b32_e32 v118, v2
	v_mov_b32_e32 v119, v2
	v_mov_b32_e32 v120, v2
	v_mov_b32_e32 v121, v2
	v_mov_b32_e32 v130, v2
	v_mov_b32_e32 v131, v2
	v_mov_b32_e32 v132, v2
	v_mov_b32_e32 v133, v2
	v_mov_b32_e32 v134, v2
	v_mov_b32_e32 v135, v2
	v_mov_b32_e32 v136, v2
	v_mov_b32_e32 v137, v2
	v_mov_b32_e32 v138, v2
	v_mov_b32_e32 v139, v2
	v_mov_b32_e32 v140, v2
	v_mov_b32_e32 v141, v2
	v_mov_b32_e32 v142, v2
	v_mov_b32_e32 v143, v2
	v_mov_b32_e32 v144, v2
	v_mov_b32_e32 v145, v2
	s_nop 0
	s_nop 0
	s_nop 0
	s_nop 0
	s_nop 0
.LBB0_2019:
	ds_read_b128 v[110:113], v227
	ds_read_b128 v[114:117], v227 offset:1024
	ds_read_b128 v[122:125], v227 offset:2048
	ds_read_b128 v[126:129], v227 offset:3072
	ds_read_b128 v[146:149], v228
	ds_read_b128 v[150:153], v228 offset:1024
	ds_read_b128 v[154:157], v228 offset:2048
	ds_read_b128 v[158:161], v228 offset:3072
	s_add_u32 s0, s10, 0xfffc0080
	s_addc_u32 s1, s11, -1
	s_cmp_eq_u32 s77, 12
	s_cselect_b32 s13, s7, s1
	s_cselect_b32 s12, s9, s0
	s_cselect_b32 s3, s55, s63
	s_cselect_b32 s2, s57, s62
	v_lshl_add_u64 v[212:213], s[10:11], 0, v[180:181]
	s_add_i32 m0, s66, 0xc000
	ds_read_b128 v[162:165], v229
	ds_read_b128 v[166:169], v229 offset:1024
	ds_read_b128 v[188:191], v229 offset:2048
	ds_read_b128 v[192:195], v229 offset:3072
	ds_read_b128 v[196:199], v229 offset:4096
	ds_read_b128 v[200:203], v229 offset:5120
	ds_read_b128 v[204:207], v229 offset:6144
	ds_read_b128 v[208:211], v229 offset:7168
	global_load_lds_dwordx4 v[212:213], off
	v_lshl_add_u64 v[212:213], s[10:11], 0, v[182:183]
	s_add_i32 m0, s66, 0xe000
	s_nop 0
	global_load_lds_dwordx4 v[212:213], off
	s_waitcnt vmcnt(8)
	s_waitcnt lgkmcnt(0)
	s_barrier
	s_setprio 1
	v_mfma_f32_16x16x32_bf16 v[142:145], v[110:113], v[162:165], v[142:145]
	v_mfma_f32_16x16x32_bf16 v[142:145], v[114:117], v[166:169], v[142:145]
	v_mfma_f32_16x16x32_bf16 v[138:141], v[122:125], v[162:165], v[138:141]
	v_mfma_f32_16x16x32_bf16 v[138:141], v[126:129], v[166:169], v[138:141]
	v_mfma_f32_16x16x32_bf16 v[134:137], v[110:113], v[188:191], v[134:137]
	v_mfma_f32_16x16x32_bf16 v[134:137], v[114:117], v[192:195], v[134:137]
	v_mfma_f32_16x16x32_bf16 v[130:133], v[122:125], v[188:191], v[130:133]
	v_mfma_f32_16x16x32_bf16 v[130:133], v[126:129], v[192:195], v[130:133]
	v_mfma_f32_16x16x32_bf16 v[118:121], v[110:113], v[196:199], v[118:121]
	v_mfma_f32_16x16x32_bf16 v[118:121], v[114:117], v[200:203], v[118:121]
	v_mfma_f32_16x16x32_bf16 v[106:109], v[122:125], v[196:199], v[106:109]
	v_mfma_f32_16x16x32_bf16 v[106:109], v[126:129], v[200:203], v[106:109]
	v_mfma_f32_16x16x32_bf16 v[102:105], v[110:113], v[204:207], v[102:105]
	v_mfma_f32_16x16x32_bf16 v[102:105], v[114:117], v[208:211], v[102:105]
	v_mfma_f32_16x16x32_bf16 v[98:101], v[122:125], v[204:207], v[98:101]
	v_mfma_f32_16x16x32_bf16 v[98:101], v[126:129], v[208:211], v[98:101]
	s_setprio 0
	s_setprio 1
	v_mfma_f32_16x16x32_bf16 v[62:65], v[146:149], v[162:165], v[62:65]
	v_mfma_f32_16x16x32_bf16 v[62:65], v[150:153], v[166:169], v[62:65]
	v_mfma_f32_16x16x32_bf16 v[58:61], v[154:157], v[162:165], v[58:61]
	v_mfma_f32_16x16x32_bf16 v[58:61], v[158:161], v[166:169], v[58:61]
	v_mfma_f32_16x16x32_bf16 v[54:57], v[146:149], v[188:191], v[54:57]
	v_mfma_f32_16x16x32_bf16 v[54:57], v[150:153], v[192:195], v[54:57]
	v_mfma_f32_16x16x32_bf16 v[50:53], v[154:157], v[188:191], v[50:53]
	v_mfma_f32_16x16x32_bf16 v[50:53], v[158:161], v[192:195], v[50:53]
	v_mfma_f32_16x16x32_bf16 v[46:49], v[146:149], v[196:199], v[46:49]
	v_mfma_f32_16x16x32_bf16 v[46:49], v[150:153], v[200:203], v[46:49]
	v_mfma_f32_16x16x32_bf16 v[42:45], v[154:157], v[196:199], v[42:45]
	v_mfma_f32_16x16x32_bf16 v[42:45], v[158:161], v[200:203], v[42:45]
	v_mfma_f32_16x16x32_bf16 v[38:41], v[146:149], v[204:207], v[38:41]
	v_mfma_f32_16x16x32_bf16 v[38:41], v[150:153], v[208:211], v[38:41]
	v_mfma_f32_16x16x32_bf16 v[34:37], v[154:157], v[204:207], v[34:37]
	v_mfma_f32_16x16x32_bf16 v[34:37], v[158:161], v[208:211], v[34:37]
	s_setprio 0
	s_barrier
	s_add_i32 s0, s75, s65
	v_lshl_add_u64 v[212:213], s[2:3], 0, v[172:173]
	s_mov_b32 m0, s0
	ds_read_b128 v[162:165], v229 offset:16384
	ds_read_b128 v[166:169], v229 offset:17408
	ds_read_b128 v[188:191], v229 offset:18432
	ds_read_b128 v[192:195], v229 offset:19456
	ds_read_b128 v[196:199], v229 offset:20480
	ds_read_b128 v[200:203], v229 offset:21504
	ds_read_b128 v[204:207], v229 offset:22528
	ds_read_b128 v[208:211], v229 offset:23552
	global_load_lds_dwordx4 v[212:213], off
	s_add_i32 m0, s0, 0x2000
	s_add_u32 s0, s2, 0x40000
	v_lshl_add_u64 v[214:215], s[2:3], 0, v[176:177]
	s_addc_u32 s1, s3, 0
	s_add_i32 s78, s76, s65
	global_load_lds_dwordx4 v[214:215], off
	v_lshl_add_u64 v[216:217], s[0:1], 0, v[172:173]
	s_mov_b32 m0, s78
	v_lshl_add_u64 v[218:219], s[12:13], 0, v[174:175]
	global_load_lds_dwordx4 v[216:217], off
	v_lshl_add_u64 v[216:217], s[0:1], 0, v[176:177]
	s_add_i32 m0, s78, 0x2000
	s_nop 0
	global_load_lds_dwordx4 v[216:217], off
	v_lshl_add_u64 v[216:217], s[12:13], 0, v[170:171]
	s_mov_b32 m0, s66
	s_nop 0
	global_load_lds_dwordx4 v[216:217], off
	s_mov_b32 m0, s67
	s_nop 0
	global_load_lds_dwordx4 v[218:219], off
	s_waitcnt vmcnt(8)
	s_waitcnt lgkmcnt(0)
	s_barrier
	s_setprio 1
	v_mfma_f32_16x16x32_bf16 v[94:97], v[110:113], v[162:165], v[94:97]
	v_mfma_f32_16x16x32_bf16 v[94:97], v[114:117], v[166:169], v[94:97]
	v_mfma_f32_16x16x32_bf16 v[90:93], v[122:125], v[162:165], v[90:93]
	v_mfma_f32_16x16x32_bf16 v[90:93], v[126:129], v[166:169], v[90:93]
	v_mfma_f32_16x16x32_bf16 v[86:89], v[110:113], v[188:191], v[86:89]
	v_mfma_f32_16x16x32_bf16 v[86:89], v[114:117], v[192:195], v[86:89]
	v_mfma_f32_16x16x32_bf16 v[82:85], v[122:125], v[188:191], v[82:85]
	v_mfma_f32_16x16x32_bf16 v[82:85], v[126:129], v[192:195], v[82:85]
	v_mfma_f32_16x16x32_bf16 v[78:81], v[110:113], v[196:199], v[78:81]
	v_mfma_f32_16x16x32_bf16 v[78:81], v[114:117], v[200:203], v[78:81]
	v_mfma_f32_16x16x32_bf16 v[74:77], v[122:125], v[196:199], v[74:77]
	v_mfma_f32_16x16x32_bf16 v[74:77], v[126:129], v[200:203], v[74:77]
	v_mfma_f32_16x16x32_bf16 v[70:73], v[110:113], v[204:207], v[70:73]
	v_mfma_f32_16x16x32_bf16 v[70:73], v[114:117], v[208:211], v[70:73]
	v_mfma_f32_16x16x32_bf16 v[66:69], v[122:125], v[204:207], v[66:69]
	v_mfma_f32_16x16x32_bf16 v[66:69], v[126:129], v[208:211], v[66:69]
	s_setprio 0
	s_setprio 1
	v_mfma_f32_16x16x32_bf16 v[30:33], v[146:149], v[162:165], v[30:33]
	v_mfma_f32_16x16x32_bf16 v[30:33], v[150:153], v[166:169], v[30:33]
	v_mfma_f32_16x16x32_bf16 v[26:29], v[154:157], v[162:165], v[26:29]
	v_mfma_f32_16x16x32_bf16 v[26:29], v[158:161], v[166:169], v[26:29]
	v_mfma_f32_16x16x32_bf16 v[22:25], v[146:149], v[188:191], v[22:25]
	v_mfma_f32_16x16x32_bf16 v[22:25], v[150:153], v[192:195], v[22:25]
	v_mfma_f32_16x16x32_bf16 v[18:21], v[154:157], v[188:191], v[18:21]
	v_mfma_f32_16x16x32_bf16 v[18:21], v[158:161], v[192:195], v[18:21]
	v_mfma_f32_16x16x32_bf16 v[14:17], v[146:149], v[196:199], v[14:17]
	v_mfma_f32_16x16x32_bf16 v[14:17], v[150:153], v[200:203], v[14:17]
	v_mfma_f32_16x16x32_bf16 v[10:13], v[154:157], v[196:199], v[10:13]
	v_mfma_f32_16x16x32_bf16 v[10:13], v[158:161], v[200:203], v[10:13]
	v_mfma_f32_16x16x32_bf16 v[6:9], v[146:149], v[204:207], v[6:9]
	v_mfma_f32_16x16x32_bf16 v[6:9], v[150:153], v[208:211], v[6:9]
	v_mfma_f32_16x16x32_bf16 v[2:5], v[154:157], v[204:207], v[2:5]
	v_mfma_f32_16x16x32_bf16 v[2:5], v[158:161], v[208:211], v[2:5]
	s_setprio 0
	s_barrier
	s_add_i32 s78, 0, 0x18000
	s_add_i32 s79, 0, 0x1c000
	v_add_u32_e32 v126, s78, v222
	v_add_u32_e32 v158, s79, v222
	ds_read_b128 v[110:113], v126
	ds_read_b128 v[114:117], v126 offset:1024
	ds_read_b128 v[122:125], v126 offset:2048
	ds_read_b128 v[126:129], v126 offset:3072
	ds_read_b128 v[146:149], v158
	ds_read_b128 v[150:153], v158 offset:1024
	ds_read_b128 v[154:157], v158 offset:2048
	ds_read_b128 v[158:161], v158 offset:3072
	s_add_u32 s0, s12, 0x40000
	s_addc_u32 s1, s13, 0
	s_mov_b32 m0, s68
	v_lshl_add_u64 v[220:221], s[0:1], 0, v[170:171]
	ds_read_b128 v[162:165], v229 offset:32768
	ds_read_b128 v[166:169], v229 offset:33792
	ds_read_b128 v[188:191], v229 offset:34816
	ds_read_b128 v[192:195], v229 offset:35840
	ds_read_b128 v[196:199], v229 offset:36864
	ds_read_b128 v[200:203], v229 offset:37888
	ds_read_b128 v[204:207], v229 offset:38912
	ds_read_b128 v[208:211], v229 offset:39936
	global_load_lds_dwordx4 v[220:221], off
	v_lshl_add_u64 v[220:221], s[0:1], 0, v[174:175]
	s_mov_b32 m0, s69
	s_nop 0
	global_load_lds_dwordx4 v[220:221], off
	s_waitcnt vmcnt(8)
	s_waitcnt lgkmcnt(0)
	s_barrier
	s_setprio 1
	v_mfma_f32_16x16x32_bf16 v[142:145], v[110:113], v[162:165], v[142:145]
	v_mfma_f32_16x16x32_bf16 v[142:145], v[114:117], v[166:169], v[142:145]
	v_mfma_f32_16x16x32_bf16 v[138:141], v[122:125], v[162:165], v[138:141]
	v_mfma_f32_16x16x32_bf16 v[138:141], v[126:129], v[166:169], v[138:141]
	v_mfma_f32_16x16x32_bf16 v[134:137], v[110:113], v[188:191], v[134:137]
	v_mfma_f32_16x16x32_bf16 v[134:137], v[114:117], v[192:195], v[134:137]
	v_mfma_f32_16x16x32_bf16 v[130:133], v[122:125], v[188:191], v[130:133]
	v_mfma_f32_16x16x32_bf16 v[130:133], v[126:129], v[192:195], v[130:133]
	v_mfma_f32_16x16x32_bf16 v[118:121], v[110:113], v[196:199], v[118:121]
	v_mfma_f32_16x16x32_bf16 v[118:121], v[114:117], v[200:203], v[118:121]
	v_mfma_f32_16x16x32_bf16 v[106:109], v[122:125], v[196:199], v[106:109]
	v_mfma_f32_16x16x32_bf16 v[106:109], v[126:129], v[200:203], v[106:109]
	v_mfma_f32_16x16x32_bf16 v[102:105], v[110:113], v[204:207], v[102:105]
	v_mfma_f32_16x16x32_bf16 v[102:105], v[114:117], v[208:211], v[102:105]
	v_mfma_f32_16x16x32_bf16 v[98:101], v[122:125], v[204:207], v[98:101]
	v_mfma_f32_16x16x32_bf16 v[98:101], v[126:129], v[208:211], v[98:101]
	s_setprio 0
	s_setprio 1
	v_mfma_f32_16x16x32_bf16 v[62:65], v[146:149], v[162:165], v[62:65]
	v_mfma_f32_16x16x32_bf16 v[62:65], v[150:153], v[166:169], v[62:65]
	v_mfma_f32_16x16x32_bf16 v[58:61], v[154:157], v[162:165], v[58:61]
	v_mfma_f32_16x16x32_bf16 v[58:61], v[158:161], v[166:169], v[58:61]
	v_mfma_f32_16x16x32_bf16 v[54:57], v[146:149], v[188:191], v[54:57]
	v_mfma_f32_16x16x32_bf16 v[54:57], v[150:153], v[192:195], v[54:57]
	v_mfma_f32_16x16x32_bf16 v[50:53], v[154:157], v[188:191], v[50:53]
	v_mfma_f32_16x16x32_bf16 v[50:53], v[158:161], v[192:195], v[50:53]
	v_mfma_f32_16x16x32_bf16 v[46:49], v[146:149], v[196:199], v[46:49]
	v_mfma_f32_16x16x32_bf16 v[46:49], v[150:153], v[200:203], v[46:49]
	v_mfma_f32_16x16x32_bf16 v[42:45], v[154:157], v[196:199], v[42:45]
	v_mfma_f32_16x16x32_bf16 v[42:45], v[158:161], v[200:203], v[42:45]
	v_mfma_f32_16x16x32_bf16 v[38:41], v[146:149], v[204:207], v[38:41]
	v_mfma_f32_16x16x32_bf16 v[38:41], v[150:153], v[208:211], v[38:41]
	v_mfma_f32_16x16x32_bf16 v[34:37], v[154:157], v[204:207], v[34:37]
	v_mfma_f32_16x16x32_bf16 v[34:37], v[158:161], v[208:211], v[34:37]
	s_setprio 0
	s_barrier
	s_add_i32 s0, s78, s65
	v_lshl_add_u64 v[212:213], v[212:213], 0, s[24:25]
	s_mov_b32 m0, s0
	ds_read_b128 v[162:165], v229 offset:49152
	ds_read_b128 v[166:169], v229 offset:50176
	ds_read_b128 v[188:191], v229 offset:51200
	ds_read_b128 v[192:195], v229 offset:52224
	ds_read_b128 v[196:199], v229 offset:53248
	ds_read_b128 v[200:203], v229 offset:54272
	ds_read_b128 v[204:207], v229 offset:55296
	ds_read_b128 v[208:211], v229 offset:56320
	global_load_lds_dwordx4 v[212:213], off
	s_add_i32 m0, s0, 0x2000
	s_add_u32 s0, s2, 0x40080
	v_lshl_add_u64 v[212:213], v[214:215], 0, s[24:25]
	s_addc_u32 s1, s3, 0
	s_add_i32 s2, s79, s65
	global_load_lds_dwordx4 v[212:213], off
	v_lshl_add_u64 v[212:213], s[0:1], 0, v[172:173]
	s_mov_b32 m0, s2
	s_nop 0
	global_load_lds_dwordx4 v[212:213], off
	v_lshl_add_u64 v[212:213], s[0:1], 0, v[176:177]
	s_add_i32 m0, s2, 0x2000
	s_nop 0
	global_load_lds_dwordx4 v[212:213], off
	v_lshl_add_u64 v[212:213], v[216:217], 0, s[24:25]
	s_mov_b32 m0, s71
	s_nop 0
	global_load_lds_dwordx4 v[212:213], off
	v_lshl_add_u64 v[212:213], v[218:219], 0, s[24:25]
	s_mov_b32 m0, s72
	s_nop 0
	global_load_lds_dwordx4 v[212:213], off
	s_waitcnt vmcnt(8)
	s_waitcnt lgkmcnt(0)
	s_barrier
	s_setprio 1
	v_mfma_f32_16x16x32_bf16 v[94:97], v[110:113], v[162:165], v[94:97]
	v_mfma_f32_16x16x32_bf16 v[94:97], v[114:117], v[166:169], v[94:97]
	v_mfma_f32_16x16x32_bf16 v[90:93], v[122:125], v[162:165], v[90:93]
	v_mfma_f32_16x16x32_bf16 v[90:93], v[126:129], v[166:169], v[90:93]
	v_mfma_f32_16x16x32_bf16 v[86:89], v[110:113], v[188:191], v[86:89]
	v_mfma_f32_16x16x32_bf16 v[86:89], v[114:117], v[192:195], v[86:89]
	v_mfma_f32_16x16x32_bf16 v[82:85], v[122:125], v[188:191], v[82:85]
	v_mfma_f32_16x16x32_bf16 v[82:85], v[126:129], v[192:195], v[82:85]
	v_mfma_f32_16x16x32_bf16 v[78:81], v[110:113], v[196:199], v[78:81]
	v_mfma_f32_16x16x32_bf16 v[78:81], v[114:117], v[200:203], v[78:81]
	v_mfma_f32_16x16x32_bf16 v[74:77], v[122:125], v[196:199], v[74:77]
	v_mfma_f32_16x16x32_bf16 v[74:77], v[126:129], v[200:203], v[74:77]
	v_mfma_f32_16x16x32_bf16 v[70:73], v[110:113], v[204:207], v[70:73]
	v_mfma_f32_16x16x32_bf16 v[70:73], v[114:117], v[208:211], v[70:73]
	v_mfma_f32_16x16x32_bf16 v[66:69], v[122:125], v[204:207], v[66:69]
	v_mfma_f32_16x16x32_bf16 v[66:69], v[126:129], v[208:211], v[66:69]
	s_setprio 0
	s_setprio 1
	v_mfma_f32_16x16x32_bf16 v[30:33], v[146:149], v[162:165], v[30:33]
	v_mfma_f32_16x16x32_bf16 v[30:33], v[150:153], v[166:169], v[30:33]
	v_mfma_f32_16x16x32_bf16 v[26:29], v[154:157], v[162:165], v[26:29]
	v_mfma_f32_16x16x32_bf16 v[26:29], v[158:161], v[166:169], v[26:29]
	v_mfma_f32_16x16x32_bf16 v[22:25], v[146:149], v[188:191], v[22:25]
	v_mfma_f32_16x16x32_bf16 v[22:25], v[150:153], v[192:195], v[22:25]
	v_mfma_f32_16x16x32_bf16 v[18:21], v[154:157], v[188:191], v[18:21]
	v_mfma_f32_16x16x32_bf16 v[18:21], v[158:161], v[192:195], v[18:21]
	v_mfma_f32_16x16x32_bf16 v[14:17], v[146:149], v[196:199], v[14:17]
	v_mfma_f32_16x16x32_bf16 v[14:17], v[150:153], v[200:203], v[14:17]
	v_mfma_f32_16x16x32_bf16 v[10:13], v[154:157], v[196:199], v[10:13]
	v_mfma_f32_16x16x32_bf16 v[10:13], v[158:161], v[200:203], v[10:13]
	v_mfma_f32_16x16x32_bf16 v[6:9], v[146:149], v[204:207], v[6:9]
	v_mfma_f32_16x16x32_bf16 v[6:9], v[150:153], v[208:211], v[6:9]
	v_mfma_f32_16x16x32_bf16 v[2:5], v[154:157], v[204:207], v[2:5]
	v_mfma_f32_16x16x32_bf16 v[2:5], v[158:161], v[208:211], v[2:5]
	s_setprio 0
	s_barrier
	s_add_i32 s77, s77, 2
	s_add_u32 s10, s10, 0x100
	s_addc_u32 s11, s11, 0
	s_add_u32 s62, s62, 0x100
	s_addc_u32 s63, s63, 0
	s_cmp_gt_u32 s77, 13
	s_cbranch_scc0 .LBB0_2019
	s_and_b64 vcc, exec, s[26:27]
	s_cbranch_vccz .LBB0_2022
	s_barrier

.LBB0_2117:
	s_ashr_i32 s29, s28, 31
	s_lshl_b64 s[0:1], s[28:29], 19
	s_add_u32 s30, s33, s0
	s_addc_u32 s31, s42, s1
	s_and_b64 s[0:1], s[6:7], exec
	s_cselect_b32 s11, s31, s39
	s_cselect_b32 s29, s30, s38
	s_ashr_i32 s27, s26, 31
	s_lshl_b64 s[0:1], s[26:27], 19
	s_add_u32 s34, s43, s0
	s_addc_u32 s35, s44, s1
	s_and_b64 s[0:1], s[6:7], exec
	s_cselect_b32 s27, s35, s3
	s_cselect_b32 s56, s34, s2
	s_add_u32 s38, s38, 0x40080
	s_addc_u32 s39, s39, 0
	s_add_u32 s57, s2, 0x100
	v_mov_b32_e32 v2, 0
	s_addc_u32 s58, s3, 0
	s_mov_b32 s59, -2
	s_waitcnt lgkmcnt(0)
	v_mov_b32_e32 v3, v2
	v_mov_b32_e32 v4, v2
	v_mov_b32_e32 v5, v2
	v_mov_b32_e32 v6, v2
	v_mov_b32_e32 v7, v2
	v_mov_b32_e32 v8, v2
	v_mov_b32_e32 v9, v2
	v_mov_b32_e32 v18, v2
	v_mov_b32_e32 v19, v2
	v_mov_b32_e32 v20, v2
	v_mov_b32_e32 v21, v2
	v_mov_b32_e32 v22, v2
	v_mov_b32_e32 v23, v2
	v_mov_b32_e32 v24, v2
	v_mov_b32_e32 v25, v2
	v_mov_b32_e32 v34, v2
	v_mov_b32_e32 v35, v2
	v_mov_b32_e32 v36, v2
	v_mov_b32_e32 v37, v2
	v_mov_b32_e32 v38, v2
	v_mov_b32_e32 v39, v2
	v_mov_b32_e32 v40, v2
	v_mov_b32_e32 v41, v2
	v_mov_b32_e32 v50, v2
	v_mov_b32_e32 v51, v2
	v_mov_b32_e32 v52, v2
	v_mov_b32_e32 v53, v2
	v_mov_b32_e32 v54, v2
	v_mov_b32_e32 v55, v2
	v_mov_b32_e32 v56, v2
	v_mov_b32_e32 v57, v2
	v_mov_b32_e32 v10, v2
	v_mov_b32_e32 v11, v2
	v_mov_b32_e32 v12, v2
	v_mov_b32_e32 v13, v2
	v_mov_b32_e32 v14, v2
	v_mov_b32_e32 v15, v2
	v_mov_b32_e32 v16, v2
	v_mov_b32_e32 v17, v2
	v_mov_b32_e32 v26, v2
	v_mov_b32_e32 v27, v2
	v_mov_b32_e32 v28, v2
	v_mov_b32_e32 v29, v2
	v_mov_b32_e32 v30, v2
	v_mov_b32_e32 v31, v2
	v_mov_b32_e32 v32, v2
	v_mov_b32_e32 v33, v2
	v_mov_b32_e32 v42, v2
	v_mov_b32_e32 v43, v2
	v_mov_b32_e32 v44, v2
	v_mov_b32_e32 v45, v2
	v_mov_b32_e32 v46, v2
	v_mov_b32_e32 v47, v2
	v_mov_b32_e32 v48, v2
	v_mov_b32_e32 v49, v2
	v_mov_b32_e32 v58, v2
	v_mov_b32_e32 v59, v2
	v_mov_b32_e32 v60, v2
	v_mov_b32_e32 v61, v2
	v_mov_b32_e32 v62, v2
	v_mov_b32_e32 v63, v2
	v_mov_b32_e32 v64, v2
	v_mov_b32_e32 v65, v2
	v_mov_b32_e32 v66, v2
	v_mov_b32_e32 v67, v2
	v_mov_b32_e32 v68, v2
	v_mov_b32_e32 v69, v2
	v_mov_b32_e32 v70, v2
	v_mov_b32_e32 v71, v2
	v_mov_b32_e32 v72, v2
	v_mov_b32_e32 v73, v2
	v_mov_b32_e32 v82, v2
	v_mov_b32_e32 v83, v2
	v_mov_b32_e32 v84, v2
	v_mov_b32_e32 v85, v2
	v_mov_b32_e32 v86, v2
	v_mov_b32_e32 v87, v2
	v_mov_b32_e32 v88, v2
	v_mov_b32_e32 v89, v2
	v_mov_b32_e32 v98, v2
	v_mov_b32_e32 v99, v2
	v_mov_b32_e32 v100, v2
	v_mov_b32_e32 v101, v2
	v_mov_b32_e32 v102, v2
	v_mov_b32_e32 v103, v2
	v_mov_b32_e32 v104, v2
	v_mov_b32_e32 v105, v2
	v_mov_b32_e32 v114, v2
	v_mov_b32_e32 v115, v2
	v_mov_b32_e32 v116, v2
	v_mov_b32_e32 v117, v2
	v_mov_b32_e32 v118, v2
	v_mov_b32_e32 v119, v2
	v_mov_b32_e32 v120, v2
	v_mov_b32_e32 v121, v2
	v_mov_b32_e32 v74, v2
	v_mov_b32_e32 v75, v2
	v_mov_b32_e32 v76, v2
	v_mov_b32_e32 v77, v2
	v_mov_b32_e32 v78, v2
	v_mov_b32_e32 v79, v2
	v_mov_b32_e32 v80, v2
	v_mov_b32_e32 v81, v2
	v_mov_b32_e32 v90, v2
	v_mov_b32_e32 v91, v2
	v_mov_b32_e32 v92, v2
	v_mov_b32_e32 v93, v2
	v_mov_b32_e32 v94, v2
	v_mov_b32_e32 v95, v2
	v_mov_b32_e32 v96, v2
	v_mov_b32_e32 v97, v2
	v_mov_b32_e32 v106, v2
	v_mov_b32_e32 v107, v2
	v_mov_b32_e32 v108, v2
	v_mov_b32_e32 v109, v2
	v_mov_b32_e32 v110, v2
	v_mov_b32_e32 v111, v2
	v_mov_b32_e32 v112, v2
	v_mov_b32_e32 v113, v2
	v_mov_b32_e32 v122, v2
	v_mov_b32_e32 v123, v2
	v_mov_b32_e32 v124, v2
	v_mov_b32_e32 v125, v2
	v_mov_b32_e32 v126, v2
	v_mov_b32_e32 v127, v2
	v_mov_b32_e32 v128, v2
	v_mov_b32_e32 v129, v2
	s_nop 0
	s_nop 0
	s_nop 0
	s_nop 0
	s_nop 0
	s_nop 0
	s_nop 0
	s_nop 0
	s_nop 0
	s_nop 0
	s_nop 0
.LBB0_2118:
	ds_read_b128 v[130:133], v186
	ds_read_b128 v[134:137], v186 offset:1024
	ds_read_b128 v[138:141], v186 offset:2048
	ds_read_b128 v[142:145], v186 offset:3072
	ds_read_b128 v[146:149], v187
	ds_read_b128 v[150:153], v187 offset:1024
	ds_read_b128 v[170:173], v187 offset:2048
	ds_read_b128 v[174:177], v187 offset:3072
	s_add_u32 s0, s38, 0xfffc0080
	s_addc_u32 s1, s39, -1
	s_cmp_eq_u32 s59, 12
	s_cselect_b32 s41, s11, s1
	s_cselect_b32 s40, s29, s0
	s_cselect_b32 s3, s27, s58
	s_cselect_b32 s2, s56, s57
	v_lshl_add_u64 v[218:219], s[38:39], 0, v[162:163]
	s_add_i32 m0, s37, 0xc000
	ds_read_b128 v[178:181], v188
	ds_read_b128 v[190:193], v188 offset:1024
	ds_read_b128 v[194:197], v188 offset:2048
	ds_read_b128 v[198:201], v188 offset:3072
	ds_read_b128 v[202:205], v188 offset:4096
	ds_read_b128 v[206:209], v188 offset:5120
	ds_read_b128 v[210:213], v188 offset:6144
	ds_read_b128 v[214:217], v188 offset:7168
	global_load_lds_dwordx4 v[218:219], off
	v_lshl_add_u64 v[218:219], s[38:39], 0, v[164:165]
	s_add_i32 m0, s37, 0xe000
	s_nop 0
	global_load_lds_dwordx4 v[218:219], off
	s_waitcnt vmcnt(8)
	s_waitcnt lgkmcnt(0)
	s_barrier
	s_setprio 1
	v_mfma_f32_16x16x32_bf16 v[126:129], v[130:133], v[178:181], v[126:129]
	v_mfma_f32_16x16x32_bf16 v[126:129], v[134:137], v[190:193], v[126:129]
	v_mfma_f32_16x16x32_bf16 v[122:125], v[138:141], v[178:181], v[122:125]
	v_mfma_f32_16x16x32_bf16 v[122:125], v[142:145], v[190:193], v[122:125]
	v_mfma_f32_16x16x32_bf16 v[110:113], v[130:133], v[194:197], v[110:113]
	v_mfma_f32_16x16x32_bf16 v[110:113], v[134:137], v[198:201], v[110:113]
	v_mfma_f32_16x16x32_bf16 v[106:109], v[138:141], v[194:197], v[106:109]
	v_mfma_f32_16x16x32_bf16 v[106:109], v[142:145], v[198:201], v[106:109]
	v_mfma_f32_16x16x32_bf16 v[94:97], v[130:133], v[202:205], v[94:97]
	v_mfma_f32_16x16x32_bf16 v[94:97], v[134:137], v[206:209], v[94:97]
	v_mfma_f32_16x16x32_bf16 v[90:93], v[138:141], v[202:205], v[90:93]
	v_mfma_f32_16x16x32_bf16 v[90:93], v[142:145], v[206:209], v[90:93]
	v_mfma_f32_16x16x32_bf16 v[78:81], v[130:133], v[210:213], v[78:81]
	v_mfma_f32_16x16x32_bf16 v[78:81], v[134:137], v[214:217], v[78:81]
	v_mfma_f32_16x16x32_bf16 v[74:77], v[138:141], v[210:213], v[74:77]
	v_mfma_f32_16x16x32_bf16 v[74:77], v[142:145], v[214:217], v[74:77]
	s_setprio 0
	s_setprio 1
	v_mfma_f32_16x16x32_bf16 v[118:121], v[146:149], v[178:181], v[118:121]
	v_mfma_f32_16x16x32_bf16 v[118:121], v[150:153], v[190:193], v[118:121]
	v_mfma_f32_16x16x32_bf16 v[114:117], v[170:173], v[178:181], v[114:117]
	v_mfma_f32_16x16x32_bf16 v[114:117], v[174:177], v[190:193], v[114:117]
	v_mfma_f32_16x16x32_bf16 v[102:105], v[146:149], v[194:197], v[102:105]
	v_mfma_f32_16x16x32_bf16 v[102:105], v[150:153], v[198:201], v[102:105]
	v_mfma_f32_16x16x32_bf16 v[98:101], v[170:173], v[194:197], v[98:101]
	v_mfma_f32_16x16x32_bf16 v[98:101], v[174:177], v[198:201], v[98:101]
	v_mfma_f32_16x16x32_bf16 v[86:89], v[146:149], v[202:205], v[86:89]
	v_mfma_f32_16x16x32_bf16 v[86:89], v[150:153], v[206:209], v[86:89]
	v_mfma_f32_16x16x32_bf16 v[82:85], v[170:173], v[202:205], v[82:85]
	v_mfma_f32_16x16x32_bf16 v[82:85], v[174:177], v[206:209], v[82:85]
	v_mfma_f32_16x16x32_bf16 v[70:73], v[146:149], v[210:213], v[70:73]
	v_mfma_f32_16x16x32_bf16 v[70:73], v[150:153], v[214:217], v[70:73]
	v_mfma_f32_16x16x32_bf16 v[66:69], v[170:173], v[210:213], v[66:69]
	v_mfma_f32_16x16x32_bf16 v[66:69], v[174:177], v[214:217], v[66:69]
	s_setprio 0
	s_barrier
	s_add_i32 s0, s54, s45
	v_lshl_add_u64 v[218:219], s[2:3], 0, v[156:157]
	s_mov_b32 m0, s0
	ds_read_b128 v[178:181], v188 offset:16384
	ds_read_b128 v[190:193], v188 offset:17408
	ds_read_b128 v[194:197], v188 offset:18432
	ds_read_b128 v[198:201], v188 offset:19456
	ds_read_b128 v[202:205], v188 offset:20480
	ds_read_b128 v[206:209], v188 offset:21504
	ds_read_b128 v[210:213], v188 offset:22528
	ds_read_b128 v[214:217], v188 offset:23552
	global_load_lds_dwordx4 v[218:219], off
	s_add_i32 m0, s0, 0x2000
	s_add_u32 s0, s2, 0x40000
	v_lshl_add_u64 v[220:221], s[2:3], 0, v[160:161]
	s_addc_u32 s1, s3, 0
	s_add_i32 s60, s55, s45
	global_load_lds_dwordx4 v[220:221], off
	v_lshl_add_u64 v[222:223], s[0:1], 0, v[156:157]
	s_mov_b32 m0, s60
	v_lshl_add_u64 v[224:225], s[40:41], 0, v[158:159]
	global_load_lds_dwordx4 v[222:223], off
	v_lshl_add_u64 v[222:223], s[0:1], 0, v[160:161]
	s_add_i32 m0, s60, 0x2000
	s_nop 0
	global_load_lds_dwordx4 v[222:223], off
	v_lshl_add_u64 v[222:223], s[40:41], 0, v[154:155]
	s_mov_b32 m0, s37
	s_nop 0
	global_load_lds_dwordx4 v[222:223], off
	s_mov_b32 m0, s46
	s_nop 0
	global_load_lds_dwordx4 v[224:225], off
	s_waitcnt vmcnt(8)
	s_waitcnt lgkmcnt(0)
	s_barrier
	s_setprio 1
	v_mfma_f32_16x16x32_bf16 v[62:65], v[130:133], v[178:181], v[62:65]
	v_mfma_f32_16x16x32_bf16 v[62:65], v[134:137], v[190:193], v[62:65]
	v_mfma_f32_16x16x32_bf16 v[58:61], v[138:141], v[178:181], v[58:61]
	v_mfma_f32_16x16x32_bf16 v[58:61], v[142:145], v[190:193], v[58:61]
	v_mfma_f32_16x16x32_bf16 v[46:49], v[130:133], v[194:197], v[46:49]
	v_mfma_f32_16x16x32_bf16 v[46:49], v[134:137], v[198:201], v[46:49]
	v_mfma_f32_16x16x32_bf16 v[42:45], v[138:141], v[194:197], v[42:45]
	v_mfma_f32_16x16x32_bf16 v[42:45], v[142:145], v[198:201], v[42:45]
	v_mfma_f32_16x16x32_bf16 v[30:33], v[130:133], v[202:205], v[30:33]
	v_mfma_f32_16x16x32_bf16 v[30:33], v[134:137], v[206:209], v[30:33]
	v_mfma_f32_16x16x32_bf16 v[26:29], v[138:141], v[202:205], v[26:29]
	v_mfma_f32_16x16x32_bf16 v[26:29], v[142:145], v[206:209], v[26:29]
	v_mfma_f32_16x16x32_bf16 v[14:17], v[130:133], v[210:213], v[14:17]
	v_mfma_f32_16x16x32_bf16 v[14:17], v[134:137], v[214:217], v[14:17]
	v_mfma_f32_16x16x32_bf16 v[10:13], v[138:141], v[210:213], v[10:13]
	v_mfma_f32_16x16x32_bf16 v[10:13], v[142:145], v[214:217], v[10:13]
	s_setprio 0
	s_setprio 1
	v_mfma_f32_16x16x32_bf16 v[54:57], v[146:149], v[178:181], v[54:57]
	v_mfma_f32_16x16x32_bf16 v[54:57], v[150:153], v[190:193], v[54:57]
	v_mfma_f32_16x16x32_bf16 v[50:53], v[170:173], v[178:181], v[50:53]
	v_mfma_f32_16x16x32_bf16 v[50:53], v[174:177], v[190:193], v[50:53]
	v_mfma_f32_16x16x32_bf16 v[38:41], v[146:149], v[194:197], v[38:41]
	v_mfma_f32_16x16x32_bf16 v[38:41], v[150:153], v[198:201], v[38:41]
	v_mfma_f32_16x16x32_bf16 v[34:37], v[170:173], v[194:197], v[34:37]
	v_mfma_f32_16x16x32_bf16 v[34:37], v[174:177], v[198:201], v[34:37]
	v_mfma_f32_16x16x32_bf16 v[22:25], v[146:149], v[202:205], v[22:25]
	v_mfma_f32_16x16x32_bf16 v[22:25], v[150:153], v[206:209], v[22:25]
	v_mfma_f32_16x16x32_bf16 v[18:21], v[170:173], v[202:205], v[18:21]
	v_mfma_f32_16x16x32_bf16 v[18:21], v[174:177], v[206:209], v[18:21]
	v_mfma_f32_16x16x32_bf16 v[6:9], v[146:149], v[210:213], v[6:9]
	v_mfma_f32_16x16x32_bf16 v[6:9], v[150:153], v[214:217], v[6:9]
	v_mfma_f32_16x16x32_bf16 v[2:5], v[170:173], v[210:213], v[2:5]
	v_mfma_f32_16x16x32_bf16 v[2:5], v[174:177], v[214:217], v[2:5]
	s_setprio 0
	s_barrier
	s_add_i32 s60, 0, 0x18000
	s_add_i32 s61, 0, 0x1c000
	v_add_u32_e32 v142, s60, v182
	v_add_u32_e32 v174, s61, v182
	ds_read_b128 v[130:133], v142
	ds_read_b128 v[134:137], v142 offset:1024
	ds_read_b128 v[138:141], v142 offset:2048
	ds_read_b128 v[142:145], v142 offset:3072
	ds_read_b128 v[146:149], v174
	ds_read_b128 v[150:153], v174 offset:1024
	ds_read_b128 v[170:173], v174 offset:2048
	ds_read_b128 v[174:177], v174 offset:3072
	s_add_u32 s0, s40, 0x40000
	s_addc_u32 s1, s41, 0
	s_mov_b32 m0, s47
	v_lshl_add_u64 v[226:227], s[0:1], 0, v[154:155]
	ds_read_b128 v[178:181], v188 offset:32768
	ds_read_b128 v[190:193], v188 offset:33792
	ds_read_b128 v[194:197], v188 offset:34816
	ds_read_b128 v[198:201], v188 offset:35840
	ds_read_b128 v[202:205], v188 offset:36864
	ds_read_b128 v[206:209], v188 offset:37888
	ds_read_b128 v[210:213], v188 offset:38912
	ds_read_b128 v[214:217], v188 offset:39936
	global_load_lds_dwordx4 v[226:227], off
	v_lshl_add_u64 v[226:227], s[0:1], 0, v[158:159]
	s_mov_b32 m0, s48
	s_nop 0
	global_load_lds_dwordx4 v[226:227], off
	s_waitcnt vmcnt(8)
	s_waitcnt lgkmcnt(0)
	s_barrier
	s_setprio 1
	v_mfma_f32_16x16x32_bf16 v[126:129], v[130:133], v[178:181], v[126:129]
	v_mfma_f32_16x16x32_bf16 v[126:129], v[134:137], v[190:193], v[126:129]
	v_mfma_f32_16x16x32_bf16 v[122:125], v[138:141], v[178:181], v[122:125]
	v_mfma_f32_16x16x32_bf16 v[122:125], v[142:145], v[190:193], v[122:125]
	v_mfma_f32_16x16x32_bf16 v[110:113], v[130:133], v[194:197], v[110:113]
	v_mfma_f32_16x16x32_bf16 v[110:113], v[134:137], v[198:201], v[110:113]
	v_mfma_f32_16x16x32_bf16 v[106:109], v[138:141], v[194:197], v[106:109]
	v_mfma_f32_16x16x32_bf16 v[106:109], v[142:145], v[198:201], v[106:109]
	v_mfma_f32_16x16x32_bf16 v[94:97], v[130:133], v[202:205], v[94:97]
	v_mfma_f32_16x16x32_bf16 v[94:97], v[134:137], v[206:209], v[94:97]
	v_mfma_f32_16x16x32_bf16 v[90:93], v[138:141], v[202:205], v[90:93]
	v_mfma_f32_16x16x32_bf16 v[90:93], v[142:145], v[206:209], v[90:93]
	v_mfma_f32_16x16x32_bf16 v[78:81], v[130:133], v[210:213], v[78:81]
	v_mfma_f32_16x16x32_bf16 v[78:81], v[134:137], v[214:217], v[78:81]
	v_mfma_f32_16x16x32_bf16 v[74:77], v[138:141], v[210:213], v[74:77]
	v_mfma_f32_16x16x32_bf16 v[74:77], v[142:145], v[214:217], v[74:77]
	s_setprio 0
	s_setprio 1
	v_mfma_f32_16x16x32_bf16 v[118:121], v[146:149], v[178:181], v[118:121]
	v_mfma_f32_16x16x32_bf16 v[118:121], v[150:153], v[190:193], v[118:121]
	v_mfma_f32_16x16x32_bf16 v[114:117], v[170:173], v[178:181], v[114:117]
	v_mfma_f32_16x16x32_bf16 v[114:117], v[174:177], v[190:193], v[114:117]
	v_mfma_f32_16x16x32_bf16 v[102:105], v[146:149], v[194:197], v[102:105]
	v_mfma_f32_16x16x32_bf16 v[102:105], v[150:153], v[198:201], v[102:105]
	v_mfma_f32_16x16x32_bf16 v[98:101], v[170:173], v[194:197], v[98:101]
	v_mfma_f32_16x16x32_bf16 v[98:101], v[174:177], v[198:201], v[98:101]
	v_mfma_f32_16x16x32_bf16 v[86:89], v[146:149], v[202:205], v[86:89]
	v_mfma_f32_16x16x32_bf16 v[86:89], v[150:153], v[206:209], v[86:89]
	v_mfma_f32_16x16x32_bf16 v[82:85], v[170:173], v[202:205], v[82:85]
	v_mfma_f32_16x16x32_bf16 v[82:85], v[174:177], v[206:209], v[82:85]
	v_mfma_f32_16x16x32_bf16 v[70:73], v[146:149], v[210:213], v[70:73]
	v_mfma_f32_16x16x32_bf16 v[70:73], v[150:153], v[214:217], v[70:73]
	v_mfma_f32_16x16x32_bf16 v[66:69], v[170:173], v[210:213], v[66:69]
	v_mfma_f32_16x16x32_bf16 v[66:69], v[174:177], v[214:217], v[66:69]
	s_setprio 0
	s_barrier
	s_add_i32 s0, s60, s45
	v_lshl_add_u64 v[218:219], v[218:219], 0, s[16:17]
	s_mov_b32 m0, s0
	ds_read_b128 v[178:181], v188 offset:49152
	ds_read_b128 v[190:193], v188 offset:50176
	ds_read_b128 v[194:197], v188 offset:51200
	ds_read_b128 v[198:201], v188 offset:52224
	ds_read_b128 v[202:205], v188 offset:53248
	ds_read_b128 v[206:209], v188 offset:54272
	ds_read_b128 v[210:213], v188 offset:55296
	ds_read_b128 v[214:217], v188 offset:56320
	global_load_lds_dwordx4 v[218:219], off
	s_add_i32 m0, s0, 0x2000
	s_add_u32 s0, s2, 0x40080
	v_lshl_add_u64 v[218:219], v[220:221], 0, s[16:17]
	s_addc_u32 s1, s3, 0
	s_add_i32 s2, s61, s45
	global_load_lds_dwordx4 v[218:219], off
	v_lshl_add_u64 v[218:219], s[0:1], 0, v[156:157]
	s_mov_b32 m0, s2
	s_nop 0
	global_load_lds_dwordx4 v[218:219], off
	v_lshl_add_u64 v[218:219], s[0:1], 0, v[160:161]
	s_add_i32 m0, s2, 0x2000
	s_nop 0
	global_load_lds_dwordx4 v[218:219], off
	v_lshl_add_u64 v[218:219], v[222:223], 0, s[16:17]
	s_mov_b32 m0, s50
	s_nop 0
	global_load_lds_dwordx4 v[218:219], off
	v_lshl_add_u64 v[218:219], v[224:225], 0, s[16:17]
	s_mov_b32 m0, s51
	s_nop 0
	global_load_lds_dwordx4 v[218:219], off
	s_waitcnt vmcnt(8)
	s_waitcnt lgkmcnt(0)
	s_barrier
	s_setprio 1
	v_mfma_f32_16x16x32_bf16 v[62:65], v[130:133], v[178:181], v[62:65]
	v_mfma_f32_16x16x32_bf16 v[62:65], v[134:137], v[190:193], v[62:65]
	v_mfma_f32_16x16x32_bf16 v[58:61], v[138:141], v[178:181], v[58:61]
	v_mfma_f32_16x16x32_bf16 v[58:61], v[142:145], v[190:193], v[58:61]
	v_mfma_f32_16x16x32_bf16 v[46:49], v[130:133], v[194:197], v[46:49]
	v_mfma_f32_16x16x32_bf16 v[46:49], v[134:137], v[198:201], v[46:49]
	v_mfma_f32_16x16x32_bf16 v[42:45], v[138:141], v[194:197], v[42:45]
	v_mfma_f32_16x16x32_bf16 v[42:45], v[142:145], v[198:201], v[42:45]
	v_mfma_f32_16x16x32_bf16 v[30:33], v[130:133], v[202:205], v[30:33]
	v_mfma_f32_16x16x32_bf16 v[30:33], v[134:137], v[206:209], v[30:33]
	v_mfma_f32_16x16x32_bf16 v[26:29], v[138:141], v[202:205], v[26:29]
	v_mfma_f32_16x16x32_bf16 v[26:29], v[142:145], v[206:209], v[26:29]
	v_mfma_f32_16x16x32_bf16 v[14:17], v[130:133], v[210:213], v[14:17]
	v_mfma_f32_16x16x32_bf16 v[14:17], v[134:137], v[214:217], v[14:17]
	v_mfma_f32_16x16x32_bf16 v[10:13], v[138:141], v[210:213], v[10:13]
	v_mfma_f32_16x16x32_bf16 v[10:13], v[142:145], v[214:217], v[10:13]
	s_setprio 0
	s_setprio 1
	v_mfma_f32_16x16x32_bf16 v[54:57], v[146:149], v[178:181], v[54:57]
	v_mfma_f32_16x16x32_bf16 v[54:57], v[150:153], v[190:193], v[54:57]
	v_mfma_f32_16x16x32_bf16 v[50:53], v[170:173], v[178:181], v[50:53]
	v_mfma_f32_16x16x32_bf16 v[50:53], v[174:177], v[190:193], v[50:53]
	v_mfma_f32_16x16x32_bf16 v[38:41], v[146:149], v[194:197], v[38:41]
	v_mfma_f32_16x16x32_bf16 v[38:41], v[150:153], v[198:201], v[38:41]
	v_mfma_f32_16x16x32_bf16 v[34:37], v[170:173], v[194:197], v[34:37]
	v_mfma_f32_16x16x32_bf16 v[34:37], v[174:177], v[198:201], v[34:37]
	v_mfma_f32_16x16x32_bf16 v[22:25], v[146:149], v[202:205], v[22:25]
	v_mfma_f32_16x16x32_bf16 v[22:25], v[150:153], v[206:209], v[22:25]
	v_mfma_f32_16x16x32_bf16 v[18:21], v[170:173], v[202:205], v[18:21]
	v_mfma_f32_16x16x32_bf16 v[18:21], v[174:177], v[206:209], v[18:21]
	v_mfma_f32_16x16x32_bf16 v[6:9], v[146:149], v[210:213], v[6:9]
	v_mfma_f32_16x16x32_bf16 v[6:9], v[150:153], v[214:217], v[6:9]
	v_mfma_f32_16x16x32_bf16 v[2:5], v[170:173], v[210:213], v[2:5]
	v_mfma_f32_16x16x32_bf16 v[2:5], v[174:177], v[214:217], v[2:5]
	s_setprio 0
	s_barrier
	s_add_i32 s59, s59, 2
	s_add_u32 s38, s38, 0x100
	s_addc_u32 s39, s39, 0
	s_add_u32 s57, s57, 0x100
	s_addc_u32 s58, s58, 0
	s_cmp_gt_u32 s59, 13
	s_cbranch_scc0 .LBB0_2118
	s_and_b64 vcc, exec, s[18:19]
	s_cbranch_vccz .LBB0_2121
	s_barrier

.LBB0_2207:
	ds_read_b128 v[148:151], v165
	ds_read_b128 v[152:155], v165 offset:1024
	ds_read_b128 v[156:159], v165 offset:2048
	ds_read_b128 v[160:163], v165 offset:3072
	ds_read_b128 v[170:173], v166
	ds_read_b128 v[174:177], v166 offset:1024
	ds_read_b128 v[178:181], v166 offset:2048
	ds_read_b128 v[182:185], v166 offset:3072
	s_add_u32 s0, s28, 0xfffc0080
	s_addc_u32 s1, s29, -1
	s_cmp_eq_u32 s53, 12
	s_cselect_b32 s31, s21, s1
	s_cselect_b32 s30, s49, s0
	s_cselect_b32 s3, s19, s52
	s_cselect_b32 s2, s50, s51
	v_lshl_add_u64 v[218:219], s[28:29], 0, v[140:141]
	s_add_i32 m0, s27, 0xc000
	ds_read_b128 v[186:189], v167
	ds_read_b128 v[190:193], v167 offset:1024
	ds_read_b128 v[194:197], v167 offset:2048
	ds_read_b128 v[198:201], v167 offset:3072
	ds_read_b128 v[202:205], v167 offset:4096
	ds_read_b128 v[206:209], v167 offset:5120
	ds_read_b128 v[210:213], v167 offset:6144
	ds_read_b128 v[214:217], v167 offset:7168
	global_load_lds_dwordx4 v[218:219], off
	v_lshl_add_u64 v[218:219], s[28:29], 0, v[142:143]
	s_add_i32 m0, s27, 0xe000
	s_nop 0
	global_load_lds_dwordx4 v[218:219], off
	s_waitcnt vmcnt(8)
	s_waitcnt lgkmcnt(0)
	s_barrier
	s_setprio 1
	v_mfma_f32_16x16x32_bf16 v[126:129], v[148:151], v[186:189], v[126:129]
	v_mfma_f32_16x16x32_bf16 v[126:129], v[152:155], v[190:193], v[126:129]
	v_mfma_f32_16x16x32_bf16 v[118:121], v[156:159], v[186:189], v[118:121]
	v_mfma_f32_16x16x32_bf16 v[118:121], v[160:163], v[190:193], v[118:121]
	v_mfma_f32_16x16x32_bf16 v[110:113], v[148:151], v[194:197], v[110:113]
	v_mfma_f32_16x16x32_bf16 v[110:113], v[152:155], v[198:201], v[110:113]
	v_mfma_f32_16x16x32_bf16 v[102:105], v[156:159], v[194:197], v[102:105]
	v_mfma_f32_16x16x32_bf16 v[102:105], v[160:163], v[198:201], v[102:105]
	v_mfma_f32_16x16x32_bf16 v[94:97], v[148:151], v[202:205], v[94:97]
	v_mfma_f32_16x16x32_bf16 v[94:97], v[152:155], v[206:209], v[94:97]
	v_mfma_f32_16x16x32_bf16 v[86:89], v[156:159], v[202:205], v[86:89]
	v_mfma_f32_16x16x32_bf16 v[86:89], v[160:163], v[206:209], v[86:89]
	v_mfma_f32_16x16x32_bf16 v[78:81], v[148:151], v[210:213], v[78:81]
	v_mfma_f32_16x16x32_bf16 v[78:81], v[152:155], v[214:217], v[78:81]
	v_mfma_f32_16x16x32_bf16 v[70:73], v[156:159], v[210:213], v[70:73]
	v_mfma_f32_16x16x32_bf16 v[70:73], v[160:163], v[214:217], v[70:73]
	s_setprio 0
	s_setprio 1
	v_mfma_f32_16x16x32_bf16 v[122:125], v[170:173], v[186:189], v[122:125]
	v_mfma_f32_16x16x32_bf16 v[122:125], v[174:177], v[190:193], v[122:125]
	v_mfma_f32_16x16x32_bf16 v[114:117], v[178:181], v[186:189], v[114:117]
	v_mfma_f32_16x16x32_bf16 v[114:117], v[182:185], v[190:193], v[114:117]
	v_mfma_f32_16x16x32_bf16 v[106:109], v[170:173], v[194:197], v[106:109]
	v_mfma_f32_16x16x32_bf16 v[106:109], v[174:177], v[198:201], v[106:109]
	v_mfma_f32_16x16x32_bf16 v[98:101], v[178:181], v[194:197], v[98:101]
	v_mfma_f32_16x16x32_bf16 v[98:101], v[182:185], v[198:201], v[98:101]
	v_mfma_f32_16x16x32_bf16 v[90:93], v[170:173], v[202:205], v[90:93]
	v_mfma_f32_16x16x32_bf16 v[90:93], v[174:177], v[206:209], v[90:93]
	v_mfma_f32_16x16x32_bf16 v[82:85], v[178:181], v[202:205], v[82:85]
	v_mfma_f32_16x16x32_bf16 v[82:85], v[182:185], v[206:209], v[82:85]
	v_mfma_f32_16x16x32_bf16 v[74:77], v[170:173], v[210:213], v[74:77]
	v_mfma_f32_16x16x32_bf16 v[74:77], v[174:177], v[214:217], v[74:77]
	v_mfma_f32_16x16x32_bf16 v[66:69], v[178:181], v[210:213], v[66:69]
	v_mfma_f32_16x16x32_bf16 v[66:69], v[182:185], v[214:217], v[66:69]
	s_setprio 0
	s_barrier
	s_add_i32 s0, s44, s35
	v_lshl_add_u64 v[218:219], s[2:3], 0, v[134:135]
	s_mov_b32 m0, s0
	ds_read_b128 v[186:189], v167 offset:16384
	ds_read_b128 v[190:193], v167 offset:17408
	ds_read_b128 v[194:197], v167 offset:18432
	ds_read_b128 v[198:201], v167 offset:19456
	ds_read_b128 v[202:205], v167 offset:20480
	ds_read_b128 v[206:209], v167 offset:21504
	ds_read_b128 v[210:213], v167 offset:22528
	ds_read_b128 v[214:217], v167 offset:23552
	global_load_lds_dwordx4 v[218:219], off
	s_add_i32 m0, s0, 0x2000
	s_add_u32 s0, s2, 0x40000
	v_lshl_add_u64 v[220:221], s[2:3], 0, v[130:131]
	s_addc_u32 s1, s3, 0
	s_add_i32 s54, s45, s35
	global_load_lds_dwordx4 v[220:221], off
	v_lshl_add_u64 v[222:223], s[0:1], 0, v[134:135]
	s_mov_b32 m0, s54
	v_lshl_add_u64 v[224:225], s[30:31], 0, v[132:133]
	global_load_lds_dwordx4 v[222:223], off
	v_lshl_add_u64 v[222:223], s[0:1], 0, v[130:131]
	s_add_i32 m0, s54, 0x2000
	s_nop 0
	global_load_lds_dwordx4 v[222:223], off
	v_lshl_add_u64 v[222:223], s[30:31], 0, v[136:137]
	s_mov_b32 m0, s27
	s_nop 0
	global_load_lds_dwordx4 v[222:223], off
	s_mov_b32 m0, s38
	s_nop 0
	global_load_lds_dwordx4 v[224:225], off
	s_waitcnt vmcnt(8)
	s_waitcnt lgkmcnt(0)
	s_barrier
	s_setprio 1
	v_mfma_f32_16x16x32_bf16 v[62:65], v[148:151], v[186:189], v[62:65]
	v_mfma_f32_16x16x32_bf16 v[62:65], v[152:155], v[190:193], v[62:65]
	v_mfma_f32_16x16x32_bf16 v[54:57], v[156:159], v[186:189], v[54:57]
	v_mfma_f32_16x16x32_bf16 v[54:57], v[160:163], v[190:193], v[54:57]
	v_mfma_f32_16x16x32_bf16 v[46:49], v[148:151], v[194:197], v[46:49]
	v_mfma_f32_16x16x32_bf16 v[46:49], v[152:155], v[198:201], v[46:49]
	v_mfma_f32_16x16x32_bf16 v[38:41], v[156:159], v[194:197], v[38:41]
	v_mfma_f32_16x16x32_bf16 v[38:41], v[160:163], v[198:201], v[38:41]
	v_mfma_f32_16x16x32_bf16 v[30:33], v[148:151], v[202:205], v[30:33]
	v_mfma_f32_16x16x32_bf16 v[30:33], v[152:155], v[206:209], v[30:33]
	v_mfma_f32_16x16x32_bf16 v[22:25], v[156:159], v[202:205], v[22:25]
	v_mfma_f32_16x16x32_bf16 v[22:25], v[160:163], v[206:209], v[22:25]
	v_mfma_f32_16x16x32_bf16 v[14:17], v[148:151], v[210:213], v[14:17]
	v_mfma_f32_16x16x32_bf16 v[14:17], v[152:155], v[214:217], v[14:17]
	v_mfma_f32_16x16x32_bf16 v[6:9], v[156:159], v[210:213], v[6:9]
	v_mfma_f32_16x16x32_bf16 v[6:9], v[160:163], v[214:217], v[6:9]
	s_setprio 0
	s_setprio 1
	v_mfma_f32_16x16x32_bf16 v[58:61], v[170:173], v[186:189], v[58:61]
	v_mfma_f32_16x16x32_bf16 v[58:61], v[174:177], v[190:193], v[58:61]
	v_mfma_f32_16x16x32_bf16 v[50:53], v[178:181], v[186:189], v[50:53]
	v_mfma_f32_16x16x32_bf16 v[50:53], v[182:185], v[190:193], v[50:53]
	v_mfma_f32_16x16x32_bf16 v[42:45], v[170:173], v[194:197], v[42:45]
	v_mfma_f32_16x16x32_bf16 v[42:45], v[174:177], v[198:201], v[42:45]
	v_mfma_f32_16x16x32_bf16 v[34:37], v[178:181], v[194:197], v[34:37]
	v_mfma_f32_16x16x32_bf16 v[34:37], v[182:185], v[198:201], v[34:37]
	v_mfma_f32_16x16x32_bf16 v[26:29], v[170:173], v[202:205], v[26:29]
	v_mfma_f32_16x16x32_bf16 v[26:29], v[174:177], v[206:209], v[26:29]
	v_mfma_f32_16x16x32_bf16 v[18:21], v[178:181], v[202:205], v[18:21]
	v_mfma_f32_16x16x32_bf16 v[18:21], v[182:185], v[206:209], v[18:21]
	v_mfma_f32_16x16x32_bf16 v[10:13], v[170:173], v[210:213], v[10:13]
	v_mfma_f32_16x16x32_bf16 v[10:13], v[174:177], v[214:217], v[10:13]
	v_mfma_f32_16x16x32_bf16 v[2:5], v[178:181], v[210:213], v[2:5]
	v_mfma_f32_16x16x32_bf16 v[2:5], v[182:185], v[214:217], v[2:5]
	s_setprio 0
	s_barrier
	s_add_i32 s54, 0, 0x18000
	s_add_i32 s55, 0, 0x1c000
	v_add_u32_e32 v160, s54, v164
	v_add_u32_e32 v169, s55, v164
	ds_read_b128 v[148:151], v160
	ds_read_b128 v[152:155], v160 offset:1024
	ds_read_b128 v[156:159], v160 offset:2048
	ds_read_b128 v[160:163], v160 offset:3072
	ds_read_b128 v[170:173], v169
	ds_read_b128 v[174:177], v169 offset:1024
	ds_read_b128 v[178:181], v169 offset:2048
	ds_read_b128 v[182:185], v169 offset:3072
	s_add_u32 s0, s30, 0x40000
	s_addc_u32 s1, s31, 0
	s_mov_b32 m0, s39
	v_lshl_add_u64 v[226:227], s[0:1], 0, v[136:137]
	ds_read_b128 v[186:189], v167 offset:32768
	ds_read_b128 v[190:193], v167 offset:33792
	ds_read_b128 v[194:197], v167 offset:34816
	ds_read_b128 v[198:201], v167 offset:35840
	ds_read_b128 v[202:205], v167 offset:36864
	ds_read_b128 v[206:209], v167 offset:37888
	ds_read_b128 v[210:213], v167 offset:38912
	ds_read_b128 v[214:217], v167 offset:39936
	global_load_lds_dwordx4 v[226:227], off
	v_lshl_add_u64 v[226:227], s[0:1], 0, v[132:133]
	s_mov_b32 m0, s40
	s_nop 0
	global_load_lds_dwordx4 v[226:227], off
	s_waitcnt vmcnt(8)
	s_waitcnt lgkmcnt(0)
	s_barrier
	s_setprio 1
	v_mfma_f32_16x16x32_bf16 v[126:129], v[148:151], v[186:189], v[126:129]
	v_mfma_f32_16x16x32_bf16 v[126:129], v[152:155], v[190:193], v[126:129]
	v_mfma_f32_16x16x32_bf16 v[118:121], v[156:159], v[186:189], v[118:121]
	v_mfma_f32_16x16x32_bf16 v[118:121], v[160:163], v[190:193], v[118:121]
	v_mfma_f32_16x16x32_bf16 v[110:113], v[148:151], v[194:197], v[110:113]
	v_mfma_f32_16x16x32_bf16 v[110:113], v[152:155], v[198:201], v[110:113]
	v_mfma_f32_16x16x32_bf16 v[102:105], v[156:159], v[194:197], v[102:105]
	v_mfma_f32_16x16x32_bf16 v[102:105], v[160:163], v[198:201], v[102:105]
	v_mfma_f32_16x16x32_bf16 v[94:97], v[148:151], v[202:205], v[94:97]
	v_mfma_f32_16x16x32_bf16 v[94:97], v[152:155], v[206:209], v[94:97]
	v_mfma_f32_16x16x32_bf16 v[86:89], v[156:159], v[202:205], v[86:89]
	v_mfma_f32_16x16x32_bf16 v[86:89], v[160:163], v[206:209], v[86:89]
	v_mfma_f32_16x16x32_bf16 v[78:81], v[148:151], v[210:213], v[78:81]
	v_mfma_f32_16x16x32_bf16 v[78:81], v[152:155], v[214:217], v[78:81]
	v_mfma_f32_16x16x32_bf16 v[70:73], v[156:159], v[210:213], v[70:73]
	v_mfma_f32_16x16x32_bf16 v[70:73], v[160:163], v[214:217], v[70:73]
	s_setprio 0
	s_setprio 1
	v_mfma_f32_16x16x32_bf16 v[122:125], v[170:173], v[186:189], v[122:125]
	v_mfma_f32_16x16x32_bf16 v[122:125], v[174:177], v[190:193], v[122:125]
	v_mfma_f32_16x16x32_bf16 v[114:117], v[178:181], v[186:189], v[114:117]
	v_mfma_f32_16x16x32_bf16 v[114:117], v[182:185], v[190:193], v[114:117]
	v_mfma_f32_16x16x32_bf16 v[106:109], v[170:173], v[194:197], v[106:109]
	v_mfma_f32_16x16x32_bf16 v[106:109], v[174:177], v[198:201], v[106:109]
	v_mfma_f32_16x16x32_bf16 v[98:101], v[178:181], v[194:197], v[98:101]
	v_mfma_f32_16x16x32_bf16 v[98:101], v[182:185], v[198:201], v[98:101]
	v_mfma_f32_16x16x32_bf16 v[90:93], v[170:173], v[202:205], v[90:93]
	v_mfma_f32_16x16x32_bf16 v[90:93], v[174:177], v[206:209], v[90:93]
	v_mfma_f32_16x16x32_bf16 v[82:85], v[178:181], v[202:205], v[82:85]
	v_mfma_f32_16x16x32_bf16 v[82:85], v[182:185], v[206:209], v[82:85]
	v_mfma_f32_16x16x32_bf16 v[74:77], v[170:173], v[210:213], v[74:77]
	v_mfma_f32_16x16x32_bf16 v[74:77], v[174:177], v[214:217], v[74:77]
	v_mfma_f32_16x16x32_bf16 v[66:69], v[178:181], v[210:213], v[66:69]
	v_mfma_f32_16x16x32_bf16 v[66:69], v[182:185], v[214:217], v[66:69]
	s_setprio 0
	s_barrier
	s_add_i32 s0, s54, s35
	v_lshl_add_u64 v[218:219], v[218:219], 0, s[14:15]
	s_mov_b32 m0, s0
	ds_read_b128 v[186:189], v167 offset:49152
	ds_read_b128 v[190:193], v167 offset:50176
	ds_read_b128 v[194:197], v167 offset:51200
	ds_read_b128 v[198:201], v167 offset:52224
	ds_read_b128 v[202:205], v167 offset:53248
	ds_read_b128 v[206:209], v167 offset:54272
	ds_read_b128 v[210:213], v167 offset:55296
	ds_read_b128 v[214:217], v167 offset:56320
	global_load_lds_dwordx4 v[218:219], off
	s_add_i32 m0, s0, 0x2000
	s_add_u32 s0, s2, 0x40080
	v_lshl_add_u64 v[218:219], v[220:221], 0, s[14:15]
	s_addc_u32 s1, s3, 0
	s_add_i32 s2, s55, s35
	global_load_lds_dwordx4 v[218:219], off
	v_lshl_add_u64 v[218:219], s[0:1], 0, v[134:135]
	s_mov_b32 m0, s2
	s_nop 0
	global_load_lds_dwordx4 v[218:219], off
	v_lshl_add_u64 v[218:219], s[0:1], 0, v[130:131]
	s_add_i32 m0, s2, 0x2000
	s_nop 0
	global_load_lds_dwordx4 v[218:219], off
	v_lshl_add_u64 v[218:219], v[222:223], 0, s[14:15]
	s_mov_b32 m0, s41
	s_nop 0
	global_load_lds_dwordx4 v[218:219], off
	v_lshl_add_u64 v[218:219], v[224:225], 0, s[14:15]
	s_mov_b32 m0, s42
	s_nop 0
	global_load_lds_dwordx4 v[218:219], off
	s_waitcnt vmcnt(8)
	s_waitcnt lgkmcnt(0)
	s_barrier
	s_setprio 1
	v_mfma_f32_16x16x32_bf16 v[62:65], v[148:151], v[186:189], v[62:65]
	v_mfma_f32_16x16x32_bf16 v[62:65], v[152:155], v[190:193], v[62:65]
	v_mfma_f32_16x16x32_bf16 v[54:57], v[156:159], v[186:189], v[54:57]
	v_mfma_f32_16x16x32_bf16 v[54:57], v[160:163], v[190:193], v[54:57]
	v_mfma_f32_16x16x32_bf16 v[46:49], v[148:151], v[194:197], v[46:49]
	v_mfma_f32_16x16x32_bf16 v[46:49], v[152:155], v[198:201], v[46:49]
	v_mfma_f32_16x16x32_bf16 v[38:41], v[156:159], v[194:197], v[38:41]
	v_mfma_f32_16x16x32_bf16 v[38:41], v[160:163], v[198:201], v[38:41]
	v_mfma_f32_16x16x32_bf16 v[30:33], v[148:151], v[202:205], v[30:33]
	v_mfma_f32_16x16x32_bf16 v[30:33], v[152:155], v[206:209], v[30:33]
	v_mfma_f32_16x16x32_bf16 v[22:25], v[156:159], v[202:205], v[22:25]
	v_mfma_f32_16x16x32_bf16 v[22:25], v[160:163], v[206:209], v[22:25]
	v_mfma_f32_16x16x32_bf16 v[14:17], v[148:151], v[210:213], v[14:17]
	v_mfma_f32_16x16x32_bf16 v[14:17], v[152:155], v[214:217], v[14:17]
	v_mfma_f32_16x16x32_bf16 v[6:9], v[156:159], v[210:213], v[6:9]
	v_mfma_f32_16x16x32_bf16 v[6:9], v[160:163], v[214:217], v[6:9]
	s_setprio 0
	s_setprio 1
	v_mfma_f32_16x16x32_bf16 v[58:61], v[170:173], v[186:189], v[58:61]
	v_mfma_f32_16x16x32_bf16 v[58:61], v[174:177], v[190:193], v[58:61]
	v_mfma_f32_16x16x32_bf16 v[50:53], v[178:181], v[186:189], v[50:53]
	v_mfma_f32_16x16x32_bf16 v[50:53], v[182:185], v[190:193], v[50:53]
	v_mfma_f32_16x16x32_bf16 v[42:45], v[170:173], v[194:197], v[42:45]
	v_mfma_f32_16x16x32_bf16 v[42:45], v[174:177], v[198:201], v[42:45]
	v_mfma_f32_16x16x32_bf16 v[34:37], v[178:181], v[194:197], v[34:37]
	v_mfma_f32_16x16x32_bf16 v[34:37], v[182:185], v[198:201], v[34:37]
	v_mfma_f32_16x16x32_bf16 v[26:29], v[170:173], v[202:205], v[26:29]
	v_mfma_f32_16x16x32_bf16 v[26:29], v[174:177], v[206:209], v[26:29]
	v_mfma_f32_16x16x32_bf16 v[18:21], v[178:181], v[202:205], v[18:21]
	v_mfma_f32_16x16x32_bf16 v[18:21], v[182:185], v[206:209], v[18:21]
	v_mfma_f32_16x16x32_bf16 v[10:13], v[170:173], v[210:213], v[10:13]
	v_mfma_f32_16x16x32_bf16 v[10:13], v[174:177], v[214:217], v[10:13]
	v_mfma_f32_16x16x32_bf16 v[2:5], v[178:181], v[210:213], v[2:5]
	v_mfma_f32_16x16x32_bf16 v[2:5], v[182:185], v[214:217], v[2:5]
	s_setprio 0
	s_barrier
	s_add_i32 s53, s53, 2
	s_add_u32 s28, s28, 0x100
	s_addc_u32 s29, s29, 0
	s_add_u32 s51, s51, 0x100
	s_addc_u32 s52, s52, 0
	s_cmp_gt_u32 s53, 13
	s_cbranch_scc0 .LBB0_2207
	s_and_b64 vcc, exec, s[16:17]
	s_cbranch_vccz .LBB0_2210
	s_barrier

.LBB0_2289:
	s_add_u32 s16, s16, 0xb0080
	s_addc_u32 s17, s17, 0
	s_add_u32 s41, s2, 0x100
	v_mov_b32_e32 v0, 0
	s_addc_u32 s42, s3, 0
	s_mov_b32 s43, -2
	v_mov_b32_e32 v1, v0
	v_mov_b32_e32 v2, v0
	v_mov_b32_e32 v3, v0
	v_mov_b32_e32 v4, v0
	v_mov_b32_e32 v5, v0
	v_mov_b32_e32 v6, v0
	v_mov_b32_e32 v7, v0
	v_mov_b32_e32 v12, v0
	v_mov_b32_e32 v13, v0
	v_mov_b32_e32 v14, v0
	v_mov_b32_e32 v15, v0
	v_mov_b32_e32 v20, v0
	v_mov_b32_e32 v21, v0
	v_mov_b32_e32 v22, v0
	v_mov_b32_e32 v23, v0
	v_mov_b32_e32 v28, v0
	v_mov_b32_e32 v29, v0
	v_mov_b32_e32 v30, v0
	v_mov_b32_e32 v31, v0
	v_mov_b32_e32 v36, v0
	v_mov_b32_e32 v37, v0
	v_mov_b32_e32 v38, v0
	v_mov_b32_e32 v39, v0
	v_mov_b32_e32 v44, v0
	v_mov_b32_e32 v45, v0
	v_mov_b32_e32 v46, v0
	v_mov_b32_e32 v47, v0
	v_mov_b32_e32 v52, v0
	v_mov_b32_e32 v53, v0
	v_mov_b32_e32 v54, v0
	v_mov_b32_e32 v55, v0
	v_mov_b32_e32 v8, v0
	v_mov_b32_e32 v9, v0
	v_mov_b32_e32 v10, v0
	v_mov_b32_e32 v11, v0
	v_mov_b32_e32 v16, v0
	v_mov_b32_e32 v17, v0
	v_mov_b32_e32 v18, v0
	v_mov_b32_e32 v19, v0
	v_mov_b32_e32 v24, v0
	v_mov_b32_e32 v25, v0
	v_mov_b32_e32 v26, v0
	v_mov_b32_e32 v27, v0
	v_mov_b32_e32 v32, v0
	v_mov_b32_e32 v33, v0
	v_mov_b32_e32 v34, v0
	v_mov_b32_e32 v35, v0
	v_mov_b32_e32 v40, v0
	v_mov_b32_e32 v41, v0
	v_mov_b32_e32 v42, v0
	v_mov_b32_e32 v43, v0
	v_mov_b32_e32 v48, v0
	v_mov_b32_e32 v49, v0
	v_mov_b32_e32 v50, v0
	v_mov_b32_e32 v51, v0
	v_mov_b32_e32 v56, v0
	v_mov_b32_e32 v57, v0
	v_mov_b32_e32 v58, v0
	v_mov_b32_e32 v59, v0
	v_mov_b32_e32 v60, v0
	v_mov_b32_e32 v61, v0
	v_mov_b32_e32 v62, v0
	v_mov_b32_e32 v63, v0
	v_mov_b32_e32 v64, v0
	v_mov_b32_e32 v65, v0
	v_mov_b32_e32 v66, v0
	v_mov_b32_e32 v67, v0
	v_mov_b32_e32 v68, v0
	v_mov_b32_e32 v69, v0
	v_mov_b32_e32 v70, v0
	v_mov_b32_e32 v71, v0
	v_mov_b32_e32 v76, v0
	v_mov_b32_e32 v77, v0
	v_mov_b32_e32 v78, v0
	v_mov_b32_e32 v79, v0
	v_mov_b32_e32 v84, v0
	v_mov_b32_e32 v85, v0
	v_mov_b32_e32 v86, v0
	v_mov_b32_e32 v87, v0
	v_mov_b32_e32 v92, v0
	v_mov_b32_e32 v93, v0
	v_mov_b32_e32 v94, v0
	v_mov_b32_e32 v95, v0
	v_mov_b32_e32 v100, v0
	v_mov_b32_e32 v101, v0
	v_mov_b32_e32 v102, v0
	v_mov_b32_e32 v103, v0
	v_mov_b32_e32 v108, v0
	v_mov_b32_e32 v109, v0
	v_mov_b32_e32 v110, v0
	v_mov_b32_e32 v111, v0
	v_mov_b32_e32 v116, v0
	v_mov_b32_e32 v117, v0
	v_mov_b32_e32 v118, v0
	v_mov_b32_e32 v119, v0
	v_mov_b32_e32 v72, v0
	v_mov_b32_e32 v73, v0
	v_mov_b32_e32 v74, v0
	v_mov_b32_e32 v75, v0
	v_mov_b32_e32 v80, v0
	v_mov_b32_e32 v81, v0
	v_mov_b32_e32 v82, v0
	v_mov_b32_e32 v83, v0
	v_mov_b32_e32 v88, v0
	v_mov_b32_e32 v89, v0
	v_mov_b32_e32 v90, v0
	v_mov_b32_e32 v91, v0
	v_mov_b32_e32 v96, v0
	v_mov_b32_e32 v97, v0
	v_mov_b32_e32 v98, v0
	v_mov_b32_e32 v99, v0
	v_mov_b32_e32 v104, v0
	v_mov_b32_e32 v105, v0
	v_mov_b32_e32 v106, v0
	v_mov_b32_e32 v107, v0
	v_mov_b32_e32 v112, v0
	v_mov_b32_e32 v113, v0
	v_mov_b32_e32 v114, v0
	v_mov_b32_e32 v115, v0
	v_mov_b32_e32 v120, v0
	v_mov_b32_e32 v121, v0
	v_mov_b32_e32 v122, v0
	v_mov_b32_e32 v123, v0
	v_mov_b32_e32 v124, v0
	v_mov_b32_e32 v125, v0
	v_mov_b32_e32 v126, v0
	v_mov_b32_e32 v127, v0
	s_nop 0
	s_nop 0
	s_nop 0
	s_nop 0
	s_nop 0
	s_nop 0
	s_nop 0
	s_nop 0
	s_nop 0
	s_nop 0
	s_nop 0
	s_nop 0
	s_nop 0
	s_nop 0
	s_nop 0
.LBB0_2290:
	ds_read_b128 v[144:147], v153
	ds_read_b128 v[156:159], v153 offset:1024
	ds_read_b128 v[160:163], v153 offset:2048
	ds_read_b128 v[164:167], v153 offset:3072
	ds_read_b128 v[168:171], v154
	ds_read_b128 v[172:175], v154 offset:1024
	ds_read_b128 v[176:179], v154 offset:2048
	ds_read_b128 v[180:183], v154 offset:3072
	s_add_u32 s2, s16, 0xfff50080
	s_addc_u32 s3, s17, -1
	s_cmp_eq_u32 s43, 40
	s_cselect_b32 s19, s5, s3
	s_cselect_b32 s18, s4, s2
	s_cselect_b32 s3, s15, s42
	s_cselect_b32 s2, s14, s41
	v_lshl_add_u64 v[148:149], s[16:17], 0, v[136:137]
	s_add_i32 m0, s26, 0xc000
	ds_read_b128 v[184:187], v155
	ds_read_b128 v[188:191], v155 offset:1024
	ds_read_b128 v[192:195], v155 offset:2048
	ds_read_b128 v[196:199], v155 offset:3072
	ds_read_b128 v[200:203], v155 offset:4096
	ds_read_b128 v[204:207], v155 offset:5120
	ds_read_b128 v[208:211], v155 offset:6144
	ds_read_b128 v[212:215], v155 offset:7168
	global_load_lds_dwordx4 v[148:149], off
	v_lshl_add_u64 v[148:149], s[16:17], 0, v[138:139]
	s_add_i32 m0, s26, 0xe000
	s_nop 0
	global_load_lds_dwordx4 v[148:149], off
	s_waitcnt vmcnt(8)
	s_waitcnt lgkmcnt(0)
	s_barrier
	s_setprio 1
	v_mfma_f32_16x16x32_bf16 v[124:127], v[144:147], v[184:187], v[124:127]
	v_mfma_f32_16x16x32_bf16 v[124:127], v[156:159], v[188:191], v[124:127]
	v_mfma_f32_16x16x32_bf16 v[120:123], v[160:163], v[184:187], v[120:123]
	v_mfma_f32_16x16x32_bf16 v[120:123], v[164:167], v[188:191], v[120:123]
	v_mfma_f32_16x16x32_bf16 v[112:115], v[144:147], v[192:195], v[112:115]
	v_mfma_f32_16x16x32_bf16 v[112:115], v[156:159], v[196:199], v[112:115]
	v_mfma_f32_16x16x32_bf16 v[104:107], v[160:163], v[192:195], v[104:107]
	v_mfma_f32_16x16x32_bf16 v[104:107], v[164:167], v[196:199], v[104:107]
	v_mfma_f32_16x16x32_bf16 v[96:99], v[144:147], v[200:203], v[96:99]
	v_mfma_f32_16x16x32_bf16 v[96:99], v[156:159], v[204:207], v[96:99]
	v_mfma_f32_16x16x32_bf16 v[88:91], v[160:163], v[200:203], v[88:91]
	v_mfma_f32_16x16x32_bf16 v[88:91], v[164:167], v[204:207], v[88:91]
	v_mfma_f32_16x16x32_bf16 v[80:83], v[144:147], v[208:211], v[80:83]
	v_mfma_f32_16x16x32_bf16 v[80:83], v[156:159], v[212:215], v[80:83]
	v_mfma_f32_16x16x32_bf16 v[72:75], v[160:163], v[208:211], v[72:75]
	v_mfma_f32_16x16x32_bf16 v[72:75], v[164:167], v[212:215], v[72:75]
	s_setprio 0
	s_setprio 1
	v_mfma_f32_16x16x32_bf16 v[116:119], v[168:171], v[184:187], v[116:119]
	v_mfma_f32_16x16x32_bf16 v[116:119], v[172:175], v[188:191], v[116:119]
	v_mfma_f32_16x16x32_bf16 v[108:111], v[176:179], v[184:187], v[108:111]
	v_mfma_f32_16x16x32_bf16 v[108:111], v[180:183], v[188:191], v[108:111]
	v_mfma_f32_16x16x32_bf16 v[100:103], v[168:171], v[192:195], v[100:103]
	v_mfma_f32_16x16x32_bf16 v[100:103], v[172:175], v[196:199], v[100:103]
	v_mfma_f32_16x16x32_bf16 v[92:95], v[176:179], v[192:195], v[92:95]
	v_mfma_f32_16x16x32_bf16 v[92:95], v[180:183], v[196:199], v[92:95]
	v_mfma_f32_16x16x32_bf16 v[84:87], v[168:171], v[200:203], v[84:87]
	v_mfma_f32_16x16x32_bf16 v[84:87], v[172:175], v[204:207], v[84:87]
	v_mfma_f32_16x16x32_bf16 v[76:79], v[176:179], v[200:203], v[76:79]
	v_mfma_f32_16x16x32_bf16 v[76:79], v[180:183], v[204:207], v[76:79]
	v_mfma_f32_16x16x32_bf16 v[68:71], v[168:171], v[208:211], v[68:71]
	v_mfma_f32_16x16x32_bf16 v[68:71], v[172:175], v[212:215], v[68:71]
	v_mfma_f32_16x16x32_bf16 v[64:67], v[176:179], v[208:211], v[64:67]
	v_mfma_f32_16x16x32_bf16 v[64:67], v[180:183], v[212:215], v[64:67]
	s_setprio 0
	s_barrier
	s_add_i32 s44, s35, s25
	v_lshl_add_u64 v[148:149], s[2:3], 0, v[130:131]
	s_mov_b32 m0, s44
	ds_read_b128 v[184:187], v155 offset:16384
	ds_read_b128 v[188:191], v155 offset:17408
	ds_read_b128 v[192:195], v155 offset:18432
	ds_read_b128 v[196:199], v155 offset:19456
	ds_read_b128 v[200:203], v155 offset:20480
	ds_read_b128 v[204:207], v155 offset:21504
	ds_read_b128 v[208:211], v155 offset:22528
	ds_read_b128 v[212:215], v155 offset:23552
	global_load_lds_dwordx4 v[148:149], off
	s_add_i32 m0, s44, 0x2000
	s_add_u32 s44, s2, 0xb0000
	v_lshl_add_u64 v[216:217], s[2:3], 0, v[134:135]
	s_addc_u32 s45, s3, 0
	s_add_i32 s46, s36, s25
	global_load_lds_dwordx4 v[216:217], off
	v_lshl_add_u64 v[218:219], s[44:45], 0, v[130:131]
	s_mov_b32 m0, s46
	v_lshl_add_u64 v[220:221], s[18:19], 0, v[132:133]
	global_load_lds_dwordx4 v[218:219], off
	v_lshl_add_u64 v[218:219], s[44:45], 0, v[134:135]
	s_add_i32 m0, s46, 0x2000
	s_nop 0
	global_load_lds_dwordx4 v[218:219], off
	v_lshl_add_u64 v[218:219], s[18:19], 0, v[128:129]
	s_mov_b32 m0, s26
	s_nop 0
	global_load_lds_dwordx4 v[218:219], off
	s_mov_b32 m0, s27
	s_nop 0
	global_load_lds_dwordx4 v[220:221], off
	s_waitcnt vmcnt(8)
	s_waitcnt lgkmcnt(0)
	s_barrier
	s_setprio 1
	v_mfma_f32_16x16x32_bf16 v[60:63], v[144:147], v[184:187], v[60:63]
	v_mfma_f32_16x16x32_bf16 v[60:63], v[156:159], v[188:191], v[60:63]
	v_mfma_f32_16x16x32_bf16 v[56:59], v[160:163], v[184:187], v[56:59]
	v_mfma_f32_16x16x32_bf16 v[56:59], v[164:167], v[188:191], v[56:59]
	v_mfma_f32_16x16x32_bf16 v[48:51], v[144:147], v[192:195], v[48:51]
	v_mfma_f32_16x16x32_bf16 v[48:51], v[156:159], v[196:199], v[48:51]
	v_mfma_f32_16x16x32_bf16 v[40:43], v[160:163], v[192:195], v[40:43]
	v_mfma_f32_16x16x32_bf16 v[40:43], v[164:167], v[196:199], v[40:43]
	v_mfma_f32_16x16x32_bf16 v[32:35], v[144:147], v[200:203], v[32:35]
	v_mfma_f32_16x16x32_bf16 v[32:35], v[156:159], v[204:207], v[32:35]
	v_mfma_f32_16x16x32_bf16 v[24:27], v[160:163], v[200:203], v[24:27]
	v_mfma_f32_16x16x32_bf16 v[24:27], v[164:167], v[204:207], v[24:27]
	v_mfma_f32_16x16x32_bf16 v[16:19], v[144:147], v[208:211], v[16:19]
	v_mfma_f32_16x16x32_bf16 v[16:19], v[156:159], v[212:215], v[16:19]
	v_mfma_f32_16x16x32_bf16 v[8:11], v[160:163], v[208:211], v[8:11]
	v_mfma_f32_16x16x32_bf16 v[8:11], v[164:167], v[212:215], v[8:11]
	s_setprio 0
	s_setprio 1
	v_mfma_f32_16x16x32_bf16 v[52:55], v[168:171], v[184:187], v[52:55]
	v_mfma_f32_16x16x32_bf16 v[52:55], v[172:175], v[188:191], v[52:55]
	v_mfma_f32_16x16x32_bf16 v[44:47], v[176:179], v[184:187], v[44:47]
	v_mfma_f32_16x16x32_bf16 v[44:47], v[180:183], v[188:191], v[44:47]
	v_mfma_f32_16x16x32_bf16 v[36:39], v[168:171], v[192:195], v[36:39]
	v_mfma_f32_16x16x32_bf16 v[36:39], v[172:175], v[196:199], v[36:39]
	v_mfma_f32_16x16x32_bf16 v[28:31], v[176:179], v[192:195], v[28:31]
	v_mfma_f32_16x16x32_bf16 v[28:31], v[180:183], v[196:199], v[28:31]
	v_mfma_f32_16x16x32_bf16 v[20:23], v[168:171], v[200:203], v[20:23]
	v_mfma_f32_16x16x32_bf16 v[20:23], v[172:175], v[204:207], v[20:23]
	v_mfma_f32_16x16x32_bf16 v[12:15], v[176:179], v[200:203], v[12:15]
	v_mfma_f32_16x16x32_bf16 v[12:15], v[180:183], v[204:207], v[12:15]
	v_mfma_f32_16x16x32_bf16 v[4:7], v[168:171], v[208:211], v[4:7]
	v_mfma_f32_16x16x32_bf16 v[4:7], v[172:175], v[212:215], v[4:7]
	v_mfma_f32_16x16x32_bf16 v[0:3], v[176:179], v[208:211], v[0:3]
	v_mfma_f32_16x16x32_bf16 v[0:3], v[180:183], v[212:215], v[0:3]
	s_setprio 0
	s_barrier
	s_add_i32 s44, 0, 0x18000
	s_add_i32 s45, 0, 0x1c000
	v_add_u32_e32 v164, s44, v151
	v_add_u32_e32 v180, s45, v151
	ds_read_b128 v[144:147], v164
	ds_read_b128 v[156:159], v164 offset:1024
	ds_read_b128 v[160:163], v164 offset:2048
	ds_read_b128 v[164:167], v164 offset:3072
	ds_read_b128 v[168:171], v180
	ds_read_b128 v[172:175], v180 offset:1024
	ds_read_b128 v[176:179], v180 offset:2048
	ds_read_b128 v[180:183], v180 offset:3072
	s_add_u32 s18, s18, 0xb0000
	s_addc_u32 s19, s19, 0
	s_mov_b32 m0, s28
	v_lshl_add_u64 v[222:223], s[18:19], 0, v[128:129]
	ds_read_b128 v[184:187], v155 offset:32768
	ds_read_b128 v[188:191], v155 offset:33792
	ds_read_b128 v[192:195], v155 offset:34816
	ds_read_b128 v[196:199], v155 offset:35840
	ds_read_b128 v[200:203], v155 offset:36864
	ds_read_b128 v[204:207], v155 offset:37888
	ds_read_b128 v[208:211], v155 offset:38912
	ds_read_b128 v[212:215], v155 offset:39936
	global_load_lds_dwordx4 v[222:223], off
	v_lshl_add_u64 v[222:223], s[18:19], 0, v[132:133]
	s_mov_b32 m0, s29
	s_nop 0
	global_load_lds_dwordx4 v[222:223], off
	s_waitcnt vmcnt(8)
	s_waitcnt lgkmcnt(0)
	s_barrier
	s_setprio 1
	v_mfma_f32_16x16x32_bf16 v[124:127], v[144:147], v[184:187], v[124:127]
	v_mfma_f32_16x16x32_bf16 v[124:127], v[156:159], v[188:191], v[124:127]
	v_mfma_f32_16x16x32_bf16 v[120:123], v[160:163], v[184:187], v[120:123]
	v_mfma_f32_16x16x32_bf16 v[120:123], v[164:167], v[188:191], v[120:123]
	v_mfma_f32_16x16x32_bf16 v[112:115], v[144:147], v[192:195], v[112:115]
	v_mfma_f32_16x16x32_bf16 v[112:115], v[156:159], v[196:199], v[112:115]
	v_mfma_f32_16x16x32_bf16 v[104:107], v[160:163], v[192:195], v[104:107]
	v_mfma_f32_16x16x32_bf16 v[104:107], v[164:167], v[196:199], v[104:107]
	v_mfma_f32_16x16x32_bf16 v[96:99], v[144:147], v[200:203], v[96:99]
	v_mfma_f32_16x16x32_bf16 v[96:99], v[156:159], v[204:207], v[96:99]
	v_mfma_f32_16x16x32_bf16 v[88:91], v[160:163], v[200:203], v[88:91]
	v_mfma_f32_16x16x32_bf16 v[88:91], v[164:167], v[204:207], v[88:91]
	v_mfma_f32_16x16x32_bf16 v[80:83], v[144:147], v[208:211], v[80:83]
	v_mfma_f32_16x16x32_bf16 v[80:83], v[156:159], v[212:215], v[80:83]
	v_mfma_f32_16x16x32_bf16 v[72:75], v[160:163], v[208:211], v[72:75]
	v_mfma_f32_16x16x32_bf16 v[72:75], v[164:167], v[212:215], v[72:75]
	s_setprio 0
	s_setprio 1
	v_mfma_f32_16x16x32_bf16 v[116:119], v[168:171], v[184:187], v[116:119]
	v_mfma_f32_16x16x32_bf16 v[116:119], v[172:175], v[188:191], v[116:119]
	v_mfma_f32_16x16x32_bf16 v[108:111], v[176:179], v[184:187], v[108:111]
	v_mfma_f32_16x16x32_bf16 v[108:111], v[180:183], v[188:191], v[108:111]
	v_mfma_f32_16x16x32_bf16 v[100:103], v[168:171], v[192:195], v[100:103]
	v_mfma_f32_16x16x32_bf16 v[100:103], v[172:175], v[196:199], v[100:103]
	v_mfma_f32_16x16x32_bf16 v[92:95], v[176:179], v[192:195], v[92:95]
	v_mfma_f32_16x16x32_bf16 v[92:95], v[180:183], v[196:199], v[92:95]
	v_mfma_f32_16x16x32_bf16 v[84:87], v[168:171], v[200:203], v[84:87]
	v_mfma_f32_16x16x32_bf16 v[84:87], v[172:175], v[204:207], v[84:87]
	v_mfma_f32_16x16x32_bf16 v[76:79], v[176:179], v[200:203], v[76:79]
	v_mfma_f32_16x16x32_bf16 v[76:79], v[180:183], v[204:207], v[76:79]
	v_mfma_f32_16x16x32_bf16 v[68:71], v[168:171], v[208:211], v[68:71]
	v_mfma_f32_16x16x32_bf16 v[68:71], v[172:175], v[212:215], v[68:71]
	v_mfma_f32_16x16x32_bf16 v[64:67], v[176:179], v[208:211], v[64:67]
	v_mfma_f32_16x16x32_bf16 v[64:67], v[180:183], v[212:215], v[64:67]
	s_setprio 0
	s_barrier
	s_add_i32 s18, s44, s25
	v_lshl_add_u64 v[148:149], v[148:149], 0, s[10:11]
	s_mov_b32 m0, s18
	ds_read_b128 v[184:187], v155 offset:49152
	ds_read_b128 v[188:191], v155 offset:50176
	ds_read_b128 v[192:195], v155 offset:51200
	ds_read_b128 v[196:199], v155 offset:52224
	ds_read_b128 v[200:203], v155 offset:53248
	ds_read_b128 v[204:207], v155 offset:54272
	ds_read_b128 v[208:211], v155 offset:55296
	ds_read_b128 v[212:215], v155 offset:56320
	global_load_lds_dwordx4 v[148:149], off
	s_add_i32 m0, s18, 0x2000
	s_add_u32 s2, s2, 0xb0080
	v_lshl_add_u64 v[148:149], v[216:217], 0, s[10:11]
	s_addc_u32 s3, s3, 0
	s_add_i32 s18, s45, s25
	global_load_lds_dwordx4 v[148:149], off
	v_lshl_add_u64 v[148:149], s[2:3], 0, v[130:131]
	s_mov_b32 m0, s18
	s_nop 0
	global_load_lds_dwordx4 v[148:149], off
	v_lshl_add_u64 v[148:149], s[2:3], 0, v[134:135]
	s_add_i32 m0, s18, 0x2000
	s_nop 0
	global_load_lds_dwordx4 v[148:149], off
	v_lshl_add_u64 v[148:149], v[218:219], 0, s[10:11]
	s_mov_b32 m0, s31
	s_nop 0
	global_load_lds_dwordx4 v[148:149], off
	v_lshl_add_u64 v[148:149], v[220:221], 0, s[10:11]
	s_mov_b32 m0, s33
	s_nop 0
	global_load_lds_dwordx4 v[148:149], off
	s_waitcnt vmcnt(8)
	s_waitcnt lgkmcnt(0)
	s_barrier
	s_setprio 1
	v_mfma_f32_16x16x32_bf16 v[60:63], v[144:147], v[184:187], v[60:63]
	v_mfma_f32_16x16x32_bf16 v[60:63], v[156:159], v[188:191], v[60:63]
	v_mfma_f32_16x16x32_bf16 v[56:59], v[160:163], v[184:187], v[56:59]
	v_mfma_f32_16x16x32_bf16 v[56:59], v[164:167], v[188:191], v[56:59]
	v_mfma_f32_16x16x32_bf16 v[48:51], v[144:147], v[192:195], v[48:51]
	v_mfma_f32_16x16x32_bf16 v[48:51], v[156:159], v[196:199], v[48:51]
	v_mfma_f32_16x16x32_bf16 v[40:43], v[160:163], v[192:195], v[40:43]
	v_mfma_f32_16x16x32_bf16 v[40:43], v[164:167], v[196:199], v[40:43]
	v_mfma_f32_16x16x32_bf16 v[32:35], v[144:147], v[200:203], v[32:35]
	v_mfma_f32_16x16x32_bf16 v[32:35], v[156:159], v[204:207], v[32:35]
	v_mfma_f32_16x16x32_bf16 v[24:27], v[160:163], v[200:203], v[24:27]
	v_mfma_f32_16x16x32_bf16 v[24:27], v[164:167], v[204:207], v[24:27]
	v_mfma_f32_16x16x32_bf16 v[16:19], v[144:147], v[208:211], v[16:19]
	v_mfma_f32_16x16x32_bf16 v[16:19], v[156:159], v[212:215], v[16:19]
	v_mfma_f32_16x16x32_bf16 v[8:11], v[160:163], v[208:211], v[8:11]
	v_mfma_f32_16x16x32_bf16 v[8:11], v[164:167], v[212:215], v[8:11]
	s_setprio 0
	s_setprio 1
	v_mfma_f32_16x16x32_bf16 v[52:55], v[168:171], v[184:187], v[52:55]
	v_mfma_f32_16x16x32_bf16 v[52:55], v[172:175], v[188:191], v[52:55]
	v_mfma_f32_16x16x32_bf16 v[44:47], v[176:179], v[184:187], v[44:47]
	v_mfma_f32_16x16x32_bf16 v[44:47], v[180:183], v[188:191], v[44:47]
	v_mfma_f32_16x16x32_bf16 v[36:39], v[168:171], v[192:195], v[36:39]
	v_mfma_f32_16x16x32_bf16 v[36:39], v[172:175], v[196:199], v[36:39]
	v_mfma_f32_16x16x32_bf16 v[28:31], v[176:179], v[192:195], v[28:31]
	v_mfma_f32_16x16x32_bf16 v[28:31], v[180:183], v[196:199], v[28:31]
	v_mfma_f32_16x16x32_bf16 v[20:23], v[168:171], v[200:203], v[20:23]
	v_mfma_f32_16x16x32_bf16 v[20:23], v[172:175], v[204:207], v[20:23]
	v_mfma_f32_16x16x32_bf16 v[12:15], v[176:179], v[200:203], v[12:15]
	v_mfma_f32_16x16x32_bf16 v[12:15], v[180:183], v[204:207], v[12:15]
	v_mfma_f32_16x16x32_bf16 v[4:7], v[168:171], v[208:211], v[4:7]
	v_mfma_f32_16x16x32_bf16 v[4:7], v[172:175], v[212:215], v[4:7]
	v_mfma_f32_16x16x32_bf16 v[0:3], v[176:179], v[208:211], v[0:3]
	v_mfma_f32_16x16x32_bf16 v[0:3], v[180:183], v[212:215], v[0:3]
	s_setprio 0
	s_barrier
	s_add_i32 s43, s43, 2
	s_add_u32 s16, s16, 0x100
	s_addc_u32 s17, s17, 0
	s_add_u32 s41, s41, 0x100
	s_addc_u32 s42, s42, 0
	s_cmp_gt_u32 s43, 41
	s_cbranch_scc0 .LBB0_2290
	s_and_b64 vcc, exec, s[12:13]
	s_cbranch_vccz .LBB0_2293
	s_barrier
